# stack v64 + every packed fp32 v_pk_mul_f32 / v_pk_fma_f32 (910 sites: EpiRms epilogues, attention O rescale, norms, bgemm) split into its two scalar ops (bit-identical)
# baseline (speedup 1.0000x reference)
; #define LAS __attribute__((address_space(3)))
;     __device__ __forceinline__ void fused(f32x4 (&acc)[2][2][4][2], const Unit& u, int wr, int wc, int fr, int fq, LAS unsigned char* lds, int wid, int lane) const {
;         const LAS float* S = (const LAS float*)(lds + 4096);
;         const int col0 = u.pn * BM + wc * 32 + 4 * fq;
;         stats(acc, u, wr, wc, fr, fq, lds, wid, lane, e1);
;         const bool defer = lin_in && !lin_out;
; #pragma unroll
;         for (int ai = 0; ai < 2; ++ai)
; #pragma unroll
;             for (int m = 0; m < 4; ++m) { const int r = ai * HALF + wr * 64 + m * 16 + fr; const float rs = S[r]; const int rb = ai * 8 + wr * 4 + m;
; #pragma unroll
;                 for (int bj = 0; bj < 2; ++bj)
; #pragma unroll
;                     for (int n = 0; n < 2; ++n) { const size_t orm = (size_t)(u.pm * BM + r) * D + col0 + bj * HALF + n * 16, oln = (size_t)(u.pm * BM + rb * 16 + 8 * bj + 2 * wc + n) * D + u.pn * BM + lane * 4;
;                         const f32x4 xv = *(const f32x4*)(xin + (lin_in ? oln : orm)); const f32x4 gv = *(const f32x4*)(g1 + col0 + bj * HALF + n * 16);
;                         const f32x4 o = xv + acc[ai][bj][m][n] * rs * gv; acc[ai][bj][m][n] = o; if (!defer) *(f32x4*)(x + (lin_out ? oln : orm)) = o; }
;                 asm volatile("" : "+v"(acc[ai][0][m][0]), "+v"(acc[ai][0][m][1]), "+v"(acc[ai][1][m][0]), "+v"(acc[ai][1][m][1]));
;                 asm volatile("" ::: "memory"); }
.LBB0_256:
	s_or_b64 exec, exec, s[30:31]
	v_readlane_b32 s39, v255, 14
	s_lshl_b32 s2, s20, 8
	s_add_i32 s16, s39, 5
	s_cmp_lt_u32 s16, 13
	s_cselect_b64 vcc, -1, 0
	s_and_b64 s[16:17], vcc, exec
	v_readlane_b32 s16, v255, 22
	s_cselect_b32 s35, s42, s27
	s_cselect_b32 s34, s41, s26
	v_readlane_b32 s17, v255, 23
	s_lshl_b32 s16, s16, 10
	s_ashr_i32 s17, s16, 31
	s_lshl_b64 s[30:31], s[16:17], 2
	s_add_u32 s70, s69, s30
	v_lshrrev_b32_e32 v132, 2, v156
	s_addc_u32 s71, s79, s31
	s_lshl_b32 s16, s95, 1
	v_and_b32_e32 v132, 12, v132
	s_or_b32 s16, s0, s16
	v_lshl_or_b32 v132, s95, 5, v132
	v_add_u32_e32 v148, s0, v157
	s_add_i32 s36, s16, s94
	v_or_b32_e32 v146, s2, v132
	s_ashr_i32 s17, s2, 31
	v_ashrrev_i32_e32 v149, 31, v148
	s_ashr_i32 s37, s36, 31
	v_ashrrev_i32_e32 v147, 31, v146
	v_lshl_or_b32 v154, v3, 2, s2
	v_mov_b32_e32 v155, s17
	v_lshlrev_b64 v[132:133], 10, v[148:149]
	s_lshl_b64 s[16:17], s[36:37], 10
	v_lshl_add_u32 v3, v157, 2, 0
	v_lshl_add_u64 v[152:153], v[132:133], 0, v[146:147]
	v_lshl_add_u64 v[156:157], s[16:17], 0, v[154:155]
	v_cndmask_b32_e32 v133, v157, v153, vcc
	v_cndmask_b32_e32 v132, v156, v152, vcc
	s_waitcnt lgkmcnt(0)
	s_barrier
	s_mov_b32 s94, s39
	v_lshrrev_b32_e32 v176, 8, v202
	v_bfe_u32 v177, v202, 6, 2
	v_and_b32_e32 v178, 15, v207
	v_lshrrev_b32_e32 v179, 4, v207
	s_lshl_b32 s16, s20, 10
	v_lshlrev_b32_e32 v180, 18, v176
	v_lshl_add_u32 v180, v177, 13, v180
	v_lshl_add_u32 v180, v207, 4, v180
	v_add_u32_e32 v180, s16, v180
	v_lshlrev_b32_e32 v181, 18, v176
	v_lshl_add_u32 v181, v178, 12, v181
	v_lshl_add_u32 v181, v177, 7, v181
	v_lshl_add_u32 v181, v179, 4, v181
	v_add_u32_e32 v181, s16, v181
	v_lshlrev_b32_e32 v175, 7, v177
	v_lshl_add_u32 v175, v179, 4, v175
	v_add_u32_e32 v175, s16, v175
	v_mov_b32_e32 v158, v180
	v_mov_b32_e32 v247, v181
	v_add_u32_e32 v159, 0x1000, v180
	v_add_u32_e32 v249, 0x40, v181
	v_add_u32_e32 v200, 0x8000, v180
	v_add_u32_e32 v251, 0x200, v181
	v_add_u32_e32 v201, 0x9000, v180
	v_add_u32_e32 v253, 0x240, v181
	v_cndmask_b32_e32 v247, v158, v247, vcc
	v_cndmask_b32_e32 v249, v159, v249, vcc
	v_cndmask_b32_e32 v251, v200, v251, vcc
	v_cndmask_b32_e32 v253, v201, v253, vcc
	s_lshl_b32 s16, s18, 20
	s_add_u32 s98, s34, s16
	s_addc_u32 s99, s35, 0
	s_add_u32 s100, s26, s16
	s_addc_u32 s101, s27, 0
	global_load_dwordx4 v[132:135], v175, s[70:71] offset:0
	global_load_dwordx4 v[140:143], v175, s[70:71] offset:64
	global_load_dwordx4 v[146:149], v175, s[70:71] offset:512
	global_load_dwordx4 v[150:153], v175, s[70:71] offset:576
	global_load_dwordx4 v[176:179], v247, s[98:99]
	global_load_dwordx4 v[180:183], v249, s[98:99]
	global_load_dwordx4 v[184:187], v251, s[98:99]
	global_load_dwordx4 v[188:191], v253, s[98:99]
	s_add_u32 s98, s98, 0x10000
	s_addc_u32 s99, s99, 0
	global_load_dwordx4 v[192:195], v247, s[98:99]
	global_load_dwordx4 v[196:199], v249, s[98:99]
	global_load_dwordx4 v[214:217], v251, s[98:99]
	global_load_dwordx4 v[218:221], v253, s[98:99]
	s_add_u32 s98, s98, 0x10000
	s_addc_u32 s99, s99, 0
	global_load_dwordx4 v[222:225], v247, s[98:99]
	global_load_dwordx4 v[226:229], v249, s[98:99]
	global_load_dwordx4 v[230:233], v251, s[98:99]
	global_load_dwordx4 v[234:237], v253, s[98:99]
	s_add_u32 s98, s98, 0x10000
	s_addc_u32 s99, s99, 0
	global_load_dwordx4 v[160:163], v247, s[98:99]
	global_load_dwordx4 v[164:167], v249, s[98:99]
	global_load_dwordx4 v[168:171], v251, s[98:99]
	global_load_dwordx4 v[154:157], v253, s[98:99]
	ds_read_b32 v246, v3 offset:4096
	ds_read_b32 v248, v3 offset:4160
	ds_read_b32 v250, v3 offset:4224
	ds_read_b32 v252, v3 offset:4288
	s_waitcnt lgkmcnt(3)
	v_mul_f32_e32 v64, v64, v246
	v_mul_f32_e32 v65, v65, v246
	v_mul_f32_e32 v66, v66, v246
	v_mul_f32_e32 v67, v67, v246
	v_mul_f32_e32 v72, v72, v246
	v_mul_f32_e32 v73, v73, v246
	v_mul_f32_e32 v74, v74, v246
	v_mul_f32_e32 v75, v75, v246
	v_mul_f32_e32 v76, v76, v246
	v_mul_f32_e32 v77, v77, v246
	v_mul_f32_e32 v78, v78, v246
	v_mul_f32_e32 v79, v79, v246
	v_mul_f32_e32 v84, v84, v246
	v_mul_f32_e32 v85, v85, v246
	v_mul_f32_e32 v86, v86, v246
	v_mul_f32_e32 v87, v87, v246
	s_waitcnt lgkmcnt(2)
	v_mul_f32_e32 v92, v92, v248
	v_mul_f32_e32 v93, v93, v248
	v_mul_f32_e32 v94, v94, v248
	v_mul_f32_e32 v95, v95, v248
	v_mul_f32_e32 v96, v96, v248
	v_mul_f32_e32 v97, v97, v248
	v_mul_f32_e32 v98, v98, v248
	v_mul_f32_e32 v99, v99, v248
	v_mul_f32_e32 v104, v104, v248
	v_mul_f32_e32 v105, v105, v248
	v_mul_f32_e32 v106, v106, v248
	v_mul_f32_e32 v107, v107, v248
	v_mul_f32_e32 v108, v108, v248
	v_mul_f32_e32 v109, v109, v248
	v_mul_f32_e32 v110, v110, v248
	v_mul_f32_e32 v111, v111, v248
	s_waitcnt lgkmcnt(1)
	v_mul_f32_e32 v116, v116, v250
	v_mul_f32_e32 v117, v117, v250
	v_mul_f32_e32 v118, v118, v250
	v_mul_f32_e32 v119, v119, v250
	v_mul_f32_e32 v124, v124, v250
	v_mul_f32_e32 v125, v125, v250
	v_mul_f32_e32 v126, v126, v250
	v_mul_f32_e32 v127, v127, v250
	v_mul_f32_e32 v128, v128, v250
	v_mul_f32_e32 v129, v129, v250
	v_mul_f32_e32 v130, v130, v250
	v_mul_f32_e32 v131, v131, v250
	v_mul_f32_e32 v120, v120, v250
	v_mul_f32_e32 v121, v121, v250
	v_mul_f32_e32 v122, v122, v250
	v_mul_f32_e32 v123, v123, v250
	s_waitcnt lgkmcnt(0)
	v_mul_f32_e32 v112, v112, v252
	v_mul_f32_e32 v113, v113, v252
	v_mul_f32_e32 v114, v114, v252
	v_mul_f32_e32 v115, v115, v252
	v_mul_f32_e32 v100, v100, v252
	v_mul_f32_e32 v101, v101, v252
	v_mul_f32_e32 v102, v102, v252
	v_mul_f32_e32 v103, v103, v252
	v_mul_f32_e32 v88, v88, v252
	v_mul_f32_e32 v89, v89, v252
	v_mul_f32_e32 v90, v90, v252
	v_mul_f32_e32 v91, v91, v252
	v_mul_f32_e32 v80, v80, v252
	v_mul_f32_e32 v81, v81, v252
	v_mul_f32_e32 v82, v82, v252
	v_mul_f32_e32 v83, v83, v252
	ds_read_b32 v246, v3 offset:4608
	ds_read_b32 v248, v3 offset:4672
	ds_read_b32 v250, v3 offset:4736
	ds_read_b32 v252, v3 offset:4800
	s_waitcnt lgkmcnt(3)
;     __device__ __forceinline__ void fused(f32x4 (&acc)[2][2][4][2], const Unit& u, int wr, int wc, int fr, int fq, LAS unsigned char* lds, int wid, int lane) const {
;     ...
;         for (int ai = 0; ai < 2; ++ai)
; #pragma unroll
;             for (int m = 0; m < 4; ++m) { const int r = ai * HALF + wr * 64 + m * 16 + fr; const float rs = S[r]; const int rb = ai * 8 + wr * 4 + m;
; #pragma unroll
;                 for (int bj = 0; bj < 2; ++bj)
; #pragma unroll
;                     for (int n = 0; n < 2; ++n) { const size_t orm = (size_t)(u.pm * BM + r) * D + col0 + bj * HALF + n * 16, oln = (size_t)(u.pm * BM + rb * 16 + 8 * bj + 2 * wc + n) * D + u.pn * BM + lane * 4;
;                         const f32x4 xv = *(const f32x4*)(xin + (lin_in ? oln : orm)); const f32x4 gv = *(const f32x4*)(g1 + col0 + bj * HALF + n * 16);
;                         const f32x4 o = xv + acc[ai][bj][m][n] * rs * gv; acc[ai][bj][m][n] = o; if (!defer) *(f32x4*)(x + (lin_out ? oln : orm)) = o; }
;                 asm volatile("" : "+v"(acc[ai][0][m][0]), "+v"(acc[ai][0][m][1]), "+v"(acc[ai][1][m][0]), "+v"(acc[ai][1][m][1]));
;                 asm volatile("" ::: "memory"); }
	v_mul_f32_e32 v68, v68, v246
	v_mul_f32_e32 v69, v69, v246
	v_mul_f32_e32 v70, v70, v246
	v_mul_f32_e32 v71, v71, v246
	v_mul_f32_e32 v60, v60, v246
	v_mul_f32_e32 v61, v61, v246
	v_mul_f32_e32 v62, v62, v246
	v_mul_f32_e32 v63, v63, v246
	v_mul_f32_e32 v56, v56, v246
	v_mul_f32_e32 v57, v57, v246
	v_mul_f32_e32 v58, v58, v246
	v_mul_f32_e32 v59, v59, v246
	v_mul_f32_e32 v52, v52, v246
	v_mul_f32_e32 v53, v53, v246
	v_mul_f32_e32 v54, v54, v246
	v_mul_f32_e32 v55, v55, v246
	s_waitcnt lgkmcnt(2)
	v_mul_f32_e32 v48, v48, v248
	v_mul_f32_e32 v49, v49, v248
	v_mul_f32_e32 v50, v50, v248
	v_mul_f32_e32 v51, v51, v248
	v_mul_f32_e32 v44, v44, v248
	v_mul_f32_e32 v45, v45, v248
	v_mul_f32_e32 v46, v46, v248
	v_mul_f32_e32 v47, v47, v248
	v_mul_f32_e32 v40, v40, v248
	v_mul_f32_e32 v41, v41, v248
	v_mul_f32_e32 v42, v42, v248
	v_mul_f32_e32 v43, v43, v248
	v_mul_f32_e32 v36, v36, v248
	v_mul_f32_e32 v37, v37, v248
	v_mul_f32_e32 v38, v38, v248
	v_mul_f32_e32 v39, v39, v248
	s_waitcnt lgkmcnt(1)
	v_mul_f32_e32 v32, v32, v250
	v_mul_f32_e32 v33, v33, v250
	v_mul_f32_e32 v34, v34, v250
	v_mul_f32_e32 v35, v35, v250
	v_mul_f32_e32 v28, v28, v250
	v_mul_f32_e32 v29, v29, v250
	v_mul_f32_e32 v30, v30, v250
	v_mul_f32_e32 v31, v31, v250
	v_mul_f32_e32 v24, v24, v250
	v_mul_f32_e32 v25, v25, v250
	v_mul_f32_e32 v26, v26, v250
	v_mul_f32_e32 v27, v27, v250
	v_mul_f32_e32 v20, v20, v250
	v_mul_f32_e32 v21, v21, v250
	v_mul_f32_e32 v22, v22, v250
	v_mul_f32_e32 v23, v23, v250
	s_waitcnt lgkmcnt(0)
	v_mul_f32_e32 v16, v16, v252
	v_mul_f32_e32 v17, v17, v252
	v_mul_f32_e32 v18, v18, v252
	v_mul_f32_e32 v19, v19, v252
	v_mul_f32_e32 v12, v12, v252
	v_mul_f32_e32 v13, v13, v252
	v_mul_f32_e32 v14, v14, v252
	v_mul_f32_e32 v15, v15, v252
	v_mul_f32_e32 v8, v8, v252
	v_mul_f32_e32 v9, v9, v252
	v_mul_f32_e32 v10, v10, v252
	v_mul_f32_e32 v11, v11, v252
	v_mul_f32_e32 v4, v4, v252
	v_mul_f32_e32 v5, v5, v252
	v_mul_f32_e32 v6, v6, v252
	v_mul_f32_e32 v7, v7, v252
	s_waitcnt vmcnt(15)
	v_fma_f32 v64, v132, v64, v176
	v_fma_f32 v65, v133, v65, v177
	v_fma_f32 v66, v134, v66, v178
	v_fma_f32 v67, v135, v67, v179
	global_store_dwordx4 v158, v[64:67], s[100:101]
	s_add_u32 s98, s98, 0x50000
	s_addc_u32 s99, s99, 0
	global_load_dwordx4 v[176:179], v247, s[98:99]
	s_waitcnt vmcnt(16)
	v_fma_f32 v72, v140, v72, v180
	v_fma_f32 v73, v141, v73, v181
	v_fma_f32 v74, v142, v74, v182
	v_fma_f32 v75, v143, v75, v183
	global_store_dwordx4 v159, v[72:75], s[100:101]
	global_load_dwordx4 v[180:183], v249, s[98:99]
	s_waitcnt vmcnt(17)
	v_fma_f32 v76, v146, v76, v184
	v_fma_f32 v77, v147, v77, v185
	v_fma_f32 v78, v148, v78, v186
	v_fma_f32 v79, v149, v79, v187
	global_store_dwordx4 v200, v[76:79], s[100:101]
	global_load_dwordx4 v[184:187], v251, s[98:99]
	s_waitcnt vmcnt(18)
	v_fma_f32 v84, v150, v84, v188
	v_fma_f32 v85, v151, v85, v189
	v_fma_f32 v86, v152, v86, v190
	v_fma_f32 v87, v153, v87, v191
	global_store_dwordx4 v201, v[84:87], s[100:101]
	global_load_dwordx4 v[188:191], v253, s[98:99]
	s_waitcnt vmcnt(19)
	v_fma_f32 v92, v132, v92, v192
	v_fma_f32 v93, v133, v93, v193
	v_fma_f32 v94, v134, v94, v194
	v_fma_f32 v95, v135, v95, v195
	s_add_u32 s100, s100, 0x10000
	s_addc_u32 s101, s101, 0
	global_store_dwordx4 v158, v[92:95], s[100:101]
	s_add_u32 s98, s98, 0x10000
	s_addc_u32 s99, s99, 0
	global_load_dwordx4 v[192:195], v247, s[98:99]
	s_waitcnt vmcnt(20)
	v_fma_f32 v96, v140, v96, v196
	v_fma_f32 v97, v141, v97, v197
	v_fma_f32 v98, v142, v98, v198
	v_fma_f32 v99, v143, v99, v199
	global_store_dwordx4 v159, v[96:99], s[100:101]
	global_load_dwordx4 v[196:199], v249, s[98:99]
	s_waitcnt vmcnt(21)
	v_fma_f32 v104, v146, v104, v214
	v_fma_f32 v105, v147, v105, v215
	v_fma_f32 v106, v148, v106, v216
	v_fma_f32 v107, v149, v107, v217
	global_store_dwordx4 v200, v[104:107], s[100:101]
	global_load_dwordx4 v[214:217], v251, s[98:99]
	s_waitcnt vmcnt(22)
	v_fma_f32 v108, v150, v108, v218
	v_fma_f32 v109, v151, v109, v219
	v_fma_f32 v110, v152, v110, v220
	v_fma_f32 v111, v153, v111, v221
	global_store_dwordx4 v201, v[108:111], s[100:101]
	global_load_dwordx4 v[218:221], v253, s[98:99]
	s_waitcnt vmcnt(23)
	v_fma_f32 v116, v132, v116, v222
	v_fma_f32 v117, v133, v117, v223
	v_fma_f32 v118, v134, v118, v224
	v_fma_f32 v119, v135, v119, v225
	s_add_u32 s100, s100, 0x10000
	s_addc_u32 s101, s101, 0
	global_store_dwordx4 v158, v[116:119], s[100:101]
	s_add_u32 s98, s98, 0x10000
	s_addc_u32 s99, s99, 0
	global_load_dwordx4 v[222:225], v247, s[98:99]
	s_waitcnt vmcnt(24)
	v_fma_f32 v124, v140, v124, v226
	v_fma_f32 v125, v141, v125, v227
	v_fma_f32 v126, v142, v126, v228
	v_fma_f32 v127, v143, v127, v229
	global_store_dwordx4 v159, v[124:127], s[100:101]
	global_load_dwordx4 v[226:229], v249, s[98:99]
	s_waitcnt vmcnt(25)
	v_fma_f32 v128, v146, v128, v230
	v_fma_f32 v129, v147, v129, v231
	v_fma_f32 v130, v148, v130, v232
	v_fma_f32 v131, v149, v131, v233
	global_store_dwordx4 v200, v[128:131], s[100:101]
	global_load_dwordx4 v[230:233], v251, s[98:99]
	s_waitcnt vmcnt(26)
	v_fma_f32 v120, v150, v120, v234
	v_fma_f32 v121, v151, v121, v235
	v_fma_f32 v122, v152, v122, v236
	v_fma_f32 v123, v153, v123, v237
	global_store_dwordx4 v201, v[120:123], s[100:101]
	global_load_dwordx4 v[234:237], v253, s[98:99]
	s_waitcnt vmcnt(27)
;     __device__ __forceinline__ void stats(const f32x4 (&v)[2][2][4][2], const Unit& u, int wr, int wc, int fr, int fq, LAS unsigned char* lds, int wid, int lane, const RmsX& e) const {
;     ...
;             for (int m = 0; m < 4; ++m) { float s = 0.f;
; #pragma unroll
;                 for (int bj = 0; bj < 2; ++bj)
; #pragma unroll
;                     for (int n = 0; n < 2; ++n) { const f32x4 t = v[ai][bj][m][n]; s += (t[0] * t[0] + t[1] * t[1]) + (t[2] * t[2] + t[3] * t[3]); }
;                 s += __shfl_xor(s, 16); s += __shfl_xor(s, 32);
;                 if (fq == 0) P[(ai * HALF + wr * 64 + m * 16 + fr) * 4 + wc] = s; }
;     __device__ __forceinline__ void fused(f32x4 (&acc)[2][2][4][2], const Unit& u, int wr, int wc, int fr, int fq, LAS unsigned char* lds, int wid, int lane) const {
;     ...
;             for (int m = 0; m < 4; ++m) { const int r = ai * HALF + wr * 64 + m * 16 + fr; const float rs = S[r]; const int rb = ai * 8 + wr * 4 + m;
; #pragma unroll
;                 for (int bj = 0; bj < 2; ++bj)
; #pragma unroll
;                     for (int n = 0; n < 2; ++n) { const size_t orm = (size_t)(u.pm * BM + r) * D + col0 + bj * HALF + n * 16, oln = (size_t)(u.pm * BM + rb * 16 + 8 * bj + 2 * wc + n) * D + u.pn * BM + lane * 4;
;                         const f32x4 xv = *(const f32x4*)(xin + (lin_in ? oln : orm)); const f32x4 gv = *(const f32x4*)(g1 + col0 + bj * HALF + n * 16);
;                         const f32x4 o = xv + acc[ai][bj][m][n] * rs * gv; acc[ai][bj][m][n] = o; if (!defer) *(f32x4*)(x + (lin_out ? oln : orm)) = o; }
;                 asm volatile("" : "+v"(acc[ai][0][m][0]), "+v"(acc[ai][0][m][1]), "+v"(acc[ai][1][m][0]), "+v"(acc[ai][1][m][1]));
;                 asm volatile("" ::: "memory"); }
	v_fma_f32 v112, v132, v112, v160
	v_fma_f32 v113, v133, v113, v161
	v_fma_f32 v114, v134, v114, v162
	v_fma_f32 v115, v135, v115, v163
	s_add_u32 s100, s100, 0x10000
	s_addc_u32 s101, s101, 0
	global_store_dwordx4 v158, v[112:115], s[100:101]
	s_add_u32 s98, s98, 0x10000
	s_addc_u32 s99, s99, 0
	global_load_dwordx4 v[160:163], v247, s[98:99]
	s_waitcnt vmcnt(28)
	v_fma_f32 v100, v140, v100, v164
	v_fma_f32 v101, v141, v101, v165
	v_fma_f32 v102, v142, v102, v166
	v_fma_f32 v103, v143, v103, v167
	global_store_dwordx4 v159, v[100:103], s[100:101]
	global_load_dwordx4 v[164:167], v249, s[98:99]
	s_waitcnt vmcnt(29)
	v_fma_f32 v88, v146, v88, v168
	v_fma_f32 v89, v147, v89, v169
	v_fma_f32 v90, v148, v90, v170
	v_fma_f32 v91, v149, v91, v171
	global_store_dwordx4 v200, v[88:91], s[100:101]
	global_load_dwordx4 v[168:171], v251, s[98:99]
	s_waitcnt vmcnt(30)
	v_fma_f32 v80, v150, v80, v154
	v_fma_f32 v81, v151, v81, v155
	v_fma_f32 v82, v152, v82, v156
	v_fma_f32 v83, v153, v83, v157
	global_store_dwordx4 v201, v[80:83], s[100:101]
	global_load_dwordx4 v[154:157], v253, s[98:99]
	s_waitcnt vmcnt(30)
	v_fma_f32 v68, v132, v68, v176
	v_fma_f32 v69, v133, v69, v177
	v_fma_f32 v70, v134, v70, v178
	v_fma_f32 v71, v135, v71, v179
	s_add_u32 s100, s100, 0x50000
	s_addc_u32 s101, s101, 0
	global_store_dwordx4 v158, v[68:71], s[100:101]
	s_waitcnt vmcnt(29)
	v_fma_f32 v60, v140, v60, v180
	v_fma_f32 v61, v141, v61, v181
	v_fma_f32 v62, v142, v62, v182
	v_fma_f32 v63, v143, v63, v183
	global_store_dwordx4 v159, v[60:63], s[100:101]
	s_waitcnt vmcnt(28)
	v_fma_f32 v56, v146, v56, v184
	v_fma_f32 v57, v147, v57, v185
	v_fma_f32 v58, v148, v58, v186
	v_fma_f32 v59, v149, v59, v187
	global_store_dwordx4 v200, v[56:59], s[100:101]
	s_waitcnt vmcnt(27)
	v_fma_f32 v52, v150, v52, v188
	v_fma_f32 v53, v151, v53, v189
	v_fma_f32 v54, v152, v54, v190
	v_fma_f32 v55, v153, v55, v191
	global_store_dwordx4 v201, v[52:55], s[100:101]
	s_waitcnt vmcnt(26)
	v_fma_f32 v48, v132, v48, v192
	v_fma_f32 v49, v133, v49, v193
	v_fma_f32 v50, v134, v50, v194
	v_fma_f32 v51, v135, v51, v195
	s_add_u32 s100, s100, 0x10000
	s_addc_u32 s101, s101, 0
	global_store_dwordx4 v158, v[48:51], s[100:101]
	s_waitcnt vmcnt(25)
	v_fma_f32 v44, v140, v44, v196
	v_fma_f32 v45, v141, v45, v197
	v_fma_f32 v46, v142, v46, v198
	v_fma_f32 v47, v143, v47, v199
	global_store_dwordx4 v159, v[44:47], s[100:101]
	s_waitcnt vmcnt(24)
	v_fma_f32 v40, v146, v40, v214
	v_fma_f32 v41, v147, v41, v215
	v_fma_f32 v42, v148, v42, v216
	v_fma_f32 v43, v149, v43, v217
	global_store_dwordx4 v200, v[40:43], s[100:101]
	s_waitcnt vmcnt(23)
	v_fma_f32 v36, v150, v36, v218
	v_fma_f32 v37, v151, v37, v219
	v_fma_f32 v38, v152, v38, v220
	v_fma_f32 v39, v153, v39, v221
	global_store_dwordx4 v201, v[36:39], s[100:101]
	s_waitcnt vmcnt(22)
	v_fma_f32 v32, v132, v32, v222
	v_fma_f32 v33, v133, v33, v223
	v_fma_f32 v34, v134, v34, v224
	v_fma_f32 v35, v135, v35, v225
	s_add_u32 s100, s100, 0x10000
	s_addc_u32 s101, s101, 0
	global_store_dwordx4 v158, v[32:35], s[100:101]
	s_waitcnt vmcnt(21)
	v_fma_f32 v28, v140, v28, v226
	v_fma_f32 v29, v141, v29, v227
	v_fma_f32 v30, v142, v30, v228
	v_fma_f32 v31, v143, v31, v229
	global_store_dwordx4 v159, v[28:31], s[100:101]
	s_waitcnt vmcnt(20)
	v_fma_f32 v24, v146, v24, v230
	v_fma_f32 v25, v147, v25, v231
	v_fma_f32 v26, v148, v26, v232
	v_fma_f32 v27, v149, v27, v233
	global_store_dwordx4 v200, v[24:27], s[100:101]
	s_waitcnt vmcnt(19)
	v_fma_f32 v20, v150, v20, v234
	v_fma_f32 v21, v151, v21, v235
	v_fma_f32 v22, v152, v22, v236
	v_fma_f32 v23, v153, v23, v237
	global_store_dwordx4 v201, v[20:23], s[100:101]
	s_waitcnt vmcnt(18)
	v_fma_f32 v16, v132, v16, v160
	v_fma_f32 v17, v133, v17, v161
	v_fma_f32 v18, v134, v18, v162
	v_fma_f32 v19, v135, v19, v163
	s_add_u32 s100, s100, 0x10000
	s_addc_u32 s101, s101, 0
	global_store_dwordx4 v158, v[16:19], s[100:101]
	s_waitcnt vmcnt(17)
	v_fma_f32 v12, v140, v12, v164
	v_fma_f32 v13, v141, v13, v165
	v_fma_f32 v14, v142, v14, v166
	v_fma_f32 v15, v143, v15, v167
	global_store_dwordx4 v159, v[12:15], s[100:101]
	s_waitcnt vmcnt(16)
	v_fma_f32 v8, v146, v8, v168
	v_fma_f32 v9, v147, v9, v169
	v_fma_f32 v10, v148, v10, v170
	v_fma_f32 v11, v149, v11, v171
	global_store_dwordx4 v200, v[8:11], s[100:101]
	s_waitcnt vmcnt(15)
	v_fma_f32 v4, v150, v4, v154
	v_fma_f32 v5, v151, v5, v155
	v_fma_f32 v6, v152, v6, v156
	v_fma_f32 v7, v153, v7, v157
	global_store_dwordx4 v201, v[4:7], s[100:101]
	s_cmp_eq_u64 s[12:13], 0
	s_cbranch_scc1 .LBB0_291
	v_mul_f32_e32 v132, v65, v65
	v_mul_f32_e32 v133, v67, v67
	v_fmac_f32_e32 v132, v64, v64
	v_fmac_f32_e32 v133, v66, v66
	v_add_f32_e32 v132, v132, v133
	v_mul_f32_e32 v133, v73, v73
	v_mul_f32_e32 v134, v75, v75
	v_fmac_f32_e32 v133, v72, v72
	v_fmac_f32_e32 v134, v74, v74
	v_add_f32_e32 v133, v133, v134
	v_add_f32_e32 v132, v132, v133
	v_mul_f32_e32 v133, v77, v77
	v_mul_f32_e32 v134, v79, v79
	v_fmac_f32_e32 v133, v76, v76
	v_fmac_f32_e32 v134, v78, v78
	v_add_f32_e32 v133, v133, v134
	v_add_f32_e32 v132, v133, v132
	v_mul_f32_e32 v133, v85, v85
	v_mul_f32_e32 v134, v87, v87
	v_fmac_f32_e32 v133, v84, v84
	v_fmac_f32_e32 v134, v86, v86
	v_add_f32_e32 v133, v133, v134
	v_add_f32_e32 v132, v133, v132
	ds_bpermute_b32 v133, v172, v132
	s_waitcnt lgkmcnt(0)
	v_add_f32_e32 v154, v132, v133
	ds_bpermute_b32 v155, v173, v154
	s_and_saveexec_b64 s[26:27], s[4:5]
	s_cbranch_execz .LBB0_259
	s_lshl_b32 s0, s23, 10
	s_add_i32 s0, s19, s0
	s_waitcnt lgkmcnt(0)
	v_add_f32_e32 v132, v154, v155
	v_lshl_add_u32 v133, v145, 4, s0
	ds_write_b32 v133, v132

; __device__ __forceinline__ unsigned pk2(float lo, float hi) { unsigned r; asm("v_cvt_pk_bf16_f32 %0, %1, %2" : "=v"(r) : "v"(lo), "v"(hi)); return r; }
;     __device__ __forceinline__ void fused(f32x4 (&acc)[2][2][4][2], const Unit& u, int wr, int wc, int fr, int fq, LAS unsigned char* lds, int wid, int lane) const {
;     ...
; #pragma unroll
;             for (int ai = 0; ai < 2; ++ai)
; #pragma unroll
;                 for (int m = 0; m < 4; ++m) { const int r = ai * HALF + wr * 64 + m * 16 + fr; const float rs = S[r]; bf16_t* hp = h + (size_t)(u.pm * BM + r) * D + col0;
; #pragma unroll
;                     for (int bj = 0; bj < 2; ++bj)
; #pragma unroll
;                         for (int n = 0; n < 2; ++n) { const f32x4 gv = *(const f32x4*)(g2 + col0 + bj * HALF + n * 16); const f32x4 o = acc[ai][bj][m][n] * rs * gv;
;                             u32x2 w; w.x = pk2(o[0], o[1]); w.y = pk2(o[2], o[3]); *(u32x2*)(hp + bj * HALF + n * 16) = w; }
;                     asm volatile("" ::: "memory"); }
.LBB0_290:
	s_or_b64 exec, exec, s[8:9]
	s_add_u32 s4, s22, s30
	s_addc_u32 s5, s33, s31
	s_waitcnt lgkmcnt(0)
	s_barrier
	v_lshrrev_b32_e32 v177, 8, v202
	v_bfe_u32 v178, v202, 6, 2
	v_and_b32_e32 v179, 15, v207
	v_lshrrev_b32_e32 v180, 4, v207
	s_lshl_b32 s16, s20, 10
	v_lshlrev_b32_e32 v175, 7, v178
	v_lshl_add_u32 v175, v180, 4, v175
	v_add_u32_e32 v175, s16, v175
	s_lshl_b32 s16, s20, 9
	v_lshlrev_b32_e32 v176, 17, v177
	v_lshl_add_u32 v176, v179, 11, v176
	v_lshl_add_u32 v176, v178, 6, v176
	v_lshl_add_u32 v176, v180, 3, v176
	v_add_u32_e32 v176, s16, v176
	s_lshl_b32 s16, s18, 19
	s_add_u32 s98, s12, s16
	s_addc_u32 s99, s13, 0
	global_load_dwordx4 v[132:135], v175, s[4:5] offset:0
	global_load_dwordx4 v[140:143], v175, s[4:5] offset:64
	global_load_dwordx4 v[146:149], v175, s[4:5] offset:512
	global_load_dwordx4 v[150:153], v175, s[4:5] offset:576
	ds_read_b32 v246, v3 offset:4096
	ds_read_b32 v248, v3 offset:4160
	ds_read_b32 v250, v3 offset:4224
	ds_read_b32 v252, v3 offset:4288
	s_waitcnt lgkmcnt(3)
	v_mul_f32_e32 v64, v64, v246
	v_mul_f32_e32 v65, v65, v246
	v_mul_f32_e32 v66, v66, v246
	v_mul_f32_e32 v67, v67, v246
	s_waitcnt vmcnt(0)
	v_mul_f32_e32 v64, v132, v64
	v_mul_f32_e32 v65, v133, v65
	v_mul_f32_e32 v66, v134, v66
	v_mul_f32_e32 v67, v135, v67
	v_cvt_pk_bf16_f32 v64, v64, v65
	v_cvt_pk_bf16_f32 v65, v66, v67
	global_store_dwordx2 v176, v[64:65], s[98:99] offset:0
	v_mul_f32_e32 v72, v72, v246
	v_mul_f32_e32 v73, v73, v246
	v_mul_f32_e32 v74, v74, v246
	v_mul_f32_e32 v75, v75, v246
	v_mul_f32_e32 v72, v140, v72
	v_mul_f32_e32 v73, v141, v73
	v_mul_f32_e32 v74, v142, v74
	v_mul_f32_e32 v75, v143, v75
	v_cvt_pk_bf16_f32 v72, v72, v73
	v_cvt_pk_bf16_f32 v73, v74, v75
	global_store_dwordx2 v176, v[72:73], s[98:99] offset:32
	v_mul_f32_e32 v76, v76, v246
	v_mul_f32_e32 v77, v77, v246
	v_mul_f32_e32 v78, v78, v246
	v_mul_f32_e32 v79, v79, v246
	v_mul_f32_e32 v76, v146, v76
	v_mul_f32_e32 v77, v147, v77
	v_mul_f32_e32 v78, v148, v78
	v_mul_f32_e32 v79, v149, v79
	v_cvt_pk_bf16_f32 v76, v76, v77
	v_cvt_pk_bf16_f32 v77, v78, v79
	global_store_dwordx2 v176, v[76:77], s[98:99] offset:256
	v_mul_f32_e32 v84, v84, v246
	v_mul_f32_e32 v85, v85, v246
	v_mul_f32_e32 v86, v86, v246
	v_mul_f32_e32 v87, v87, v246
	v_mul_f32_e32 v84, v150, v84
	v_mul_f32_e32 v85, v151, v85
	v_mul_f32_e32 v86, v152, v86
	v_mul_f32_e32 v87, v153, v87
	v_cvt_pk_bf16_f32 v84, v84, v85
	v_cvt_pk_bf16_f32 v85, v86, v87
	global_store_dwordx2 v176, v[84:85], s[98:99] offset:288
	s_waitcnt lgkmcnt(2)
	s_add_u32 s98, s98, 0x8000
	s_addc_u32 s99, s99, 0
	v_mul_f32_e32 v92, v92, v248
	v_mul_f32_e32 v93, v93, v248
	v_mul_f32_e32 v94, v94, v248
	v_mul_f32_e32 v95, v95, v248
	v_mul_f32_e32 v92, v132, v92
	v_mul_f32_e32 v93, v133, v93
	v_mul_f32_e32 v94, v134, v94
	v_mul_f32_e32 v95, v135, v95
	v_cvt_pk_bf16_f32 v92, v92, v93
	v_cvt_pk_bf16_f32 v93, v94, v95
	global_store_dwordx2 v176, v[92:93], s[98:99] offset:0
	v_mul_f32_e32 v96, v96, v248
	v_mul_f32_e32 v97, v97, v248
	v_mul_f32_e32 v98, v98, v248
	v_mul_f32_e32 v99, v99, v248
	v_mul_f32_e32 v96, v140, v96
	v_mul_f32_e32 v97, v141, v97
	v_mul_f32_e32 v98, v142, v98
	v_mul_f32_e32 v99, v143, v99
	v_cvt_pk_bf16_f32 v96, v96, v97
	v_cvt_pk_bf16_f32 v97, v98, v99
	global_store_dwordx2 v176, v[96:97], s[98:99] offset:32
	v_mul_f32_e32 v104, v104, v248
	v_mul_f32_e32 v105, v105, v248
	v_mul_f32_e32 v106, v106, v248
	v_mul_f32_e32 v107, v107, v248
	v_mul_f32_e32 v104, v146, v104
	v_mul_f32_e32 v105, v147, v105
	v_mul_f32_e32 v106, v148, v106
	v_mul_f32_e32 v107, v149, v107
	v_cvt_pk_bf16_f32 v104, v104, v105
	v_cvt_pk_bf16_f32 v105, v106, v107
	global_store_dwordx2 v176, v[104:105], s[98:99] offset:256
	v_mul_f32_e32 v108, v108, v248
	v_mul_f32_e32 v109, v109, v248
	v_mul_f32_e32 v110, v110, v248
	v_mul_f32_e32 v111, v111, v248
	v_mul_f32_e32 v108, v150, v108
	v_mul_f32_e32 v109, v151, v109
	v_mul_f32_e32 v110, v152, v110
	v_mul_f32_e32 v111, v153, v111
	v_cvt_pk_bf16_f32 v108, v108, v109
	v_cvt_pk_bf16_f32 v109, v110, v111
	global_store_dwordx2 v176, v[108:109], s[98:99] offset:288
	s_waitcnt lgkmcnt(1)
	s_add_u32 s98, s98, 0x8000
	s_addc_u32 s99, s99, 0
	v_mul_f32_e32 v116, v116, v250
	v_mul_f32_e32 v117, v117, v250
	v_mul_f32_e32 v118, v118, v250
	v_mul_f32_e32 v119, v119, v250
	v_mul_f32_e32 v116, v132, v116
	v_mul_f32_e32 v117, v133, v117
	v_mul_f32_e32 v118, v134, v118
	v_mul_f32_e32 v119, v135, v119
	v_cvt_pk_bf16_f32 v116, v116, v117
	v_cvt_pk_bf16_f32 v117, v118, v119
	global_store_dwordx2 v176, v[116:117], s[98:99] offset:0
	v_mul_f32_e32 v124, v124, v250
	v_mul_f32_e32 v125, v125, v250
	v_mul_f32_e32 v126, v126, v250
	v_mul_f32_e32 v127, v127, v250
	v_mul_f32_e32 v124, v140, v124
	v_mul_f32_e32 v125, v141, v125
	v_mul_f32_e32 v126, v142, v126
	v_mul_f32_e32 v127, v143, v127
	v_cvt_pk_bf16_f32 v124, v124, v125
	v_cvt_pk_bf16_f32 v125, v126, v127
	global_store_dwordx2 v176, v[124:125], s[98:99] offset:32
	v_mul_f32_e32 v128, v128, v250
	v_mul_f32_e32 v129, v129, v250
	v_mul_f32_e32 v130, v130, v250
	v_mul_f32_e32 v131, v131, v250
	v_mul_f32_e32 v128, v146, v128
	v_mul_f32_e32 v129, v147, v129
	v_mul_f32_e32 v130, v148, v130
	v_mul_f32_e32 v131, v149, v131
	v_cvt_pk_bf16_f32 v128, v128, v129
	v_cvt_pk_bf16_f32 v129, v130, v131
	global_store_dwordx2 v176, v[128:129], s[98:99] offset:256
	v_mul_f32_e32 v120, v120, v250
	v_mul_f32_e32 v121, v121, v250
	v_mul_f32_e32 v122, v122, v250
	v_mul_f32_e32 v123, v123, v250
	v_mul_f32_e32 v120, v150, v120
	v_mul_f32_e32 v121, v151, v121
	v_mul_f32_e32 v122, v152, v122
	v_mul_f32_e32 v123, v153, v123
	v_cvt_pk_bf16_f32 v120, v120, v121
	v_cvt_pk_bf16_f32 v121, v122, v123
	global_store_dwordx2 v176, v[120:121], s[98:99] offset:288
	s_waitcnt lgkmcnt(0)
; __device__ __forceinline__ unsigned pk2(float lo, float hi) { unsigned r; asm("v_cvt_pk_bf16_f32 %0, %1, %2" : "=v"(r) : "v"(lo), "v"(hi)); return r; }
;     __device__ __forceinline__ void fused(f32x4 (&acc)[2][2][4][2], const Unit& u, int wr, int wc, int fr, int fq, LAS unsigned char* lds, int wid, int lane) const {
;     ...
; #pragma unroll
;             for (int ai = 0; ai < 2; ++ai)
; #pragma unroll
;                 for (int m = 0; m < 4; ++m) { const int r = ai * HALF + wr * 64 + m * 16 + fr; const float rs = S[r]; bf16_t* hp = h + (size_t)(u.pm * BM + r) * D + col0;
; #pragma unroll
;                     for (int bj = 0; bj < 2; ++bj)
; #pragma unroll
;                         for (int n = 0; n < 2; ++n) { const f32x4 gv = *(const f32x4*)(g2 + col0 + bj * HALF + n * 16); const f32x4 o = acc[ai][bj][m][n] * rs * gv;
;                             u32x2 w; w.x = pk2(o[0], o[1]); w.y = pk2(o[2], o[3]); *(u32x2*)(hp + bj * HALF + n * 16) = w; }
;                     asm volatile("" ::: "memory"); }
	s_add_u32 s98, s98, 0x8000
	s_addc_u32 s99, s99, 0
	v_mul_f32_e32 v112, v112, v252
	v_mul_f32_e32 v113, v113, v252
	v_mul_f32_e32 v114, v114, v252
	v_mul_f32_e32 v115, v115, v252
	v_mul_f32_e32 v112, v132, v112
	v_mul_f32_e32 v113, v133, v113
	v_mul_f32_e32 v114, v134, v114
	v_mul_f32_e32 v115, v135, v115
	v_cvt_pk_bf16_f32 v112, v112, v113
	v_cvt_pk_bf16_f32 v113, v114, v115
	global_store_dwordx2 v176, v[112:113], s[98:99] offset:0
	v_mul_f32_e32 v100, v100, v252
	v_mul_f32_e32 v101, v101, v252
	v_mul_f32_e32 v102, v102, v252
	v_mul_f32_e32 v103, v103, v252
	v_mul_f32_e32 v100, v140, v100
	v_mul_f32_e32 v101, v141, v101
	v_mul_f32_e32 v102, v142, v102
	v_mul_f32_e32 v103, v143, v103
	v_cvt_pk_bf16_f32 v100, v100, v101
	v_cvt_pk_bf16_f32 v101, v102, v103
	global_store_dwordx2 v176, v[100:101], s[98:99] offset:32
	v_mul_f32_e32 v88, v88, v252
	v_mul_f32_e32 v89, v89, v252
	v_mul_f32_e32 v90, v90, v252
	v_mul_f32_e32 v91, v91, v252
	v_mul_f32_e32 v88, v146, v88
	v_mul_f32_e32 v89, v147, v89
	v_mul_f32_e32 v90, v148, v90
	v_mul_f32_e32 v91, v149, v91
	v_cvt_pk_bf16_f32 v88, v88, v89
	v_cvt_pk_bf16_f32 v89, v90, v91
	global_store_dwordx2 v176, v[88:89], s[98:99] offset:256
	v_mul_f32_e32 v80, v80, v252
	v_mul_f32_e32 v81, v81, v252
	v_mul_f32_e32 v82, v82, v252
	v_mul_f32_e32 v83, v83, v252
	v_mul_f32_e32 v80, v150, v80
	v_mul_f32_e32 v81, v151, v81
	v_mul_f32_e32 v82, v152, v82
	v_mul_f32_e32 v83, v153, v83
	v_cvt_pk_bf16_f32 v80, v80, v81
	v_cvt_pk_bf16_f32 v81, v82, v83
	global_store_dwordx2 v176, v[80:81], s[98:99] offset:288
	ds_read_b32 v246, v3 offset:4608
	ds_read_b32 v248, v3 offset:4672
	ds_read_b32 v250, v3 offset:4736
	ds_read_b32 v252, v3 offset:4800
	s_waitcnt lgkmcnt(3)
	s_add_u32 s98, s98, 0x28000
	s_addc_u32 s99, s99, 0
	v_mul_f32_e32 v68, v68, v246
	v_mul_f32_e32 v69, v69, v246
	v_mul_f32_e32 v70, v70, v246
	v_mul_f32_e32 v71, v71, v246
	v_mul_f32_e32 v68, v132, v68
	v_mul_f32_e32 v69, v133, v69
	v_mul_f32_e32 v70, v134, v70
	v_mul_f32_e32 v71, v135, v71
	v_cvt_pk_bf16_f32 v68, v68, v69
	v_cvt_pk_bf16_f32 v69, v70, v71
	global_store_dwordx2 v176, v[68:69], s[98:99] offset:0
	v_mul_f32_e32 v60, v60, v246
	v_mul_f32_e32 v61, v61, v246
	v_mul_f32_e32 v62, v62, v246
	v_mul_f32_e32 v63, v63, v246
	v_mul_f32_e32 v60, v140, v60
	v_mul_f32_e32 v61, v141, v61
	v_mul_f32_e32 v62, v142, v62
	v_mul_f32_e32 v63, v143, v63
	v_cvt_pk_bf16_f32 v60, v60, v61
	v_cvt_pk_bf16_f32 v61, v62, v63
	global_store_dwordx2 v176, v[60:61], s[98:99] offset:32
	v_mul_f32_e32 v56, v56, v246
	v_mul_f32_e32 v57, v57, v246
	v_mul_f32_e32 v58, v58, v246
	v_mul_f32_e32 v59, v59, v246
	v_mul_f32_e32 v56, v146, v56
	v_mul_f32_e32 v57, v147, v57
	v_mul_f32_e32 v58, v148, v58
	v_mul_f32_e32 v59, v149, v59
	v_cvt_pk_bf16_f32 v56, v56, v57
	v_cvt_pk_bf16_f32 v57, v58, v59
	global_store_dwordx2 v176, v[56:57], s[98:99] offset:256
	v_mul_f32_e32 v52, v52, v246
	v_mul_f32_e32 v53, v53, v246
	v_mul_f32_e32 v54, v54, v246
	v_mul_f32_e32 v55, v55, v246
	v_mul_f32_e32 v52, v150, v52
	v_mul_f32_e32 v53, v151, v53
	v_mul_f32_e32 v54, v152, v54
	v_mul_f32_e32 v55, v153, v55
	v_cvt_pk_bf16_f32 v52, v52, v53
	v_cvt_pk_bf16_f32 v53, v54, v55
	global_store_dwordx2 v176, v[52:53], s[98:99] offset:288
	s_waitcnt lgkmcnt(2)
; __device__ __forceinline__ unsigned pk2(float lo, float hi) { unsigned r; asm("v_cvt_pk_bf16_f32 %0, %1, %2" : "=v"(r) : "v"(lo), "v"(hi)); return r; }
;     __device__ __forceinline__ void fused(f32x4 (&acc)[2][2][4][2], const Unit& u, int wr, int wc, int fr, int fq, LAS unsigned char* lds, int wid, int lane) const {
;     ...
; #pragma unroll
;             for (int ai = 0; ai < 2; ++ai)
; #pragma unroll
;                 for (int m = 0; m < 4; ++m) { const int r = ai * HALF + wr * 64 + m * 16 + fr; const float rs = S[r]; bf16_t* hp = h + (size_t)(u.pm * BM + r) * D + col0;
; #pragma unroll
;                     for (int bj = 0; bj < 2; ++bj)
; #pragma unroll
;                         for (int n = 0; n < 2; ++n) { const f32x4 gv = *(const f32x4*)(g2 + col0 + bj * HALF + n * 16); const f32x4 o = acc[ai][bj][m][n] * rs * gv;
;                             u32x2 w; w.x = pk2(o[0], o[1]); w.y = pk2(o[2], o[3]); *(u32x2*)(hp + bj * HALF + n * 16) = w; }
;                     asm volatile("" ::: "memory"); }
	s_add_u32 s98, s98, 0x8000
	s_addc_u32 s99, s99, 0
	v_mul_f32_e32 v48, v48, v248
	v_mul_f32_e32 v49, v49, v248
	v_mul_f32_e32 v50, v50, v248
	v_mul_f32_e32 v51, v51, v248
	v_mul_f32_e32 v48, v132, v48
	v_mul_f32_e32 v49, v133, v49
	v_mul_f32_e32 v50, v134, v50
	v_mul_f32_e32 v51, v135, v51
	v_cvt_pk_bf16_f32 v48, v48, v49
	v_cvt_pk_bf16_f32 v49, v50, v51
	global_store_dwordx2 v176, v[48:49], s[98:99] offset:0
	v_mul_f32_e32 v44, v44, v248
	v_mul_f32_e32 v45, v45, v248
	v_mul_f32_e32 v46, v46, v248
	v_mul_f32_e32 v47, v47, v248
	v_mul_f32_e32 v44, v140, v44
	v_mul_f32_e32 v45, v141, v45
	v_mul_f32_e32 v46, v142, v46
	v_mul_f32_e32 v47, v143, v47
	v_cvt_pk_bf16_f32 v44, v44, v45
	v_cvt_pk_bf16_f32 v45, v46, v47
	global_store_dwordx2 v176, v[44:45], s[98:99] offset:32
	v_mul_f32_e32 v40, v40, v248
	v_mul_f32_e32 v41, v41, v248
	v_mul_f32_e32 v42, v42, v248
	v_mul_f32_e32 v43, v43, v248
	v_mul_f32_e32 v40, v146, v40
	v_mul_f32_e32 v41, v147, v41
	v_mul_f32_e32 v42, v148, v42
	v_mul_f32_e32 v43, v149, v43
	v_cvt_pk_bf16_f32 v40, v40, v41
	v_cvt_pk_bf16_f32 v41, v42, v43
	global_store_dwordx2 v176, v[40:41], s[98:99] offset:256
	v_mul_f32_e32 v36, v36, v248
	v_mul_f32_e32 v37, v37, v248
	v_mul_f32_e32 v38, v38, v248
	v_mul_f32_e32 v39, v39, v248
	v_mul_f32_e32 v36, v150, v36
	v_mul_f32_e32 v37, v151, v37
	v_mul_f32_e32 v38, v152, v38
	v_mul_f32_e32 v39, v153, v39
	v_cvt_pk_bf16_f32 v36, v36, v37
	v_cvt_pk_bf16_f32 v37, v38, v39
	global_store_dwordx2 v176, v[36:37], s[98:99] offset:288
	s_waitcnt lgkmcnt(1)
	s_add_u32 s98, s98, 0x8000
	s_addc_u32 s99, s99, 0
	v_mul_f32_e32 v32, v32, v250
	v_mul_f32_e32 v33, v33, v250
	v_mul_f32_e32 v34, v34, v250
	v_mul_f32_e32 v35, v35, v250
	v_mul_f32_e32 v32, v132, v32
	v_mul_f32_e32 v33, v133, v33
	v_mul_f32_e32 v34, v134, v34
	v_mul_f32_e32 v35, v135, v35
	v_cvt_pk_bf16_f32 v32, v32, v33
	v_cvt_pk_bf16_f32 v33, v34, v35
	global_store_dwordx2 v176, v[32:33], s[98:99] offset:0
	v_mul_f32_e32 v28, v28, v250
	v_mul_f32_e32 v29, v29, v250
	v_mul_f32_e32 v30, v30, v250
	v_mul_f32_e32 v31, v31, v250
	v_mul_f32_e32 v28, v140, v28
	v_mul_f32_e32 v29, v141, v29
	v_mul_f32_e32 v30, v142, v30
	v_mul_f32_e32 v31, v143, v31
	v_cvt_pk_bf16_f32 v28, v28, v29
	v_cvt_pk_bf16_f32 v29, v30, v31
	global_store_dwordx2 v176, v[28:29], s[98:99] offset:32
	v_mul_f32_e32 v24, v24, v250
	v_mul_f32_e32 v25, v25, v250
	v_mul_f32_e32 v26, v26, v250
	v_mul_f32_e32 v27, v27, v250
	v_mul_f32_e32 v24, v146, v24
	v_mul_f32_e32 v25, v147, v25
	v_mul_f32_e32 v26, v148, v26
	v_mul_f32_e32 v27, v149, v27
	v_cvt_pk_bf16_f32 v24, v24, v25
	v_cvt_pk_bf16_f32 v25, v26, v27
	global_store_dwordx2 v176, v[24:25], s[98:99] offset:256
	v_mul_f32_e32 v20, v20, v250
	v_mul_f32_e32 v21, v21, v250
	v_mul_f32_e32 v22, v22, v250
	v_mul_f32_e32 v23, v23, v250
	v_mul_f32_e32 v20, v150, v20
	v_mul_f32_e32 v21, v151, v21
	v_mul_f32_e32 v22, v152, v22
	v_mul_f32_e32 v23, v153, v23
	v_cvt_pk_bf16_f32 v20, v20, v21
	v_cvt_pk_bf16_f32 v21, v22, v23
	global_store_dwordx2 v176, v[20:21], s[98:99] offset:288
	s_waitcnt lgkmcnt(0)
	s_add_u32 s98, s98, 0x8000
	s_addc_u32 s99, s99, 0
	v_mul_f32_e32 v16, v16, v252
	v_mul_f32_e32 v17, v17, v252
	v_mul_f32_e32 v18, v18, v252
	v_mul_f32_e32 v19, v19, v252
	v_mul_f32_e32 v16, v132, v16
	v_mul_f32_e32 v17, v133, v17
	v_mul_f32_e32 v18, v134, v18
	v_mul_f32_e32 v19, v135, v19
	v_cvt_pk_bf16_f32 v16, v16, v17
	v_cvt_pk_bf16_f32 v17, v18, v19
	global_store_dwordx2 v176, v[16:17], s[98:99] offset:0
	v_mul_f32_e32 v12, v12, v252
	v_mul_f32_e32 v13, v13, v252
	v_mul_f32_e32 v14, v14, v252
	v_mul_f32_e32 v15, v15, v252
	v_mul_f32_e32 v12, v140, v12
	v_mul_f32_e32 v13, v141, v13
	v_mul_f32_e32 v14, v142, v14
	v_mul_f32_e32 v15, v143, v15
	v_cvt_pk_bf16_f32 v12, v12, v13
	v_cvt_pk_bf16_f32 v13, v14, v15
	global_store_dwordx2 v176, v[12:13], s[98:99] offset:32
	v_mul_f32_e32 v8, v8, v252
	v_mul_f32_e32 v9, v9, v252
	v_mul_f32_e32 v10, v10, v252
	v_mul_f32_e32 v11, v11, v252
	v_mul_f32_e32 v8, v146, v8
	v_mul_f32_e32 v9, v147, v9
	v_mul_f32_e32 v10, v148, v10
	v_mul_f32_e32 v11, v149, v11
	v_cvt_pk_bf16_f32 v8, v8, v9
	v_cvt_pk_bf16_f32 v9, v10, v11
	global_store_dwordx2 v176, v[8:9], s[98:99] offset:256
	v_mul_f32_e32 v4, v4, v252
	v_mul_f32_e32 v5, v5, v252
	v_mul_f32_e32 v6, v6, v252
	v_mul_f32_e32 v7, v7, v252
	v_mul_f32_e32 v4, v150, v4
	v_mul_f32_e32 v5, v151, v5
	v_mul_f32_e32 v6, v152, v6
	v_mul_f32_e32 v7, v153, v7
	v_cvt_pk_bf16_f32 v4, v4, v5
	v_cvt_pk_bf16_f32 v5, v6, v7
	global_store_dwordx2 v176, v[4:5], s[98:99] offset:288

; #define BG_STAGE(kk_, slot_) do { const int _n = (kk_) >> 2, _kt = (kk_) & 3; const int _so = (slot_) * STG; \
;         const bf16_t* _a = outs + ((size_t)_n * M + (size_t)pm * 256) * 256 + _kt * 64; const bf16_t* _b = wbr + ((size_t)_n * 1024 + (size_t)pn * 128) * 256 + _kt * 64; \
;         BG_LD(_so, _a); BG_LD(_so + HTB, _a + 128 * 256); BG_LDX(_so + 2 * HTB, _b, voffB); } while (0)
; #define BG_WAIT(n) asm volatile("s_waitcnt vmcnt(" #n ")" ::: "memory")
; #define BG_BAR() do { __builtin_amdgcn_s_barrier(); asm volatile("" ::: "memory"); } while (0)
; __device__ __forceinline__ void bgemm_phase(LAS unsigned char* lds, const bf16_t* outs, const bf16_t* wbr, const bf16_t* zg, bf16_t* merged) {
;     ...
;         for (int n = 0; n < 4; ++n) {
;             const int kk0 = n * 4;
;             BG_WAIT(6); BG_BAR(); { const int s2 = slot >= 1 ? slot - 1 : 2; BG_STAGE(kk0 + 2, s2); } BG_COMPUTE(slot); slot = slot == 2 ? 0 : slot + 1;
;             BG_WAIT(6); BG_BAR(); { const int s2 = slot >= 1 ? slot - 1 : 2; BG_STAGE(kk0 + 3, s2); } BG_COMPUTE(slot); slot = slot == 2 ? 0 : slot + 1;
;             BG_WAIT(6); BG_BAR(); if (n < 3) { const int s2 = slot >= 1 ? slot - 1 : 2; BG_STAGE(kk0 + 4, s2); } BG_COMPUTE(slot); slot = slot == 2 ? 0 : slot + 1;
;             if (n < 3) { BG_WAIT(6); } else { BG_WAIT(0); }
;             BG_BAR(); if (n < 3) { const int s2 = slot >= 1 ? slot - 1 : 2; BG_STAGE(kk0 + 5, s2); }
.LBB0_296:
	s_mul_i32 s17, s16, 0xc000
	s_add_i32 s22, s17, 0xffff4000
	s_cmp_gt_i32 s16, 0
	s_cselect_b32 s22, s22, 0x18000
	v_lshl_add_u64 v[4:5], v[198:199], 0, s[20:21]
	s_add_i32 s22, s30, s22
	s_waitcnt vmcnt(6)
	s_barrier
	v_lshl_add_u64 v[6:7], v[196:197], 0, s[20:21]
	v_lshl_add_u64 v[12:13], v[4:5], 0, s[48:49]
	s_mov_b32 m0, s22
	v_lshl_add_u64 v[14:15], v[6:7], 0, s[48:49]
	global_load_lds_dwordx4 v[12:13], off
	s_add_i32 m0, s22, 0x2000
	v_lshl_add_u64 v[16:17], v[4:5], 0, s[50:51]
	global_load_lds_dwordx4 v[14:15], off
	s_add_i32 m0, s22, 0x4000
	v_lshl_add_u64 v[8:9], s[26:27], 0, v[110:111]
	v_lshl_add_u64 v[18:19], v[6:7], 0, s[50:51]
	global_load_lds_dwordx4 v[16:17], off
	s_add_i32 m0, s22, 0x6000
	v_lshl_add_u64 v[20:21], v[8:9], 0, s[48:49]
	s_add_i32 s17, s17, 0
	global_load_lds_dwordx4 v[18:19], off
	s_add_i32 m0, s22, 0x8000
	v_add_u32_e32 v140, s17, v3
	v_add_u32_e32 v60, s17, v145
	global_load_lds_dwordx4 v[20:21], off
	s_add_i32 m0, s22, 0xa000
	s_add_i32 s17, s16, 1
	s_cmp_lg_u32 s16, 2
	s_cselect_b32 s16, s17, 0
	s_mul_i32 s17, s16, 0xc000
	v_lshl_add_u64 v[10:11], s[26:27], 0, v[108:109]
	s_add_i32 s22, s17, 0xffff4000
	v_lshl_add_u64 v[22:23], v[10:11], 0, s[48:49]
	s_cmp_gt_i32 s16, 0
	global_load_lds_dwordx4 v[22:23], off
	s_cselect_b32 s22, s22, 0x18000
	ds_read_b128 v[12:15], v60 offset:32768
	ds_read_b128 v[16:19], v140
	ds_read_b128 v[20:23], v140 offset:1024
	ds_read_b128 v[24:27], v60 offset:33792
	ds_read_b128 v[32:35], v60 offset:34816
	ds_read_b128 v[36:39], v60 offset:35840
	ds_read_b128 v[44:47], v60 offset:36864
	ds_read_b128 v[48:51], v60 offset:37888
	ds_read_b128 v[56:59], v60 offset:38912
	ds_read_b128 v[60:63], v60 offset:39936
	ds_read_b128 v[64:67], v140 offset:2048
	ds_read_b128 v[68:71], v140 offset:3072
	ds_read_b128 v[84:87], v140 offset:4096
	ds_read_b128 v[88:91], v140 offset:5120
	ds_read_b128 v[218:221], v140 offset:6144
	ds_read_b128 v[222:225], v140 offset:7168
	s_add_i32 s22, s30, s22
	v_lshl_add_u64 v[140:141], v[4:5], 0, s[52:53]
	s_waitcnt vmcnt(6)
	s_barrier
	s_mov_b32 m0, s22
	v_lshl_add_u64 v[142:143], v[6:7], 0, s[52:53]
	global_load_lds_dwordx4 v[140:141], off
	s_add_i32 m0, s22, 0x2000
	v_lshl_add_u64 v[200:201], v[4:5], 0, s[54:55]
	global_load_lds_dwordx4 v[142:143], off
	s_add_i32 m0, s22, 0x4000
	s_waitcnt lgkmcnt(0)
	v_mfma_f32_16x16x32_bf16 v[28:31], v[12:15], v[16:19], 0
	global_load_lds_dwordx4 v[200:201], off
	s_add_i32 m0, s22, 0x6000
	v_mfma_f32_16x16x32_bf16 v[40:43], v[32:35], v[16:19], 0
	v_lshl_add_u64 v[226:227], v[10:11], 0, s[52:53]
	s_add_i32 s17, s17, 0
	v_add_u32_e32 v228, s17, v145
	v_mfma_f32_16x16x32_bf16 v[52:55], v[44:47], v[16:19], 0
	v_add_u32_e32 v217, s17, v3
	s_add_i32 s17, s16, 1
	v_mov_b64_e32 v[200:201], v[194:195]
	v_mfma_f32_16x16x32_bf16 v[16:19], v[56:59], v[16:19], 0
	s_mov_b64 s[28:29], 0x1000000
	v_lshl_add_u64 v[194:195], v[194:195], 0, s[28:29]
	v_mfma_f32_16x16x32_bf16 v[72:75], v[12:15], v[64:67], 0
	v_mfma_f32_16x16x32_bf16 v[76:79], v[32:35], v[64:67], 0
	v_mfma_f32_16x16x32_bf16 v[80:83], v[44:47], v[64:67], 0
	v_mfma_f32_16x16x32_bf16 v[64:67], v[56:59], v[64:67], 0
	v_mfma_f32_16x16x32_bf16 v[92:95], v[12:15], v[84:87], 0
	v_mfma_f32_16x16x32_bf16 v[96:99], v[32:35], v[84:87], 0
	v_mfma_f32_16x16x32_bf16 v[132:135], v[44:47], v[84:87], 0
	v_mfma_f32_16x16x32_bf16 v[84:87], v[56:59], v[84:87], 0
	v_mfma_f32_16x16x32_bf16 v[12:15], v[12:15], v[218:221], 0
	v_mfma_f32_16x16x32_bf16 v[32:35], v[32:35], v[218:221], 0
	v_mfma_f32_16x16x32_bf16 v[44:47], v[44:47], v[218:221], 0
	v_mfma_f32_16x16x32_bf16 v[56:59], v[56:59], v[218:221], 0
	v_lshl_add_u64 v[218:219], v[6:7], 0, s[54:55]
	v_lshl_add_u64 v[220:221], v[8:9], 0, s[52:53]
	global_load_lds_dwordx4 v[218:219], off
	s_add_i32 m0, s22, 0x8000
	v_mfma_f32_16x16x32_bf16 v[28:31], v[24:27], v[20:23], v[28:31]
	global_load_lds_dwordx4 v[220:221], off
	s_add_i32 m0, s22, 0xa000
	v_mfma_f32_16x16x32_bf16 v[40:43], v[36:39], v[20:23], v[40:43]
	global_load_lds_dwordx4 v[226:227], off
	s_cmp_lg_u32 s16, 2
	v_mfma_f32_16x16x32_bf16 v[52:55], v[48:51], v[20:23], v[52:55]
	s_cselect_b32 s16, s17, 0
	s_mul_i32 s17, s16, 0xc000
	s_add_i32 s22, s17, 0xffff4000
	v_mfma_f32_16x16x32_bf16 v[16:19], v[60:63], v[20:23], v[16:19]
	s_cmp_gt_i32 s16, 0
	s_cselect_b32 s22, s22, 0x18000
	s_add_i32 s22, s30, s22
	v_mfma_f32_16x16x32_bf16 v[20:23], v[24:27], v[68:71], v[72:75]
	s_mov_b32 m0, s22
	s_add_i32 s17, s17, 0
	v_add_u32_e32 v141, s17, v145
	v_mfma_f32_16x16x32_bf16 v[72:75], v[36:39], v[68:71], v[76:79]
	v_add_u32_e32 v140, s17, v3
	s_add_i32 s17, s16, 1
	v_mfma_f32_16x16x32_bf16 v[76:79], v[48:51], v[68:71], v[80:83]
	v_mfma_f32_16x16x32_bf16 v[64:67], v[60:63], v[68:71], v[64:67]
	v_mfma_f32_16x16x32_bf16 v[68:71], v[24:27], v[88:91], v[92:95]
	v_mfma_f32_16x16x32_bf16 v[80:83], v[36:39], v[88:91], v[96:99]
	v_mfma_f32_16x16x32_bf16 v[12:15], v[24:27], v[222:225], v[12:15]
	v_mfma_f32_16x16x32_bf16 v[24:27], v[36:39], v[222:225], v[32:35]
	ds_read_b128 v[36:39], v228 offset:32768
	v_mfma_f32_16x16x32_bf16 v[92:95], v[48:51], v[88:91], v[132:135]
	v_mfma_f32_16x16x32_bf16 v[84:87], v[60:63], v[88:91], v[84:87]
	v_mfma_f32_16x16x32_bf16 v[32:35], v[48:51], v[222:225], v[44:47]
	v_mfma_f32_16x16x32_bf16 v[44:47], v[60:63], v[222:225], v[56:59]
	ds_read_b128 v[48:51], v217
	s_nop 1
	ds_read_b128 v[56:59], v217 offset:1024
	ds_read_b128 v[60:63], v228 offset:33792
	ds_read_b128 v[88:91], v228 offset:34816
	ds_read_b128 v[96:99], v228 offset:35840
	ds_read_b128 v[132:135], v228 offset:36864
	ds_read_b128 v[218:221], v228 offset:37888
	ds_read_b128 v[222:225], v228 offset:38912
	ds_read_b128 v[226:229], v228 offset:39936
	s_waitcnt lgkmcnt(0)
	v_mfma_f32_16x16x32_bf16 v[28:31], v[36:39], v[48:51], v[28:31]
	v_mfma_f32_16x16x32_bf16 v[40:43], v[88:91], v[48:51], v[40:43]
	v_mfma_f32_16x16x32_bf16 v[52:55], v[132:135], v[48:51], v[52:55]
	v_mfma_f32_16x16x32_bf16 v[16:19], v[222:225], v[48:51], v[16:19]
	ds_read_b128 v[48:51], v217 offset:2048
	ds_read_b128 v[230:233], v217 offset:3072
	s_waitcnt lgkmcnt(0)
	v_mfma_f32_16x16x32_bf16 v[20:23], v[36:39], v[48:51], v[20:23]
	v_mfma_f32_16x16x32_bf16 v[72:75], v[88:91], v[48:51], v[72:75]
	v_mfma_f32_16x16x32_bf16 v[76:79], v[132:135], v[48:51], v[76:79]
	v_mfma_f32_16x16x32_bf16 v[48:51], v[222:225], v[48:51], v[64:67]
	s_nop 2
	ds_read_b128 v[64:67], v217 offset:4096
	ds_read_b128 v[234:237], v217 offset:5120
	s_waitcnt lgkmcnt(0)
	v_mfma_f32_16x16x32_bf16 v[68:71], v[36:39], v[64:67], v[68:71]
	v_mfma_f32_16x16x32_bf16 v[80:83], v[88:91], v[64:67], v[80:83]
	v_mfma_f32_16x16x32_bf16 v[92:95], v[132:135], v[64:67], v[92:95]
	v_mfma_f32_16x16x32_bf16 v[64:67], v[222:225], v[64:67], v[84:87]
	s_nop 2
	ds_read_b128 v[84:87], v217 offset:6144
	ds_read_b128 v[238:241], v217 offset:7168
	s_waitcnt vmcnt(6)
	s_barrier
; #define BG_STAGE(kk_, slot_) do { const int _n = (kk_) >> 2, _kt = (kk_) & 3; const int _so = (slot_) * STG; \
;         const bf16_t* _a = outs + ((size_t)_n * M + (size_t)pm * 256) * 256 + _kt * 64; const bf16_t* _b = wbr + ((size_t)_n * 1024 + (size_t)pn * 128) * 256 + _kt * 64; \
;         BG_LD(_so, _a); BG_LD(_so + HTB, _a + 128 * 256); BG_LDX(_so + 2 * HTB, _b, voffB); } while (0)
; #define BG_WAIT(n) asm volatile("s_waitcnt vmcnt(" #n ")" ::: "memory")
; #define BG_BAR() do { __builtin_amdgcn_s_barrier(); asm volatile("" ::: "memory"); } while (0)
; __device__ __forceinline__ void bgemm_phase(LAS unsigned char* lds, const bf16_t* outs, const bf16_t* wbr, const bf16_t* zg, bf16_t* merged) {
;     ...
;         for (int n = 0; n < 4; ++n) {
;             const int kk0 = n * 4;
;             BG_WAIT(6); BG_BAR(); { const int s2 = slot >= 1 ? slot - 1 : 2; BG_STAGE(kk0 + 2, s2); } BG_COMPUTE(slot); slot = slot == 2 ? 0 : slot + 1;
;             BG_WAIT(6); BG_BAR(); { const int s2 = slot >= 1 ? slot - 1 : 2; BG_STAGE(kk0 + 3, s2); } BG_COMPUTE(slot); slot = slot == 2 ? 0 : slot + 1;
;             BG_WAIT(6); BG_BAR(); if (n < 3) { const int s2 = slot >= 1 ? slot - 1 : 2; BG_STAGE(kk0 + 4, s2); } BG_COMPUTE(slot); slot = slot == 2 ? 0 : slot + 1;
;             if (n < 3) { BG_WAIT(6); } else { BG_WAIT(0); }
;             BG_BAR(); if (n < 3) { const int s2 = slot >= 1 ? slot - 1 : 2; BG_STAGE(kk0 + 5, s2); }
	s_waitcnt lgkmcnt(0)
	v_mfma_f32_16x16x32_bf16 v[12:15], v[36:39], v[84:87], v[12:15]
	v_mfma_f32_16x16x32_bf16 v[24:27], v[88:91], v[84:87], v[24:27]
	v_lshl_add_u64 v[88:89], v[4:5], 0, s[58:59]
	v_lshl_add_u64 v[90:91], v[6:7], 0, s[58:59]
	v_mfma_f32_16x16x32_bf16 v[32:35], v[132:135], v[84:87], v[32:35]
	v_lshl_add_u64 v[132:133], v[8:9], 0, s[60:61]
	v_lshl_add_u64 v[134:135], v[10:11], 0, s[60:61]
	v_lshl_add_u64 v[8:9], v[8:9], 0, s[66:67]
	v_mfma_f32_16x16x32_bf16 v[36:39], v[222:225], v[84:87], v[44:47]
	v_lshl_add_u64 v[84:85], v[4:5], 0, s[56:57]
	v_lshl_add_u64 v[86:87], v[6:7], 0, s[56:57]
	global_load_lds_dwordx4 v[84:85], off
	s_add_i32 m0, s22, 0x2000
	v_mfma_f32_16x16x32_bf16 v[28:31], v[60:63], v[56:59], v[28:31]
	global_load_lds_dwordx4 v[86:87], off
	s_add_i32 m0, s22, 0x4000
	v_mfma_f32_16x16x32_bf16 v[20:23], v[60:63], v[230:233], v[20:23]
	global_load_lds_dwordx4 v[88:89], off
	s_add_i32 m0, s22, 0x6000
	v_mfma_f32_16x16x32_bf16 v[68:71], v[60:63], v[234:237], v[68:71]
	global_load_lds_dwordx4 v[90:91], off
	s_add_i32 m0, s22, 0x8000
	v_mfma_f32_16x16x32_bf16 v[12:15], v[60:63], v[238:241], v[12:15]
	global_load_lds_dwordx4 v[132:133], off
	s_add_i32 m0, s22, 0xa000
	v_mfma_f32_16x16x32_bf16 v[40:43], v[96:99], v[56:59], v[40:43]
	global_load_lds_dwordx4 v[134:135], off
	ds_read_b128 v[60:63], v141 offset:32768
	v_mfma_f32_16x16x32_bf16 v[44:47], v[218:221], v[56:59], v[52:55]
	s_cmp_lg_u32 s16, 2
	s_cselect_b32 s16, s17, 0
	s_mul_i32 s17, s16, 0xc000
	v_mfma_f32_16x16x32_bf16 v[16:19], v[226:229], v[56:59], v[16:19]
	s_add_i32 s22, s17, 0xffff4000
	s_cmp_gt_i32 s16, 0
	s_cselect_b32 s22, s22, 0x18000
	v_mfma_f32_16x16x32_bf16 v[52:55], v[96:99], v[230:233], v[72:75]
	s_add_i32 s22, s30, s22
	s_mov_b32 m0, s22
	v_lshl_add_u64 v[10:11], v[10:11], 0, s[66:67]
	v_mfma_f32_16x16x32_bf16 v[56:59], v[218:221], v[230:233], v[76:79]
	s_add_i32 s17, s17, 0
	v_add_u32_e32 v217, s17, v3
	v_mfma_f32_16x16x32_bf16 v[48:51], v[226:229], v[230:233], v[48:51]
	v_mfma_f32_16x16x32_bf16 v[72:75], v[96:99], v[234:237], v[80:83]
	s_nop 2
	ds_read_b128 v[80:83], v140
	ds_read_b128 v[84:87], v140 offset:1024
	ds_read_b128 v[88:91], v141 offset:33792
	v_mfma_f32_16x16x32_bf16 v[76:79], v[218:221], v[234:237], v[92:95]
	v_mfma_f32_16x16x32_bf16 v[64:67], v[226:229], v[234:237], v[64:67]
	v_mfma_f32_16x16x32_bf16 v[24:27], v[96:99], v[238:241], v[24:27]
	s_nop 0
	ds_read_b128 v[92:95], v141 offset:34816
	ds_read_b128 v[96:99], v141 offset:35840
	v_mfma_f32_16x16x32_bf16 v[32:35], v[218:221], v[238:241], v[32:35]
	ds_read_b128 v[132:135], v141 offset:36864
	ds_read_b128 v[218:221], v141 offset:37888
	v_mfma_f32_16x16x32_bf16 v[36:39], v[226:229], v[238:241], v[36:39]
	ds_read_b128 v[222:225], v141 offset:38912
	ds_read_b128 v[226:229], v141 offset:39936
	s_waitcnt lgkmcnt(0)
	v_mfma_f32_16x16x32_bf16 v[28:31], v[60:63], v[80:83], v[28:31]
	v_mfma_f32_16x16x32_bf16 v[40:43], v[92:95], v[80:83], v[40:43]
	v_mfma_f32_16x16x32_bf16 v[44:47], v[132:135], v[80:83], v[44:47]
	v_mfma_f32_16x16x32_bf16 v[16:19], v[222:225], v[80:83], v[16:19]
	ds_read_b128 v[80:83], v140 offset:2048
	ds_read_b128 v[230:233], v140 offset:3072
	s_waitcnt lgkmcnt(0)
	v_mfma_f32_16x16x32_bf16 v[20:23], v[60:63], v[80:83], v[20:23]
	v_mfma_f32_16x16x32_bf16 v[52:55], v[92:95], v[80:83], v[52:55]
	v_mfma_f32_16x16x32_bf16 v[56:59], v[132:135], v[80:83], v[56:59]
	v_mfma_f32_16x16x32_bf16 v[48:51], v[222:225], v[80:83], v[48:51]
	ds_read_b128 v[80:83], v140 offset:4096
	ds_read_b128 v[234:237], v140 offset:5120
	s_waitcnt lgkmcnt(0)
	v_mfma_f32_16x16x32_bf16 v[68:71], v[60:63], v[80:83], v[68:71]
	v_mfma_f32_16x16x32_bf16 v[72:75], v[92:95], v[80:83], v[72:75]
	v_mfma_f32_16x16x32_bf16 v[76:79], v[132:135], v[80:83], v[76:79]
	v_mfma_f32_16x16x32_bf16 v[64:67], v[222:225], v[80:83], v[64:67]
	ds_read_b128 v[80:83], v140 offset:6144
	ds_read_b128 v[238:241], v140 offset:7168
	s_waitcnt vmcnt(6)
	s_barrier
	s_waitcnt lgkmcnt(0)
	v_mfma_f32_16x16x32_bf16 v[12:15], v[60:63], v[80:83], v[12:15]
	v_mfma_f32_16x16x32_bf16 v[24:27], v[92:95], v[80:83], v[24:27]
	v_mfma_f32_16x16x32_bf16 v[32:35], v[132:135], v[80:83], v[32:35]
	v_mfma_f32_16x16x32_bf16 v[36:39], v[222:225], v[80:83], v[36:39]
	v_lshl_add_u64 v[80:81], v[4:5], 0, s[62:63]
	v_lshl_add_u64 v[82:83], v[6:7], 0, s[62:63]
	global_load_lds_dwordx4 v[80:81], off
	s_add_i32 m0, s22, 0x2000
	v_mfma_f32_16x16x32_bf16 v[60:63], v[226:229], v[84:87], v[16:19]
	global_load_lds_dwordx4 v[82:83], off
	s_add_i32 m0, s22, 0x4000
	s_nop 0
	v_lshl_add_u64 v[16:17], v[4:5], 0, s[64:65]
	v_lshl_add_u64 v[18:19], v[6:7], 0, s[64:65]
	global_load_lds_dwordx4 v[16:17], off
	s_add_i32 m0, s22, 0x6000
	v_mfma_f32_16x16x32_bf16 v[28:31], v[88:91], v[84:87], v[28:31]
	global_load_lds_dwordx4 v[18:19], off
	s_add_i32 m0, s22, 0x8000
	v_mfma_f32_16x16x32_bf16 v[4:7], v[88:91], v[230:233], v[20:23]
	global_load_lds_dwordx4 v[8:9], off
	s_add_i32 m0, s22, 0xa000
	s_nop 0
	v_add_u32_e32 v20, s17, v145
	global_load_lds_dwordx4 v[10:11], off
	v_mfma_f32_16x16x32_bf16 v[44:47], v[218:221], v[84:87], v[44:47]
	s_add_i32 s17, s16, 1
	s_cmp_lg_u32 s16, 2
	s_cselect_b32 s16, s17, 0
	v_mfma_f32_16x16x32_bf16 v[52:55], v[96:99], v[230:233], v[52:55]
	s_add_u32 s20, s20, 0x800000
	s_addc_u32 s21, s21, 0
	s_add_u32 s26, s26, 0x80000
	v_mfma_f32_16x16x32_bf16 v[56:59], v[218:221], v[230:233], v[56:59]
	s_addc_u32 s27, s27, 0
	s_cmp_eq_u32 s20, 0x1800000
	v_mfma_f32_16x16x32_bf16 v[48:51], v[226:229], v[230:233], v[48:51]
	v_mfma_f32_16x16x32_bf16 v[222:225], v[218:221], v[234:237], v[76:79]
	v_mfma_f32_16x16x32_bf16 v[230:233], v[226:229], v[234:237], v[64:67]
	v_mfma_f32_16x16x32_bf16 v[242:245], v[96:99], v[238:241], v[24:27]
	v_mfma_f32_16x16x32_bf16 v[218:221], v[218:221], v[238:241], v[32:35]
	v_mfma_f32_16x16x32_bf16 v[36:39], v[226:229], v[238:241], v[36:39]
	ds_read_b128 v[226:229], v20 offset:32768
	s_nop 0
	ds_read_b128 v[32:35], v217
	ds_read_b128 v[24:27], v217 offset:1024
	ds_read_b128 v[8:11], v20 offset:33792
	v_mfma_f32_16x16x32_bf16 v[40:43], v[96:99], v[84:87], v[40:43]
	v_mfma_f32_16x16x32_bf16 v[68:71], v[88:91], v[234:237], v[68:71]
	v_mfma_f32_16x16x32_bf16 v[132:135], v[96:99], v[234:237], v[72:75]
	v_mfma_f32_16x16x32_bf16 v[234:237], v[88:91], v[238:241], v[12:15]
	ds_read_b128 v[246:249], v20 offset:34816
	s_nop 1
	ds_read_b128 v[12:15], v20 offset:35840
	ds_read_b128 v[250:253], v20 offset:36864
	ds_read_b128 v[16:19], v20 offset:37888
	ds_read_b128 v[140:143], v20 offset:38912
	ds_read_b128 v[20:23], v20 offset:39936
	s_waitcnt lgkmcnt(0)
; __device__ __forceinline__ float bflo(unsigned w) { return __uint_as_float(w << 16); }
; __device__ __forceinline__ float bfhi(unsigned w) { return __uint_as_float(w & 0xffff0000u); }
; __device__ __forceinline__ float sigm(float x) { return frcp(1.f + fexp(-x)); }
; __device__ __forceinline__ void bgemm_phase(LAS unsigned char* lds, const bf16_t* outs, const bf16_t* wbr, const bf16_t* zg, bf16_t* merged) {
;     ...
;             size_t goff = (((size_t)n * 64 + pm) * 8 + pn) * 32768 + (size_t)(((wm * 4) * 4 + wn * 2) * 64 + fq * 16 + fr) * 8;
;             asm volatile("" : "+v"(goff) :: "memory");
;             const bf16_t* gp0 = zg + goff;
;             u32x4 gv[2][2];
; #pragma unroll
;             for (int mi = 0; mi < 2; ++mi)
; #pragma unroll
;                 for (int g = 0; g < 2; ++g) gv[mi][g] = *(const u32x4*)(gp0 + (mi * 4 + g) * 512);
;             BG_COMPUTE(slot); slot = slot == 2 ? 0 : slot + 1;
; #pragma unroll
;             for (int hf = 0; hf < 2; ++hf) {
;                 u32x4 gn[2][2];
;                 if (hf == 0) {
; #pragma unroll
;                     for (int mi = 0; mi < 2; ++mi)
; #pragma unroll
;                         for (int g = 0; g < 2; ++g) gn[mi][g] = *(const u32x4*)(gp0 + ((2 + mi) * 4 + g) * 512);
;                 }
; #pragma unroll
;                 for (int mi = 0; mi < 2; ++mi)
; #pragma unroll
;                     for (int g = 0; g < 2; ++g) { const u32x4 gq = gv[mi][g]; const int m2 = hf * 2 + mi;
;                         tot[m2][2 * g][0] += sigm(bflo(gq.x)) * acc[m2][2 * g][0]; tot[m2][2 * g][1] += sigm(bfhi(gq.x)) * acc[m2][2 * g][1];
;                         tot[m2][2 * g][2] += sigm(bflo(gq.y)) * acc[m2][2 * g][2]; tot[m2][2 * g][3] += sigm(bfhi(gq.y)) * acc[m2][2 * g][3];
;                         tot[m2][2 * g + 1][0] += sigm(bflo(gq.z)) * acc[m2][2 * g + 1][0]; tot[m2][2 * g + 1][1] += sigm(bfhi(gq.z)) * acc[m2][2 * g + 1][1];
;                         tot[m2][2 * g + 1][2] += sigm(bflo(gq.w)) * acc[m2][2 * g + 1][2]; tot[m2][2 * g + 1][3] += sigm(bfhi(gq.w)) * acc[m2][2 * g + 1][3];
	v_mfma_f32_16x16x32_bf16 v[238:241], v[226:229], v[32:35], v[28:31]
	s_nop 2
	ds_read_b128 v[28:31], v217 offset:2048
	ds_read_b128 v[64:67], v217 offset:3072
	v_mfma_f32_16x16x32_bf16 v[96:99], v[246:249], v[32:35], v[40:43]
	v_mfma_f32_16x16x32_bf16 v[92:95], v[250:253], v[32:35], v[44:47]
	v_mfma_f32_16x16x32_bf16 v[88:91], v[140:143], v[32:35], v[60:63]
	s_waitcnt lgkmcnt(0)
	v_mfma_f32_16x16x32_bf16 v[84:87], v[226:229], v[28:31], v[4:7]
	s_nop 2
	ds_read_b128 v[4:7], v217 offset:4096
	ds_read_b128 v[32:35], v217 offset:5120
	v_mfma_f32_16x16x32_bf16 v[80:83], v[246:249], v[28:31], v[52:55]
	v_mfma_f32_16x16x32_bf16 v[76:79], v[250:253], v[28:31], v[56:59]
	v_mfma_f32_16x16x32_bf16 v[72:75], v[140:143], v[28:31], v[48:51]
	s_waitcnt lgkmcnt(0)
	v_mfma_f32_16x16x32_bf16 v[68:71], v[226:229], v[4:7], v[68:71]
	v_mfma_f32_16x16x32_bf16 v[56:59], v[246:249], v[4:7], v[132:135]
	v_mfma_f32_16x16x32_bf16 v[48:51], v[250:253], v[4:7], v[222:225]
	v_mfma_f32_16x16x32_bf16 v[40:43], v[140:143], v[4:7], v[230:233]
	ds_read_b128 v[4:7], v217 offset:6144
	ds_read_b128 v[28:31], v217 offset:7168
	s_waitcnt lgkmcnt(0)
	v_mfma_f32_16x16x32_bf16 v[36:39], v[140:143], v[4:7], v[36:39]
	v_lshl_add_u64 v[140:141], v[200:201], 1, s[8:9]
	v_add_co_u32_e32 v142, vcc, s80, v140
	v_mfma_f32_16x16x32_bf16 v[60:63], v[226:229], v[4:7], v[234:237]
	s_nop 0
	v_addc_co_u32_e32 v143, vcc, 0, v141, vcc
	v_add_co_u32_e32 v200, vcc, s81, v140
	v_mfma_f32_16x16x32_bf16 v[52:55], v[246:249], v[4:7], v[242:245]
	s_nop 0
	v_addc_co_u32_e32 v201, vcc, 0, v141, vcc
	global_load_dwordx4 v[132:135], v[140:141], off offset:1024
	v_mfma_f32_16x16x32_bf16 v[44:47], v[250:253], v[4:7], v[218:221]
	s_nop 2
	v_add_co_u32_e32 v218, vcc, s82, v140
	v_mfma_f32_16x16x32_bf16 v[4:7], v[8:11], v[24:27], v[238:241]
	s_nop 0
	v_addc_co_u32_e32 v219, vcc, 0, v141, vcc
	v_mfma_f32_16x16x32_bf16 v[96:99], v[12:15], v[24:27], v[96:99]
	v_mfma_f32_16x16x32_bf16 v[92:95], v[16:19], v[24:27], v[92:95]
	v_mfma_f32_16x16x32_bf16 v[24:27], v[20:23], v[24:27], v[88:91]
	v_mfma_f32_16x16x32_bf16 v[84:87], v[8:11], v[64:67], v[84:87]
	s_nop 1
	global_load_dwordx4 v[88:91], v[140:141], off
	s_nop 0
	global_load_dwordx4 v[140:143], v[142:143], off offset:1024
	v_mfma_f32_16x16x32_bf16 v[80:83], v[12:15], v[64:67], v[80:83]
	s_waitcnt vmcnt(0)
	v_lshlrev_b32_e32 v220, 16, v141
	v_mfma_f32_16x16x32_bf16 v[76:79], v[16:19], v[64:67], v[76:79]
	v_and_b32_e32 v141, 0xffff0000, v141
	v_lshlrev_b32_e32 v221, 16, v142
	v_and_b32_e32 v142, 0xffff0000, v142
	v_mfma_f32_16x16x32_bf16 v[64:67], v[20:23], v[64:67], v[72:75]
	v_lshlrev_b32_e32 v222, 16, v143
	v_and_b32_e32 v143, 0xffff0000, v143
	v_mul_f32_e32 v220, 0xbfb8aa3b, v220
	v_mfma_f32_16x16x32_bf16 v[68:71], v[8:11], v[32:35], v[68:71]
	global_load_dwordx4 v[72:75], v[200:201], off offset:-4096
	v_mul_f32_e32 v141, 0xbfb8aa3b, v141
	v_mul_f32_e32 v221, 0xbfb8aa3b, v221
	v_mfma_f32_16x16x32_bf16 v[56:59], v[12:15], v[32:35], v[56:59]
	v_mul_f32_e32 v142, 0xbfb8aa3b, v142
	v_mul_f32_e32 v222, 0xbfb8aa3b, v222
	v_mul_f32_e32 v143, 0xbfb8aa3b, v143
	v_mfma_f32_16x16x32_bf16 v[48:51], v[16:19], v[32:35], v[48:51]
	v_exp_f32_e32 v220, v220
	v_exp_f32_e32 v141, v141
	v_exp_f32_e32 v221, v221
	v_mfma_f32_16x16x32_bf16 v[32:35], v[20:23], v[32:35], v[40:43]
	v_exp_f32_e32 v142, v142
	v_exp_f32_e32 v222, v222
	v_exp_f32_e32 v143, v143
	global_load_dwordx4 v[40:43], v[200:201], off
	v_mfma_f32_16x16x32_bf16 v[8:11], v[8:11], v[28:31], v[60:63]
	v_add_f32_e32 v143, 1.0, v143
	s_waitcnt vmcnt(1)
	v_lshlrev_b32_e32 v217, 16, v74
	global_load_dwordx4 v[60:63], v[200:201], off offset:1024
	v_mfma_f32_16x16x32_bf16 v[12:15], v[12:15], v[28:31], v[52:55]
	v_lshlrev_b32_e32 v200, 16, v72
	v_and_b32_e32 v72, 0xffff0000, v72
	v_lshlrev_b32_e32 v201, 16, v73
	global_load_dwordx4 v[52:55], v[218:219], off
	v_mfma_f32_16x16x32_bf16 v[16:19], v[16:19], v[28:31], v[44:47]
	v_and_b32_e32 v73, 0xffff0000, v73
	v_and_b32_e32 v74, 0xffff0000, v74
	v_mul_f32_e32 v200, 0xbfb8aa3b, v200
	global_load_dwordx4 v[44:47], v[218:219], off offset:1024
	v_mfma_f32_16x16x32_bf16 v[20:23], v[20:23], v[28:31], v[36:39]
	v_lshlrev_b32_e32 v28, 16, v88
	v_and_b32_e32 v29, 0xffff0000, v88
	v_lshlrev_b32_e32 v30, 16, v89
	v_and_b32_e32 v31, 0xffff0000, v89
	v_lshlrev_b32_e32 v36, 16, v90
	v_and_b32_e32 v37, 0xffff0000, v90
	v_lshlrev_b32_e32 v38, 16, v91
	v_and_b32_e32 v39, 0xffff0000, v91
	v_lshlrev_b32_e32 v88, 16, v132
	v_and_b32_e32 v89, 0xffff0000, v132
	v_lshlrev_b32_e32 v90, 16, v133
	v_and_b32_e32 v91, 0xffff0000, v133
	v_lshlrev_b32_e32 v132, 16, v134
	v_and_b32_e32 v133, 0xffff0000, v134
	v_lshlrev_b32_e32 v134, 16, v135
	v_and_b32_e32 v135, 0xffff0000, v135
	v_lshlrev_b32_e32 v218, 16, v75
	v_and_b32_e32 v75, 0xffff0000, v75
	v_lshlrev_b32_e32 v219, 16, v140
	v_and_b32_e32 v140, 0xffff0000, v140
	s_waitcnt vmcnt(3)
; __device__ __forceinline__ float bflo(unsigned w) { return __uint_as_float(w << 16); }
; __device__ __forceinline__ float bfhi(unsigned w) { return __uint_as_float(w & 0xffff0000u); }
; __device__ __forceinline__ float sigm(float x) { return frcp(1.f + fexp(-x)); }
; __device__ __forceinline__ void bgemm_phase(LAS unsigned char* lds, const bf16_t* outs, const bf16_t* wbr, const bf16_t* zg, bf16_t* merged) {
;     ...
; #pragma unroll
;                 for (int mi = 0; mi < 2; ++mi)
; #pragma unroll
;                     for (int g = 0; g < 2; ++g) { const u32x4 gq = gv[mi][g]; const int m2 = hf * 2 + mi;
;                         tot[m2][2 * g][0] += sigm(bflo(gq.x)) * acc[m2][2 * g][0]; tot[m2][2 * g][1] += sigm(bfhi(gq.x)) * acc[m2][2 * g][1];
;                         tot[m2][2 * g][2] += sigm(bflo(gq.y)) * acc[m2][2 * g][2]; tot[m2][2 * g][3] += sigm(bfhi(gq.y)) * acc[m2][2 * g][3];
;                         tot[m2][2 * g + 1][0] += sigm(bflo(gq.z)) * acc[m2][2 * g + 1][0]; tot[m2][2 * g + 1][1] += sigm(bfhi(gq.z)) * acc[m2][2 * g + 1][1];
;                         tot[m2][2 * g + 1][2] += sigm(bflo(gq.w)) * acc[m2][2 * g + 1][2]; tot[m2][2 * g + 1][3] += sigm(bfhi(gq.w)) * acc[m2][2 * g + 1][3];
;                         acc[m2][2 * g] = ZERO4; acc[m2][2 * g + 1] = ZERO4; }
	v_lshlrev_b32_e32 v223, 16, v40
	v_and_b32_e32 v40, 0xffff0000, v40
	v_lshlrev_b32_e32 v224, 16, v41
	v_and_b32_e32 v41, 0xffff0000, v41
	v_lshlrev_b32_e32 v225, 16, v42
	v_and_b32_e32 v42, 0xffff0000, v42
	v_lshlrev_b32_e32 v226, 16, v43
	v_and_b32_e32 v43, 0xffff0000, v43
	v_mul_f32_e32 v28, 0xbfb8aa3b, v28
	v_mul_f32_e32 v29, 0xbfb8aa3b, v29
	v_mul_f32_e32 v30, 0xbfb8aa3b, v30
	v_mul_f32_e32 v31, 0xbfb8aa3b, v31
	v_mul_f32_e32 v36, 0xbfb8aa3b, v36
	v_mul_f32_e32 v37, 0xbfb8aa3b, v37
	v_mul_f32_e32 v38, 0xbfb8aa3b, v38
	v_mul_f32_e32 v39, 0xbfb8aa3b, v39
	v_mul_f32_e32 v88, 0xbfb8aa3b, v88
	v_mul_f32_e32 v89, 0xbfb8aa3b, v89
	v_mul_f32_e32 v90, 0xbfb8aa3b, v90
	v_mul_f32_e32 v91, 0xbfb8aa3b, v91
	v_mul_f32_e32 v132, 0xbfb8aa3b, v132
	v_mul_f32_e32 v133, 0xbfb8aa3b, v133
	v_mul_f32_e32 v134, 0xbfb8aa3b, v134
	v_mul_f32_e32 v135, 0xbfb8aa3b, v135
	v_mul_f32_e32 v72, 0xbfb8aa3b, v72
	v_mul_f32_e32 v201, 0xbfb8aa3b, v201
	v_mul_f32_e32 v73, 0xbfb8aa3b, v73
	v_mul_f32_e32 v217, 0xbfb8aa3b, v217
	v_mul_f32_e32 v74, 0xbfb8aa3b, v74
	v_mul_f32_e32 v218, 0xbfb8aa3b, v218
	v_mul_f32_e32 v75, 0xbfb8aa3b, v75
	v_mul_f32_e32 v219, 0xbfb8aa3b, v219
	v_mul_f32_e32 v140, 0xbfb8aa3b, v140
	v_mul_f32_e32 v223, 0xbfb8aa3b, v223
	v_mul_f32_e32 v40, 0xbfb8aa3b, v40
	v_mul_f32_e32 v224, 0xbfb8aa3b, v224
	v_mul_f32_e32 v41, 0xbfb8aa3b, v41
	v_mul_f32_e32 v225, 0xbfb8aa3b, v225
	v_mul_f32_e32 v42, 0xbfb8aa3b, v42
	v_mul_f32_e32 v226, 0xbfb8aa3b, v226
	v_mul_f32_e32 v43, 0xbfb8aa3b, v43
	v_exp_f32_e32 v28, v28
	v_exp_f32_e32 v29, v29
	v_exp_f32_e32 v30, v30
	v_exp_f32_e32 v31, v31
	v_exp_f32_e32 v36, v36
	v_exp_f32_e32 v37, v37
	v_exp_f32_e32 v38, v38
	s_waitcnt vmcnt(2)
	v_lshlrev_b32_e32 v227, 16, v60
	v_and_b32_e32 v60, 0xffff0000, v60
	v_lshlrev_b32_e32 v228, 16, v61
	v_and_b32_e32 v61, 0xffff0000, v61
	v_lshlrev_b32_e32 v229, 16, v62
	v_and_b32_e32 v62, 0xffff0000, v62
	v_lshlrev_b32_e32 v230, 16, v63
	v_and_b32_e32 v63, 0xffff0000, v63
	s_waitcnt vmcnt(1)
	v_lshlrev_b32_e32 v231, 16, v52
	v_and_b32_e32 v52, 0xffff0000, v52
	v_lshlrev_b32_e32 v232, 16, v53
	v_and_b32_e32 v53, 0xffff0000, v53
	v_lshlrev_b32_e32 v233, 16, v54
	v_and_b32_e32 v54, 0xffff0000, v54
	v_lshlrev_b32_e32 v234, 16, v55
	v_and_b32_e32 v55, 0xffff0000, v55
	s_waitcnt vmcnt(0)
	v_lshlrev_b32_e32 v235, 16, v44
	v_and_b32_e32 v44, 0xffff0000, v44
	v_lshlrev_b32_e32 v236, 16, v45
	v_and_b32_e32 v45, 0xffff0000, v45
	v_lshlrev_b32_e32 v237, 16, v46
	v_and_b32_e32 v46, 0xffff0000, v46
	v_lshlrev_b32_e32 v238, 16, v47
	v_and_b32_e32 v47, 0xffff0000, v47
	v_mul_f32_e32 v227, 0xbfb8aa3b, v227
	v_mul_f32_e32 v60, 0xbfb8aa3b, v60
	v_mul_f32_e32 v228, 0xbfb8aa3b, v228
	v_mul_f32_e32 v61, 0xbfb8aa3b, v61
	v_mul_f32_e32 v229, 0xbfb8aa3b, v229
	v_mul_f32_e32 v62, 0xbfb8aa3b, v62
	v_mul_f32_e32 v230, 0xbfb8aa3b, v230
	v_mul_f32_e32 v63, 0xbfb8aa3b, v63
	v_mul_f32_e32 v231, 0xbfb8aa3b, v231
	v_mul_f32_e32 v52, 0xbfb8aa3b, v52
	v_mul_f32_e32 v232, 0xbfb8aa3b, v232
	v_mul_f32_e32 v53, 0xbfb8aa3b, v53
	v_mul_f32_e32 v233, 0xbfb8aa3b, v233
	v_mul_f32_e32 v54, 0xbfb8aa3b, v54
	v_mul_f32_e32 v234, 0xbfb8aa3b, v234
	v_mul_f32_e32 v55, 0xbfb8aa3b, v55
	v_mul_f32_e32 v235, 0xbfb8aa3b, v235
	v_mul_f32_e32 v44, 0xbfb8aa3b, v44
	v_mul_f32_e32 v236, 0xbfb8aa3b, v236
	v_mul_f32_e32 v45, 0xbfb8aa3b, v45
	v_mul_f32_e32 v237, 0xbfb8aa3b, v237
	v_mul_f32_e32 v46, 0xbfb8aa3b, v46
	v_mul_f32_e32 v238, 0xbfb8aa3b, v238
	v_mul_f32_e32 v47, 0xbfb8aa3b, v47
	v_exp_f32_e32 v39, v39
	v_exp_f32_e32 v88, v88
	v_exp_f32_e32 v89, v89
	v_exp_f32_e32 v90, v90
	v_exp_f32_e32 v91, v91
	v_exp_f32_e32 v132, v132
	v_exp_f32_e32 v133, v133
	v_exp_f32_e32 v134, v134
	v_exp_f32_e32 v135, v135
	v_exp_f32_e32 v200, v200
	v_exp_f32_e32 v72, v72
	v_exp_f32_e32 v201, v201
	v_exp_f32_e32 v73, v73
	v_exp_f32_e32 v217, v217
	v_exp_f32_e32 v74, v74
	v_exp_f32_e32 v218, v218
	v_exp_f32_e32 v75, v75
	v_exp_f32_e32 v219, v219
	v_exp_f32_e32 v140, v140
	v_exp_f32_e32 v223, v223
	v_exp_f32_e32 v239, v40
	v_exp_f32_e32 v224, v224
	v_exp_f32_e32 v240, v41
	v_exp_f32_e32 v225, v225
	v_exp_f32_e32 v241, v42
	v_exp_f32_e32 v226, v226
	v_exp_f32_e32 v242, v43
	v_exp_f32_e32 v227, v227
	v_exp_f32_e32 v60, v60
	v_exp_f32_e32 v228, v228
	v_exp_f32_e32 v61, v61
	v_exp_f32_e32 v229, v229
	v_exp_f32_e32 v62, v62
	v_exp_f32_e32 v230, v230
	v_exp_f32_e32 v63, v63
	v_exp_f32_e32 v231, v231
	v_exp_f32_e32 v52, v52
	v_exp_f32_e32 v232, v232
	v_exp_f32_e32 v53, v53
	v_exp_f32_e32 v233, v233
	v_exp_f32_e32 v54, v54
	v_exp_f32_e32 v234, v234
	v_exp_f32_e32 v55, v55
	v_exp_f32_e32 v235, v235
	v_exp_f32_e32 v243, v44
	v_exp_f32_e32 v236, v236
	v_exp_f32_e32 v244, v45
	v_exp_f32_e32 v237, v237
	v_exp_f32_e32 v245, v46
	v_exp_f32_e32 v238, v238
	v_exp_f32_e32 v246, v47
	v_add_f32_e32 v28, 1.0, v28
	v_add_f32_e32 v29, 1.0, v29
	v_add_f32_e32 v30, 1.0, v30
	v_add_f32_e32 v31, 1.0, v31
	v_add_f32_e32 v36, 1.0, v36
	v_add_f32_e32 v37, 1.0, v37
	v_add_f32_e32 v38, 1.0, v38
	v_add_f32_e32 v39, 1.0, v39
	v_add_f32_e32 v40, 1.0, v88
	v_add_f32_e32 v41, 1.0, v89
	v_add_f32_e32 v42, 1.0, v90
	v_add_f32_e32 v43, 1.0, v91
	v_add_f32_e32 v44, 1.0, v132
	v_add_f32_e32 v45, 1.0, v133
	v_add_f32_e32 v46, 1.0, v134
	v_add_f32_e32 v47, 1.0, v135
	v_add_f32_e32 v88, 1.0, v200
	v_add_f32_e32 v72, 1.0, v72
	v_add_f32_e32 v89, 1.0, v201
	v_add_f32_e32 v73, 1.0, v73
	v_add_f32_e32 v90, 1.0, v217
	v_add_f32_e32 v74, 1.0, v74
	v_add_f32_e32 v91, 1.0, v218
	v_add_f32_e32 v75, 1.0, v75
	v_add_f32_e32 v132, 1.0, v219
	v_add_f32_e32 v133, 1.0, v140
	v_add_f32_e32 v134, 1.0, v220
	v_add_f32_e32 v135, 1.0, v141
	v_add_f32_e32 v140, 1.0, v221
	v_add_f32_e32 v141, 1.0, v142
	v_add_f32_e32 v142, 1.0, v222
; __device__ __forceinline__ float bflo(unsigned w) { return __uint_as_float(w << 16); }
; __device__ __forceinline__ float bfhi(unsigned w) { return __uint_as_float(w & 0xffff0000u); }
; __device__ __forceinline__ float sigm(float x) { return frcp(1.f + fexp(-x)); }
; __device__ __forceinline__ void bgemm_phase(LAS unsigned char* lds, const bf16_t* outs, const bf16_t* wbr, const bf16_t* zg, bf16_t* merged) {
;     ...
; #pragma unroll
;                 for (int mi = 0; mi < 2; ++mi)
; #pragma unroll
;                     for (int g = 0; g < 2; ++g) { const u32x4 gq = gv[mi][g]; const int m2 = hf * 2 + mi;
;                         tot[m2][2 * g][0] += sigm(bflo(gq.x)) * acc[m2][2 * g][0]; tot[m2][2 * g][1] += sigm(bfhi(gq.x)) * acc[m2][2 * g][1];
;                         tot[m2][2 * g][2] += sigm(bflo(gq.y)) * acc[m2][2 * g][2]; tot[m2][2 * g][3] += sigm(bfhi(gq.y)) * acc[m2][2 * g][3];
;                         tot[m2][2 * g + 1][0] += sigm(bflo(gq.z)) * acc[m2][2 * g + 1][0]; tot[m2][2 * g + 1][1] += sigm(bfhi(gq.z)) * acc[m2][2 * g + 1][1];
;                         tot[m2][2 * g + 1][2] += sigm(bflo(gq.w)) * acc[m2][2 * g + 1][2]; tot[m2][2 * g + 1][3] += sigm(bfhi(gq.w)) * acc[m2][2 * g + 1][3];
;                         acc[m2][2 * g] = ZERO4; acc[m2][2 * g + 1] = ZERO4; }
	v_add_f32_e32 v200, 1.0, v223
	v_add_f32_e32 v201, 1.0, v239
	v_add_f32_e32 v217, 1.0, v224
	v_add_f32_e32 v218, 1.0, v240
	v_add_f32_e32 v219, 1.0, v225
	v_add_f32_e32 v220, 1.0, v241
	v_add_f32_e32 v221, 1.0, v226
	v_add_f32_e32 v222, 1.0, v242
	v_add_f32_e32 v223, 1.0, v227
	v_add_f32_e32 v224, 1.0, v60
	v_add_f32_e32 v225, 1.0, v228
	v_add_f32_e32 v226, 1.0, v61
	v_add_f32_e32 v227, 1.0, v229
	v_add_f32_e32 v228, 1.0, v62
	v_add_f32_e32 v229, 1.0, v230
	v_add_f32_e32 v230, 1.0, v63
	v_add_f32_e32 v231, 1.0, v231
	v_add_f32_e32 v239, 1.0, v52
	v_add_f32_e32 v232, 1.0, v232
	v_add_f32_e32 v240, 1.0, v53
	v_add_f32_e32 v233, 1.0, v233
	v_add_f32_e32 v241, 1.0, v54
	v_add_f32_e32 v234, 1.0, v234
	v_add_f32_e32 v242, 1.0, v55
	v_add_f32_e32 v235, 1.0, v235
	v_add_f32_e32 v243, 1.0, v243
	v_add_f32_e32 v236, 1.0, v236
	v_add_f32_e32 v244, 1.0, v244
	v_add_f32_e32 v237, 1.0, v237
	v_add_f32_e32 v245, 1.0, v245
	v_add_f32_e32 v238, 1.0, v238
	v_add_f32_e32 v246, 1.0, v246
	v_rcp_f32_e32 v28, v28
	v_rcp_f32_e32 v29, v29
	v_rcp_f32_e32 v30, v30
	v_rcp_f32_e32 v31, v31
	v_rcp_f32_e32 v36, v36
	v_rcp_f32_e32 v37, v37
	v_rcp_f32_e32 v38, v38
	v_rcp_f32_e32 v39, v39
	v_rcp_f32_e32 v40, v40
	v_rcp_f32_e32 v41, v41
	v_rcp_f32_e32 v42, v42
	v_rcp_f32_e32 v43, v43
	v_rcp_f32_e32 v44, v44
	v_rcp_f32_e32 v45, v45
	v_rcp_f32_e32 v46, v46
	v_rcp_f32_e32 v47, v47
	v_rcp_f32_e32 v52, v88
	v_rcp_f32_e32 v53, v72
	v_rcp_f32_e32 v54, v89
	v_rcp_f32_e32 v55, v73
	v_rcp_f32_e32 v60, v90
	v_rcp_f32_e32 v61, v74
	v_rcp_f32_e32 v62, v91
	v_rcp_f32_e32 v63, v75
	v_rcp_f32_e32 v72, v132
	v_rcp_f32_e32 v73, v133
	v_rcp_f32_e32 v74, v134
	v_rcp_f32_e32 v75, v135
	v_rcp_f32_e32 v88, v140
	v_rcp_f32_e32 v89, v141
	v_rcp_f32_e32 v90, v142
	v_rcp_f32_e32 v91, v143
	v_rcp_f32_e32 v132, v200
	v_rcp_f32_e32 v133, v201
	v_rcp_f32_e32 v134, v217
	v_rcp_f32_e32 v135, v218
	v_rcp_f32_e32 v140, v219
	v_rcp_f32_e32 v141, v220
	v_rcp_f32_e32 v142, v221
	v_rcp_f32_e32 v143, v222
	v_rcp_f32_e32 v200, v223
	v_rcp_f32_e32 v201, v224
	v_rcp_f32_e32 v218, v225
	v_rcp_f32_e32 v219, v226
	v_rcp_f32_e32 v220, v227
	v_rcp_f32_e32 v221, v228
	v_rcp_f32_e32 v222, v229
	v_rcp_f32_e32 v223, v230
	v_rcp_f32_e32 v224, v231
	v_rcp_f32_e32 v225, v239
	v_rcp_f32_e32 v226, v232
	v_rcp_f32_e32 v227, v240
	v_rcp_f32_e32 v228, v233
	v_rcp_f32_e32 v229, v241
	v_rcp_f32_e32 v230, v234
	v_rcp_f32_e32 v231, v242
	v_rcp_f32_e32 v232, v235
	v_rcp_f32_e32 v233, v243
	v_rcp_f32_e32 v234, v236
	v_rcp_f32_e32 v235, v244
	v_rcp_f32_e32 v236, v237
	v_rcp_f32_e32 v237, v245
	v_rcp_f32_e32 v238, v238
	v_rcp_f32_e32 v239, v246
	v_fma_f32 v190, v28, v4, v190
	v_fma_f32 v191, v29, v5, v191
	v_fma_f32 v192, v30, v6, v192
	v_fma_f32 v193, v31, v7, v193
	v_fma_f32 v186, v36, v96, v186
	v_fma_f32 v187, v37, v97, v187
	v_fma_f32 v188, v38, v98, v188
	v_fma_f32 v189, v39, v99, v189
	v_fma_f32 v182, v40, v92, v182
	v_fma_f32 v183, v41, v93, v183
	v_fma_f32 v184, v42, v94, v184
	v_fma_f32 v185, v43, v95, v185
	v_fma_f32 v178, v44, v24, v178
	v_fma_f32 v179, v45, v25, v179
	v_fma_f32 v180, v46, v26, v180
	v_fma_f32 v181, v47, v27, v181
	v_fma_f32 v174, v52, v84, v174
	v_fma_f32 v175, v53, v85, v175
	v_fma_f32 v176, v54, v86, v176
	v_fma_f32 v177, v55, v87, v177
	v_fma_f32 v170, v60, v80, v170
	v_fma_f32 v171, v61, v81, v171
	v_fma_f32 v172, v62, v82, v172
	v_fma_f32 v173, v63, v83, v173
	v_fma_f32 v166, v72, v76, v166
	v_fma_f32 v167, v73, v77, v167
	v_fma_f32 v168, v74, v78, v168
	v_fma_f32 v169, v75, v79, v169
	v_fma_f32 v162, v88, v64, v162
	v_fma_f32 v163, v89, v65, v163
	v_fma_f32 v164, v90, v66, v164
	v_fma_f32 v165, v91, v67, v165
	v_fma_f32 v158, v68, v132, v158
	v_fma_f32 v159, v69, v133, v159
	v_fma_f32 v160, v70, v134, v160
	v_fma_f32 v161, v71, v135, v161
	v_fma_f32 v154, v56, v140, v154
	v_fma_f32 v155, v57, v141, v155
	v_fma_f32 v156, v58, v142, v156
	v_fma_f32 v157, v59, v143, v157
	v_fma_f32 v150, v48, v200, v150
	v_fma_f32 v151, v49, v201, v151
	v_fma_f32 v152, v50, v218, v152
	v_fma_f32 v153, v51, v219, v153
	v_fma_f32 v146, v32, v220, v146
	v_fma_f32 v147, v33, v221, v147
	v_fma_f32 v148, v34, v222, v148
	v_fma_f32 v149, v35, v223, v149
	v_fma_f32 v128, v8, v224, v128
	v_fma_f32 v129, v9, v225, v129
	v_fma_f32 v130, v10, v226, v130
	v_fma_f32 v131, v11, v227, v131
	v_fma_f32 v124, v12, v228, v124
	v_fma_f32 v125, v13, v229, v125
	v_fma_f32 v126, v14, v230, v126
	v_fma_f32 v127, v15, v231, v127
	v_fma_f32 v120, v16, v232, v120
	v_fma_f32 v121, v17, v233, v121
	v_fma_f32 v122, v18, v234, v122
	v_fma_f32 v123, v19, v235, v123
	v_fma_f32 v116, v20, v236, v116
	v_fma_f32 v117, v21, v237, v117
	v_fma_f32 v118, v22, v238, v118
	v_fma_f32 v119, v23, v239, v119
	s_cbranch_scc0 .LBB0_296
	s_add_u32 s16, s14, 0x1800100
	s_addc_u32 s17, s15, 0
	s_waitcnt vmcnt(6)
	s_barrier
; #define BG_STAGE(kk_, slot_) do { const int _n = (kk_) >> 2, _kt = (kk_) & 3; const int _so = (slot_) * STG; \
;         const bf16_t* _a = outs + ((size_t)_n * M + (size_t)pm * 256) * 256 + _kt * 64; const bf16_t* _b = wbr + ((size_t)_n * 1024 + (size_t)pn * 128) * 256 + _kt * 64; \
;         BG_LD(_so, _a); BG_LD(_so + HTB, _a + 128 * 256); BG_LDX(_so + 2 * HTB, _b, voffB); } while (0)
; #define BG_WAIT(n) asm volatile("s_waitcnt vmcnt(" #n ")" ::: "memory")
; #define BG_BAR() do { __builtin_amdgcn_s_barrier(); asm volatile("" ::: "memory"); } while (0)
; __device__ __forceinline__ void bgemm_phase(LAS unsigned char* lds, const bf16_t* outs, const bf16_t* wbr, const bf16_t* zg, bf16_t* merged) {
;     ...
;         for (int n = 0; n < 4; ++n) {
;             const int kk0 = n * 4;
;             BG_WAIT(6); BG_BAR(); { const int s2 = slot >= 1 ? slot - 1 : 2; BG_STAGE(kk0 + 2, s2); } BG_COMPUTE(slot); slot = slot == 2 ? 0 : slot + 1;
;             BG_WAIT(6); BG_BAR(); { const int s2 = slot >= 1 ? slot - 1 : 2; BG_STAGE(kk0 + 3, s2); } BG_COMPUTE(slot); slot = slot == 2 ? 0 : slot + 1;
;             BG_WAIT(6); BG_BAR(); if (n < 3) { const int s2 = slot >= 1 ? slot - 1 : 2; BG_STAGE(kk0 + 4, s2); } BG_COMPUTE(slot); slot = slot == 2 ? 0 : slot + 1;
;             if (n < 3) { BG_WAIT(6); } else { BG_WAIT(0); }
;             BG_BAR(); if (n < 3) { const int s2 = slot >= 1 ? slot - 1 : 2; BG_STAGE(kk0 + 5, s2); }
	v_lshl_add_u64 v[4:5], s[16:17], 0, v[104:105]
	s_mov_b32 m0, s31
	v_add_u32_e32 v98, 0, v214
	global_load_lds_dwordx4 v[4:5], off
	v_lshl_add_u64 v[4:5], s[16:17], 0, v[100:101]
	s_add_u32 s16, s14, 0x1810100
	s_mov_b32 m0, s34
	s_addc_u32 s17, s15, 0
	global_load_lds_dwordx4 v[4:5], off
	v_lshl_add_u64 v[4:5], s[16:17], 0, v[104:105]
	s_add_i32 m0, s30, 0x1c000
	s_nop 0
	global_load_lds_dwordx4 v[4:5], off
	s_add_i32 m0, s30, 0x1e000
	v_lshl_add_u64 v[4:5], s[16:17], 0, v[100:101]
	s_add_u32 s16, s18, 0x180100
	s_addc_u32 s17, s19, 0
	global_load_lds_dwordx4 v[4:5], off
	v_lshl_add_u64 v[4:5], s[16:17], 0, v[102:103]
	s_add_i32 m0, s30, 0x20000
	s_nop 0
	global_load_lds_dwordx4 v[4:5], off
	v_lshl_add_u64 v[4:5], s[16:17], 0, v[0:1]
	s_add_i32 m0, s30, 0x22000
	s_add_u32 s16, s14, 0x1800180
	global_load_lds_dwordx4 v[4:5], off
	v_add_u32_e32 v4, 0, v3
	v_add_u32_e32 v5, 0, v145
	ds_read_b128 v[6:9], v4
	ds_read_b128 v[10:13], v4 offset:2048
	ds_read_b128 v[14:17], v4 offset:4096
	ds_read_b128 v[18:21], v4 offset:6144
	ds_read_b128 v[22:25], v5 offset:32768
	ds_read_b128 v[26:29], v5 offset:34816
	ds_read_b128 v[30:33], v5 offset:36864
	ds_read_b128 v[34:37], v5 offset:38912
	s_waitcnt lgkmcnt(0)
	v_mfma_f32_16x16x32_bf16 v[38:41], v[22:25], v[6:9], 0
	s_addc_u32 s17, s15, 0
	s_mov_b32 m0, s30
	s_add_u32 s14, s14, 0x1810180
	v_mfma_f32_16x16x32_bf16 v[42:45], v[26:29], v[6:9], 0
	s_addc_u32 s15, s15, 0
	v_mfma_f32_16x16x32_bf16 v[46:49], v[30:33], v[6:9], 0
	v_mfma_f32_16x16x32_bf16 v[6:9], v[34:37], v[6:9], 0
	v_mfma_f32_16x16x32_bf16 v[50:53], v[22:25], v[10:13], 0
	v_mfma_f32_16x16x32_bf16 v[54:57], v[26:29], v[10:13], 0
	v_mfma_f32_16x16x32_bf16 v[58:61], v[30:33], v[10:13], 0
	v_mfma_f32_16x16x32_bf16 v[10:13], v[34:37], v[10:13], 0
	v_mfma_f32_16x16x32_bf16 v[62:65], v[22:25], v[14:17], 0
	v_mfma_f32_16x16x32_bf16 v[66:69], v[26:29], v[14:17], 0
	v_mfma_f32_16x16x32_bf16 v[70:73], v[30:33], v[14:17], 0
	v_mfma_f32_16x16x32_bf16 v[14:17], v[34:37], v[14:17], 0
	v_mfma_f32_16x16x32_bf16 v[22:25], v[22:25], v[18:21], 0
	v_mfma_f32_16x16x32_bf16 v[26:29], v[26:29], v[18:21], 0
	v_mfma_f32_16x16x32_bf16 v[30:33], v[30:33], v[18:21], 0
	v_mfma_f32_16x16x32_bf16 v[18:21], v[34:37], v[18:21], 0
	ds_read_b128 v[34:37], v4 offset:1024
	ds_read_b128 v[74:77], v4 offset:3072
	ds_read_b128 v[78:81], v4 offset:5120
	ds_read_b128 v[82:85], v4 offset:7168
	ds_read_b128 v[86:89], v5 offset:33792
	ds_read_b128 v[90:93], v5 offset:35840
	ds_read_b128 v[94:97], v5 offset:37888
	ds_read_b128 v[194:197], v5 offset:39936
	s_waitcnt vmcnt(6)
	s_barrier
	s_waitcnt lgkmcnt(0)
	v_mfma_f32_16x16x32_bf16 v[38:41], v[86:89], v[34:37], v[38:41]
	v_mfma_f32_16x16x32_bf16 v[42:45], v[90:93], v[34:37], v[42:45]
	v_mfma_f32_16x16x32_bf16 v[46:49], v[94:97], v[34:37], v[46:49]
	v_mfma_f32_16x16x32_bf16 v[6:9], v[194:197], v[34:37], v[6:9]
	v_mfma_f32_16x16x32_bf16 v[34:37], v[86:89], v[74:77], v[50:53]
	v_mfma_f32_16x16x32_bf16 v[50:53], v[90:93], v[74:77], v[54:57]
	v_mfma_f32_16x16x32_bf16 v[54:57], v[94:97], v[74:77], v[58:61]
	v_mfma_f32_16x16x32_bf16 v[58:61], v[86:89], v[78:81], v[62:65]
	v_mfma_f32_16x16x32_bf16 v[62:65], v[90:93], v[78:81], v[66:69]
	v_mfma_f32_16x16x32_bf16 v[66:69], v[94:97], v[78:81], v[70:73]
	s_nop 2
	v_lshl_add_u64 v[70:71], s[16:17], 0, v[104:105]
	global_load_lds_dwordx4 v[70:71], off
	v_lshl_add_u64 v[70:71], s[16:17], 0, v[100:101]
	s_mov_b32 m0, s42
	v_mfma_f32_16x16x32_bf16 v[10:13], v[194:197], v[74:77], v[10:13]
	global_load_lds_dwordx4 v[70:71], off
	v_lshl_add_u64 v[70:71], s[14:15], 0, v[104:105]
	s_mov_b32 m0, s41
	v_mfma_f32_16x16x32_bf16 v[14:17], v[194:197], v[78:81], v[14:17]
	global_load_lds_dwordx4 v[70:71], off
	v_lshl_add_u64 v[70:71], s[14:15], 0, v[100:101]
	s_add_u32 s14, s18, 0x180180
	s_mov_b32 m0, s40
	s_addc_u32 s15, s19, 0
	global_load_lds_dwordx4 v[70:71], off
	v_lshl_add_u64 v[70:71], s[14:15], 0, v[102:103]
	s_mov_b32 m0, s39
	v_mfma_f32_16x16x32_bf16 v[22:25], v[86:89], v[82:85], v[22:25]
	global_load_lds_dwordx4 v[70:71], off
	v_lshl_add_u64 v[70:71], s[14:15], 0, v[0:1]
	s_mov_b32 m0, s38
	v_mfma_f32_16x16x32_bf16 v[26:29], v[90:93], v[82:85], v[26:29]
	global_load_lds_dwordx4 v[70:71], off
	s_add_i32 s14, 0, 0x18000
	v_mfma_f32_16x16x32_bf16 v[30:33], v[94:97], v[82:85], v[30:33]
	v_add_u32_e32 v99, s14, v3
	s_add_u32 s12, s12, s37
	s_addc_u32 s13, s13, 0
	v_mfma_f32_16x16x32_bf16 v[18:21], v[194:197], v[82:85], v[18:21]
	ds_read_b128 v[70:73], v4 offset:49152
	ds_read_b128 v[74:77], v4 offset:51200
	ds_read_b128 v[78:81], v4 offset:53248
	ds_read_b128 v[82:85], v4 offset:55296
	ds_read_b128 v[86:89], v98 offset:49152
	ds_read_b128 v[90:93], v98 offset:51200
	ds_read_b128 v[94:97], v98 offset:53248
	ds_read_b128 v[194:197], v98 offset:55296
	s_waitcnt lgkmcnt(0)
	v_mfma_f32_16x16x32_bf16 v[38:41], v[86:89], v[70:73], v[38:41]
	v_mfma_f32_16x16x32_bf16 v[42:45], v[90:93], v[70:73], v[42:45]
	v_mfma_f32_16x16x32_bf16 v[46:49], v[94:97], v[70:73], v[46:49]
	v_mfma_f32_16x16x32_bf16 v[6:9], v[194:197], v[70:73], v[6:9]
	v_mfma_f32_16x16x32_bf16 v[34:37], v[86:89], v[74:77], v[34:37]
	v_mfma_f32_16x16x32_bf16 v[50:53], v[90:93], v[74:77], v[50:53]
	v_mfma_f32_16x16x32_bf16 v[54:57], v[94:97], v[74:77], v[54:57]
	v_mfma_f32_16x16x32_bf16 v[10:13], v[194:197], v[74:77], v[10:13]
	v_mfma_f32_16x16x32_bf16 v[58:61], v[86:89], v[78:81], v[58:61]
	v_mfma_f32_16x16x32_bf16 v[62:65], v[90:93], v[78:81], v[62:65]
	v_mfma_f32_16x16x32_bf16 v[66:69], v[94:97], v[78:81], v[66:69]
	v_mfma_f32_16x16x32_bf16 v[14:17], v[194:197], v[78:81], v[14:17]
	v_mfma_f32_16x16x32_bf16 v[22:25], v[86:89], v[82:85], v[22:25]
	v_mfma_f32_16x16x32_bf16 v[26:29], v[90:93], v[82:85], v[26:29]
	v_mfma_f32_16x16x32_bf16 v[30:33], v[94:97], v[82:85], v[30:33]
	v_mfma_f32_16x16x32_bf16 v[18:21], v[194:197], v[82:85], v[18:21]
	ds_read_b128 v[70:73], v4 offset:50176
	ds_read_b128 v[74:77], v4 offset:52224
	ds_read_b128 v[78:81], v4 offset:54272
	ds_read_b128 v[82:85], v4 offset:56320
	ds_read_b128 v[86:89], v98 offset:50176
	ds_read_b128 v[90:93], v98 offset:52224
	ds_read_b128 v[94:97], v98 offset:54272
	ds_read_b128 v[194:197], v98 offset:56320
	s_waitcnt vmcnt(6)
	s_barrier
; #define BG_STAGE(kk_, slot_) do { const int _n = (kk_) >> 2, _kt = (kk_) & 3; const int _so = (slot_) * STG; \
;         const bf16_t* _a = outs + ((size_t)_n * M + (size_t)pm * 256) * 256 + _kt * 64; const bf16_t* _b = wbr + ((size_t)_n * 1024 + (size_t)pn * 128) * 256 + _kt * 64; \
;         BG_LD(_so, _a); BG_LD(_so + HTB, _a + 128 * 256); BG_LDX(_so + 2 * HTB, _b, voffB); } while (0)
; #define BG_WAIT(n) asm volatile("s_waitcnt vmcnt(" #n ")" ::: "memory")
; #define BG_BAR() do { __builtin_amdgcn_s_barrier(); asm volatile("" ::: "memory"); } while (0)
; __device__ __forceinline__ void bgemm_phase(LAS unsigned char* lds, const bf16_t* outs, const bf16_t* wbr, const bf16_t* zg, bf16_t* merged) {
;     ...
;             BG_WAIT(6); BG_BAR(); { const int s2 = slot >= 1 ? slot - 1 : 2; BG_STAGE(kk0 + 2, s2); } BG_COMPUTE(slot); slot = slot == 2 ? 0 : slot + 1;
;             BG_WAIT(6); BG_BAR(); { const int s2 = slot >= 1 ? slot - 1 : 2; BG_STAGE(kk0 + 3, s2); } BG_COMPUTE(slot); slot = slot == 2 ? 0 : slot + 1;
;             BG_WAIT(6); BG_BAR(); if (n < 3) { const int s2 = slot >= 1 ? slot - 1 : 2; BG_STAGE(kk0 + 4, s2); } BG_COMPUTE(slot); slot = slot == 2 ? 0 : slot + 1;
;             if (n < 3) { BG_WAIT(6); } else { BG_WAIT(0); }
;             BG_BAR(); if (n < 3) { const int s2 = slot >= 1 ? slot - 1 : 2; BG_STAGE(kk0 + 5, s2); }
;             size_t goff = (((size_t)n * 64 + pm) * 8 + pn) * 32768 + (size_t)(((wm * 4) * 4 + wn * 2) * 64 + fq * 16 + fr) * 8;
;             asm volatile("" : "+v"(goff) :: "memory");
;             const bf16_t* gp0 = zg + goff;
;             u32x4 gv[2][2];
; #pragma unroll
;             for (int mi = 0; mi < 2; ++mi)
; #pragma unroll
;                 for (int g = 0; g < 2; ++g) gv[mi][g] = *(const u32x4*)(gp0 + (mi * 4 + g) * 512);
;             BG_COMPUTE(slot); slot = slot == 2 ? 0 : slot + 1;
	v_add_u32_e32 v98, s14, v214
	s_waitcnt lgkmcnt(0)
	v_mfma_f32_16x16x32_bf16 v[38:41], v[86:89], v[70:73], v[38:41]
	v_mfma_f32_16x16x32_bf16 v[42:45], v[90:93], v[70:73], v[42:45]
	v_mfma_f32_16x16x32_bf16 v[46:49], v[94:97], v[70:73], v[46:49]
	v_mfma_f32_16x16x32_bf16 v[6:9], v[194:197], v[70:73], v[6:9]
	v_mfma_f32_16x16x32_bf16 v[34:37], v[86:89], v[74:77], v[34:37]
	v_mfma_f32_16x16x32_bf16 v[50:53], v[90:93], v[74:77], v[50:53]
	v_mfma_f32_16x16x32_bf16 v[54:57], v[94:97], v[74:77], v[54:57]
	v_mfma_f32_16x16x32_bf16 v[10:13], v[194:197], v[74:77], v[10:13]
	v_mfma_f32_16x16x32_bf16 v[58:61], v[86:89], v[78:81], v[58:61]
	v_mfma_f32_16x16x32_bf16 v[62:65], v[90:93], v[78:81], v[62:65]
	v_mfma_f32_16x16x32_bf16 v[66:69], v[94:97], v[78:81], v[66:69]
	v_mfma_f32_16x16x32_bf16 v[14:17], v[194:197], v[78:81], v[14:17]
	v_mfma_f32_16x16x32_bf16 v[22:25], v[86:89], v[82:85], v[22:25]
	v_mfma_f32_16x16x32_bf16 v[26:29], v[90:93], v[82:85], v[26:29]
	v_mfma_f32_16x16x32_bf16 v[30:33], v[94:97], v[82:85], v[30:33]
	v_mfma_f32_16x16x32_bf16 v[18:21], v[194:197], v[82:85], v[18:21]
	ds_read_b128 v[70:73], v98 offset:7168
	ds_read_b128 v[74:77], v98 offset:5120
	ds_read_b128 v[78:81], v98 offset:3072
	ds_read_b128 v[82:85], v98 offset:1024
	ds_read_b128 v[86:89], v99 offset:7168
	ds_read_b128 v[90:93], v99 offset:5120
	ds_read_b128 v[94:97], v99 offset:3072
	ds_read_b128 v[194:197], v99 offset:1024
	ds_read_b128 v[198:201], v98 offset:6144
	ds_read_b128 v[218:221], v98 offset:4096
	ds_read_b128 v[222:225], v98 offset:2048
	ds_read_b128 v[226:229], v98
	ds_read_b128 v[230:233], v99 offset:6144
	ds_read_b128 v[234:237], v99 offset:4096
	ds_read_b128 v[238:241], v99 offset:2048
	ds_read_b128 v[242:245], v99
	s_waitcnt vmcnt(0)
	s_waitcnt lgkmcnt(0)
	v_mfma_f32_16x16x32_bf16 v[38:41], v[226:229], v[242:245], v[38:41]
	s_barrier
	v_mfma_f32_16x16x32_bf16 v[42:45], v[222:225], v[242:245], v[42:45]
	v_mfma_f32_16x16x32_bf16 v[46:49], v[218:221], v[242:245], v[46:49]
	v_mfma_f32_16x16x32_bf16 v[6:9], v[198:201], v[242:245], v[6:9]
	v_mfma_f32_16x16x32_bf16 v[50:53], v[222:225], v[238:241], v[50:53]
	v_mfma_f32_16x16x32_bf16 v[34:37], v[226:229], v[238:241], v[34:37]
	v_mfma_f32_16x16x32_bf16 v[54:57], v[218:221], v[238:241], v[54:57]
	v_mfma_f32_16x16x32_bf16 v[10:13], v[198:201], v[238:241], v[10:13]
	v_mfma_f32_16x16x32_bf16 v[58:61], v[226:229], v[234:237], v[58:61]
	v_mfma_f32_16x16x32_bf16 v[62:65], v[222:225], v[234:237], v[62:65]
	v_mfma_f32_16x16x32_bf16 v[66:69], v[218:221], v[234:237], v[66:69]
	v_mfma_f32_16x16x32_bf16 v[14:17], v[198:201], v[234:237], v[14:17]
	v_mfma_f32_16x16x32_bf16 v[22:25], v[226:229], v[230:233], v[22:25]
	v_mfma_f32_16x16x32_bf16 v[26:29], v[222:225], v[230:233], v[26:29]
	v_mfma_f32_16x16x32_bf16 v[30:33], v[218:221], v[230:233], v[30:33]
	v_mfma_f32_16x16x32_bf16 v[18:21], v[198:201], v[230:233], v[18:21]
	v_mfma_f32_16x16x32_bf16 v[38:41], v[82:85], v[194:197], v[38:41]
	v_mfma_f32_16x16x32_bf16 v[42:45], v[78:81], v[194:197], v[42:45]
	v_mfma_f32_16x16x32_bf16 v[46:49], v[74:77], v[194:197], v[46:49]
	v_mfma_f32_16x16x32_bf16 v[6:9], v[70:73], v[194:197], v[6:9]
	v_mfma_f32_16x16x32_bf16 v[194:197], v[78:81], v[94:97], v[50:53]
	s_nop 2
	v_lshl_add_u64 v[50:51], s[12:13], 0, v[106:107]
	s_mov_b64 s[12:13], 0x3000000
	v_lshl_add_u64 v[50:51], v[50:51], 0, s[12:13]
	v_mfma_f32_16x16x32_bf16 v[34:37], v[82:85], v[94:97], v[34:37]
	v_lshl_add_u64 v[140:141], v[50:51], 1, s[8:9]
	v_add_co_u32_e32 v50, vcc, s80, v140
	v_mfma_f32_16x16x32_bf16 v[198:201], v[74:77], v[94:97], v[54:57]
	s_nop 0
	v_addc_co_u32_e32 v51, vcc, 0, v141, vcc
	v_add_co_u32_e32 v142, vcc, s81, v140
	v_mfma_f32_16x16x32_bf16 v[10:13], v[70:73], v[94:97], v[10:13]
	s_nop 0
	v_addc_co_u32_e32 v143, vcc, 0, v141, vcc
	s_mov_b32 s12, s90
	v_mfma_f32_16x16x32_bf16 v[56:59], v[82:85], v[90:93], v[58:61]
	v_mfma_f32_16x16x32_bf16 v[60:63], v[78:81], v[90:93], v[62:65]
	v_mfma_f32_16x16x32_bf16 v[94:97], v[74:77], v[90:93], v[66:69]
	v_mfma_f32_16x16x32_bf16 v[14:17], v[70:73], v[90:93], v[14:17]
	v_mfma_f32_16x16x32_bf16 v[22:25], v[82:85], v[86:89], v[22:25]
	v_mfma_f32_16x16x32_bf16 v[26:29], v[78:81], v[86:89], v[26:29]
	v_mfma_f32_16x16x32_bf16 v[30:33], v[74:77], v[86:89], v[30:33]
	v_mfma_f32_16x16x32_bf16 v[18:21], v[70:73], v[86:89], v[18:21]
	global_load_dwordx4 v[88:91], v[140:141], off
	global_load_dwordx4 v[76:79], v[140:141], off offset:1024
	global_load_dwordx4 v[64:67], v[142:143], off offset:-4096
	global_load_dwordx4 v[52:55], v[50:51], off offset:1024
	ds_read_b128 v[68:71], v4
	ds_read_b128 v[72:75], v4 offset:2048
	ds_read_b128 v[80:83], v4 offset:4096
	ds_read_b128 v[84:87], v4 offset:6144
	ds_read_b128 v[218:221], v5 offset:32768
	ds_read_b128 v[222:225], v5 offset:34816
	ds_read_b128 v[226:229], v5 offset:36864
	ds_read_b128 v[230:233], v5 offset:38912
	s_waitcnt lgkmcnt(0)
	v_mfma_f32_16x16x32_bf16 v[38:41], v[218:221], v[68:71], v[38:41]
	v_mfma_f32_16x16x32_bf16 v[42:45], v[222:225], v[68:71], v[42:45]
	v_mfma_f32_16x16x32_bf16 v[46:49], v[226:229], v[68:71], v[46:49]
	v_mfma_f32_16x16x32_bf16 v[6:9], v[230:233], v[68:71], v[6:9]
	v_mfma_f32_16x16x32_bf16 v[34:37], v[218:221], v[72:75], v[34:37]
	v_mfma_f32_16x16x32_bf16 v[68:71], v[222:225], v[72:75], v[194:197]
	v_mfma_f32_16x16x32_bf16 v[194:197], v[226:229], v[72:75], v[198:201]
	v_mfma_f32_16x16x32_bf16 v[10:13], v[230:233], v[72:75], v[10:13]
	v_mfma_f32_16x16x32_bf16 v[198:201], v[218:221], v[80:83], v[56:59]
	v_mfma_f32_16x16x32_bf16 v[234:237], v[222:225], v[80:83], v[60:63]
	v_mfma_f32_16x16x32_bf16 v[238:241], v[226:229], v[80:83], v[94:97]
	v_mfma_f32_16x16x32_bf16 v[14:17], v[230:233], v[80:83], v[14:17]
	v_mfma_f32_16x16x32_bf16 v[22:25], v[218:221], v[84:87], v[22:25]
	v_mfma_f32_16x16x32_bf16 v[218:221], v[222:225], v[84:87], v[26:29]
	v_mfma_f32_16x16x32_bf16 v[222:225], v[226:229], v[84:87], v[30:33]
	v_mfma_f32_16x16x32_bf16 v[226:229], v[230:233], v[84:87], v[18:21]
	s_nop 2
	ds_read_b128 v[18:21], v4 offset:1024
	ds_read_b128 v[26:29], v4 offset:3072
	ds_read_b128 v[30:33], v4 offset:5120
	ds_read_b128 v[230:233], v4 offset:7168
	ds_read_b128 v[242:245], v5 offset:33792
	ds_read_b128 v[246:249], v5 offset:35840
	ds_read_b128 v[250:253], v5 offset:37888
	ds_read_b128 v[132:135], v5 offset:39936
	s_waitcnt lgkmcnt(0)
; __device__ __forceinline__ float bflo(unsigned w) { return __uint_as_float(w << 16); }
; __device__ __forceinline__ float bfhi(unsigned w) { return __uint_as_float(w & 0xffff0000u); }
; __device__ __forceinline__ float sigm(float x) { return frcp(1.f + fexp(-x)); }
; __device__ __forceinline__ void bgemm_phase(LAS unsigned char* lds, const bf16_t* outs, const bf16_t* wbr, const bf16_t* zg, bf16_t* merged) {
;     ...
;             BG_COMPUTE(slot); slot = slot == 2 ? 0 : slot + 1;
; #pragma unroll
;             for (int hf = 0; hf < 2; ++hf) {
;                 u32x4 gn[2][2];
;                 if (hf == 0) {
; #pragma unroll
;                     for (int mi = 0; mi < 2; ++mi)
; #pragma unroll
;                         for (int g = 0; g < 2; ++g) gn[mi][g] = *(const u32x4*)(gp0 + ((2 + mi) * 4 + g) * 512);
;                 }
; #pragma unroll
;                 for (int mi = 0; mi < 2; ++mi)
; #pragma unroll
;                     for (int g = 0; g < 2; ++g) { const u32x4 gq = gv[mi][g]; const int m2 = hf * 2 + mi;
;                         tot[m2][2 * g][0] += sigm(bflo(gq.x)) * acc[m2][2 * g][0]; tot[m2][2 * g][1] += sigm(bfhi(gq.x)) * acc[m2][2 * g][1];
;                         tot[m2][2 * g][2] += sigm(bflo(gq.y)) * acc[m2][2 * g][2]; tot[m2][2 * g][3] += sigm(bfhi(gq.y)) * acc[m2][2 * g][3];
;                         tot[m2][2 * g + 1][0] += sigm(bflo(gq.z)) * acc[m2][2 * g + 1][0]; tot[m2][2 * g + 1][1] += sigm(bfhi(gq.z)) * acc[m2][2 * g + 1][1];
;                         tot[m2][2 * g + 1][2] += sigm(bflo(gq.w)) * acc[m2][2 * g + 1][2]; tot[m2][2 * g + 1][3] += sigm(bfhi(gq.w)) * acc[m2][2 * g + 1][3];
;                         acc[m2][2 * g] = ZERO4; acc[m2][2 * g + 1] = ZERO4; }
	v_mfma_f32_16x16x32_bf16 v[96:99], v[242:245], v[18:21], v[38:41]
	v_mfma_f32_16x16x32_bf16 v[92:95], v[246:249], v[18:21], v[42:45]
	v_mfma_f32_16x16x32_bf16 v[84:87], v[250:253], v[18:21], v[46:49]
	v_mfma_f32_16x16x32_bf16 v[80:83], v[132:135], v[18:21], v[6:9]
	v_mfma_f32_16x16x32_bf16 v[72:75], v[242:245], v[26:29], v[34:37]
	s_nop 1
	v_add_co_u32_e32 v8, vcc, s82, v140
	v_mfma_f32_16x16x32_bf16 v[68:71], v[246:249], v[26:29], v[68:71]
	s_nop 0
	v_addc_co_u32_e32 v9, vcc, 0, v141, vcc
	v_mfma_f32_16x16x32_bf16 v[60:63], v[250:253], v[26:29], v[194:197]
	v_mfma_f32_16x16x32_bf16 v[56:59], v[132:135], v[26:29], v[10:13]
	v_mfma_f32_16x16x32_bf16 v[48:51], v[242:245], v[30:33], v[198:201]
	v_mfma_f32_16x16x32_bf16 v[40:43], v[246:249], v[30:33], v[234:237]
	v_mfma_f32_16x16x32_bf16 v[36:39], v[250:253], v[30:33], v[238:241]
	v_mfma_f32_16x16x32_bf16 v[28:31], v[132:135], v[30:33], v[14:17]
	global_load_dwordx4 v[44:47], v[142:143], off
	global_load_dwordx4 v[32:35], v[142:143], off offset:1024
	v_mfma_f32_16x16x32_bf16 v[4:7], v[132:135], v[230:233], v[226:229]
	s_waitcnt vmcnt(0)
	v_lshlrev_b32_e32 v132, 16, v88
	v_and_b32_e32 v88, 0xffff0000, v88
	v_mul_f32_e32 v88, 0xbfb8aa3b, v88
	v_exp_f32_e32 v88, v88
	v_mfma_f32_16x16x32_bf16 v[24:27], v[242:245], v[230:233], v[22:25]
	s_nop 2
	global_load_dwordx4 v[20:23], v[8:9], off
	s_nop 0
	global_load_dwordx4 v[8:11], v[8:9], off offset:1024
	v_mul_f32_e32 v132, 0xbfb8aa3b, v132
	v_add_f32_e32 v88, 1.0, v88
	v_rcp_f32_e32 v88, v88
	v_mfma_f32_16x16x32_bf16 v[16:19], v[246:249], v[230:233], v[218:221]
	v_exp_f32_e32 v132, v132
	v_fmac_f32_e32 v191, v88, v97
	v_lshlrev_b32_e32 v88, 16, v89
	v_and_b32_e32 v89, 0xffff0000, v89
	v_mul_f32_e32 v89, 0xbfb8aa3b, v89
	v_exp_f32_e32 v89, v89
	v_mfma_f32_16x16x32_bf16 v[12:15], v[250:253], v[230:233], v[222:225]
	v_mul_f32_e32 v88, 0xbfb8aa3b, v88
	v_exp_f32_e32 v88, v88
	v_add_f32_e32 v89, 1.0, v89
	v_rcp_f32_e32 v89, v89
	v_add_f32_e32 v132, 1.0, v132
	v_rcp_f32_e32 v132, v132
	v_add_f32_e32 v88, 1.0, v88
	v_fmac_f32_e32 v193, v89, v99
	v_lshlrev_b32_e32 v89, 16, v90
	v_and_b32_e32 v90, 0xffff0000, v90
	v_mul_f32_e32 v90, 0xbfb8aa3b, v90
	v_exp_f32_e32 v90, v90
	v_mul_f32_e32 v89, 0xbfb8aa3b, v89
	v_exp_f32_e32 v89, v89
	v_rcp_f32_e32 v88, v88
	v_add_f32_e32 v90, 1.0, v90
	v_rcp_f32_e32 v90, v90
	v_add_f32_e32 v89, 1.0, v89
	v_rcp_f32_e32 v89, v89
	v_fma_f32 v96, v132, v96, v190
	v_fmac_f32_e32 v187, v90, v93
	v_lshlrev_b32_e32 v90, 16, v91
	v_and_b32_e32 v91, 0xffff0000, v91
	v_mul_f32_e32 v91, 0xbfb8aa3b, v91
	v_exp_f32_e32 v91, v91
	v_mul_f32_e32 v90, 0xbfb8aa3b, v90
	v_exp_f32_e32 v90, v90
	v_fma_f32 v88, v88, v98, v192
	v_add_f32_e32 v91, 1.0, v91
	v_rcp_f32_e32 v91, v91
	v_add_f32_e32 v90, 1.0, v90
	v_rcp_f32_e32 v90, v90
	v_fma_f32 v89, v89, v92, v186
	v_fmac_f32_e32 v189, v91, v95
	v_lshlrev_b32_e32 v91, 16, v76
	v_and_b32_e32 v76, 0xffff0000, v76
	v_mul_f32_e32 v76, 0xbfb8aa3b, v76
	v_exp_f32_e32 v76, v76
	v_mul_f32_e32 v91, 0xbfb8aa3b, v91
	v_exp_f32_e32 v91, v91
	v_fma_f32 v90, v90, v94, v188
	v_add_f32_e32 v76, 1.0, v76
	v_rcp_f32_e32 v76, v76
	v_add_f32_e32 v91, 1.0, v91
	v_rcp_f32_e32 v91, v91
	v_fmac_f32_e32 v183, v76, v85
	v_lshlrev_b32_e32 v76, 16, v77
	v_and_b32_e32 v77, 0xffff0000, v77
	v_mul_f32_e32 v77, 0xbfb8aa3b, v77
	v_exp_f32_e32 v77, v77
	v_mul_f32_e32 v76, 0xbfb8aa3b, v76
	v_exp_f32_e32 v76, v76
	v_fma_f32 v84, v91, v84, v182
	v_add_f32_e32 v77, 1.0, v77
	v_rcp_f32_e32 v77, v77
	v_add_f32_e32 v76, 1.0, v76
	v_rcp_f32_e32 v76, v76
	v_fmac_f32_e32 v185, v77, v87
	v_lshlrev_b32_e32 v77, 16, v78
	v_and_b32_e32 v78, 0xffff0000, v78
	v_mul_f32_e32 v78, 0xbfb8aa3b, v78
	v_exp_f32_e32 v78, v78
	v_mul_f32_e32 v77, 0xbfb8aa3b, v77
	v_exp_f32_e32 v77, v77
	v_fma_f32 v76, v76, v86, v184
	v_add_f32_e32 v78, 1.0, v78
	v_rcp_f32_e32 v78, v78
	v_add_f32_e32 v77, 1.0, v77
	v_rcp_f32_e32 v77, v77
	v_fmac_f32_e32 v179, v78, v81
	v_lshlrev_b32_e32 v78, 16, v79
	v_and_b32_e32 v79, 0xffff0000, v79
	v_mul_f32_e32 v79, 0xbfb8aa3b, v79
	v_exp_f32_e32 v79, v79
	v_mul_f32_e32 v78, 0xbfb8aa3b, v78
	v_exp_f32_e32 v78, v78
	v_fma_f32 v77, v77, v80, v178
	v_add_f32_e32 v79, 1.0, v79
	v_rcp_f32_e32 v79, v79
	v_add_f32_e32 v78, 1.0, v78
	v_rcp_f32_e32 v78, v78
	v_fmac_f32_e32 v181, v79, v83
	v_lshlrev_b32_e32 v79, 16, v64
	v_and_b32_e32 v64, 0xffff0000, v64
	v_mul_f32_e32 v64, 0xbfb8aa3b, v64
	v_exp_f32_e32 v64, v64
	v_mul_f32_e32 v79, 0xbfb8aa3b, v79
	v_exp_f32_e32 v79, v79
	v_fma_f32 v78, v78, v82, v180
	v_add_f32_e32 v64, 1.0, v64
	v_rcp_f32_e32 v64, v64
	v_add_f32_e32 v79, 1.0, v79
	v_rcp_f32_e32 v79, v79
	v_fmac_f32_e32 v175, v64, v73
	v_lshlrev_b32_e32 v64, 16, v65
	v_and_b32_e32 v65, 0xffff0000, v65
	v_mul_f32_e32 v65, 0xbfb8aa3b, v65
	v_exp_f32_e32 v65, v65
	v_mul_f32_e32 v64, 0xbfb8aa3b, v64
	v_exp_f32_e32 v64, v64
	v_fma_f32 v72, v79, v72, v174
	v_add_f32_e32 v65, 1.0, v65
	v_rcp_f32_e32 v65, v65
	v_add_f32_e32 v64, 1.0, v64
	v_rcp_f32_e32 v64, v64
	v_fmac_f32_e32 v177, v65, v75
	v_lshlrev_b32_e32 v65, 16, v66
	v_and_b32_e32 v66, 0xffff0000, v66
	v_mul_f32_e32 v66, 0xbfb8aa3b, v66
	v_exp_f32_e32 v66, v66
	v_mul_f32_e32 v65, 0xbfb8aa3b, v65
	v_exp_f32_e32 v65, v65
	v_fma_f32 v64, v64, v74, v176
	v_add_f32_e32 v66, 1.0, v66
	v_rcp_f32_e32 v66, v66
	v_add_f32_e32 v65, 1.0, v65
	v_rcp_f32_e32 v65, v65
	v_fmac_f32_e32 v171, v66, v69
	v_lshlrev_b32_e32 v66, 16, v67
	v_and_b32_e32 v67, 0xffff0000, v67
	v_mul_f32_e32 v67, 0xbfb8aa3b, v67
	v_exp_f32_e32 v67, v67
	v_mul_f32_e32 v66, 0xbfb8aa3b, v66
	v_exp_f32_e32 v66, v66
	v_fma_f32 v65, v65, v68, v170
	v_add_f32_e32 v67, 1.0, v67
	v_rcp_f32_e32 v67, v67
	v_add_f32_e32 v66, 1.0, v66
	v_rcp_f32_e32 v66, v66
; __device__ __forceinline__ float bflo(unsigned w) { return __uint_as_float(w << 16); }
; __device__ __forceinline__ float bfhi(unsigned w) { return __uint_as_float(w & 0xffff0000u); }
; __device__ __forceinline__ float sigm(float x) { return frcp(1.f + fexp(-x)); }
; __device__ __forceinline__ void bgemm_phase(LAS unsigned char* lds, const bf16_t* outs, const bf16_t* wbr, const bf16_t* zg, bf16_t* merged) {
;     ...
; #pragma unroll
;                 for (int mi = 0; mi < 2; ++mi)
; #pragma unroll
;                     for (int g = 0; g < 2; ++g) { const u32x4 gq = gv[mi][g]; const int m2 = hf * 2 + mi;
;                         tot[m2][2 * g][0] += sigm(bflo(gq.x)) * acc[m2][2 * g][0]; tot[m2][2 * g][1] += sigm(bfhi(gq.x)) * acc[m2][2 * g][1];
;                         tot[m2][2 * g][2] += sigm(bflo(gq.y)) * acc[m2][2 * g][2]; tot[m2][2 * g][3] += sigm(bfhi(gq.y)) * acc[m2][2 * g][3];
;                         tot[m2][2 * g + 1][0] += sigm(bflo(gq.z)) * acc[m2][2 * g + 1][0]; tot[m2][2 * g + 1][1] += sigm(bfhi(gq.z)) * acc[m2][2 * g + 1][1];
;                         tot[m2][2 * g + 1][2] += sigm(bflo(gq.w)) * acc[m2][2 * g + 1][2]; tot[m2][2 * g + 1][3] += sigm(bfhi(gq.w)) * acc[m2][2 * g + 1][3];
;                         acc[m2][2 * g] = ZERO4; acc[m2][2 * g + 1] = ZERO4; }
	v_fmac_f32_e32 v173, v67, v71
	v_lshlrev_b32_e32 v67, 16, v52
	v_and_b32_e32 v52, 0xffff0000, v52
	v_mul_f32_e32 v52, 0xbfb8aa3b, v52
	v_exp_f32_e32 v52, v52
	v_mul_f32_e32 v67, 0xbfb8aa3b, v67
	v_exp_f32_e32 v67, v67
	v_fma_f32 v66, v66, v70, v172
	v_add_f32_e32 v52, 1.0, v52
	v_rcp_f32_e32 v52, v52
	v_add_f32_e32 v67, 1.0, v67
	v_rcp_f32_e32 v67, v67
	v_fmac_f32_e32 v167, v52, v61
	v_lshlrev_b32_e32 v52, 16, v53
	v_and_b32_e32 v53, 0xffff0000, v53
	v_mul_f32_e32 v53, 0xbfb8aa3b, v53
	v_exp_f32_e32 v53, v53
	v_mul_f32_e32 v52, 0xbfb8aa3b, v52
	v_exp_f32_e32 v52, v52
	v_fma_f32 v60, v67, v60, v166
	v_add_f32_e32 v53, 1.0, v53
	v_rcp_f32_e32 v53, v53
	v_add_f32_e32 v52, 1.0, v52
	v_rcp_f32_e32 v52, v52
	v_fmac_f32_e32 v169, v53, v63
	v_lshlrev_b32_e32 v53, 16, v54
	v_and_b32_e32 v54, 0xffff0000, v54
	v_mul_f32_e32 v54, 0xbfb8aa3b, v54
	v_exp_f32_e32 v54, v54
	v_mul_f32_e32 v53, 0xbfb8aa3b, v53
	v_exp_f32_e32 v53, v53
	v_fma_f32 v52, v52, v62, v168
	v_add_f32_e32 v54, 1.0, v54
	v_rcp_f32_e32 v54, v54
	v_add_f32_e32 v53, 1.0, v53
	v_rcp_f32_e32 v53, v53
	v_fmac_f32_e32 v163, v54, v57
	v_lshlrev_b32_e32 v54, 16, v55
	v_and_b32_e32 v55, 0xffff0000, v55
	v_mul_f32_e32 v55, 0xbfb8aa3b, v55
	v_exp_f32_e32 v55, v55
	v_mul_f32_e32 v54, 0xbfb8aa3b, v54
	v_exp_f32_e32 v54, v54
	v_fma_f32 v53, v53, v56, v162
	v_add_f32_e32 v55, 1.0, v55
	v_rcp_f32_e32 v55, v55
	v_add_f32_e32 v54, 1.0, v54
	v_rcp_f32_e32 v54, v54
	v_fmac_f32_e32 v165, v55, v59
	v_lshlrev_b32_e32 v55, 16, v44
	v_and_b32_e32 v44, 0xffff0000, v44
	v_mul_f32_e32 v44, 0xbfb8aa3b, v44
	v_exp_f32_e32 v44, v44
	v_mul_f32_e32 v55, 0xbfb8aa3b, v55
	v_exp_f32_e32 v55, v55
	v_fma_f32 v54, v54, v58, v164
	v_add_f32_e32 v44, 1.0, v44
	v_rcp_f32_e32 v44, v44
	v_add_f32_e32 v55, 1.0, v55
	v_rcp_f32_e32 v55, v55
	v_fmac_f32_e32 v159, v49, v44
	v_lshlrev_b32_e32 v44, 16, v45
	v_and_b32_e32 v45, 0xffff0000, v45
	v_mul_f32_e32 v45, 0xbfb8aa3b, v45
	v_exp_f32_e32 v45, v45
	v_mul_f32_e32 v44, 0xbfb8aa3b, v44
	v_exp_f32_e32 v44, v44
	v_fma_f32 v48, v48, v55, v158
	v_add_f32_e32 v45, 1.0, v45
	v_rcp_f32_e32 v45, v45
	v_add_f32_e32 v44, 1.0, v44
	v_rcp_f32_e32 v44, v44
	v_fmac_f32_e32 v161, v51, v45
	v_lshlrev_b32_e32 v45, 16, v46
	v_mul_f32_e32 v45, 0xbfb8aa3b, v45
	v_exp_f32_e32 v45, v45
	v_fma_f32 v44, v50, v44, v160
	v_add_f32_e32 v45, 1.0, v45
	v_rcp_f32_e32 v45, v45
	s_nop 0
	v_fma_f32 v40, v40, v45, v154
	v_and_b32_e32 v45, 0xffff0000, v46
	v_mul_f32_e32 v45, 0xbfb8aa3b, v45
	v_exp_f32_e32 v45, v45
	s_nop 0
	v_add_f32_e32 v45, 1.0, v45
	v_rcp_f32_e32 v45, v45
	s_nop 0
	v_fmac_f32_e32 v155, v41, v45
	v_lshlrev_b32_e32 v41, 16, v47
	v_mul_f32_e32 v41, 0xbfb8aa3b, v41
	v_exp_f32_e32 v41, v41
	s_nop 0
	v_add_f32_e32 v41, 1.0, v41
	v_rcp_f32_e32 v41, v41
	s_nop 0
	v_fma_f32 v41, v42, v41, v156
	v_and_b32_e32 v42, 0xffff0000, v47
	v_mul_f32_e32 v42, 0xbfb8aa3b, v42
	v_exp_f32_e32 v42, v42
	s_nop 0
	v_add_f32_e32 v42, 1.0, v42
	v_rcp_f32_e32 v42, v42
	s_nop 0
	v_fmac_f32_e32 v157, v43, v42
	v_lshlrev_b32_e32 v42, 16, v32
	v_and_b32_e32 v32, 0xffff0000, v32
	v_mul_f32_e32 v32, 0xbfb8aa3b, v32
	v_exp_f32_e32 v32, v32
	v_mul_f32_e32 v42, 0xbfb8aa3b, v42
	v_exp_f32_e32 v42, v42
	v_add_f32_e32 v32, 1.0, v32
	v_rcp_f32_e32 v32, v32
	v_add_f32_e32 v42, 1.0, v42
	v_rcp_f32_e32 v42, v42
	v_fmac_f32_e32 v151, v37, v32
	v_lshlrev_b32_e32 v32, 16, v33
	v_and_b32_e32 v33, 0xffff0000, v33
	v_mul_f32_e32 v33, 0xbfb8aa3b, v33
	v_exp_f32_e32 v33, v33
	v_mul_f32_e32 v32, 0xbfb8aa3b, v32
	v_exp_f32_e32 v32, v32
	v_fma_f32 v36, v36, v42, v150
	v_add_f32_e32 v33, 1.0, v33
	v_rcp_f32_e32 v33, v33
	v_add_f32_e32 v32, 1.0, v32
	v_rcp_f32_e32 v32, v32
	v_fmac_f32_e32 v153, v39, v33
	v_lshlrev_b32_e32 v33, 16, v34
	v_mul_f32_e32 v33, 0xbfb8aa3b, v33
	v_exp_f32_e32 v33, v33
	v_fma_f32 v32, v38, v32, v152
	v_add_f32_e32 v33, 1.0, v33
	v_rcp_f32_e32 v33, v33
	s_nop 0
	v_fma_f32 v28, v28, v33, v146
	v_and_b32_e32 v33, 0xffff0000, v34
	v_mul_f32_e32 v33, 0xbfb8aa3b, v33
	v_exp_f32_e32 v33, v33
	s_nop 0
	v_add_f32_e32 v33, 1.0, v33
	v_rcp_f32_e32 v33, v33
	s_nop 0
	v_fmac_f32_e32 v147, v29, v33
	v_lshlrev_b32_e32 v29, 16, v35
	v_mul_f32_e32 v29, 0xbfb8aa3b, v29
	v_exp_f32_e32 v29, v29
	s_nop 0
	v_add_f32_e32 v29, 1.0, v29
	v_rcp_f32_e32 v29, v29
	s_nop 0
	v_fma_f32 v29, v30, v29, v148
	v_and_b32_e32 v30, 0xffff0000, v35
	v_mul_f32_e32 v30, 0xbfb8aa3b, v30
	v_exp_f32_e32 v30, v30
	s_nop 0
	v_add_f32_e32 v30, 1.0, v30
	v_rcp_f32_e32 v30, v30
	s_nop 0
	v_fmac_f32_e32 v149, v31, v30
	s_waitcnt vmcnt(1)
; __device__ __forceinline__ unsigned pk2(float lo, float hi) { unsigned r; asm("v_cvt_pk_bf16_f32 %0, %1, %2" : "=v"(r) : "v"(lo), "v"(hi)); return r; }
; __device__ __forceinline__ float bflo(unsigned w) { return __uint_as_float(w << 16); }
; __device__ __forceinline__ float bfhi(unsigned w) { return __uint_as_float(w & 0xffff0000u); }
; __device__ __forceinline__ float sigm(float x) { return frcp(1.f + fexp(-x)); }
; __device__ __forceinline__ void bgemm_phase(LAS unsigned char* lds, const bf16_t* outs, const bf16_t* wbr, const bf16_t* zg, bf16_t* merged) {
;     ...
; #pragma unroll
;                 for (int mi = 0; mi < 2; ++mi)
; #pragma unroll
;                     for (int g = 0; g < 2; ++g) { const u32x4 gq = gv[mi][g]; const int m2 = hf * 2 + mi;
;                         tot[m2][2 * g][0] += sigm(bflo(gq.x)) * acc[m2][2 * g][0]; tot[m2][2 * g][1] += sigm(bfhi(gq.x)) * acc[m2][2 * g][1];
;                         tot[m2][2 * g][2] += sigm(bflo(gq.y)) * acc[m2][2 * g][2]; tot[m2][2 * g][3] += sigm(bfhi(gq.y)) * acc[m2][2 * g][3];
;                         tot[m2][2 * g + 1][0] += sigm(bflo(gq.z)) * acc[m2][2 * g + 1][0]; tot[m2][2 * g + 1][1] += sigm(bfhi(gq.z)) * acc[m2][2 * g + 1][1];
;                         tot[m2][2 * g + 1][2] += sigm(bflo(gq.w)) * acc[m2][2 * g + 1][2]; tot[m2][2 * g + 1][3] += sigm(bfhi(gq.w)) * acc[m2][2 * g + 1][3];
;                         acc[m2][2 * g] = ZERO4; acc[m2][2 * g + 1] = ZERO4; }
;                 if (hf == 0) {
; #pragma unroll
;                     for (int mi = 0; mi < 2; ++mi)
; #pragma unroll
;                         for (int g = 0; g < 2; ++g) gv[mi][g] = gn[mi][g];
;                 }
;             }
;         }
; #pragma unroll
;         for (int mi = 0; mi < 4; ++mi) { size_t ooff = (size_t)(pm * 256 + wm * 64 + mi * 16 + fr) * D + pn * 128 + wn * 64 + fq * 8; asm volatile("" : "+v"(ooff)); bf16_t* op = merged + ooff;
; #pragma unroll
;             for (int g = 0; g < 2; ++g) { u32x4 w; w.x = pk2(tot[mi][2 * g][0], tot[mi][2 * g][1]); w.y = pk2(tot[mi][2 * g][2], tot[mi][2 * g][3]);
;                 w.z = pk2(tot[mi][2 * g + 1][0], tot[mi][2 * g + 1][1]); w.w = pk2(tot[mi][2 * g + 1][2], tot[mi][2 * g + 1][3]); *(u32x4*)(op + g * 32) = w; } }
	v_lshlrev_b32_e32 v30, 16, v20
	v_and_b32_e32 v20, 0xffff0000, v20
	v_mul_f32_e32 v20, 0xbfb8aa3b, v20
	v_exp_f32_e32 v20, v20
	v_mul_f32_e32 v30, 0xbfb8aa3b, v30
	v_exp_f32_e32 v30, v30
	v_add_f32_e32 v20, 1.0, v20
	v_rcp_f32_e32 v20, v20
	v_add_f32_e32 v30, 1.0, v30
	v_rcp_f32_e32 v30, v30
	v_fmac_f32_e32 v129, v25, v20
	v_lshlrev_b32_e32 v20, 16, v21
	v_and_b32_e32 v21, 0xffff0000, v21
	v_mul_f32_e32 v21, 0xbfb8aa3b, v21
	v_exp_f32_e32 v21, v21
	v_mul_f32_e32 v20, 0xbfb8aa3b, v20
	v_exp_f32_e32 v20, v20
	v_fma_f32 v24, v24, v30, v128
	v_add_f32_e32 v21, 1.0, v21
	v_rcp_f32_e32 v21, v21
	v_add_f32_e32 v20, 1.0, v20
	v_rcp_f32_e32 v20, v20
	v_fmac_f32_e32 v131, v27, v21
	v_lshlrev_b32_e32 v21, 16, v22
	v_mul_f32_e32 v21, 0xbfb8aa3b, v21
	v_exp_f32_e32 v21, v21
	v_fma_f32 v20, v26, v20, v130
	v_add_f32_e32 v21, 1.0, v21
	v_rcp_f32_e32 v21, v21
	s_nop 0
	v_fma_f32 v16, v16, v21, v124
	v_and_b32_e32 v21, 0xffff0000, v22
	v_mul_f32_e32 v21, 0xbfb8aa3b, v21
	v_exp_f32_e32 v21, v21
	s_nop 0
	v_add_f32_e32 v21, 1.0, v21
	v_rcp_f32_e32 v21, v21
	s_nop 0
	v_fmac_f32_e32 v125, v17, v21
	v_lshlrev_b32_e32 v17, 16, v23
	v_mul_f32_e32 v17, 0xbfb8aa3b, v17
	v_exp_f32_e32 v17, v17
	s_nop 0
	v_add_f32_e32 v17, 1.0, v17
	v_rcp_f32_e32 v17, v17
	s_nop 0
	v_fma_f32 v17, v18, v17, v126
	v_and_b32_e32 v18, 0xffff0000, v23
	v_mul_f32_e32 v18, 0xbfb8aa3b, v18
	v_exp_f32_e32 v18, v18
	s_nop 0
	v_add_f32_e32 v18, 1.0, v18
	v_rcp_f32_e32 v18, v18
	s_nop 0
	v_fmac_f32_e32 v127, v19, v18
	s_waitcnt vmcnt(0)
	v_lshlrev_b32_e32 v18, 16, v8
	v_and_b32_e32 v8, 0xffff0000, v8
	v_mul_f32_e32 v8, 0xbfb8aa3b, v8
	v_exp_f32_e32 v8, v8
	v_mul_f32_e32 v18, 0xbfb8aa3b, v18
	v_exp_f32_e32 v18, v18
	v_add_f32_e32 v8, 1.0, v8
	v_rcp_f32_e32 v8, v8
	v_add_f32_e32 v18, 1.0, v18
	v_rcp_f32_e32 v18, v18
	v_fmac_f32_e32 v121, v13, v8
	v_lshlrev_b32_e32 v8, 16, v9
	v_mul_f32_e32 v8, 0xbfb8aa3b, v8
	v_exp_f32_e32 v8, v8
	v_fma_f32 v12, v12, v18, v120
	v_lshl_or_b32 v18, s36, 7, v216
	v_add_f32_e32 v8, 1.0, v8
	v_rcp_f32_e32 v8, v8
	s_nop 0
	v_fma_f32 v13, v14, v8, v122
	v_and_b32_e32 v8, 0xffff0000, v9
	v_mul_f32_e32 v8, 0xbfb8aa3b, v8
	v_exp_f32_e32 v8, v8
	s_nop 0
	v_add_f32_e32 v8, 1.0, v8
	v_rcp_f32_e32 v8, v8
	s_nop 0
	v_fmac_f32_e32 v123, v15, v8
	v_lshlrev_b32_e32 v8, 16, v10
	v_mul_f32_e32 v8, 0xbfb8aa3b, v8
	v_exp_f32_e32 v8, v8
	s_nop 0
	v_add_f32_e32 v8, 1.0, v8
	v_rcp_f32_e32 v8, v8
	s_nop 0
	v_fma_f32 v14, v4, v8, v116
	v_and_b32_e32 v4, 0xffff0000, v10
	v_mul_f32_e32 v4, 0xbfb8aa3b, v4
	v_exp_f32_e32 v4, v4
	v_lshl_add_u32 v8, s35, 5, v215
	v_ashrrev_i32_e32 v9, 31, v8
	v_add_f32_e32 v4, 1.0, v4
	v_rcp_f32_e32 v4, v4
	s_nop 0
	v_fmac_f32_e32 v117, v5, v4
	v_lshlrev_b32_e32 v4, 16, v11
	v_mul_f32_e32 v4, 0xbfb8aa3b, v4
	v_exp_f32_e32 v4, v4
	s_nop 0
	v_add_f32_e32 v4, 1.0, v4
	v_rcp_f32_e32 v4, v4
	s_nop 0
	v_fma_f32 v15, v6, v4, v118
	v_and_b32_e32 v4, 0xffff0000, v11
	v_mul_f32_e32 v4, 0xbfb8aa3b, v4
	v_exp_f32_e32 v4, v4
	v_cvt_pk_bf16_f32 v6, v89, v187
	s_nop 0
	v_add_f32_e32 v4, 1.0, v4
	v_rcp_f32_e32 v4, v4
	s_nop 0
	v_fmac_f32_e32 v119, v7, v4
	v_lshlrev_b64 v[4:5], 10, v[8:9]
	v_or_b32_e32 v4, v4, v18
	v_cvt_pk_bf16_f32 v7, v90, v189
	s_nop 0
	v_lshl_add_u64 v[10:11], v[4:5], 1, s[4:5]
	v_cvt_pk_bf16_f32 v4, v96, v191
	v_cvt_pk_bf16_f32 v5, v88, v193
	global_store_dwordx4 v[10:11], v[4:7], off
	s_nop 1
	v_cvt_pk_bf16_f32 v4, v84, v183
	v_cvt_pk_bf16_f32 v5, v76, v185
	v_cvt_pk_bf16_f32 v6, v77, v179
	v_cvt_pk_bf16_f32 v7, v78, v181
	global_store_dwordx4 v[10:11], v[4:7], off offset:64
	s_nop 1
	v_or_b32_e32 v4, 16, v8
	v_ashrrev_i32_e32 v5, 31, v4
	v_lshlrev_b64 v[4:5], 10, v[4:5]
	v_or_b32_e32 v4, v4, v18
	v_cvt_pk_bf16_f32 v6, v65, v171
	v_cvt_pk_bf16_f32 v7, v66, v173
	s_nop 0
	v_lshl_add_u64 v[10:11], v[4:5], 1, s[4:5]
	v_cvt_pk_bf16_f32 v4, v72, v175
	v_cvt_pk_bf16_f32 v5, v64, v177
	global_store_dwordx4 v[10:11], v[4:7], off
	s_nop 1
	v_cvt_pk_bf16_f32 v4, v60, v167
	v_cvt_pk_bf16_f32 v5, v52, v169
	v_cvt_pk_bf16_f32 v6, v53, v163
	v_cvt_pk_bf16_f32 v7, v54, v165
	global_store_dwordx4 v[10:11], v[4:7], off offset:64
	s_nop 1
	v_or_b32_e32 v4, 32, v8
	v_ashrrev_i32_e32 v5, 31, v4
	v_lshlrev_b64 v[4:5], 10, v[4:5]
	v_or_b32_e32 v4, v4, v18
	v_cvt_pk_bf16_f32 v6, v40, v155
	v_cvt_pk_bf16_f32 v7, v41, v157
	s_nop 0
	v_lshl_add_u64 v[10:11], v[4:5], 1, s[4:5]
	v_cvt_pk_bf16_f32 v4, v48, v159
	v_cvt_pk_bf16_f32 v5, v44, v161
	global_store_dwordx4 v[10:11], v[4:7], off
	s_nop 1
	v_cvt_pk_bf16_f32 v4, v36, v151
	v_cvt_pk_bf16_f32 v5, v32, v153
	v_cvt_pk_bf16_f32 v6, v28, v147
	v_cvt_pk_bf16_f32 v7, v29, v149
	global_store_dwordx4 v[10:11], v[4:7], off offset:64
	s_nop 1
	v_or_b32_e32 v4, 48, v8
	v_ashrrev_i32_e32 v5, 31, v4
	v_lshlrev_b64 v[4:5], 10, v[4:5]
	v_or_b32_e32 v4, v4, v18
	v_cvt_pk_bf16_f32 v6, v16, v125
	v_cvt_pk_bf16_f32 v7, v17, v127
	s_nop 0
	v_lshl_add_u64 v[8:9], v[4:5], 1, s[4:5]
	v_cvt_pk_bf16_f32 v4, v24, v129
	v_cvt_pk_bf16_f32 v5, v20, v131
	global_store_dwordx4 v[8:9], v[4:7], off
	s_nop 1
	v_cvt_pk_bf16_f32 v4, v12, v121
	v_cvt_pk_bf16_f32 v5, v13, v123
	v_cvt_pk_bf16_f32 v6, v14, v117
	v_cvt_pk_bf16_f32 v7, v15, v119
	global_store_dwordx4 v[8:9], v[4:7], off offset:64
	s_barrier
	s_add_i32 s0, s12, s0
	s_cmpk_gt_i32 s0, 0x1ff
	s_cbranch_scc0 .LBB0_295

; __device__ __forceinline__ unsigned pk2(float lo, float hi) { unsigned r; asm("v_cvt_pk_bf16_f32 %0, %1, %2" : "=v"(r) : "v"(lo), "v"(hi)); return r; }
; __device__ __forceinline__ float bflo(unsigned w) { return __uint_as_float(w << 16); }
; __device__ __forceinline__ float bfhi(unsigned w) { return __uint_as_float(w & 0xffff0000u); }
; __device__ __forceinline__ float silu(float x) { return x * sigm(x); }
; __device__ __forceinline__ void lds_barrier() { asm volatile("s_waitcnt lgkmcnt(0)" ::: "memory"); __builtin_amdgcn_s_barrier(); asm volatile("" ::: "memory"); }
; __device__ __forceinline__ void hgrn_item(const Params& p, int l, int item, int pass, LAS unsigned char* lds) {
;     ...
;             float ss = o[0] * o[0] + o[1] * o[1] + o[2] * o[2] + o[3] * o[3]; ss += __shfl_xor(ss, 16); ss += __shfl_xor(ss, 32);
;             if (fq == 0) ssq[wv * 16 + fr] = ss;
;             lds_barrier();
;             const float tot = ssq[fr] + ssq[16 + fr] + ssq[32 + fr] + ssq[48 + fr]; const float rstd = rsqrtf(tot * (1.f / 64.f) + EPS);
;             const size_t T = T0 + fr; const u32x2 gw = *(const u32x2*)(p.z + T * ZLD + 1536 + head * 64 + wv * 16 + fq * 4);
;             u32x2 w; w.x = pk2(o[0] * rstd * ng[0] * silu(bflo(gw.x)), o[1] * rstd * ng[1] * silu(bfhi(gw.x)));
;             w.y = pk2(o[2] * rstd * ng[2] * silu(bflo(gw.y)), o[3] * rstd * ng[3] * silu(bfhi(gw.y)));
;             *(u32x2*)(p.outs + ((size_t)1 * M + T) * 256 + head * 64 + wv * 16 + fq * 4) = w;
.LBB0_305:
	s_or_b64 exec, exec, s[4:5]
	v_or_b32_e32 v0, s36, v46
	v_or_b32_e32 v0, 0x70, v0
	v_mov_b64_e32 v[8:9], s[34:35]
	s_mul_i32 s0, s37, 0x1600
	v_mad_u64_u32 v[8:9], s[4:5], v0, s2, v[8:9]
	v_add_u32_e32 v9, s0, v9
	v_lshl_add_u64 v[8:9], v[8:9], 0, v[36:37]
	v_mov_b32_e32 v35, v2
	v_lshl_add_u64 v[8:9], v[8:9], 0, v[34:35]
	s_waitcnt lgkmcnt(0)
	s_barrier
	v_lshl_add_u64 v[8:9], v[8:9], 0, v[32:33]
	global_load_dwordx2 v[8:9], v[8:9], off offset:3072
	ds_read2_b32 v[10:11], v70 offset0:192 offset1:208
	ds_read2_b32 v[12:13], v70 offset0:224 offset1:240
	s_waitcnt lgkmcnt(2)
	v_mov_b32_e32 v1, s37
	v_lshlrev_b64 v[0:1], 9, v[0:1]
	v_lshl_add_u64 v[0:1], s[30:31], 0, v[0:1]
	s_waitcnt lgkmcnt(1)
	v_add_f32_e32 v3, v10, v11
	s_waitcnt lgkmcnt(0)
	v_add_f32_e32 v3, v3, v12
	v_add_f32_e32 v3, v3, v13
	v_fmamk_f32 v3, v3, 0x3c800000, v204
	v_mul_f32_e32 v10, 0x4b800000, v3
	v_cmp_gt_f32_e64 s[4:5], s93, v3
	v_lshl_add_u64 v[0:1], v[0:1], 0, v[36:37]
	v_lshl_add_u64 v[0:1], v[0:1], 0, v[34:35]
	v_cndmask_b32_e64 v3, v3, v10, s[4:5]
	v_rsq_f32_e32 v3, v3
	v_lshl_add_u64 v[0:1], v[0:1], 0, v[32:33]
	v_add_co_u32_e32 v0, vcc, 0x800000, v0
	v_mul_f32_e32 v10, 0x45800000, v3
	v_cndmask_b32_e64 v3, v3, v10, s[4:5]
	v_mul_f32_e32 v11, v4, v3
	v_mul_f32_e32 v5, v5, v3
	v_mul_f32_e32 v13, v6, v3
	v_mul_f32_e32 v7, v7, v3
	v_addc_co_u32_e32 v1, vcc, 0, v1, vcc
	s_waitcnt vmcnt(0)
	v_lshlrev_b32_e32 v10, 16, v8
	v_and_b32_e32 v4, 0xffff0000, v8
	v_lshlrev_b32_e32 v12, 16, v9
	v_and_b32_e32 v6, 0xffff0000, v9
	v_mul_f32_e32 v3, 0xbfb8aa3b, v10
	v_mul_f32_e32 v8, 0xbfb8aa3b, v4
	v_mul_f32_e32 v9, 0xbfb8aa3b, v12
	v_mul_f32_e32 v14, 0xbfb8aa3b, v6
	v_exp_f32_e32 v3, v3
	v_exp_f32_e32 v8, v8
	v_exp_f32_e32 v9, v9
	v_exp_f32_e32 v14, v14
	v_add_f32_e32 v3, 1.0, v3
	v_add_f32_e32 v8, 1.0, v8
	v_add_f32_e32 v9, 1.0, v9
	v_add_f32_e32 v14, 1.0, v14
	v_rcp_f32_e32 v30, v3
	v_rcp_f32_e32 v20, v8
	v_rcp_f32_e32 v28, v9
	v_rcp_f32_e32 v22, v14
	v_mul_f32_e32 v8, v30, v10
	v_mul_f32_e32 v9, v31, v11
	v_mul_f32_e32 v4, v20, v4
	v_mul_f32_e32 v5, v21, v5
	v_mul_f32_e32 v10, v28, v12
	v_mul_f32_e32 v11, v29, v13
	v_mul_f32_e32 v6, v22, v6
	v_mul_f32_e32 v7, v23, v7
	v_mul_f32_e32 v4, v4, v5
	v_mul_f32_e32 v5, v10, v11
	v_mul_f32_e32 v3, v8, v9
	v_mul_f32_e32 v6, v6, v7
	v_cvt_pk_bf16_f32 v4, v3, v4
	v_cvt_pk_bf16_f32 v5, v5, v6
	global_store_dwordx2 v[0:1], v[4:5], off
	s_waitcnt lgkmcnt(0)
	s_barrier

; __device__ __forceinline__ float bflo(unsigned w) { return __uint_as_float(w << 16); }
; __device__ __forceinline__ float bfhi(unsigned w) { return __uint_as_float(w & 0xffff0000u); }
; __device__ __forceinline__ float gelu_t(float x) { return x * sigm(1.5957691216057308f * (x + 0.044715f * x * x * x)); }
; __device__ __forceinline__ void gmlp_item(const Params& p, int l, int item, LAS unsigned char* lds) {
;     ...
;     const int nks = (wid >> 1) + 1;
;     const size_t Tw = T0 + wid * 16 + fr;
;     bf16x8 bwp[4]; u32x2 uwp[4];
;     { const bf16_t* wp = p.gmw + (((size_t)l * 4 + g) * 128 + wid * 16 + fr) * 128 + fq * 8;
; #pragma unroll
;       for (int ks = 0; ks < 4; ++ks) bwp[ks] = *(const bf16x8*)(wp + (ks < nks ? ks : 0) * 32);
; #pragma unroll
;       for (int ct = 0; ct < 4; ++ct) uwp[ct] = *(const u32x2*)(p.z + Tw * ZLD + 1792 + g * 64 + ct * 16 + fq * 4); }
;     const float bsv = p.gm_bs[((size_t)l * 4 + g) * 128 + wid * 16 + fr];
;     { const int pp = tid >> 2, qd = tid & 3; const bf16_t* vp = p.z + (T0 + pp) * ZLD + 2048 + qd * 16;
;       float keep[16]; float ss = 0.f;
; #pragma unroll
;       for (int i = 0; i < 16; ++i) keep[i] = 0.f;
; #pragma unroll
;       for (int gg = 0; gg < 4; ++gg) { const u32x4 w0 = *(const u32x4*)(vp + gg * 64), w1 = *(const u32x4*)(vp + gg * 64 + 8);
;           const float v[16] = {bflo(w0.x), bfhi(w0.x), bflo(w0.y), bfhi(w0.y), bflo(w0.z), bfhi(w0.z), bflo(w0.w), bfhi(w0.w),
;                                bflo(w1.x), bfhi(w1.x), bflo(w1.y), bfhi(w1.y), bflo(w1.z), bfhi(w1.z), bflo(w1.w), bfhi(w1.w)};
; #pragma unroll
;           for (int i = 0; i < 16; ++i) { const float ge = gelu_t(v[i]); ss += ge * ge; keep[i] = (gg == g) ? ge : keep[i]; } }
.LBB0_319:
	s_and_b64 vcc, exec, s[6:7]
	s_cbranch_vccz .LBB0_342
	v_mov_b32_e32 v34, v202
	s_bfe_u32 s37, s72, 0x20003
	s_lshl_b32 s96, s37, 7
	v_ashrrev_i32_e32 v30, 2, v34
	v_and_b32_e32 v32, 15, v34
	v_and_b32_e32 v0, -16, v30
	s_or_b32 s6, s26, s96
	v_ashrrev_i32_e32 v1, 31, v0
	v_or_b32_e32 v4, s6, v32
	v_mov_b32_e32 v5, s27
	v_lshl_add_u64 v[22:23], v[4:5], 0, v[0:1]
	v_bfe_u32 v48, v34, 4, 2
	v_ashrrev_i32_e32 v33, 7, v34
	v_lshlrev_b64 v[4:5], 8, v[22:23]
	v_lshl_add_u64 v[4:5], s[4:5], 0, v[4:5]
	v_lshlrev_b32_e32 v28, 4, v48
	v_mov_b32_e32 v29, v2
	v_cmp_gt_i32_e32 vcc, 1, v33
	v_lshl_add_u64 v[4:5], v[4:5], 0, v[28:29]
	v_mov_b32_e32 v7, v2
	v_cndmask_b32_e64 v6, 64, 0, vcc
	v_mov_b32_e32 v20, s0
	s_add_i32 s0, s21, 0xffffff00
	s_waitcnt lgkmcnt(0)
	s_barrier
	v_lshl_add_u64 v[6:7], v[4:5], 0, v[6:7]
	v_cmp_gt_i32_e32 vcc, 2, v33
	v_mov_b32_e32 v21, s14
	s_ashr_i32 s14, s0, 6
	global_load_dwordx4 v[16:19], v[4:5], off
	global_load_dwordx4 v[12:15], v[6:7], off
	v_cndmask_b32_e64 v6, v243, 0, vcc
	v_mov_b32_e32 v7, v2
	s_ashr_i32 s15, s14, 31
	s_lshl_b32 s0, s16, 5
	v_lshl_add_u64 v[6:7], v[4:5], 0, v[6:7]
	v_cmp_gt_i32_e64 s[8:9], 3, v33
	s_and_b32 s0, s0, 0x780
	global_load_dwordx4 v[8:11], v[6:7], off
	v_cndmask_b32_e64 v6, v254, 0, s[8:9]
	s_lshl_b64 s[8:9], s[14:15], 11
	s_or_b32 s8, s8, s0
	v_lshl_add_u64 v[46:47], s[8:9], 0, v[0:1]
	v_or_b32_e32 v46, v46, v32
	v_mov_b64_e32 v[26:27], s[34:35]
	s_movk_i32 s0, 0x1600
	v_mad_u64_u32 v[0:1], s[14:15], v46, s0, v[26:27]
	v_mad_i32_i24 v1, v47, s0, v1
	v_lshlrev_b32_e32 v24, 3, v48
	v_mov_b32_e32 v25, v2
	v_mov_b32_e32 v7, v2
	v_lshl_add_u64 v[0:1], v[0:1], 0, s[96:97]
	v_lshl_add_u64 v[4:5], v[4:5], 0, v[6:7]
	v_lshl_add_u64 v[0:1], v[0:1], 0, v[24:25]
	v_lshl_add_u64 v[20:21], v[22:23], 2, v[20:21]
	v_ashrrev_i32_e32 v31, 31, v30
	global_load_dwordx4 v[4:7], v[4:5], off
	s_nop 0
	global_load_dwordx2 v[44:45], v[0:1], off offset:3584
	global_load_dwordx2 v[42:43], v[0:1], off offset:3616
	global_load_dwordx2 v[40:41], v[0:1], off offset:3648
	s_nop 0
	global_load_dwordx2 v[0:1], v[0:1], off offset:3680
	s_cmp_eq_u32 s37, 0
	global_load_dword v3, v[20:21], off
	v_lshl_add_u64 v[20:21], s[8:9], 0, v[30:31]
	v_mad_u64_u32 v[22:23], s[8:9], v20, s0, v[26:27]
	v_lshlrev_b32_e32 v20, 4, v34
	v_and_b32_e32 v29, 48, v20
	v_mad_i32_i24 v23, v21, s0, v23
	v_lshlrev_b32_e32 v20, 1, v29
	v_mov_b32_e32 v21, v2
	v_lshl_add_u64 v[20:21], v[22:23], 0, v[20:21]
	s_mov_b64 s[8:9], 0x1000
	v_lshl_add_u64 v[24:25], v[20:21], 0, s[8:9]
	v_add_co_u32_e64 v20, s[8:9], s80, v20
	v_lshlrev_b32_e32 v30, 1, v30
	s_nop 0
	v_addc_co_u32_e64 v21, s[8:9], 0, v21, s[8:9]
	global_load_dwordx4 v[20:23], v[20:21], off
	s_nop 0
	global_load_dwordx4 v[34:37], v[24:25], off offset:16
	global_load_dwordx4 v[102:105], v[24:25], off offset:144
	global_load_dwordx4 v[106:109], v[24:25], off offset:128
	global_load_dwordx4 v[110:113], v[24:25], off offset:272
	global_load_dwordx4 v[114:117], v[24:25], off offset:256
	global_load_dwordx4 v[118:121], v[24:25], off offset:400
	global_load_dwordx4 v[122:125], v[24:25], off offset:384
	s_cselect_b64 s[8:9], -1, 0
	s_cmp_eq_u32 s37, 1
	v_cmp_lt_i32_e64 s[6:7], 0, v33
	v_cmp_lt_i32_e64 s[4:5], 1, v33
	v_cmp_lt_i32_e32 vcc, 2, v33
	s_waitcnt vmcnt(7)
	v_lshlrev_b32_e32 v26, 16, v20
	v_mul_f32_e32 v31, 0x3d372713, v26
	v_mul_f32_e32 v31, v31, v26
	v_fma_f32 v31, v31, v26, v26
	v_mul_f32_e32 v31, 0x3fcc422a, v31
	v_mul_f32_e32 v31, 0xbfb8aa3b, v31
	v_exp_f32_e32 v31, v31
	v_and_b32_e32 v20, 0xffff0000, v20
	v_lshlrev_b32_e32 v27, 16, v21
	v_and_b32_e32 v21, 0xffff0000, v21
	v_add_f32_e32 v31, 1.0, v31
	v_rcp_f32_e32 v31, v31
	v_lshlrev_b32_e32 v38, 16, v22
	v_and_b32_e32 v22, 0xffff0000, v22
	v_lshlrev_b32_e32 v39, 16, v23
	v_mul_f32_e32 v26, v31, v26
	v_mul_f32_e32 v31, 0x3d372713, v20
	v_mul_f32_e32 v31, v31, v20
	v_fma_f32 v31, v31, v20, v20
	v_mul_f32_e32 v31, 0x3fcc422a, v31
	v_mul_f32_e32 v31, 0xbfb8aa3b, v31
	v_exp_f32_e32 v31, v31
	v_cndmask_b32_e64 v53, 0, v26, s[8:9]
	v_and_b32_e32 v23, 0xffff0000, v23
	s_waitcnt vmcnt(6)
	v_lshlrev_b32_e32 v49, 16, v34
	v_add_f32_e32 v31, 1.0, v31
	v_rcp_f32_e32 v31, v31
	v_and_b32_e32 v34, 0xffff0000, v34
	v_lshlrev_b32_e32 v50, 16, v35
	v_and_b32_e32 v35, 0xffff0000, v35
	v_mul_f32_e32 v20, v31, v20
	v_mul_f32_e32 v31, v20, v20
	v_fmac_f32_e32 v31, v26, v26
	v_cndmask_b32_e64 v26, 0, v20, s[8:9]
	v_mul_f32_e32 v20, 0x3d372713, v27
	v_mul_f32_e32 v20, v20, v27
	v_fma_f32 v20, v20, v27, v27
	v_mul_f32_e32 v20, 0x3fcc422a, v20
	v_mul_f32_e32 v20, 0xbfb8aa3b, v20
	v_exp_f32_e32 v20, v20
	v_lshlrev_b32_e32 v51, 16, v36
	v_and_b32_e32 v36, 0xffff0000, v36
	v_lshlrev_b32_e32 v52, 16, v37
	v_add_f32_e32 v20, 1.0, v20
	v_rcp_f32_e32 v20, v20
	v_and_b32_e32 v37, 0xffff0000, v37
	v_mul_f32_e32 v20, v20, v27
	v_fmac_f32_e32 v31, v20, v20
	v_cndmask_b32_e64 v27, 0, v20, s[8:9]
	v_mul_f32_e32 v20, 0x3d372713, v21
	v_mul_f32_e32 v20, v20, v21
	v_fma_f32 v20, v20, v21, v21
	v_mul_f32_e32 v20, 0x3fcc422a, v20
	v_mul_f32_e32 v20, 0xbfb8aa3b, v20
	v_exp_f32_e32 v20, v20
	s_nop 0
	v_add_f32_e32 v20, 1.0, v20
	v_rcp_f32_e32 v20, v20
	s_nop 0
	v_mul_f32_e32 v20, v20, v21
	v_fmac_f32_e32 v31, v20, v20
	v_cndmask_b32_e64 v54, 0, v20, s[8:9]
	v_mul_f32_e32 v20, 0x3d372713, v38
	v_mul_f32_e32 v20, v20, v38
	v_fma_f32 v20, v20, v38, v38
	v_mul_f32_e32 v20, 0x3fcc422a, v20
	v_mul_f32_e32 v20, 0xbfb8aa3b, v20
	v_exp_f32_e32 v20, v20
	s_nop 0
	v_add_f32_e32 v20, 1.0, v20
	v_rcp_f32_e32 v20, v20
	s_nop 0
	v_mul_f32_e32 v20, v20, v38
	v_fmac_f32_e32 v31, v20, v20
	v_cndmask_b32_e64 v38, 0, v20, s[8:9]
	v_mul_f32_e32 v20, 0x3d372713, v22
	v_mul_f32_e32 v20, v20, v22
; __device__ __forceinline__ float bflo(unsigned w) { return __uint_as_float(w << 16); }
; __device__ __forceinline__ float bfhi(unsigned w) { return __uint_as_float(w & 0xffff0000u); }
; __device__ __forceinline__ float gelu_t(float x) { return x * sigm(1.5957691216057308f * (x + 0.044715f * x * x * x)); }
; __device__ __forceinline__ void gmlp_item(const Params& p, int l, int item, LAS unsigned char* lds) {
;     ...
;       for (int gg = 0; gg < 4; ++gg) { const u32x4 w0 = *(const u32x4*)(vp + gg * 64), w1 = *(const u32x4*)(vp + gg * 64 + 8);
;           const float v[16] = {bflo(w0.x), bfhi(w0.x), bflo(w0.y), bfhi(w0.y), bflo(w0.z), bfhi(w0.z), bflo(w0.w), bfhi(w0.w),
;                                bflo(w1.x), bfhi(w1.x), bflo(w1.y), bfhi(w1.y), bflo(w1.z), bfhi(w1.z), bflo(w1.w), bfhi(w1.w)};
; #pragma unroll
;           for (int i = 0; i < 16; ++i) { const float ge = gelu_t(v[i]); ss += ge * ge; keep[i] = (gg == g) ? ge : keep[i]; } }
	v_fma_f32 v20, v20, v22, v22
	v_mul_f32_e32 v20, 0x3fcc422a, v20
	v_mul_f32_e32 v20, 0xbfb8aa3b, v20
	v_exp_f32_e32 v20, v20
	s_nop 0
	v_add_f32_e32 v20, 1.0, v20
	v_rcp_f32_e32 v20, v20
	s_nop 0
	v_mul_f32_e32 v20, v20, v22
	v_fmac_f32_e32 v31, v20, v20
	v_cndmask_b32_e64 v55, 0, v20, s[8:9]
	v_mul_f32_e32 v20, 0x3d372713, v39
	v_mul_f32_e32 v20, v20, v39
	v_fma_f32 v20, v20, v39, v39
	v_mul_f32_e32 v20, 0x3fcc422a, v20
	v_mul_f32_e32 v20, 0xbfb8aa3b, v20
	v_exp_f32_e32 v20, v20
	s_nop 0
	v_add_f32_e32 v20, 1.0, v20
	v_rcp_f32_e32 v20, v20
	s_nop 0
	v_mul_f32_e32 v20, v20, v39
	v_fmac_f32_e32 v31, v20, v20
	v_cndmask_b32_e64 v39, 0, v20, s[8:9]
	v_mul_f32_e32 v20, 0x3d372713, v23
	v_mul_f32_e32 v20, v20, v23
	v_fma_f32 v20, v20, v23, v23
	v_mul_f32_e32 v20, 0x3fcc422a, v20
	v_mul_f32_e32 v20, 0xbfb8aa3b, v20
	v_exp_f32_e32 v20, v20
	s_nop 0
	v_add_f32_e32 v20, 1.0, v20
	v_rcp_f32_e32 v20, v20
	s_nop 0
	v_mul_f32_e32 v20, v20, v23
	v_fmac_f32_e32 v31, v20, v20
	v_cndmask_b32_e64 v56, 0, v20, s[8:9]
	v_mul_f32_e32 v20, 0x3d372713, v49
	v_mul_f32_e32 v20, v20, v49
	v_fma_f32 v20, v20, v49, v49
	v_mul_f32_e32 v20, 0x3fcc422a, v20
	v_mul_f32_e32 v20, 0xbfb8aa3b, v20
	v_exp_f32_e32 v20, v20
	s_nop 0
	v_add_f32_e32 v20, 1.0, v20
	v_rcp_f32_e32 v20, v20
	s_nop 0
	v_mul_f32_e32 v20, v20, v49
	v_fmac_f32_e32 v31, v20, v20
	v_cndmask_b32_e64 v49, 0, v20, s[8:9]
	v_mul_f32_e32 v20, 0x3d372713, v34
	v_mul_f32_e32 v20, v20, v34
	v_fma_f32 v20, v20, v34, v34
	v_mul_f32_e32 v20, 0x3fcc422a, v20
	v_mul_f32_e32 v20, 0xbfb8aa3b, v20
	v_exp_f32_e32 v20, v20
	s_nop 0
	v_add_f32_e32 v20, 1.0, v20
	v_rcp_f32_e32 v20, v20
	s_nop 0
	v_mul_f32_e32 v20, v20, v34
	v_fmac_f32_e32 v31, v20, v20
	v_cndmask_b32_e64 v57, 0, v20, s[8:9]
	v_mul_f32_e32 v20, 0x3d372713, v50
	v_mul_f32_e32 v20, v20, v50
	v_fma_f32 v20, v20, v50, v50
	v_mul_f32_e32 v20, 0x3fcc422a, v20
	v_mul_f32_e32 v20, 0xbfb8aa3b, v20
	v_exp_f32_e32 v20, v20
	s_nop 0
	v_add_f32_e32 v20, 1.0, v20
	v_rcp_f32_e32 v20, v20
	s_nop 0
	v_mul_f32_e32 v20, v20, v50
	v_fmac_f32_e32 v31, v20, v20
	v_cndmask_b32_e64 v50, 0, v20, s[8:9]
	v_mul_f32_e32 v20, 0x3d372713, v35
	v_mul_f32_e32 v20, v20, v35
	v_fma_f32 v20, v20, v35, v35
	v_mul_f32_e32 v20, 0x3fcc422a, v20
	v_mul_f32_e32 v20, 0xbfb8aa3b, v20
	v_exp_f32_e32 v20, v20
	s_nop 0
	v_add_f32_e32 v20, 1.0, v20
	v_rcp_f32_e32 v20, v20
	s_nop 0
	v_mul_f32_e32 v20, v20, v35
	v_fmac_f32_e32 v31, v20, v20
	v_cndmask_b32_e64 v58, 0, v20, s[8:9]
	v_mul_f32_e32 v20, 0x3d372713, v51
	v_mul_f32_e32 v20, v20, v51
	v_fma_f32 v20, v20, v51, v51
	v_mul_f32_e32 v20, 0x3fcc422a, v20
	v_mul_f32_e32 v20, 0xbfb8aa3b, v20
	v_exp_f32_e32 v20, v20
	s_nop 0
	v_add_f32_e32 v20, 1.0, v20
	v_rcp_f32_e32 v20, v20
	s_nop 0
	v_mul_f32_e32 v20, v20, v51
	v_fmac_f32_e32 v31, v20, v20
	v_cndmask_b32_e64 v51, 0, v20, s[8:9]
	v_mul_f32_e32 v20, 0x3d372713, v36
	v_mul_f32_e32 v20, v20, v36
	v_fma_f32 v20, v20, v36, v36
	v_mul_f32_e32 v20, 0x3fcc422a, v20
	v_mul_f32_e32 v20, 0xbfb8aa3b, v20
	v_exp_f32_e32 v20, v20
	s_nop 0
	v_add_f32_e32 v20, 1.0, v20
	v_rcp_f32_e32 v20, v20
	s_nop 0
	v_mul_f32_e32 v20, v20, v36
	v_fmac_f32_e32 v31, v20, v20
	v_cndmask_b32_e64 v59, 0, v20, s[8:9]
	v_mul_f32_e32 v20, 0x3d372713, v52
	v_mul_f32_e32 v20, v20, v52
	v_fma_f32 v20, v20, v52, v52
	v_mul_f32_e32 v20, 0x3fcc422a, v20
	v_mul_f32_e32 v20, 0xbfb8aa3b, v20
	v_exp_f32_e32 v20, v20
	s_nop 0
	v_add_f32_e32 v20, 1.0, v20
	v_rcp_f32_e32 v20, v20
	s_nop 0
	v_mul_f32_e32 v20, v20, v52
	v_fmac_f32_e32 v31, v20, v20
	v_cndmask_b32_e64 v52, 0, v20, s[8:9]
	v_mul_f32_e32 v20, 0x3d372713, v37
	v_mul_f32_e32 v20, v20, v37
	v_fma_f32 v20, v20, v37, v37
	v_mul_f32_e32 v20, 0x3fcc422a, v20
	v_mul_f32_e32 v20, 0xbfb8aa3b, v20
	v_exp_f32_e32 v20, v20
	s_nop 0
	v_add_f32_e32 v20, 1.0, v20
	v_rcp_f32_e32 v20, v20
	s_nop 0
	v_mul_f32_e32 v20, v20, v37
	v_fmac_f32_e32 v31, v20, v20
	v_cndmask_b32_e64 v60, 0, v20, s[8:9]
	s_waitcnt vmcnt(4)
	v_mov_b32_e32 v20, v102
	v_mov_b32_e32 v21, v103
	v_mov_b32_e32 v22, v104
	v_mov_b32_e32 v23, v105
	v_mov_b32_e32 v34, v106
	v_mov_b32_e32 v35, v107
	v_mov_b32_e32 v36, v108
	v_mov_b32_e32 v37, v109
	s_cselect_b64 s[8:9], -1, 0
	s_cmp_eq_u32 s37, 2
	v_lshlrev_b32_e32 v65, 16, v20
	v_lshlrev_b32_e32 v61, 16, v34
	v_mul_f32_e32 v69, 0x3d372713, v61
	v_mul_f32_e32 v69, v69, v61
	v_fma_f32 v69, v69, v61, v61
	v_mul_f32_e32 v69, 0x3fcc422a, v69
	v_mul_f32_e32 v69, 0xbfb8aa3b, v69
	v_exp_f32_e32 v69, v69
	v_and_b32_e32 v34, 0xffff0000, v34
	v_lshlrev_b32_e32 v62, 16, v35
	v_and_b32_e32 v35, 0xffff0000, v35
	v_add_f32_e32 v69, 1.0, v69
	v_rcp_f32_e32 v69, v69
	v_lshlrev_b32_e32 v63, 16, v36
	v_and_b32_e32 v36, 0xffff0000, v36
	v_lshlrev_b32_e32 v64, 16, v37
	v_mul_f32_e32 v61, v69, v61
	v_fmac_f32_e32 v31, v61, v61
	v_cndmask_b32_e64 v53, v53, v61, s[8:9]
	v_mul_f32_e32 v61, 0x3d372713, v34
	v_mul_f32_e32 v61, v61, v34
	v_fma_f32 v61, v61, v34, v34
	v_mul_f32_e32 v61, 0x3fcc422a, v61
	v_mul_f32_e32 v61, 0xbfb8aa3b, v61
	v_exp_f32_e32 v61, v61
	v_and_b32_e32 v37, 0xffff0000, v37
	v_and_b32_e32 v20, 0xffff0000, v20
	v_lshlrev_b32_e32 v66, 16, v21
	v_add_f32_e32 v61, 1.0, v61
	v_rcp_f32_e32 v61, v61
	v_and_b32_e32 v21, 0xffff0000, v21
	v_lshlrev_b32_e32 v67, 16, v22
	v_and_b32_e32 v22, 0xffff0000, v22
	v_mul_f32_e32 v34, v61, v34
	v_fmac_f32_e32 v31, v34, v34
	v_cndmask_b32_e64 v26, v26, v34, s[8:9]
	v_mul_f32_e32 v34, 0x3d372713, v62
	v_mul_f32_e32 v34, v34, v62
	v_fma_f32 v34, v34, v62, v62
	v_mul_f32_e32 v34, 0x3fcc422a, v34
	v_mul_f32_e32 v34, 0xbfb8aa3b, v34
	v_exp_f32_e32 v34, v34
	v_lshlrev_b32_e32 v68, 16, v23
	v_and_b32_e32 v23, 0xffff0000, v23
	v_add_f32_e32 v34, 1.0, v34
	v_rcp_f32_e32 v34, v34
; __device__ __forceinline__ float bflo(unsigned w) { return __uint_as_float(w << 16); }
; __device__ __forceinline__ float bfhi(unsigned w) { return __uint_as_float(w & 0xffff0000u); }
; __device__ __forceinline__ float gelu_t(float x) { return x * sigm(1.5957691216057308f * (x + 0.044715f * x * x * x)); }
; __device__ __forceinline__ void gmlp_item(const Params& p, int l, int item, LAS unsigned char* lds) {
;     ...
;       for (int gg = 0; gg < 4; ++gg) { const u32x4 w0 = *(const u32x4*)(vp + gg * 64), w1 = *(const u32x4*)(vp + gg * 64 + 8);
;           const float v[16] = {bflo(w0.x), bfhi(w0.x), bflo(w0.y), bfhi(w0.y), bflo(w0.z), bfhi(w0.z), bflo(w0.w), bfhi(w0.w),
;                                bflo(w1.x), bfhi(w1.x), bflo(w1.y), bfhi(w1.y), bflo(w1.z), bfhi(w1.z), bflo(w1.w), bfhi(w1.w)};
; #pragma unroll
;           for (int i = 0; i < 16; ++i) { const float ge = gelu_t(v[i]); ss += ge * ge; keep[i] = (gg == g) ? ge : keep[i]; } }
	s_nop 0
	v_mul_f32_e32 v34, v34, v62
	v_fmac_f32_e32 v31, v34, v34
	v_cndmask_b32_e64 v27, v27, v34, s[8:9]
	v_mul_f32_e32 v34, 0x3d372713, v35
	v_mul_f32_e32 v34, v34, v35
	v_fma_f32 v34, v34, v35, v35
	v_mul_f32_e32 v34, 0x3fcc422a, v34
	v_mul_f32_e32 v34, 0xbfb8aa3b, v34
	v_exp_f32_e32 v34, v34
	s_nop 0
	v_add_f32_e32 v34, 1.0, v34
	v_rcp_f32_e32 v34, v34
	s_nop 0
	v_mul_f32_e32 v34, v34, v35
	v_fmac_f32_e32 v31, v34, v34
	v_cndmask_b32_e64 v54, v54, v34, s[8:9]
	v_mul_f32_e32 v34, 0x3d372713, v63
	v_mul_f32_e32 v34, v34, v63
	v_fma_f32 v34, v34, v63, v63
	v_mul_f32_e32 v34, 0x3fcc422a, v34
	v_mul_f32_e32 v34, 0xbfb8aa3b, v34
	v_exp_f32_e32 v34, v34
	s_nop 0
	v_add_f32_e32 v34, 1.0, v34
	v_rcp_f32_e32 v34, v34
	s_nop 0
	v_mul_f32_e32 v34, v34, v63
	v_fmac_f32_e32 v31, v34, v34
	v_cndmask_b32_e64 v38, v38, v34, s[8:9]
	v_mul_f32_e32 v34, 0x3d372713, v36
	v_mul_f32_e32 v34, v34, v36
	v_fma_f32 v34, v34, v36, v36
	v_mul_f32_e32 v34, 0x3fcc422a, v34
	v_mul_f32_e32 v34, 0xbfb8aa3b, v34
	v_exp_f32_e32 v34, v34
	s_nop 0
	v_add_f32_e32 v34, 1.0, v34
	v_rcp_f32_e32 v34, v34
	s_nop 0
	v_mul_f32_e32 v34, v34, v36
	v_fmac_f32_e32 v31, v34, v34
	v_cndmask_b32_e64 v61, v55, v34, s[8:9]
	v_mul_f32_e32 v34, 0x3d372713, v64
	v_mul_f32_e32 v34, v34, v64
	v_fma_f32 v34, v34, v64, v64
	v_mul_f32_e32 v34, 0x3fcc422a, v34
	v_mul_f32_e32 v34, 0xbfb8aa3b, v34
	v_exp_f32_e32 v34, v34
	s_nop 0
	v_add_f32_e32 v34, 1.0, v34
	v_rcp_f32_e32 v34, v34
	s_nop 0
	v_mul_f32_e32 v34, v34, v64
	v_fmac_f32_e32 v31, v34, v34
	v_cndmask_b32_e64 v39, v39, v34, s[8:9]
	v_mul_f32_e32 v34, 0x3d372713, v37
	v_mul_f32_e32 v34, v34, v37
	v_fma_f32 v34, v34, v37, v37
	v_mul_f32_e32 v34, 0x3fcc422a, v34
	v_mul_f32_e32 v34, 0xbfb8aa3b, v34
	v_exp_f32_e32 v34, v34
	s_nop 0
	v_add_f32_e32 v34, 1.0, v34
	v_rcp_f32_e32 v34, v34
	s_nop 0
	v_mul_f32_e32 v34, v34, v37
	v_fmac_f32_e32 v31, v34, v34
	v_cndmask_b32_e64 v62, v56, v34, s[8:9]
	v_mul_f32_e32 v34, 0x3d372713, v65
	v_mul_f32_e32 v34, v34, v65
	v_fma_f32 v34, v34, v65, v65
	v_mul_f32_e32 v34, 0x3fcc422a, v34
	v_mul_f32_e32 v34, 0xbfb8aa3b, v34
	v_exp_f32_e32 v34, v34
	s_nop 0
	v_add_f32_e32 v34, 1.0, v34
	v_rcp_f32_e32 v34, v34
	s_nop 0
	v_mul_f32_e32 v34, v34, v65
	v_fmac_f32_e32 v31, v34, v34
	v_cndmask_b32_e64 v49, v49, v34, s[8:9]
	v_mul_f32_e32 v34, 0x3d372713, v20
	v_mul_f32_e32 v34, v34, v20
	v_fma_f32 v34, v34, v20, v20
	v_mul_f32_e32 v34, 0x3fcc422a, v34
	v_mul_f32_e32 v34, 0xbfb8aa3b, v34
	v_exp_f32_e32 v34, v34
	s_nop 0
	v_add_f32_e32 v34, 1.0, v34
	v_rcp_f32_e32 v34, v34
	s_nop 0
	v_mul_f32_e32 v20, v34, v20
	v_fmac_f32_e32 v31, v20, v20
	v_cndmask_b32_e64 v63, v57, v20, s[8:9]
	v_mul_f32_e32 v20, 0x3d372713, v66
	v_mul_f32_e32 v20, v20, v66
	v_fma_f32 v20, v20, v66, v66
	v_mul_f32_e32 v20, 0x3fcc422a, v20
	v_mul_f32_e32 v20, 0xbfb8aa3b, v20
	v_exp_f32_e32 v20, v20
	s_nop 0
	v_add_f32_e32 v20, 1.0, v20
	v_rcp_f32_e32 v20, v20
	s_nop 0
	v_mul_f32_e32 v20, v20, v66
	v_fmac_f32_e32 v31, v20, v20
	v_cndmask_b32_e64 v64, v50, v20, s[8:9]
	v_mul_f32_e32 v20, 0x3d372713, v21
	v_mul_f32_e32 v20, v20, v21
	v_fma_f32 v20, v20, v21, v21
	v_mul_f32_e32 v20, 0x3fcc422a, v20
	v_mul_f32_e32 v20, 0xbfb8aa3b, v20
	v_exp_f32_e32 v20, v20
	s_nop 0
	v_add_f32_e32 v20, 1.0, v20
	v_rcp_f32_e32 v20, v20
	s_nop 0
	v_mul_f32_e32 v20, v20, v21
	v_fmac_f32_e32 v31, v20, v20
	v_cndmask_b32_e64 v65, v58, v20, s[8:9]
	v_mul_f32_e32 v20, 0x3d372713, v67
	v_mul_f32_e32 v20, v20, v67
	v_fma_f32 v20, v20, v67, v67
	v_mul_f32_e32 v20, 0x3fcc422a, v20
	v_mul_f32_e32 v20, 0xbfb8aa3b, v20
	v_exp_f32_e32 v20, v20
	s_nop 0
	v_add_f32_e32 v20, 1.0, v20
	v_rcp_f32_e32 v20, v20
	s_nop 0
	v_mul_f32_e32 v20, v20, v67
	v_fmac_f32_e32 v31, v20, v20
	v_cndmask_b32_e64 v66, v51, v20, s[8:9]
	v_mul_f32_e32 v20, 0x3d372713, v22
	v_mul_f32_e32 v20, v20, v22
	v_fma_f32 v20, v20, v22, v22
	v_mul_f32_e32 v20, 0x3fcc422a, v20
	v_mul_f32_e32 v20, 0xbfb8aa3b, v20
	v_exp_f32_e32 v20, v20
	s_nop 0
	v_add_f32_e32 v20, 1.0, v20
	v_rcp_f32_e32 v20, v20
	s_nop 0
	v_mul_f32_e32 v20, v20, v22
	v_fmac_f32_e32 v31, v20, v20
	v_cndmask_b32_e64 v59, v59, v20, s[8:9]
	v_mul_f32_e32 v20, 0x3d372713, v68
	v_mul_f32_e32 v20, v20, v68
	v_fma_f32 v20, v20, v68, v68
	v_mul_f32_e32 v20, 0x3fcc422a, v20
	v_mul_f32_e32 v20, 0xbfb8aa3b, v20
	v_exp_f32_e32 v20, v20
	s_nop 0
	v_add_f32_e32 v20, 1.0, v20
	v_rcp_f32_e32 v20, v20
	s_nop 0
	v_mul_f32_e32 v20, v20, v68
	v_fmac_f32_e32 v31, v20, v20
	v_cndmask_b32_e64 v67, v52, v20, s[8:9]
	v_mul_f32_e32 v20, 0x3d372713, v23
	v_mul_f32_e32 v20, v20, v23
	v_fma_f32 v20, v20, v23, v23
	v_mul_f32_e32 v20, 0x3fcc422a, v20
	v_mul_f32_e32 v20, 0xbfb8aa3b, v20
	v_exp_f32_e32 v20, v20
	s_nop 0
	v_add_f32_e32 v20, 1.0, v20
	v_rcp_f32_e32 v20, v20
	s_nop 0
	v_mul_f32_e32 v20, v20, v23
	v_fmac_f32_e32 v31, v20, v20
	v_cndmask_b32_e64 v60, v60, v20, s[8:9]
	s_waitcnt vmcnt(2)
; __device__ __forceinline__ float bflo(unsigned w) { return __uint_as_float(w << 16); }
; __device__ __forceinline__ float bfhi(unsigned w) { return __uint_as_float(w & 0xffff0000u); }
; __device__ __forceinline__ float gelu_t(float x) { return x * sigm(1.5957691216057308f * (x + 0.044715f * x * x * x)); }
; __device__ __forceinline__ void gmlp_item(const Params& p, int l, int item, LAS unsigned char* lds) {
;     ...
;       for (int gg = 0; gg < 4; ++gg) { const u32x4 w0 = *(const u32x4*)(vp + gg * 64), w1 = *(const u32x4*)(vp + gg * 64 + 8);
;           const float v[16] = {bflo(w0.x), bfhi(w0.x), bflo(w0.y), bfhi(w0.y), bflo(w0.z), bfhi(w0.z), bflo(w0.w), bfhi(w0.w),
;                                bflo(w1.x), bfhi(w1.x), bflo(w1.y), bfhi(w1.y), bflo(w1.z), bfhi(w1.z), bflo(w1.w), bfhi(w1.w)};
; #pragma unroll
;           for (int i = 0; i < 16; ++i) { const float ge = gelu_t(v[i]); ss += ge * ge; keep[i] = (gg == g) ? ge : keep[i]; } }
	v_mov_b32_e32 v20, v110
	v_mov_b32_e32 v21, v111
	v_mov_b32_e32 v22, v112
	v_mov_b32_e32 v23, v113
	v_mov_b32_e32 v34, v114
	v_mov_b32_e32 v35, v115
	v_mov_b32_e32 v36, v116
	v_mov_b32_e32 v37, v117
	s_cselect_b64 s[8:9], -1, 0
	s_cmp_eq_u32 s37, 3
	v_lshlrev_b32_e32 v69, 16, v20
	v_lshlrev_b32_e32 v50, 16, v34
	v_mul_f32_e32 v55, 0x3d372713, v50
	v_mul_f32_e32 v55, v55, v50
	v_fma_f32 v55, v55, v50, v50
	v_mul_f32_e32 v55, 0x3fcc422a, v55
	v_mul_f32_e32 v55, 0xbfb8aa3b, v55
	v_exp_f32_e32 v55, v55
	v_and_b32_e32 v34, 0xffff0000, v34
	v_lshlrev_b32_e32 v51, 16, v35
	v_and_b32_e32 v35, 0xffff0000, v35
	v_add_f32_e32 v55, 1.0, v55
	v_rcp_f32_e32 v55, v55
	v_lshlrev_b32_e32 v52, 16, v36
	v_and_b32_e32 v36, 0xffff0000, v36
	v_lshlrev_b32_e32 v68, 16, v37
	v_mul_f32_e32 v50, v55, v50
	v_fmac_f32_e32 v31, v50, v50
	v_cndmask_b32_e64 v58, v53, v50, s[8:9]
	v_mul_f32_e32 v50, 0x3d372713, v34
	v_mul_f32_e32 v50, v50, v34
	v_fma_f32 v50, v50, v34, v34
	v_mul_f32_e32 v50, 0x3fcc422a, v50
	v_mul_f32_e32 v50, 0xbfb8aa3b, v50
	v_exp_f32_e32 v50, v50
	v_and_b32_e32 v37, 0xffff0000, v37
	v_and_b32_e32 v20, 0xffff0000, v20
	v_lshlrev_b32_e32 v70, 16, v21
	v_add_f32_e32 v50, 1.0, v50
	v_rcp_f32_e32 v50, v50
	v_and_b32_e32 v21, 0xffff0000, v21
	v_lshlrev_b32_e32 v71, 16, v22
	v_and_b32_e32 v22, 0xffff0000, v22
	v_mul_f32_e32 v34, v50, v34
	v_cndmask_b32_e64 v57, v26, v34, s[8:9]
	v_mul_f32_e32 v26, 0x3d372713, v51
	v_mul_f32_e32 v26, v26, v51
	v_fma_f32 v26, v26, v51, v51
	v_mul_f32_e32 v26, 0x3fcc422a, v26
	v_mul_f32_e32 v26, 0xbfb8aa3b, v26
	v_exp_f32_e32 v26, v26
	v_fmac_f32_e32 v31, v34, v34
	v_lshlrev_b32_e32 v72, 16, v23
	v_and_b32_e32 v23, 0xffff0000, v23
	v_add_f32_e32 v26, 1.0, v26
	v_rcp_f32_e32 v26, v26
	s_nop 0
	v_mul_f32_e32 v26, v26, v51
	v_fmac_f32_e32 v31, v26, v26
	v_cndmask_b32_e64 v56, v27, v26, s[8:9]
	v_mul_f32_e32 v26, 0x3d372713, v35
	v_mul_f32_e32 v26, v26, v35
	v_fma_f32 v26, v26, v35, v35
	v_mul_f32_e32 v26, 0x3fcc422a, v26
	v_mul_f32_e32 v26, 0xbfb8aa3b, v26
	v_exp_f32_e32 v26, v26
	s_nop 0
	v_add_f32_e32 v26, 1.0, v26
	v_rcp_f32_e32 v26, v26
	s_nop 0
	v_mul_f32_e32 v26, v26, v35
	v_fmac_f32_e32 v31, v26, v26
	v_cndmask_b32_e64 v55, v54, v26, s[8:9]
	v_mul_f32_e32 v26, 0x3d372713, v52
	v_mul_f32_e32 v26, v26, v52
	v_fma_f32 v26, v26, v52, v52
	v_mul_f32_e32 v26, 0x3fcc422a, v26
	v_mul_f32_e32 v26, 0xbfb8aa3b, v26
	v_exp_f32_e32 v26, v26
	s_nop 0
	v_add_f32_e32 v26, 1.0, v26
	v_rcp_f32_e32 v26, v26
	s_nop 0
	v_mul_f32_e32 v26, v26, v52
	v_fmac_f32_e32 v31, v26, v26
	v_cndmask_b32_e64 v54, v38, v26, s[8:9]
	v_mul_f32_e32 v26, 0x3d372713, v36
	v_mul_f32_e32 v26, v26, v36
	v_fma_f32 v26, v26, v36, v36
	v_mul_f32_e32 v26, 0x3fcc422a, v26
	v_mul_f32_e32 v26, 0xbfb8aa3b, v26
	v_exp_f32_e32 v26, v26
	s_nop 0
	v_add_f32_e32 v26, 1.0, v26
	v_rcp_f32_e32 v26, v26
	s_nop 0
	v_mul_f32_e32 v26, v26, v36
	v_fmac_f32_e32 v31, v26, v26
	v_cndmask_b32_e64 v53, v61, v26, s[8:9]
	v_mul_f32_e32 v26, 0x3d372713, v68
	v_mul_f32_e32 v26, v26, v68
	v_fma_f32 v26, v26, v68, v68
	v_mul_f32_e32 v26, 0x3fcc422a, v26
	v_mul_f32_e32 v26, 0xbfb8aa3b, v26
	v_exp_f32_e32 v26, v26
	s_nop 0
	v_add_f32_e32 v26, 1.0, v26
	v_rcp_f32_e32 v26, v26
	s_nop 0
	v_mul_f32_e32 v26, v26, v68
	v_fmac_f32_e32 v31, v26, v26
	v_cndmask_b32_e64 v52, v39, v26, s[8:9]
	v_mul_f32_e32 v26, 0x3d372713, v37
	v_mul_f32_e32 v26, v26, v37
	v_fma_f32 v26, v26, v37, v37
	v_mul_f32_e32 v26, 0x3fcc422a, v26
	v_mul_f32_e32 v26, 0xbfb8aa3b, v26
	v_exp_f32_e32 v26, v26
	s_nop 0
	v_add_f32_e32 v26, 1.0, v26
	v_rcp_f32_e32 v26, v26
	s_nop 0
	v_mul_f32_e32 v26, v26, v37
	v_fmac_f32_e32 v31, v26, v26
	v_cndmask_b32_e64 v51, v62, v26, s[8:9]
	v_mul_f32_e32 v26, 0x3d372713, v69
	v_mul_f32_e32 v26, v26, v69
	v_fma_f32 v26, v26, v69, v69
	v_mul_f32_e32 v26, 0x3fcc422a, v26
	v_mul_f32_e32 v26, 0xbfb8aa3b, v26
	v_exp_f32_e32 v26, v26
	s_nop 0
	v_add_f32_e32 v26, 1.0, v26
	v_rcp_f32_e32 v26, v26
	s_nop 0
	v_mul_f32_e32 v26, v26, v69
	v_fmac_f32_e32 v31, v26, v26
	v_cndmask_b32_e64 v49, v49, v26, s[8:9]
	v_mul_f32_e32 v26, 0x3d372713, v20
	v_mul_f32_e32 v26, v26, v20
	v_fma_f32 v26, v26, v20, v20
	v_mul_f32_e32 v26, 0x3fcc422a, v26
	v_mul_f32_e32 v26, 0xbfb8aa3b, v26
	v_exp_f32_e32 v26, v26
	s_nop 0
	v_add_f32_e32 v26, 1.0, v26
	v_rcp_f32_e32 v26, v26
	s_nop 0
	v_mul_f32_e32 v20, v26, v20
	v_fmac_f32_e32 v31, v20, v20
	v_cndmask_b32_e64 v50, v63, v20, s[8:9]
	v_mul_f32_e32 v20, 0x3d372713, v70
	v_mul_f32_e32 v20, v20, v70
	v_fma_f32 v20, v20, v70, v70
	v_mul_f32_e32 v20, 0x3fcc422a, v20
	v_mul_f32_e32 v20, 0xbfb8aa3b, v20
	v_exp_f32_e32 v20, v20
	s_nop 0
	v_add_f32_e32 v20, 1.0, v20
	v_rcp_f32_e32 v20, v20
	s_nop 0
	v_mul_f32_e32 v20, v20, v70
	v_fmac_f32_e32 v31, v20, v20
	v_cndmask_b32_e64 v38, v64, v20, s[8:9]
	v_mul_f32_e32 v20, 0x3d372713, v21
	v_mul_f32_e32 v20, v20, v21
	v_fma_f32 v20, v20, v21, v21
	v_mul_f32_e32 v20, 0x3fcc422a, v20
	v_mul_f32_e32 v20, 0xbfb8aa3b, v20
	v_exp_f32_e32 v20, v20
	s_nop 0
	v_add_f32_e32 v20, 1.0, v20
	v_rcp_f32_e32 v20, v20
	s_nop 0
	v_mul_f32_e32 v20, v20, v21
	v_fmac_f32_e32 v31, v20, v20
	v_cndmask_b32_e64 v39, v65, v20, s[8:9]
	v_mul_f32_e32 v20, 0x3d372713, v71
	v_mul_f32_e32 v20, v20, v71
	v_fma_f32 v20, v20, v71, v71
	v_mul_f32_e32 v20, 0x3fcc422a, v20
	v_mul_f32_e32 v20, 0xbfb8aa3b, v20
	v_exp_f32_e32 v20, v20
	s_nop 0
	v_add_f32_e32 v20, 1.0, v20
	v_rcp_f32_e32 v20, v20
	s_nop 0
	v_mul_f32_e32 v20, v20, v71
	v_fmac_f32_e32 v31, v20, v20
	v_cndmask_b32_e64 v35, v66, v20, s[8:9]
	v_mul_f32_e32 v20, 0x3d372713, v22
	v_mul_f32_e32 v20, v20, v22
	v_fma_f32 v20, v20, v22, v22
	v_mul_f32_e32 v20, 0x3fcc422a, v20
	v_mul_f32_e32 v20, 0xbfb8aa3b, v20
	v_exp_f32_e32 v20, v20
	s_nop 0
	v_add_f32_e32 v20, 1.0, v20
	v_rcp_f32_e32 v20, v20
	s_nop 0
	v_mul_f32_e32 v20, v20, v22
	v_fmac_f32_e32 v31, v20, v20
	v_cndmask_b32_e64 v37, v59, v20, s[8:9]
	v_mul_f32_e32 v20, 0x3d372713, v72
	v_mul_f32_e32 v20, v20, v72
	v_fma_f32 v20, v20, v72, v72
	v_mul_f32_e32 v20, 0x3fcc422a, v20
	v_mul_f32_e32 v20, 0xbfb8aa3b, v20
	v_exp_f32_e32 v20, v20
	s_nop 0
	v_add_f32_e32 v20, 1.0, v20
	v_rcp_f32_e32 v20, v20
	s_nop 0
	v_mul_f32_e32 v20, v20, v72
	v_fmac_f32_e32 v31, v20, v20
	v_cndmask_b32_e64 v34, v67, v20, s[8:9]
	v_mul_f32_e32 v20, 0x3d372713, v23
	v_mul_f32_e32 v20, v20, v23
	v_fma_f32 v20, v20, v23, v23
	v_mul_f32_e32 v20, 0x3fcc422a, v20
	v_mul_f32_e32 v20, 0xbfb8aa3b, v20
	v_exp_f32_e32 v20, v20
	s_nop 0
	v_add_f32_e32 v20, 1.0, v20
	v_rcp_f32_e32 v20, v20
	s_nop 0
	v_mul_f32_e32 v20, v20, v23
	v_fmac_f32_e32 v31, v20, v20
	v_cndmask_b32_e64 v36, v60, v20, s[8:9]
	s_waitcnt vmcnt(0)
; __device__ __forceinline__ float bflo(unsigned w) { return __uint_as_float(w << 16); }
; __device__ __forceinline__ float bfhi(unsigned w) { return __uint_as_float(w & 0xffff0000u); }
; __device__ __forceinline__ float gelu_t(float x) { return x * sigm(1.5957691216057308f * (x + 0.044715f * x * x * x)); }
; __device__ __forceinline__ void gmlp_item(const Params& p, int l, int item, LAS unsigned char* lds) {
;     ...
;       for (int gg = 0; gg < 4; ++gg) { const u32x4 w0 = *(const u32x4*)(vp + gg * 64), w1 = *(const u32x4*)(vp + gg * 64 + 8);
;           const float v[16] = {bflo(w0.x), bfhi(w0.x), bflo(w0.y), bfhi(w0.y), bflo(w0.z), bfhi(w0.z), bflo(w0.w), bfhi(w0.w),
;                                bflo(w1.x), bfhi(w1.x), bflo(w1.y), bfhi(w1.y), bflo(w1.z), bfhi(w1.z), bflo(w1.w), bfhi(w1.w)};
; #pragma unroll
;           for (int i = 0; i < 16; ++i) { const float ge = gelu_t(v[i]); ss += ge * ge; keep[i] = (gg == g) ? ge : keep[i]; } }
	v_mov_b32_e32 v20, v118
	v_mov_b32_e32 v21, v119
	v_mov_b32_e32 v22, v120
	v_mov_b32_e32 v23, v121
	s_nop 0
	v_mov_b32_e32 v24, v122
	v_mov_b32_e32 v25, v123
	v_mov_b32_e32 v26, v124
	v_mov_b32_e32 v27, v125
	s_cselect_b64 s[8:9], -1, 0
	s_waitcnt vmcnt(0)
	v_lshlrev_b32_e32 v59, 16, v24
	v_mul_f32_e32 v63, 0x3d372713, v59
	v_mul_f32_e32 v63, v63, v59
	v_fma_f32 v63, v63, v59, v59
	v_mul_f32_e32 v63, 0x3fcc422a, v63
	v_mul_f32_e32 v63, 0xbfb8aa3b, v63
	v_exp_f32_e32 v63, v63
	v_and_b32_e32 v24, 0xffff0000, v24
	v_lshlrev_b32_e32 v60, 16, v25
	v_and_b32_e32 v25, 0xffff0000, v25
	v_add_f32_e32 v63, 1.0, v63
	v_rcp_f32_e32 v63, v63
	v_lshlrev_b32_e32 v61, 16, v26
	v_and_b32_e32 v26, 0xffff0000, v26
	v_lshlrev_b32_e32 v62, 16, v27
	v_mul_f32_e32 v59, v63, v59
	v_fmac_f32_e32 v31, v59, v59
	v_cndmask_b32_e64 v58, v58, v59, s[8:9]
	v_mul_f32_e32 v59, 0x3d372713, v24
	v_mul_f32_e32 v59, v59, v24
	v_fma_f32 v59, v59, v24, v24
	v_mul_f32_e32 v59, 0x3fcc422a, v59
	v_mul_f32_e32 v59, 0xbfb8aa3b, v59
	v_exp_f32_e32 v59, v59
	v_and_b32_e32 v27, 0xffff0000, v27
	v_add_f32_e32 v59, 1.0, v59
	v_rcp_f32_e32 v59, v59
	s_nop 0
	v_mul_f32_e32 v24, v59, v24
	v_fmac_f32_e32 v31, v24, v24
	v_cndmask_b32_e64 v57, v57, v24, s[8:9]
	v_mul_f32_e32 v24, 0x3d372713, v60
	v_mul_f32_e32 v24, v24, v60
	v_fma_f32 v24, v24, v60, v60
	v_mul_f32_e32 v24, 0x3fcc422a, v24
	v_mul_f32_e32 v24, 0xbfb8aa3b, v24
	v_exp_f32_e32 v24, v24
	s_nop 0
	v_add_f32_e32 v24, 1.0, v24
	v_rcp_f32_e32 v24, v24
	s_nop 0
	v_mul_f32_e32 v24, v24, v60
	v_fmac_f32_e32 v31, v24, v24
	v_cndmask_b32_e64 v56, v56, v24, s[8:9]
	v_mul_f32_e32 v24, 0x3d372713, v25
	v_mul_f32_e32 v24, v24, v25
	v_fma_f32 v24, v24, v25, v25
	v_mul_f32_e32 v24, 0x3fcc422a, v24
	v_mul_f32_e32 v24, 0xbfb8aa3b, v24
	v_exp_f32_e32 v24, v24
	s_nop 0
	v_add_f32_e32 v24, 1.0, v24
	v_rcp_f32_e32 v24, v24
	s_nop 0
	v_mul_f32_e32 v24, v24, v25
	v_fmac_f32_e32 v31, v24, v24
	v_cndmask_b32_e64 v55, v55, v24, s[8:9]
	v_mul_f32_e32 v24, 0x3d372713, v61
	v_mul_f32_e32 v24, v24, v61
	v_fma_f32 v24, v24, v61, v61
	v_mul_f32_e32 v24, 0x3fcc422a, v24
	v_mul_f32_e32 v24, 0xbfb8aa3b, v24
	v_exp_f32_e32 v24, v24
	v_lshlrev_b32_e32 v25, 16, v20
	v_add_f32_e32 v24, 1.0, v24
	v_rcp_f32_e32 v24, v24
	s_nop 0
	v_mul_f32_e32 v24, v24, v61
	v_fmac_f32_e32 v31, v24, v24
	v_cndmask_b32_e64 v54, v54, v24, s[8:9]
	v_mul_f32_e32 v24, 0x3d372713, v26
	v_mul_f32_e32 v24, v24, v26
	v_fma_f32 v24, v24, v26, v26
	v_mul_f32_e32 v24, 0x3fcc422a, v24
	v_mul_f32_e32 v24, 0xbfb8aa3b, v24
	v_exp_f32_e32 v24, v24
	s_nop 0
	v_add_f32_e32 v24, 1.0, v24
	v_rcp_f32_e32 v24, v24
	s_nop 0
	v_mul_f32_e32 v24, v24, v26
	v_fmac_f32_e32 v31, v24, v24
	v_cndmask_b32_e64 v53, v53, v24, s[8:9]
	v_mul_f32_e32 v24, 0x3d372713, v62
	v_mul_f32_e32 v24, v24, v62
	v_fma_f32 v24, v24, v62, v62
	v_mul_f32_e32 v24, 0x3fcc422a, v24
	v_mul_f32_e32 v24, 0xbfb8aa3b, v24
	v_exp_f32_e32 v24, v24
	v_mov_b32_e32 v26, v25
	v_add_f32_e32 v24, 1.0, v24
	v_rcp_f32_e32 v24, v24
	s_nop 0
	v_mul_f32_e32 v24, v24, v62
	v_fmac_f32_e32 v31, v24, v24
	v_cndmask_b32_e64 v52, v52, v24, s[8:9]
	v_mul_f32_e32 v24, 0x3d372713, v27
	v_mul_f32_e32 v24, v24, v27
	v_fma_f32 v24, v24, v27, v27
	v_mul_f32_e32 v24, 0x3fcc422a, v24
	v_mul_f32_e32 v24, 0xbfb8aa3b, v24
	v_exp_f32_e32 v24, v24
	s_nop 0
	v_add_f32_e32 v24, 1.0, v24
	v_rcp_f32_e32 v24, v24
	s_nop 0
	v_mul_f32_e32 v24, v24, v27
	v_fmac_f32_e32 v31, v24, v24
	v_cndmask_b32_e64 v51, v51, v24, s[8:9]
	v_and_b32_e32 v24, 0xffff0000, v20
	v_mul_f32_e32 v20, 0x3d372713, v25
	v_mul_f32_e32 v20, v20, v25
	v_fmac_f32_e32 v26, v20, v26
	v_mul_f32_e32 v20, 0x3fcc422a, v26
	v_mul_f32_e32 v20, 0xbfb8aa3b, v20
	v_exp_f32_e32 v20, v20
	v_mov_b32_e32 v26, v24
	v_add_f32_e32 v20, 1.0, v20
	v_rcp_f32_e32 v27, v20
	v_mul_f32_e32 v20, 0x3d372713, v24
	v_mul_f32_e32 v20, v20, v24
	v_fmac_f32_e32 v26, v20, v26
	v_mul_f32_e32 v20, 0x3fcc422a, v26
	v_mul_f32_e32 v20, 0xbfb8aa3b, v20
	v_exp_f32_e32 v20, v20
	s_nop 0
	v_add_f32_e32 v20, 1.0, v20
	v_rcp_f32_e32 v26, v20
	s_nop 0
	v_mul_f32_e32 v24, v26, v24
	v_mul_f32_e32 v25, v27, v25
	s_nop 0
	v_mul_f32_e32 v26, v24, v24
	v_mul_f32_e32 v27, v25, v25
	v_cndmask_b32_e64 v49, v49, v25, s[8:9]
	v_add_f32_e32 v20, v27, v31
	v_lshlrev_b32_e32 v25, 16, v21
	v_add_f32_e32 v31, v26, v20
	v_cndmask_b32_e64 v20, v50, v24, s[8:9]
	v_and_b32_e32 v24, 0xffff0000, v21
	v_mul_f32_e32 v21, 0x3d372713, v25
	v_mul_f32_e32 v21, v21, v25
	v_mov_b32_e32 v26, v25
	v_fmac_f32_e32 v26, v21, v26
	v_mul_f32_e32 v21, 0x3fcc422a, v26
	v_mul_f32_e32 v21, 0xbfb8aa3b, v21
	v_exp_f32_e32 v21, v21
	v_mov_b32_e32 v26, v24
	v_add_f32_e32 v21, 1.0, v21
	v_rcp_f32_e32 v27, v21
	v_mul_f32_e32 v21, 0x3d372713, v24
	v_mul_f32_e32 v21, v21, v24
	v_fmac_f32_e32 v26, v21, v26
	v_mul_f32_e32 v21, 0x3fcc422a, v26
	v_mul_f32_e32 v21, 0xbfb8aa3b, v21
	v_exp_f32_e32 v21, v21
	s_nop 0
	v_add_f32_e32 v21, 1.0, v21
	v_rcp_f32_e32 v26, v21
	s_nop 0
	v_mul_f32_e32 v24, v26, v24
	v_mul_f32_e32 v25, v27, v25
	s_nop 0
	v_mul_f32_e32 v26, v24, v24
	v_mul_f32_e32 v27, v25, v25
	s_nop 0
	v_add_f32_e32 v21, v27, v31
	v_cndmask_b32_e64 v31, v38, v25, s[8:9]
	v_lshlrev_b32_e32 v25, 16, v22
	v_add_f32_e32 v38, v26, v21
	v_cndmask_b32_e64 v21, v39, v24, s[8:9]
	v_and_b32_e32 v24, 0xffff0000, v22
	v_mul_f32_e32 v22, 0x3d372713, v25
	v_mul_f32_e32 v22, v22, v25
	v_mov_b32_e32 v26, v25
	v_fmac_f32_e32 v26, v22, v26
	v_mul_f32_e32 v22, 0x3fcc422a, v26
	v_mul_f32_e32 v22, 0xbfb8aa3b, v22
	v_exp_f32_e32 v22, v22
	v_mov_b32_e32 v26, v24
	v_add_f32_e32 v22, 1.0, v22
; __device__ __forceinline__ bf16_t f2bf(float f) { return (bf16_t)(pk2(f, 0.f) & 0xffffu); }
; __device__ __forceinline__ float gelu_t(float x) { return x * sigm(1.5957691216057308f * (x + 0.044715f * x * x * x)); }
; __device__ __forceinline__ void lds_barrier() { asm volatile("s_waitcnt lgkmcnt(0)" ::: "memory"); __builtin_amdgcn_s_barrier(); asm volatile("" ::: "memory"); }
; __device__ __forceinline__ void gmlp_item(const Params& p, int l, int item, LAS unsigned char* lds) {
;     ...
;           for (int i = 0; i < 16; ++i) { const float ge = gelu_t(v[i]); ss += ge * ge; keep[i] = (gg == g) ? ge : keep[i]; } }
;       ss += __shfl_xor(ss, 1); ss += __shfl_xor(ss, 2);
;       const float rstd = rsqrtf(ss * (1.f / 256.f) + EPS);
;       const float* ng = p.gm_norm_g + l * 256 + g * 64 + qd * 16;
; #pragma unroll
;       for (int i = 0; i < 16; ++i) vnT[(qd * 16 + i) * 136 + pp] = f2bf(keep[i] * rstd * ng[i]);
;     }
;     lds_barrier();
;     { f32x4 acc[4];
; #pragma unroll
;       for (int ct = 0; ct < 4; ++ct) acc[ct] = ZERO4;
	v_rcp_f32_e32 v27, v22
	v_mul_f32_e32 v22, 0x3d372713, v24
	v_mul_f32_e32 v22, v22, v24
	v_fmac_f32_e32 v26, v22, v26
	v_mul_f32_e32 v22, 0x3fcc422a, v26
	v_mul_f32_e32 v22, 0xbfb8aa3b, v22
	v_exp_f32_e32 v22, v22
	s_nop 0
	v_add_f32_e32 v22, 1.0, v22
	v_rcp_f32_e32 v26, v22
	s_nop 0
	v_mul_f32_e32 v24, v26, v24
	v_mul_f32_e32 v25, v27, v25
	s_nop 0
	v_mul_f32_e32 v26, v24, v24
	v_mul_f32_e32 v27, v25, v25
	v_cndmask_b32_e64 v22, v35, v25, s[8:9]
	v_add_f32_e32 v27, v27, v38
	v_add_f32_e32 v25, v26, v27
	v_lshlrev_b32_e32 v27, 16, v23
	v_and_b32_e32 v26, 0xffff0000, v23
	v_mul_f32_e32 v23, 0x3d372713, v27
	v_mul_f32_e32 v23, v23, v27
	v_mov_b32_e32 v35, v27
	v_fmac_f32_e32 v35, v23, v35
	v_mul_f32_e32 v23, 0x3fcc422a, v35
	v_mul_f32_e32 v23, 0xbfb8aa3b, v23
	v_exp_f32_e32 v23, v23
	v_mov_b32_e32 v35, v26
	v_cndmask_b32_e64 v24, v37, v24, s[8:9]
	v_add_f32_e32 v23, 1.0, v23
	v_rcp_f32_e32 v39, v23
	v_mul_f32_e32 v23, 0x3d372713, v26
	v_mul_f32_e32 v23, v23, v26
	v_fmac_f32_e32 v35, v23, v35
	v_mul_f32_e32 v23, 0x3fcc422a, v35
	v_mul_f32_e32 v23, 0xbfb8aa3b, v23
	v_exp_f32_e32 v23, v23
	s_nop 0
	v_add_f32_e32 v23, 1.0, v23
	v_rcp_f32_e32 v38, v23
	s_nop 0
	v_mul_f32_e32 v38, v38, v26
	v_mul_f32_e32 v39, v39, v27
	s_nop 0
	v_cndmask_b32_e64 v26, v34, v39, s[8:9]
	v_and_b32_e32 v34, 64, v207
	v_mul_f32_e32 v60, v38, v38
	v_mul_f32_e32 v61, v39, v39
	v_xor_b32_e32 v27, 1, v207
	v_add_u32_e32 v34, 64, v34
	v_add_f32_e32 v23, v61, v25
	v_cndmask_b32_e64 v25, v36, v38, s[8:9]
	v_cmp_lt_i32_e64 s[8:9], v27, v34
	v_add_f32_e32 v23, v60, v23
	v_mov_b32_e32 v39, 0
	v_cndmask_b32_e64 v27, v207, v27, s[8:9]
	v_lshlrev_b32_e32 v27, 2, v27
	ds_bpermute_b32 v27, v27, v23
	s_waitcnt lgkmcnt(0)
	v_add_f32_e32 v23, v23, v27
	v_xor_b32_e32 v27, 2, v207
	v_cmp_lt_i32_e64 s[8:9], v27, v34
	s_nop 1
	v_cndmask_b32_e64 v27, v207, v27, s[8:9]
	v_lshlrev_b32_e32 v27, 2, v27
	ds_bpermute_b32 v27, v27, v23
	s_waitcnt lgkmcnt(0)
	v_add_f32_e32 v23, v23, v27
	v_fmamk_f32 v23, v23, 0x3b800000, v204
	v_cmp_gt_f32_e64 s[8:9], s93, v23
	v_mul_f32_e32 v27, 0x4b800000, v23
	s_nop 0
	v_cndmask_b32_e64 v23, v23, v27, s[8:9]
	v_rsq_f32_e32 v23, v23
	s_nop 0
	v_mul_f32_e32 v27, 0x45800000, v23
	v_cndmask_b32_e64 v27, v23, v27, s[8:9]
	s_lshl_b64 s[8:9], s[28:29], 2
	s_add_u32 s0, s23, s8
	s_addc_u32 s9, s36, s9
	s_lshl_b32 s8, s37, 8
	s_add_u32 s8, s0, s8
	s_addc_u32 s9, s9, 0
	v_lshlrev_b32_e32 v23, 2, v29
	global_load_dwordx4 v[34:37], v23, s[8:9]
	v_mul_u32_u24_e32 v29, 0x110, v29
	v_add3_u32 v29, 0, v30, v29
	v_mul_f32_e32 v30, v57, v27
	v_mul_f32_e32 v38, v58, v27
	v_mul_f32_e32 v20, v20, v27
	s_movk_i32 s0, 0x110
	s_waitcnt vmcnt(0)
	v_mul_f32_e32 v30, v35, v30
	v_cvt_pk_bf16_f32 v30, v30, v2
	ds_write_b16 v29, v30 offset:272
	v_mul_f32_e32 v30, v56, v27
	v_mul_f32_e32 v30, v36, v30
	v_mul_f32_e32 v34, v34, v38
	v_cvt_pk_bf16_f32 v30, v30, v2
	v_cvt_pk_bf16_f32 v34, v34, v2
	ds_write_b16 v29, v30 offset:544
	v_mul_f32_e32 v30, v55, v27
	ds_write_b16 v29, v34
	v_mul_f32_e32 v30, v37, v30
	global_load_dwordx4 v[34:37], v23, s[8:9] offset:16
	v_cvt_pk_bf16_f32 v30, v30, v2
	ds_write_b16 v29, v30 offset:816
	v_mul_f32_e32 v30, v54, v27
	v_mov_b32_e32 v38, 0
	s_waitcnt vmcnt(0)
	v_mul_f32_e32 v30, v34, v30
	v_cvt_pk_bf16_f32 v30, v30, v2
	ds_write_b16 v29, v30 offset:1088
	v_mul_f32_e32 v30, v53, v27
	v_mul_f32_e32 v30, v35, v30
	v_cvt_pk_bf16_f32 v30, v30, v2
	ds_write_b16 v29, v30 offset:1360
	v_mul_f32_e32 v30, v52, v27
	v_mul_f32_e32 v30, v36, v30
	v_cvt_pk_bf16_f32 v30, v30, v2
	ds_write_b16 v29, v30 offset:1632
	v_mul_f32_e32 v30, v51, v27
	v_mul_f32_e32 v30, v37, v30
	global_load_dwordx4 v[34:37], v23, s[8:9] offset:32
	v_cvt_pk_bf16_f32 v30, v30, v2
	ds_write_b16 v29, v30 offset:1904
	v_mul_f32_e32 v30, v49, v27
	s_waitcnt vmcnt(0)
	v_mul_f32_e32 v20, v35, v20
	v_cvt_pk_bf16_f32 v20, v20, v2
	ds_write_b16 v29, v20 offset:2448
	v_mul_f32_e32 v20, v31, v27
	v_mul_f32_e32 v20, v36, v20
	v_cvt_pk_bf16_f32 v20, v20, v2
	ds_write_b16 v29, v20 offset:2720
	v_mul_f32_e32 v20, v21, v27
	v_mul_f32_e32 v30, v34, v30
	v_mul_f32_e32 v20, v37, v20
	v_cvt_pk_bf16_f32 v30, v30, v2
	v_cvt_pk_bf16_f32 v20, v20, v2
	ds_write_b16 v29, v30 offset:2176
	ds_write_b16 v29, v20 offset:2992
	v_mul_f32_e32 v30, v22, v27
	global_load_dwordx4 v[20:23], v23, s[8:9] offset:48
	v_mov_b32_e32 v36, 0
	v_cmp_lt_i32_e64 s[8:9], -1, v33
	v_mov_b32_e32 v37, 0
	v_mov_b32_e32 v33, v36
	v_mov_b32_e32 v34, v36
	v_mov_b32_e32 v35, v36
	v_mov_b32_e32 v31, v36
	s_waitcnt vmcnt(0)
	v_mul_f32_e32 v20, v20, v30
	v_cvt_pk_bf16_f32 v20, v20, v2
	ds_write_b16 v29, v20 offset:3264
	v_mul_f32_e32 v20, v24, v27
	v_mul_f32_e32 v20, v21, v20
	v_cvt_pk_bf16_f32 v20, v20, v2
	ds_write_b16 v29, v20 offset:3536
	v_mul_f32_e32 v20, v26, v27
	v_mul_f32_e32 v20, v22, v20
	v_cvt_pk_bf16_f32 v20, v20, v2
	ds_write_b16 v29, v20 offset:3808
	v_mul_f32_e32 v20, v25, v27
	v_mul_f32_e32 v20, v23, v20
	v_cvt_pk_bf16_f32 v20, v20, v2
	ds_write_b16 v29, v20 offset:4080
	s_waitcnt lgkmcnt(0)
	s_barrier
	v_add_u32_e32 v20, 0, v28
	v_mad_u32_u24 v49, v32, s0, v20
	v_mov_b32_e32 v32, 0
	v_mov_b32_e32 v28, v36
	v_mov_b32_e32 v29, v36
	v_mov_b32_e32 v30, v36
	v_mov_b32_e32 v24, v36
	v_mov_b32_e32 v25, v36
	v_mov_b32_e32 v26, v36
	v_mov_b32_e32 v27, v36
	v_mov_b32_e32 v20, v36
	v_mov_b32_e32 v21, v36
	v_mov_b32_e32 v22, v36
	v_mov_b32_e32 v23, v36
	s_and_saveexec_b64 s[14:15], s[8:9]
	s_cbranch_execnz .LBB0_344
	s_or_b64 exec, exec, s[14:15]
	s_and_saveexec_b64 s[8:9], s[6:7]
	s_cbranch_execnz .LBB0_345

; __device__ __forceinline__ float fexp(float x) { return __builtin_amdgcn_exp2f(x * LOG2E); }
; __device__ __forceinline__ void hgrn_item(const Params& p, int l, int item, int pass, LAS unsigned char* lds) {
;     ...
;         for (int s = 0; s < seg; ++s) { const float* Sp = p.hgS + (iseg + s) * 4096 + wv * 16 + fr; const float* Dp = p.hgD + (iseg + s) * 64;
; #pragma unroll
;             for (int kt = 0; kt < 4; ++kt) { const f32x4 dl = *(const f32x4*)(Dp + kt * 16 + fq * 4);
; #pragma unroll
;                 for (int j = 0; j < 4; ++j) S[kt][j] = fexp(dl[j]) * S[kt][j] + Sp[(kt * 16 + fq * 4 + j) * 64]; } }
.LBB0_329:
	v_lshl_add_u64 v[56:57], v[30:31], 0, s[4:5]
	v_add_co_u32_e32 v58, vcc, s80, v56
	global_load_dwordx4 v[38:41], v[34:35], off offset:-128
	global_load_dwordx4 v[42:45], v[34:35], off offset:-64
	global_load_dwordx4 v[48:51], v[34:35], off
	global_load_dwordx4 v[52:55], v[34:35], off offset:64
	v_addc_co_u32_e32 v59, vcc, 0, v57, vcc
	v_add_co_u32_e32 v60, vcc, s81, v56
	s_add_u32 s4, s4, 0x4000
	s_nop 0
	v_addc_co_u32_e32 v61, vcc, 0, v57, vcc
	v_add_co_u32_e32 v62, vcc, s82, v56
	s_addc_u32 s5, s5, 0
	s_nop 0
	v_addc_co_u32_e32 v63, vcc, 0, v57, vcc
	global_load_dword v64, v[56:57], off
	global_load_dword v65, v[56:57], off offset:256
	global_load_dword v66, v[56:57], off offset:512
	global_load_dword v67, v[56:57], off offset:768
	s_nop 0
	global_load_dword v56, v[62:63], off
	global_load_dword v68, v[60:61], off
	global_load_dword v69, v[60:61], off offset:256
	global_load_dword v70, v[60:61], off offset:512
	global_load_dword v71, v[60:61], off offset:768
	global_load_dword v72, v[62:63], off offset:512
	global_load_dword v73, v[62:63], off offset:768
	global_load_dword v57, v[62:63], off offset:256
	s_nop 0
	global_load_dword v60, v[60:61], off offset:-4096
	s_nop 0
	global_load_dword v62, v[58:59], off offset:512
	global_load_dword v63, v[58:59], off offset:768
	global_load_dword v61, v[58:59], off offset:256
	v_lshl_add_u64 v[34:35], v[34:35], 0, s[48:49]
	s_cmp_eq_u32 s0, s4
	s_waitcnt vmcnt(19)
	v_mul_f32_e32 v3, 0x3fb8aa3b, v38
	v_mul_f32_e32 v21, 0x3fb8aa3b, v39
	v_mul_f32_e32 v23, 0x3fb8aa3b, v40
	v_mul_f32_e32 v29, 0x3fb8aa3b, v41
	s_waitcnt vmcnt(18)
	v_mul_f32_e32 v33, 0x3fb8aa3b, v42
	v_mul_f32_e32 v37, 0x3fb8aa3b, v43
	v_mul_f32_e32 v44, 0x3fb8aa3b, v44
	v_mul_f32_e32 v45, 0x3fb8aa3b, v45
	s_waitcnt vmcnt(17)
	v_mul_f32_e32 v48, 0x3fb8aa3b, v48
	v_mul_f32_e32 v49, 0x3fb8aa3b, v49
	v_mul_f32_e32 v50, 0x3fb8aa3b, v50
	v_mul_f32_e32 v51, 0x3fb8aa3b, v51
	s_waitcnt vmcnt(16)
	v_mul_f32_e32 v52, 0x3fb8aa3b, v52
	v_mul_f32_e32 v53, 0x3fb8aa3b, v53
	v_mul_f32_e32 v54, 0x3fb8aa3b, v54
	v_mul_f32_e32 v55, 0x3fb8aa3b, v55
	v_exp_f32_e32 v38, v3
	v_exp_f32_e32 v39, v21
	v_exp_f32_e32 v40, v23
	v_exp_f32_e32 v41, v29
	v_exp_f32_e32 v42, v33
	v_exp_f32_e32 v43, v37
	v_exp_f32_e32 v44, v44
	v_exp_f32_e32 v45, v45
	v_exp_f32_e32 v48, v48
	v_exp_f32_e32 v50, v50
	v_exp_f32_e32 v52, v52
	v_exp_f32_e32 v54, v54
	v_exp_f32_e32 v55, v55
	v_exp_f32_e32 v53, v53
	v_exp_f32_e32 v51, v51
	v_exp_f32_e32 v49, v49
	s_waitcnt vmcnt(5)
	v_fma_f32 v10, v10, v54, v72
	v_fma_f32 v11, v11, v55, v73
	s_waitcnt vmcnt(4)
	v_fma_f32 v8, v8, v52, v56
	v_fma_f32 v9, v9, v53, v57
	v_fma_f32 v6, v6, v50, v70
	v_fma_f32 v7, v7, v51, v71
	v_fma_f32 v4, v4, v48, v68
	v_fma_f32 v5, v5, v49, v69
	s_waitcnt vmcnt(1)
	v_fma_f32 v18, v18, v44, v62
	v_fma_f32 v19, v19, v45, v63
	s_waitcnt vmcnt(0)
	v_fma_f32 v16, v16, v42, v60
	v_fma_f32 v17, v17, v43, v61
	v_fma_f32 v14, v14, v40, v66
	v_fma_f32 v15, v15, v41, v67
	v_fma_f32 v12, v12, v38, v64
	v_fma_f32 v13, v13, v39, v65
	s_cbranch_scc0 .LBB0_329
	v_mov_b64_e32 v[42:43], s[96:97]
	s_branch .LBB0_332

; __device__ __forceinline__ unsigned pk2(float lo, float hi) { unsigned r; asm("v_cvt_pk_bf16_f32 %0, %1, %2" : "=v"(r) : "v"(lo), "v"(hi)); return r; }
; __device__ __forceinline__ float bflo(unsigned w) { return __uint_as_float(w << 16); }
; __device__ __forceinline__ float bfhi(unsigned w) { return __uint_as_float(w & 0xffff0000u); }
; __device__ __forceinline__ float silu(float x) { return x * sigm(x); }
; __device__ __forceinline__ void lds_barrier() { asm volatile("s_waitcnt lgkmcnt(0)" ::: "memory"); __builtin_amdgcn_s_barrier(); asm volatile("" ::: "memory"); }
; __device__ __forceinline__ void hgrn_item(const Params& p, int l, int item, int pass, LAS unsigned char* lds) {
;     ...
;             float ss = o[0] * o[0] + o[1] * o[1] + o[2] * o[2] + o[3] * o[3]; ss += __shfl_xor(ss, 16); ss += __shfl_xor(ss, 32);
;             if (fq == 0) ssq[wv * 16 + fr] = ss;
;             lds_barrier();
;             const float tot = ssq[fr] + ssq[16 + fr] + ssq[32 + fr] + ssq[48 + fr]; const float rstd = rsqrtf(tot * (1.f / 64.f) + EPS);
;             const size_t T = T0 + fr; const u32x2 gw = *(const u32x2*)(p.z + T * ZLD + 1536 + head * 64 + wv * 16 + fq * 4);
;             u32x2 w; w.x = pk2(o[0] * rstd * ng[0] * silu(bflo(gw.x)), o[1] * rstd * ng[1] * silu(bfhi(gw.x)));
;             w.y = pk2(o[2] * rstd * ng[2] * silu(bflo(gw.y)), o[3] * rstd * ng[3] * silu(bfhi(gw.y)));
;             *(u32x2*)(p.outs + ((size_t)1 * M + T) * 256 + head * 64 + wv * 16 + fq * 4) = w;
.LBB0_333:
	s_or_b64 exec, exec, s[18:19]
	s_waitcnt vmcnt(8)
	v_and_b32_e32 v79, 0xffff, v70
	s_waitcnt lgkmcnt(0)
	s_barrier
	v_add_u32_e32 v70, 0x1800, v45
	s_waitcnt lgkmcnt(0)
	ds_read2_b32 v[0:1], v70 offset0:192 offset1:208
	v_and_b32_e32 v61, 0xffff, v20
	v_and_b32_e32 v78, 0xffff, v22
	s_waitcnt vmcnt(4)
	v_and_b32_e32 v64, 0xffff, v74
	s_waitcnt vmcnt(3)
	v_and_b32_e32 v66, 0xffff, v75
	s_waitcnt lgkmcnt(0)
	v_add_f32_e32 v20, v0, v1
	ds_read2_b32 v[0:1], v70 offset0:224 offset1:240
	v_and_b32_e32 v63, 0xffff, v30
	v_and_b32_e32 v3, 0xffff, v28
	s_mov_b64 s[16:17], 0x2000
	v_and_b32_e32 v62, 0xffff, v71
	s_waitcnt lgkmcnt(0)
	v_add_f32_e32 v0, v20, v0
	v_add_f32_e32 v0, v0, v1
	v_fmamk_f32 v0, v0, 0x3c800000, v204
	v_cmp_gt_f32_e64 s[18:19], s93, v0
	v_mul_f32_e32 v1, 0x4b800000, v0
	v_and_b32_e32 v65, 0xffff, v72
	v_cndmask_b32_e64 v0, v0, v1, s[18:19]
	v_rsq_f32_e32 v0, v0
	v_and_b32_e32 v71, 0xffff, v73
	s_waitcnt vmcnt(2)
	v_and_b32_e32 v72, 0xffff, v76
	s_waitcnt vmcnt(1)
	v_and_b32_e32 v67, 0xffff, v77
	v_mul_f32_e32 v1, 0x45800000, v0
	v_cndmask_b32_e64 v22, v0, v1, s[18:19]
	v_mul_f32_e32 v75, v24, v22
	v_mul_f32_e32 v25, v25, v22
	s_add_u32 s70, s70, 0x16000
	s_addc_u32 s71, s71, 0
	s_cmp_eq_u32 s70, 0x9a000
	s_waitcnt vmcnt(0)
	v_mov_b32_e32 v0, v102
	v_mov_b32_e32 v1, v103
	v_lshlrev_b32_e32 v74, 16, v0
	v_and_b32_e32 v24, 0xffff0000, v0
	v_mul_f32_e32 v20, 0xbfb8aa3b, v74
	v_mul_f32_e32 v0, 0xbfb8aa3b, v24
	v_exp_f32_e32 v20, v20
	v_exp_f32_e32 v0, v0
	v_add_f32_e32 v20, 1.0, v20
	v_add_f32_e32 v0, 1.0, v0
	v_rcp_f32_e32 v30, v20
	v_rcp_f32_e32 v20, v0
	v_mul_f32_e32 v74, v30, v74
	v_mul_f32_e32 v75, v31, v75
	v_mul_f32_e32 v24, v20, v24
	v_mul_f32_e32 v25, v21, v25
	v_mul_f32_e32 v28, v74, v75
	v_mul_f32_e32 v0, v24, v25
	v_lshlrev_b32_e32 v24, 16, v1
	v_mul_f32_e32 v20, 0xbfb8aa3b, v24
	v_exp_f32_e32 v20, v20
	v_cvt_pk_bf16_f32 v0, v28, v0
	v_mul_f32_e32 v25, v26, v22
	v_add_f32_e32 v20, 1.0, v20
	v_rcp_f32_e32 v28, v20
	s_nop 0
	v_mul_f32_e32 v24, v28, v24
	v_mul_f32_e32 v25, v29, v25
	s_nop 0
	v_mul_f32_e32 v20, v24, v25
	v_and_b32_e32 v24, 0xffff0000, v1
	v_mul_f32_e32 v1, 0xbfb8aa3b, v24
	v_exp_f32_e32 v1, v1
	v_mul_f32_e32 v25, v27, v22
	v_add_f32_e32 v1, 1.0, v1
	v_rcp_f32_e32 v22, v1
	s_nop 0
	v_mul_f32_e32 v24, v22, v24
	v_mul_f32_e32 v25, v23, v25
	s_nop 0
	v_mul_f32_e32 v1, v24, v25
	v_cvt_pk_bf16_f32 v1, v20, v1
	global_store_dwordx2 v[38:39], v[0:1], off
	v_lshl_add_u64 v[38:39], v[38:39], 0, s[16:17]
	s_cbranch_scc1 .LBB0_338

; #define LAS __attribute__((address_space(3)))
; __device__ __forceinline__ unsigned pk2(float lo, float hi) { unsigned r; asm("v_cvt_pk_bf16_f32 %0, %1, %2" : "=v"(r) : "v"(lo), "v"(hi)); return r; }
; __device__ __forceinline__ bf16_t f2bf(float f) { return (bf16_t)(pk2(f, 0.f) & 0xffffu); }
; __device__ __forceinline__ float fexp(float x) { return __builtin_amdgcn_exp2f(x * LOG2E); }
; __device__ __forceinline__ void hgrn_item(const Params& p, int l, int item, int pass, LAS unsigned char* lds) {
;     ...
;           if (pass == 1) {
; #pragma unroll
;               for (int j = 0; j < 4; ++j) { const int s = fq * 4 + j; Qs[s * 72 + wv * 16 + fr] = f2bf(silu(qv[j]) * fexp(cs[j])); Ks[s * 72 + wv * 16 + fr] = f2bf(kf[j] * fexp(fminf(-cs[j], 80.f))); } } }
;         segb += blast;
;         lds_barrier();
;         f32x4 o = ZERO4;
;         if (pass == 1) {
;             const bf16x8 ka0 = *(const LAS bf16x8*)(Ks + fr * 72 + fq * 8), ka1 = *(const LAS bf16x8*)(Ks + fr * 72 + 32 + fq * 8);
;             const bf16x8 qb0 = *(const LAS bf16x8*)(Qs + fr * 72 + fq * 8), qb1 = *(const LAS bf16x8*)(Qs + fr * 72 + 32 + fq * 8);
;             f32x4 sc = mfma16(ka0, qb0, ZERO4); sc = mfma16(ka1, qb1, sc);
; #pragma unroll
;             for (int j = 0; j < 4; ++j) sc[j] = (fq * 4 + j <= fr) ? sc[j] : 0.f;
;             u32x4 pw; pw.x = pk2(sc[0], sc[1]); pw.y = pk2(sc[2], sc[3]); pw.z = 0u; pw.w = 0u;
;             o = mfma16(vfrag, as_bf8(pw), o);
; #pragma unroll
;             for (int kk = 0; kk < 2; ++kk) {
;                 u32x4 sw; sw.x = pk2(S[2 * kk][0], S[2 * kk][1]); sw.y = pk2(S[2 * kk][2], S[2 * kk][3]); sw.z = pk2(S[2 * kk + 1][0], S[2 * kk + 1][1]); sw.w = pk2(S[2 * kk + 1][2], S[2 * kk + 1][3]);
;                 const u32x2 q0 = *(const LAS u32x2*)(Qs + fr * 72 + (2 * kk) * 16 + fq * 4), q1 = *(const LAS u32x2*)(Qs + fr * 72 + (2 * kk + 1) * 16 + fq * 4);
;                 u32x4 qw; qw.x = q0.x; qw.y = q0.y; qw.z = q1.x; qw.w = q1.y;
;                 o = mfma16(as_bf8(sw), as_bf8(qw), o);
;             }
;         }
; #pragma unroll
;         for (int kt = 0; kt < 4; ++kt) { const u32x2 kh = *(const LAS u32x2*)(KHt + (kt * 16 + fr) * 16 + fq * 4); u32x4 kw; kw.x = kh.x; kw.y = kh.y; kw.z = 0u; kw.w = 0u;
;             const f32x4 dv = *(const LAS f32x4*)(decs + kt * 16 + fq * 4); S[kt] = mfma16(as_bf8(kw), vfrag, S[kt] * dv); }
.LBB0_336:
	s_or_b64 exec, exec, s[18:19]
	v_lshlrev_b32_e32 v61, 16, v61
	v_lshl_or_b32 v0, v62, 16, v3
	v_mul_f32_e32 v62, 0xbfb8aa3b, v61
	v_exp_f32_e32 v62, v62
	v_lshlrev_b32_e32 v63, 16, v63
	v_lshlrev_b32_e32 v65, 16, v65
	v_lshlrev_b32_e32 v66, 16, v66
	v_add_f32_e32 v62, 1.0, v62
	v_rcp_f32_e32 v62, v62
	s_waitcnt vmcnt(13)
	v_lshl_or_b32 v1, v67, 16, v64
	v_mov_b32_e32 v3, v2
	v_mul_f32_e32 v61, v62, v61
	v_mul_f32_e32 v62, 0x3fb8aa3b, v81
	v_exp_f32_e32 v62, v62
	s_nop 0
	v_mul_f32_e32 v61, v61, v62
	v_cvt_pk_bf16_f32 v61, v61, v2
	ds_write_b16 v52, v61
	v_max_f32_e64 v61, -v81, -v81
	v_min_f32_e32 v61, 0x42a00000, v61
	v_mul_f32_e32 v61, 0x3fb8aa3b, v61
	v_exp_f32_e32 v61, v61
	s_nop 0
	v_mul_f32_e32 v24, v24, v61
	v_cvt_pk_bf16_f32 v24, v24, v2
	ds_write_b16 v52, v24 offset:2304
	v_mul_f32_e32 v24, 0xbfb8aa3b, v63
	v_exp_f32_e32 v24, v24
	v_mul_f32_e32 v61, 0x3fb8aa3b, v80
	v_exp_f32_e32 v61, v61
	v_add_f32_e32 v24, 1.0, v24
	v_rcp_f32_e32 v24, v24
	s_nop 0
	v_mul_f32_e32 v24, v24, v63
	v_mul_f32_e32 v24, v24, v61
	v_cvt_pk_bf16_f32 v24, v24, v2
	ds_write_b16 v52, v24 offset:144
	v_max_f32_e64 v24, -v80, -v80
	v_min_f32_e32 v24, 0x42a00000, v24
	v_mul_f32_e32 v24, 0x3fb8aa3b, v24
	v_exp_f32_e32 v24, v24
	v_add_u32_e32 v61, v69, v68
	v_mul_f32_e32 v24, v25, v24
	v_cvt_pk_bf16_f32 v24, v24, v2
	ds_write_b16 v52, v24 offset:2448
	v_mul_f32_e32 v24, 0xbfb8aa3b, v65
	v_exp_f32_e32 v24, v24
	v_mul_f32_e32 v25, 0x3fb8aa3b, v79
	v_exp_f32_e32 v25, v25
	v_add_f32_e32 v24, 1.0, v24
	v_rcp_f32_e32 v24, v24
	s_nop 0
	v_mul_f32_e32 v24, v24, v65
	v_mul_f32_e32 v24, v24, v25
	v_cvt_pk_bf16_f32 v24, v24, v2
	ds_write_b16 v52, v24 offset:288
	v_max_f32_e64 v24, -v79, -v79
	v_min_f32_e32 v24, 0x42a00000, v24
	v_mul_f32_e32 v24, 0x3fb8aa3b, v24
	v_exp_f32_e32 v24, v24
	v_mul_f32_e32 v25, 0x3fb8aa3b, v78
	v_exp_f32_e32 v25, v25
	v_mul_f32_e32 v24, v26, v24
	v_cvt_pk_bf16_f32 v24, v24, v2
	ds_write_b16 v52, v24 offset:2592
	v_mul_f32_e32 v24, 0xbfb8aa3b, v66
	v_exp_f32_e32 v24, v24
	s_nop 0
	v_add_f32_e32 v24, 1.0, v24
	v_rcp_f32_e32 v24, v24
	s_nop 0
	v_mul_f32_e32 v24, v24, v66
	v_mul_f32_e32 v24, v24, v25
	v_cvt_pk_bf16_f32 v24, v24, v2
	ds_write_b16 v52, v24 offset:432
	v_max_f32_e64 v24, -v78, -v78
	v_min_f32_e32 v24, 0x42a00000, v24
	v_mul_f32_e32 v24, 0x3fb8aa3b, v24
	v_exp_f32_e32 v24, v24
	s_nop 0
	v_mul_f32_e32 v24, v27, v24
	v_cvt_pk_bf16_f32 v24, v24, v2
	ds_write_b16 v52, v24 offset:2736
	s_waitcnt lgkmcnt(0)
	s_barrier
	ds_read_b128 v[24:27], v50 offset:2304
	ds_read_b128 v[62:65], v50 offset:2368
	ds_read_b128 v[78:81], v50
	ds_read_b128 v[82:85], v50 offset:64
	s_waitcnt lgkmcnt(1)
	v_mfma_f32_16x16x32_bf16 v[24:27], v[24:27], v[78:81], 0
	ds_read2_b64 v[78:81], v48 offset1:4
	s_waitcnt lgkmcnt(1)
	v_mfma_f32_16x16x32_bf16 v[24:27], v[62:65], v[82:85], v[24:27]
	v_cvt_pk_bf16_f32 v62, v12, v13
	v_cvt_pk_bf16_f32 v63, v14, v15
	v_cvt_pk_bf16_f32 v64, v16, v17
	v_cvt_pk_bf16_f32 v65, v18, v19
	ds_read_b128 v[82:85], v61 offset:6656
	s_nop 6
	v_cndmask_b32_e64 v24, v24, 0, s[4:5]
	v_cndmask_b32_e64 v25, 0, v25, s[6:7]
	v_cndmask_b32_e64 v26, v26, 0, s[8:9]
	v_cndmask_b32_e64 v27, v27, 0, s[10:11]
	v_cvt_pk_bf16_f32 v24, v24, v25
	v_cvt_pk_bf16_f32 v25, v26, v27
	v_mov_b32_e32 v26, v2
	v_mov_b32_e32 v27, v2
	s_waitcnt lgkmcnt(0)
	v_mul_f32_e32 v12, v12, v82
	v_mul_f32_e32 v13, v13, v83
	v_mul_f32_e32 v14, v14, v84
	v_mul_f32_e32 v15, v15, v85
	v_mfma_f32_16x16x32_bf16 v[24:27], v[0:3], v[24:27], 0
	v_mfma_f32_16x16x32_bf16 v[24:27], v[62:65], v[78:81], v[24:27]
	ds_read2_b64 v[78:81], v48 offset0:8 offset1:12
	v_cvt_pk_bf16_f32 v62, v4, v5
	v_cvt_pk_bf16_f32 v63, v6, v7
	v_cvt_pk_bf16_f32 v64, v8, v9
	v_cvt_pk_bf16_f32 v65, v10, v11
	s_waitcnt lgkmcnt(0)
	v_mfma_f32_16x16x32_bf16 v[24:27], v[62:65], v[78:81], v[24:27]
	ds_read2st64_b64 v[62:65], v35 offset0:9 offset1:10
	v_mov_b32_e32 v80, v2
	v_mov_b32_e32 v81, v2
	s_waitcnt lgkmcnt(0)
	v_mov_b32_e32 v78, v62
	v_mov_b32_e32 v79, v63
	v_mov_b32_e32 v62, v64
	v_mov_b32_e32 v63, v65
	v_mfma_f32_16x16x32_bf16 v[12:15], v[78:81], v[0:3], v[12:15]
	ds_read_b128 v[78:81], v61 offset:6720
	v_mov_b32_e32 v64, v2
	v_mov_b32_e32 v65, v2
	s_waitcnt lgkmcnt(0)
	v_mul_f32_e32 v16, v16, v78
	v_mul_f32_e32 v17, v17, v79
	v_mul_f32_e32 v18, v18, v80
	v_mul_f32_e32 v19, v19, v81
	s_nop 1
	v_mfma_f32_16x16x32_bf16 v[16:19], v[62:65], v[0:3], v[16:19]
	ds_read_b64 v[62:63], v35 offset:5632
	ds_read_b128 v[78:81], v61 offset:6784
	s_waitcnt lgkmcnt(0)
	v_mul_f32_e32 v4, v4, v78
	v_mul_f32_e32 v5, v5, v79
	v_mul_f32_e32 v6, v6, v80
	v_mul_f32_e32 v7, v7, v81
	s_nop 1
	v_mfma_f32_16x16x32_bf16 v[4:7], v[62:65], v[0:3], v[4:7]
	ds_read_b64 v[62:63], v44 offset:4608
	ds_read_b128 v[78:81], v61 offset:6848
	s_waitcnt lgkmcnt(0)
	v_mul_f32_e32 v8, v8, v78
	v_mul_f32_e32 v9, v9, v79
	v_mul_f32_e32 v10, v10, v80
	v_mul_f32_e32 v11, v11, v81
	s_nop 1
	v_mfma_f32_16x16x32_bf16 v[8:11], v[62:65], v[0:3], v[8:11]
	v_mul_f32_e32 v0, v25, v25
	v_fmac_f32_e32 v0, v24, v24
	v_fmac_f32_e32 v0, v26, v26
	v_fmac_f32_e32 v0, v27, v27
	ds_bpermute_b32 v1, v49, v0
	s_waitcnt lgkmcnt(0)
	v_add_f32_e32 v0, v0, v1
	ds_bpermute_b32 v1, v51, v0
	s_and_saveexec_b64 s[18:19], vcc
	s_cbranch_execz .LBB0_333
	s_waitcnt lgkmcnt(0)
	v_add_f32_e32 v0, v0, v1
	v_add_u32_e32 v1, v53, v60
	ds_write_b32 v1, v0 offset:6912
	s_branch .LBB0_333

; #define LAS __attribute__((address_space(3)))
; __device__ __forceinline__ bf16_t f2bf(float f) { return (bf16_t)(pk2(f, 0.f) & 0xffffu); }
; __device__ __forceinline__ float bf2f(unsigned b) { return __uint_as_float(b << 16); }
; __device__ __forceinline__ f32x4 mfma16(bf16x8 a, bf16x8 b, f32x4 c) { return __builtin_amdgcn_mfma_f32_16x16x32_bf16(a, b, c, 0, 0, 0); }
; __device__ __forceinline__ void lds_barrier() { asm volatile("s_waitcnt lgkmcnt(0)" ::: "memory"); __builtin_amdgcn_s_barrier(); asm volatile("" ::: "memory"); }
; __device__ __forceinline__ void lru_item(const Params& p, int l, int item, LAS unsigned char* lds) {
;     ...
;     unsigned xr[19];
; #pragma unroll
;     for (int i = 0; i < 19; ++i) { const int t = t0 - 3 + i; xr[i] = (t >= 0) ? (unsigned)p.z[(Tb + (t >= 0 ? t : 0)) * ZLD + 2304 + ch] : 0u; }
;     bf16x8 wa0[4], wa1[4], wx0[4], wx1[4];
;     { const bf16_t* wap = p.waT + (((size_t)l * 4 + h) * 64 + fr) * 64 + fq * 8; const bf16_t* wxp = p.wxT + (((size_t)l * 4 + h) * 64 + fr) * 64 + fq * 8;
; #pragma unroll
;       for (int jt = 0; jt < 4; ++jt) { wa0[jt] = *(const bf16x8*)(wap + jt * 1024); wa1[jt] = *(const bf16x8*)(wap + jt * 1024 + 32); wx0[jt] = *(const bf16x8*)(wxp + jt * 1024); wx1[jt] = *(const bf16x8*)(wxp + jt * 1024 + 32); } }
;     { const float cb = p.conv_b[l * 256 + ch], cw0 = p.conv_w[(l * 4 + 0) * 256 + ch], cw1 = p.conv_w[(l * 4 + 1) * 256 + ch], cw2 = p.conv_w[(l * 4 + 2) * 256 + ch], cw3 = p.conv_w[(l * 4 + 3) * 256 + ch];
; #pragma unroll
;       for (int i = 0; i < 16; ++i) { const float xc = cb + bf2f(xr[i]) * cw0 + bf2f(xr[i + 1]) * cw1 + bf2f(xr[i + 2]) * cw2 + bf2f(xr[i + 3]) * cw3; xa[i * 72 + lane] = f2bf(xc); xf[i * 66 + lane] = xc; } }
;     lds_barrier();
;     { const bf16x8 a0 = *(const LAS bf16x8*)(xa + fr * 72 + fq * 8), a1 = *(const LAS bf16x8*)(xa + fr * 72 + 32 + fq * 8);
; #pragma unroll
;       for (int jt = 0; jt < 4; ++jt) {
;           f32x4 pa = mfma16(a0, wa0[jt], ZERO4); pa = mfma16(a1, wa1[jt], pa);
;           f32x4 px = mfma16(a0, wx0[jt], ZERO4); px = mfma16(a1, wx1[jt], px);
;           const int cj = l * 256 + h * 64 + jt * 16 + fr; const float bav = p.ba[cj], bxv = p.bx[cj], sp = p.spl[cj];
.LBB0_393:
	s_or_b64 exec, exec, s[74:75]
	s_movk_i32 s4, 0x2a00
	v_and_b32_e32 v91, 15, v1
	s_or_b32 s98, s16, s40
	v_or_b32_e32 v148, s98, v91
	v_ashrrev_i32_e32 v149, 31, v148
	v_lshlrev_b64 v[148:149], 2, v[148:149]
	v_lshl_add_u64 v[150:151], s[30:31], 0, v[148:149]
	v_lshl_add_u64 v[152:153], s[6:7], 0, v[148:149]
	v_lshl_add_u64 v[154:155], s[34:35], 0, v[148:149]
	global_load_dword v156, v[150:151], off
	global_load_dword v157, v[152:153], off
	global_load_dword v158, v[154:155], off
	global_load_dword v159, v[150:151], off offset:64
	global_load_dword v160, v[152:153], off offset:64
	global_load_dword v161, v[154:155], off offset:64
	global_load_dword v162, v[150:151], off offset:128
	global_load_dword v163, v[152:153], off offset:128
	global_load_dword v164, v[154:155], off offset:128
	global_load_dword v165, v[150:151], off offset:192
	global_load_dword v166, v[152:153], off offset:192
	global_load_dword v167, v[154:155], off offset:192
	v_mul_lo_u32 v4, v0, s4
	s_or_b32 s4, s12, s16
	v_add_u32_e32 v79, 0, v4
	v_or_b32_e32 v4, s4, v91
	v_mov_b32_e32 v5, s13
	v_lshlrev_b64 v[4:5], 7, v[4:5]
	v_lshl_add_u64 v[6:7], s[70:71], 0, v[4:5]
	v_and_b32_e32 v20, 48, v3
	v_mov_b32_e32 v21, v2
	v_lshl_add_u64 v[6:7], v[6:7], 0, v[20:21]
	v_lshl_add_u64 v[4:5], s[36:37], 0, v[4:5]
	v_add_co_u32_e32 v8, vcc, s80, v6
	v_lshl_add_u64 v[4:5], v[4:5], 0, v[20:21]
	s_nop 0
	v_addc_co_u32_e32 v9, vcc, 0, v7, vcc
	v_or_b32_e32 v100, s40, v78
	v_mov_b32_e32 v98, s17
	v_mov_b32_e32 v99, s22
	v_add_co_u32_e32 v16, vcc, s80, v4
	v_ashrrev_i32_e32 v101, 31, v100
	s_nop 0
	v_addc_co_u32_e32 v17, vcc, 0, v5, vcc
	v_lshl_add_u64 v[98:99], v[100:101], 2, v[98:99]
	global_load_dwordx4 v[60:63], v[6:7], off
	global_load_dwordx4 v[64:67], v[6:7], off offset:64
	global_load_dwordx4 v[68:71], v[4:5], off
	global_load_dwordx4 v[72:75], v[4:5], off offset:64
	global_load_dwordx4 v[44:47], v[6:7], off offset:2048
	global_load_dwordx4 v[48:51], v[6:7], off offset:2112
	global_load_dwordx4 v[52:55], v[4:5], off offset:2048
	global_load_dwordx4 v[56:59], v[4:5], off offset:2112
	global_load_dwordx4 v[28:31], v[8:9], off
	global_load_dwordx4 v[32:35], v[8:9], off offset:64
	global_load_dwordx4 v[36:39], v[16:17], off
	global_load_dwordx4 v[40:43], v[16:17], off offset:64
	s_nop 0
	global_load_dwordx4 v[4:7], v[8:9], off offset:2048
	s_nop 0
	global_load_dwordx4 v[8:11], v[8:9], off offset:2112
	s_nop 0
	global_load_dwordx4 v[12:15], v[16:17], off offset:2048
	s_nop 0
	global_load_dwordx4 v[16:19], v[16:17], off offset:2112
	v_mov_b32_e32 v96, s33
	global_load_dword v21, v[98:99], off
	v_or_b32_e32 v98, s87, v78
	v_mov_b32_e32 v97, s44
	v_ashrrev_i32_e32 v99, 31, v98
	v_lshl_add_u64 v[96:97], v[98:99], 2, v[96:97]
	global_load_dword v98, v[96:97], off
	global_load_dword v99, v[96:97], off offset:1024
	global_load_dword v100, v[96:97], off offset:2048
	s_nop 0
	global_load_dword v96, v[96:97], off offset:3072
	v_lshlrev_b32_e32 v78, 1, v3
	v_add_u32_e32 v97, v79, v78
	v_add_u32_e32 v80, v97, v78
	s_or_b32 s4, s16, s40
	s_mov_b32 s16, 0xf800000
	v_lshrrev_b32_e32 v92, 4, v3
	v_lshl_add_u32 v1, v1, 3, 0
	v_add_u32_e32 v1, 0x15000, v1
	s_waitcnt vmcnt(3)
	v_lshlrev_b32_e32 v88, 16, v88
	v_lshlrev_b32_e32 v87, 16, v87
	v_lshlrev_b32_e32 v85, 16, v85
	v_lshlrev_b32_e32 v83, 16, v83
	v_lshlrev_b32_e32 v26, 16, v26
	v_lshlrev_b32_e32 v22, 16, v22
	v_lshlrev_b32_e32 v24, 16, v24
	v_lshlrev_b32_e32 v23, 16, v23
	v_lshlrev_b32_e32 v27, 16, v27
	v_lshlrev_b32_e32 v25, 16, v25
	v_lshlrev_b32_e32 v82, 16, v82
	v_lshlrev_b32_e32 v81, 16, v81
	v_lshlrev_b32_e32 v86, 16, v86
	v_lshlrev_b32_e32 v84, 16, v84
	v_lshlrev_b32_e32 v90, 16, v90
	v_lshlrev_b32_e32 v89, 16, v89
	v_lshlrev_b32_e32 v94, 16, v94
	v_lshlrev_b32_e32 v93, 16, v93
	v_lshlrev_b32_e32 v95, 16, v95
	v_cmp_lt_i32_e32 vcc, 2, v76
	s_nop 1
	v_cndmask_b32_e32 v88, 0, v88, vcc
	v_cmp_lt_i32_e32 vcc, 1, v76
	s_nop 1
	v_cndmask_b32_e32 v87, 0, v87, vcc
	v_cmp_lt_i32_e32 vcc, 0, v76
	s_nop 1
	v_cndmask_b32_e32 v85, 0, v85, vcc
	v_fma_f32 v88, v88, v98, v21
	s_waitcnt vmcnt(2)
	v_fmac_f32_e32 v88, v87, v99
	v_fma_f32 v87, v87, v98, v21
	s_waitcnt vmcnt(1)
	v_fmac_f32_e32 v88, v85, v100
	v_fmac_f32_e32 v87, v85, v99
	s_waitcnt vmcnt(0)
	v_fmac_f32_e32 v88, v83, v96
	v_cvt_pk_bf16_f32 v101, v88, v2
	v_fmac_f32_e32 v87, v83, v100
	v_fma_f32 v85, v85, v98, v21
	ds_write_b16 v97, v101
	v_fmac_f32_e32 v87, v26, v96
	v_cvt_pk_bf16_f32 v101, v87, v2
	v_fmac_f32_e32 v85, v83, v99
	v_fma_f32 v83, v83, v98, v21
	ds_write_b16 v97, v101 offset:144
	v_add_u32_e32 v101, 0x800, v80
	v_fmac_f32_e32 v85, v26, v100
	v_fmac_f32_e32 v83, v26, v99
	ds_write2_b32 v101, v88, v87 offset0:64 offset1:130
	v_fmac_f32_e32 v85, v22, v96
	v_cvt_pk_bf16_f32 v87, v85, v2
	v_fmac_f32_e32 v83, v22, v100
	v_fma_f32 v26, v26, v98, v21
	ds_write_b16 v97, v87 offset:288
	v_fmac_f32_e32 v83, v24, v96
	v_cvt_pk_bf16_f32 v87, v83, v2
	v_fmac_f32_e32 v26, v22, v99
	v_fma_f32 v22, v22, v98, v21
	ds_write_b16 v97, v87 offset:432
	v_add_u32_e32 v87, 0xa00, v80
	v_fmac_f32_e32 v26, v24, v100
	v_fmac_f32_e32 v22, v24, v99
	ds_write2_b32 v87, v85, v83 offset0:68 offset1:134
	v_fmac_f32_e32 v26, v23, v96
	v_cvt_pk_bf16_f32 v83, v26, v2
	v_fmac_f32_e32 v22, v23, v100
	ds_write_b16 v97, v83 offset:576
	v_fmac_f32_e32 v22, v27, v96
	v_cvt_pk_bf16_f32 v83, v22, v2
	ds_write_b16 v97, v83 offset:720
	v_add_u32_e32 v83, 0xc00, v80
	ds_write2_b32 v83, v26, v22 offset0:72 offset1:138
	v_fma_f32 v22, v24, v98, v21
	v_fmac_f32_e32 v22, v23, v99
	v_fma_f32 v23, v23, v98, v21
	v_fmac_f32_e32 v22, v27, v100
	v_fmac_f32_e32 v23, v27, v99
	v_fmac_f32_e32 v22, v25, v96
	v_cvt_pk_bf16_f32 v24, v22, v2
; #define LAS __attribute__((address_space(3)))
; __device__ __forceinline__ bf16_t f2bf(float f) { return (bf16_t)(pk2(f, 0.f) & 0xffffu); }
; __device__ __forceinline__ float bf2f(unsigned b) { return __uint_as_float(b << 16); }
; __device__ __forceinline__ float fexp(float x) { return __builtin_amdgcn_exp2f(x * LOG2E); }
; __device__ __forceinline__ float sigm(float x) { return frcp(1.f + fexp(-x)); }
; __device__ __forceinline__ f32x4 mfma16(bf16x8 a, bf16x8 b, f32x4 c) { return __builtin_amdgcn_mfma_f32_16x16x32_bf16(a, b, c, 0, 0, 0); }
; __device__ __forceinline__ void lds_barrier() { asm volatile("s_waitcnt lgkmcnt(0)" ::: "memory"); __builtin_amdgcn_s_barrier(); asm volatile("" ::: "memory"); }
; __device__ __forceinline__ void lru_item(const Params& p, int l, int item, LAS unsigned char* lds) {
;     ...
;       for (int i = 0; i < 16; ++i) { const float xc = cb + bf2f(xr[i]) * cw0 + bf2f(xr[i + 1]) * cw1 + bf2f(xr[i + 2]) * cw2 + bf2f(xr[i + 3]) * cw3; xa[i * 72 + lane] = f2bf(xc); xf[i * 66 + lane] = xc; } }
;     lds_barrier();
;     { const bf16x8 a0 = *(const LAS bf16x8*)(xa + fr * 72 + fq * 8), a1 = *(const LAS bf16x8*)(xa + fr * 72 + 32 + fq * 8);
; #pragma unroll
;       for (int jt = 0; jt < 4; ++jt) {
;           f32x4 pa = mfma16(a0, wa0[jt], ZERO4); pa = mfma16(a1, wa1[jt], pa);
;           f32x4 px = mfma16(a0, wx0[jt], ZERO4); px = mfma16(a1, wx1[jt], px);
;           const int cj = l * 256 + h * 64 + jt * 16 + fr; const float bav = p.ba[cj], bxv = p.bx[cj], sp = p.spl[cj];
; #pragma unroll
;           for (int jj = 0; jj < 4; ++jj) { const int t = fq * 4 + jj; const float r = sigm(pa[jj] + bav), ig = sigm(px[jj] + bxv); const float la = -8.f * r * sp;
;               const float a = fexp(la); float mult = sqrtf(fmaxf(1.f - fexp(2.f * la), 0.f)); if (t0 + t == 0) mult = 1.f;
;               const int li = t * 66 + jt * 16 + fr; const float xcv = xf[li]; sa[li] = a; xf[li] = mult * ig * xcv; }
	v_fmac_f32_e32 v23, v25, v100
	ds_write_b16 v97, v24 offset:864
	v_fmac_f32_e32 v23, v82, v96
	v_cvt_pk_bf16_f32 v24, v23, v2
	ds_write_b16 v97, v24 offset:1008
	v_add_u32_e32 v24, 0xe00, v80
	ds_write2_b32 v24, v22, v23 offset0:76 offset1:142
	v_fma_f32 v22, v27, v98, v21
	v_fmac_f32_e32 v22, v25, v99
	v_fmac_f32_e32 v22, v82, v100
	v_fmac_f32_e32 v22, v81, v96
	v_cvt_pk_bf16_f32 v23, v22, v2
	ds_write_b16 v97, v23 offset:1152
	v_fma_f32 v23, v25, v98, v21
	v_fmac_f32_e32 v23, v82, v99
	v_fmac_f32_e32 v23, v81, v100
	v_fmac_f32_e32 v23, v86, v96
	v_cvt_pk_bf16_f32 v24, v23, v2
	ds_write_b16 v97, v24 offset:1296
	v_add_u32_e32 v24, 0x1000, v80
	ds_write2_b32 v24, v22, v23 offset0:80 offset1:146
	v_fma_f32 v22, v82, v98, v21
	v_fmac_f32_e32 v22, v81, v99
	v_fmac_f32_e32 v22, v86, v100
	v_fmac_f32_e32 v22, v84, v96
	v_cvt_pk_bf16_f32 v23, v22, v2
	ds_write_b16 v97, v23 offset:1440
	v_fma_f32 v23, v81, v98, v21
	v_fmac_f32_e32 v23, v86, v99
	v_fmac_f32_e32 v23, v84, v100
	v_fmac_f32_e32 v23, v90, v96
	v_cvt_pk_bf16_f32 v24, v23, v2
	ds_write_b16 v97, v24 offset:1584
	v_add_u32_e32 v24, 0x1200, v80
	ds_write2_b32 v24, v22, v23 offset0:84 offset1:150
	v_fma_f32 v22, v86, v98, v21
	v_fmac_f32_e32 v22, v84, v99
	v_fmac_f32_e32 v22, v90, v100
	v_fmac_f32_e32 v22, v89, v96
	v_cvt_pk_bf16_f32 v23, v22, v2
	ds_write_b16 v97, v23 offset:1728
	v_fma_f32 v23, v84, v98, v21
	v_fmac_f32_e32 v23, v90, v99
	v_fmac_f32_e32 v23, v89, v100
	v_fmac_f32_e32 v23, v94, v96
	v_cvt_pk_bf16_f32 v24, v23, v2
	ds_write_b16 v97, v24 offset:1872
	v_add_u32_e32 v24, 0x1400, v80
	ds_write2_b32 v24, v22, v23 offset0:88 offset1:154
	v_fma_f32 v22, v90, v98, v21
	v_fmac_f32_e32 v22, v89, v99
	v_fmac_f32_e32 v21, v89, v98
	v_fmac_f32_e32 v22, v94, v100
	v_fmac_f32_e32 v21, v94, v99
	v_fmac_f32_e32 v22, v93, v96
	v_cvt_pk_bf16_f32 v23, v22, v2
	v_fmac_f32_e32 v21, v93, v100
	ds_write_b16 v97, v23 offset:2016
	v_fmac_f32_e32 v21, v95, v96
	v_cvt_pk_bf16_f32 v23, v21, v2
	ds_write_b16 v97, v23 offset:2160
	v_add_u32_e32 v23, 0x1600, v80
	ds_write2_b32 v23, v22, v21 offset0:92 offset1:158
	v_mul_u32_u24_e32 v21, 0x90, v91
	s_waitcnt lgkmcnt(0)
	s_barrier
	v_add3_u32 v24, v79, v21, v20
	ds_read_b128 v[20:23], v24
	ds_read_b128 v[24:27], v24 offset:64
	s_waitcnt lgkmcnt(1)
	v_mfma_f32_16x16x32_bf16 v[60:63], v[20:23], v[60:63], 0
	v_or_b32_e32 v86, s4, v91
	v_ashrrev_i32_e32 v87, 31, v86
	s_waitcnt lgkmcnt(0)
	v_mfma_f32_16x16x32_bf16 v[82:85], v[24:27], v[64:67], v[60:63]
	v_mfma_f32_16x16x32_bf16 v[60:63], v[20:23], v[68:71], 0
	v_mfma_f32_16x16x32_bf16 v[70:73], v[24:27], v[72:75], v[60:63]
	v_mfma_f32_16x16x32_bf16 v[44:47], v[20:23], v[44:47], 0
	s_nop 5
	v_lshlrev_b64 v[60:61], 2, v[86:87]
	v_lshl_add_u64 v[64:65], s[30:31], 0, v[60:61]
	v_lshl_add_u64 v[62:63], s[6:7], 0, v[60:61]
	v_lshl_add_u64 v[60:61], s[34:35], 0, v[60:61]
	v_mfma_f32_16x16x32_bf16 v[48:51], v[24:27], v[48:51], v[44:47]
	s_waitcnt vmcnt(0)
	v_mov_b32_e32 v81, v156
	v_mov_b32_e32 v86, v157
	v_mov_b32_e32 v87, v158
	v_add_f32_e32 v66, v82, v81
	v_mul_f32_e32 v66, 0xbfb8aa3b, v66
	v_exp_f32_e32 v66, v66
	s_waitcnt vmcnt(1)
	v_add_f32_e32 v67, v70, v86
	v_mul_f32_e32 v67, 0xbfb8aa3b, v67
	v_exp_f32_e32 v67, v67
	v_add_f32_e32 v66, 1.0, v66
	v_rcp_f32_e32 v66, v66
	v_mfma_f32_16x16x32_bf16 v[44:47], v[20:23], v[52:55], 0
	v_add_f32_e32 v67, 1.0, v67
	v_rcp_f32_e32 v68, v67
	v_mul_f32_e32 v66, 0xc1000000, v66
	s_waitcnt vmcnt(0)
	v_mul_f32_e32 v66, v87, v66
	v_mul_f32_e32 v67, 0x3fb8aa3b, v66
	v_add_f32_e32 v66, v66, v66
	v_mul_f32_e32 v66, 0x3fb8aa3b, v66
	v_exp_f32_e32 v66, v66
	v_exp_f32_e32 v69, v67
	v_mfma_f32_16x16x32_bf16 v[44:47], v[24:27], v[56:59], v[44:47]
	v_sub_f32_e32 v66, 1.0, v66
	v_max_f32_e32 v66, 0, v66
	v_cmp_gt_f32_e32 vcc, s16, v66
	v_mul_f32_e32 v67, 0x4f800000, v66
	v_mfma_f32_16x16x32_bf16 v[28:31], v[20:23], v[28:31], 0
	v_cndmask_b32_e32 v66, v66, v67, vcc
	v_sqrt_f32_e32 v67, v66
	v_mfma_f32_16x16x32_bf16 v[32:35], v[24:27], v[32:35], v[28:31]
	v_add_u32_e32 v70, -1, v67
	v_fma_f32 v74, -v70, v67, v66
	v_cmp_ge_f32_e64 s[4:5], 0, v74
	v_add_u32_e32 v74, 1, v67
	v_mfma_f32_16x16x32_bf16 v[28:31], v[20:23], v[36:39], 0
	v_cndmask_b32_e64 v70, v67, v70, s[4:5]
	v_fma_f32 v67, -v74, v67, v66
	v_cmp_lt_f32_e64 s[4:5], 0, v67
	v_mfma_f32_16x16x32_bf16 v[28:31], v[24:27], v[40:43], v[28:31]
	s_nop 0
	v_cndmask_b32_e64 v67, v70, v74, s[4:5]
	v_mul_f32_e32 v70, 0x37800000, v67
	v_cndmask_b32_e32 v67, v67, v70, vcc
	v_cmp_class_f32_e32 vcc, v66, v205
	s_movk_i32 s4, 0x108
	v_mfma_f32_16x16x32_bf16 v[4:7], v[20:23], v[4:7], 0
	v_cndmask_b32_e32 v66, v67, v66, vcc
	v_or_b32_e32 v67, v76, v92
	v_cmp_eq_u32_e32 vcc, 0, v67
	v_mfma_f32_16x16x32_bf16 v[8:11], v[24:27], v[8:11], v[4:7]
	s_nop 0
	v_cndmask_b32_e64 v70, v66, 1.0, vcc
	v_mad_u32_u24 v66, v92, s4, v91
	v_lshl_add_u32 v74, v66, 2, v79
	v_add_u32_e32 v75, 0x800, v74
	ds_read2_b32 v[66:67], v75 offset0:64 offset1:80
	v_mul_f32_e32 v68, v68, v70
	ds_write_b32 v74, v69 offset:6528
	v_mfma_f32_16x16x32_bf16 v[4:7], v[20:23], v[12:15], 0
	s_waitcnt lgkmcnt(1)
; __device__ __forceinline__ float fexp(float x) { return __builtin_amdgcn_exp2f(x * LOG2E); }
; __device__ __forceinline__ float sigm(float x) { return frcp(1.f + fexp(-x)); }
; __device__ __forceinline__ void lru_item(const Params& p, int l, int item, LAS unsigned char* lds) {
;     ...
;           const int cj = l * 256 + h * 64 + jt * 16 + fr; const float bav = p.ba[cj], bxv = p.bx[cj], sp = p.spl[cj];
; #pragma unroll
;           for (int jj = 0; jj < 4; ++jj) { const int t = fq * 4 + jj; const float r = sigm(pa[jj] + bav), ig = sigm(px[jj] + bxv); const float la = -8.f * r * sp;
;               const float a = fexp(la); float mult = sqrtf(fmaxf(1.f - fexp(2.f * la), 0.f)); if (t0 + t == 0) mult = 1.f;
;               const int li = t * 66 + jt * 16 + fr; const float xcv = xf[li]; sa[li] = a; xf[li] = mult * ig * xcv; }
	v_mul_f32_e32 v66, v66, v68
	ds_write_b32 v74, v66 offset:2304
	v_add_f32_e32 v66, v83, v81
	v_mul_f32_e32 v66, 0xbfb8aa3b, v66
	v_exp_f32_e32 v66, v66
	v_add_f32_e32 v68, v71, v86
	v_mul_f32_e32 v68, 0xbfb8aa3b, v68
	v_exp_f32_e32 v68, v68
	v_add_f32_e32 v66, 1.0, v66
	v_rcp_f32_e32 v66, v66
	v_mfma_f32_16x16x32_bf16 v[4:7], v[24:27], v[16:19], v[4:7]
	v_add_f32_e32 v68, 1.0, v68
	v_rcp_f32_e32 v70, v68
	v_mul_f32_e32 v66, 0xc1000000, v66
	v_mul_f32_e32 v66, v87, v66
	v_mul_f32_e32 v68, 0x3fb8aa3b, v66
	v_add_f32_e32 v66, v66, v66
	v_mul_f32_e32 v66, 0x3fb8aa3b, v66
	v_exp_f32_e32 v66, v66
	v_exp_f32_e32 v71, v68
	v_sub_f32_e32 v66, 1.0, v66
	v_max_f32_e32 v66, 0, v66
	v_cmp_gt_f32_e64 s[4:5], s16, v66
	v_mul_f32_e32 v68, 0x4f800000, v66
	s_nop 0
	v_cndmask_b32_e64 v66, v66, v68, s[4:5]
	v_sqrt_f32_e32 v68, v66
	s_nop 0
	v_add_u32_e32 v69, -1, v68
	v_fma_f32 v76, -v69, v68, v66
	v_cmp_ge_f32_e64 s[6:7], 0, v76
	v_add_u32_e32 v76, 1, v68
	s_nop 0
	v_cndmask_b32_e64 v69, v68, v69, s[6:7]
	v_fma_f32 v68, -v76, v68, v66
	v_cmp_lt_f32_e64 s[6:7], 0, v68
	s_nop 1
	v_cndmask_b32_e64 v68, v69, v76, s[6:7]
	v_mul_f32_e32 v69, 0x37800000, v68
	v_cndmask_b32_e64 v68, v68, v69, s[4:5]
	v_cmp_class_f32_e64 s[4:5], v66, v205
	s_nop 1
	v_cndmask_b32_e64 v66, v68, v66, s[4:5]
	ds_read2_b32 v[68:69], v75 offset0:130 offset1:146
	v_mul_f32_e32 v66, v70, v66
	ds_write_b32 v74, v71 offset:6792
	s_waitcnt lgkmcnt(1)
	v_mul_f32_e32 v66, v68, v66
	ds_write_b32 v74, v66 offset:2568
	v_add_f32_e32 v66, v84, v81
	v_mul_f32_e32 v66, 0xbfb8aa3b, v66
	v_exp_f32_e32 v66, v66
	v_add_f32_e32 v68, v72, v86
	v_mul_f32_e32 v68, 0xbfb8aa3b, v68
	v_exp_f32_e32 v68, v68
	v_add_f32_e32 v66, 1.0, v66
	v_rcp_f32_e32 v66, v66
	v_add_f32_e32 v68, 1.0, v68
	v_rcp_f32_e32 v68, v68
	v_mul_f32_e32 v66, 0xc1000000, v66
	v_mul_f32_e32 v66, v87, v66
	v_mul_f32_e32 v70, 0x3fb8aa3b, v66
	v_add_f32_e32 v66, v66, v66
	v_mul_f32_e32 v66, 0x3fb8aa3b, v66
	v_exp_f32_e32 v66, v66
	v_exp_f32_e32 v72, v70
	v_sub_f32_e32 v66, 1.0, v66
	v_max_f32_e32 v66, 0, v66
	v_cmp_gt_f32_e64 s[4:5], s16, v66
	v_mul_f32_e32 v70, 0x4f800000, v66
	s_nop 0
	v_cndmask_b32_e64 v66, v66, v70, s[4:5]
	v_sqrt_f32_e32 v70, v66
	s_nop 0
	v_add_u32_e32 v71, -1, v70
	v_fma_f32 v76, -v71, v70, v66
	v_cmp_ge_f32_e64 s[6:7], 0, v76
	v_add_u32_e32 v76, 1, v70
	s_nop 0
	v_cndmask_b32_e64 v71, v70, v71, s[6:7]
	v_fma_f32 v70, -v76, v70, v66
	v_cmp_lt_f32_e64 s[6:7], 0, v70
	s_nop 1
	v_cndmask_b32_e64 v70, v71, v76, s[6:7]
	v_mul_f32_e32 v71, 0x37800000, v70
	v_cndmask_b32_e64 v70, v70, v71, s[4:5]
	v_cmp_class_f32_e64 s[4:5], v66, v205
	s_nop 1
	v_cndmask_b32_e64 v66, v70, v66, s[4:5]
	ds_read2_b32 v[70:71], v75 offset0:196 offset1:212
	v_mul_f32_e32 v66, v68, v66
	v_add_f32_e32 v68, v73, v86
	v_mul_f32_e32 v68, 0xbfb8aa3b, v68
	v_exp_f32_e32 v68, v68
	s_waitcnt lgkmcnt(0)
	v_mul_f32_e32 v66, v70, v66
	ds_write_b32 v74, v66 offset:2832
	v_add_f32_e32 v66, v85, v81
	v_mul_f32_e32 v66, 0xbfb8aa3b, v66
	v_exp_f32_e32 v66, v66
	v_add_f32_e32 v68, 1.0, v68
	v_rcp_f32_e32 v70, v68
	ds_write_b32 v74, v72 offset:7056
	v_add_f32_e32 v66, 1.0, v66
	v_rcp_f32_e32 v66, v66
	s_nop 0
	v_mul_f32_e32 v66, 0xc1000000, v66
	v_mul_f32_e32 v66, v87, v66
	v_mul_f32_e32 v68, 0x3fb8aa3b, v66
	v_add_f32_e32 v66, v66, v66
	v_mul_f32_e32 v66, 0x3fb8aa3b, v66
	v_exp_f32_e32 v66, v66
	v_exp_f32_e32 v68, v68
	v_sub_f32_e32 v66, 1.0, v66
	v_max_f32_e32 v66, 0, v66
	v_cmp_gt_f32_e64 s[4:5], s16, v66
	v_mul_f32_e32 v72, 0x4f800000, v66
	s_nop 0
	v_cndmask_b32_e64 v66, v66, v72, s[4:5]
	v_sqrt_f32_e32 v72, v66
	s_nop 0
	v_add_u32_e32 v73, -1, v72
	v_fma_f32 v76, -v73, v72, v66
	v_cmp_ge_f32_e64 s[6:7], 0, v76
	v_add_u32_e32 v76, 1, v72
	s_nop 0
	v_cndmask_b32_e64 v73, v72, v73, s[6:7]
	v_fma_f32 v72, -v76, v72, v66
	v_cmp_lt_f32_e64 s[6:7], 0, v72
	s_nop 1
	v_cndmask_b32_e64 v72, v73, v76, s[6:7]
	v_mul_f32_e32 v73, 0x37800000, v72
	v_cndmask_b32_e64 v72, v72, v73, s[4:5]
	v_cmp_class_f32_e64 s[4:5], v66, v205
	s_nop 1
	v_cndmask_b32_e64 v76, v72, v66, s[4:5]
	v_add_u32_e32 v66, 0xc00, v74
	ds_read2_b32 v[72:73], v66 offset0:6 offset1:22
	v_mov_b32_e32 v52, v159
	v_mov_b32_e32 v53, v160
	v_mov_b32_e32 v54, v161
	v_mul_f32_e32 v70, v70, v76
	s_waitcnt lgkmcnt(0)
	v_mul_f32_e32 v70, v72, v70
	s_waitcnt vmcnt(2)
	v_add_f32_e32 v48, v48, v52
	v_mul_f32_e32 v48, 0xbfb8aa3b, v48
	v_exp_f32_e32 v48, v48
	s_waitcnt vmcnt(1)
	v_add_f32_e32 v44, v44, v53
	v_mul_f32_e32 v44, 0xbfb8aa3b, v44
	v_exp_f32_e32 v44, v44
	v_add_f32_e32 v48, 1.0, v48
	v_rcp_f32_e32 v48, v48
	v_add_f32_e32 v45, v45, v53
	v_add_f32_e32 v44, 1.0, v44
	v_rcp_f32_e32 v44, v44
	v_mul_f32_e32 v48, 0xc1000000, v48
	s_waitcnt vmcnt(0)
; __device__ __forceinline__ float fexp(float x) { return __builtin_amdgcn_exp2f(x * LOG2E); }
; __device__ __forceinline__ float sigm(float x) { return frcp(1.f + fexp(-x)); }
; __device__ __forceinline__ void lru_item(const Params& p, int l, int item, LAS unsigned char* lds) {
;     ...
;           const int cj = l * 256 + h * 64 + jt * 16 + fr; const float bav = p.ba[cj], bxv = p.bx[cj], sp = p.spl[cj];
; #pragma unroll
;           for (int jj = 0; jj < 4; ++jj) { const int t = fq * 4 + jj; const float r = sigm(pa[jj] + bav), ig = sigm(px[jj] + bxv); const float la = -8.f * r * sp;
;               const float a = fexp(la); float mult = sqrtf(fmaxf(1.f - fexp(2.f * la), 0.f)); if (t0 + t == 0) mult = 1.f;
;               const int li = t * 66 + jt * 16 + fr; const float xcv = xf[li]; sa[li] = a; xf[li] = mult * ig * xcv; }
	v_mul_f32_e32 v48, v54, v48
	v_mul_f32_e32 v55, 0x3fb8aa3b, v48
	v_add_f32_e32 v48, v48, v48
	v_mul_f32_e32 v48, 0x3fb8aa3b, v48
	v_exp_f32_e32 v48, v48
	v_exp_f32_e32 v55, v55
	v_mul_f32_e32 v45, 0xbfb8aa3b, v45
	v_exp_f32_e32 v45, v45
	v_sub_f32_e32 v48, 1.0, v48
	v_max_f32_e32 v48, 0, v48
	v_cmp_gt_f32_e64 s[4:5], s16, v48
	v_mul_f32_e32 v56, 0x4f800000, v48
	ds_write_b32 v74, v55 offset:6592
	v_cndmask_b32_e64 v48, v48, v56, s[4:5]
	v_sqrt_f32_e32 v56, v48
	v_add_f32_e32 v45, 1.0, v45
	v_rcp_f32_e32 v45, v45
	v_add_u32_e32 v57, -1, v56
	v_fma_f32 v58, -v57, v56, v48
	v_cmp_ge_f32_e64 s[6:7], 0, v58
	v_add_u32_e32 v58, 1, v56
	s_nop 0
	v_cndmask_b32_e64 v57, v56, v57, s[6:7]
	v_fma_f32 v56, -v58, v56, v48
	v_cmp_lt_f32_e64 s[6:7], 0, v56
	s_nop 1
	v_cndmask_b32_e64 v56, v57, v58, s[6:7]
	v_mul_f32_e32 v57, 0x37800000, v56
	v_cndmask_b32_e64 v56, v56, v57, s[4:5]
	v_cmp_class_f32_e64 s[4:5], v48, v205
	s_nop 1
	v_cndmask_b32_e64 v48, v56, v48, s[4:5]
	v_cndmask_b32_e64 v48, v48, 1.0, vcc
	v_mul_f32_e32 v44, v44, v48
	v_mul_f32_e32 v48, v67, v44
	v_add_f32_e32 v44, v49, v52
	v_mul_f32_e32 v44, 0xbfb8aa3b, v44
	v_exp_f32_e32 v44, v44
	s_nop 0
	v_add_f32_e32 v44, 1.0, v44
	v_rcp_f32_e32 v44, v44
	s_nop 0
	v_mul_f32_e32 v44, 0xc1000000, v44
	v_mul_f32_e32 v44, v54, v44
	v_mul_f32_e32 v49, 0x3fb8aa3b, v44
	v_add_f32_e32 v44, v44, v44
	v_mul_f32_e32 v44, 0x3fb8aa3b, v44
	v_exp_f32_e32 v44, v44
	v_exp_f32_e32 v49, v49
	v_sub_f32_e32 v44, 1.0, v44
	v_max_f32_e32 v44, 0, v44
	v_cmp_gt_f32_e64 s[4:5], s16, v44
	v_mul_f32_e32 v55, 0x4f800000, v44
	ds_write_b32 v74, v49 offset:6856
	v_cndmask_b32_e64 v44, v44, v55, s[4:5]
	v_sqrt_f32_e32 v55, v44
	s_nop 0
	v_add_u32_e32 v56, -1, v55
	v_fma_f32 v57, -v56, v55, v44
	v_cmp_ge_f32_e64 s[6:7], 0, v57
	v_add_u32_e32 v57, 1, v55
	s_nop 0
	v_cndmask_b32_e64 v56, v55, v56, s[6:7]
	v_fma_f32 v55, -v57, v55, v44
	v_cmp_lt_f32_e64 s[6:7], 0, v55
	s_nop 1
	v_cndmask_b32_e64 v55, v56, v57, s[6:7]
	v_mul_f32_e32 v56, 0x37800000, v55
	v_cndmask_b32_e64 v55, v55, v56, s[4:5]
	v_cmp_class_f32_e64 s[4:5], v44, v205
	s_nop 1
	v_cndmask_b32_e64 v44, v55, v44, s[4:5]
	v_mul_f32_e32 v44, v45, v44
	v_mul_f32_e32 v44, v69, v44
	ds_write_b32 v74, v44 offset:2632
	v_add_f32_e32 v44, v50, v52
	v_mul_f32_e32 v44, 0xbfb8aa3b, v44
	v_exp_f32_e32 v44, v44
	v_add_f32_e32 v45, v46, v53
	v_mul_f32_e32 v45, 0xbfb8aa3b, v45
	v_exp_f32_e32 v45, v45
	v_add_f32_e32 v44, 1.0, v44
	v_rcp_f32_e32 v44, v44
	v_add_f32_e32 v45, 1.0, v45
	v_rcp_f32_e32 v45, v45
	v_mul_f32_e32 v44, 0xc1000000, v44
	v_mul_f32_e32 v44, v54, v44
	v_mul_f32_e32 v46, 0x3fb8aa3b, v44
	v_add_f32_e32 v44, v44, v44
	v_mul_f32_e32 v44, 0x3fb8aa3b, v44
	v_exp_f32_e32 v44, v44
	v_exp_f32_e32 v46, v46
	v_sub_f32_e32 v44, 1.0, v44
	v_max_f32_e32 v44, 0, v44
	v_cmp_gt_f32_e64 s[4:5], s16, v44
	v_mul_f32_e32 v49, 0x4f800000, v44
	ds_write_b32 v74, v46 offset:7120
	v_cndmask_b32_e64 v44, v44, v49, s[4:5]
	v_sqrt_f32_e32 v49, v44
	s_nop 0
	v_add_u32_e32 v50, -1, v49
	v_fma_f32 v55, -v50, v49, v44
	v_cmp_ge_f32_e64 s[6:7], 0, v55
	v_add_u32_e32 v55, 1, v49
	s_nop 0
	v_cndmask_b32_e64 v50, v49, v50, s[6:7]
	v_fma_f32 v49, -v55, v49, v44
	v_cmp_lt_f32_e64 s[6:7], 0, v49
	s_nop 1
	v_cndmask_b32_e64 v49, v50, v55, s[6:7]
	v_mul_f32_e32 v50, 0x37800000, v49
	v_cndmask_b32_e64 v49, v49, v50, s[4:5]
	v_cmp_class_f32_e64 s[4:5], v44, v205
	s_nop 1
	v_cndmask_b32_e64 v44, v49, v44, s[4:5]
	v_mul_f32_e32 v44, v45, v44
	v_mul_f32_e32 v44, v71, v44
	ds_write_b32 v74, v44 offset:2896
	v_add_f32_e32 v44, v51, v52
	v_mul_f32_e32 v44, 0xbfb8aa3b, v44
	v_exp_f32_e32 v44, v44
	v_add_f32_e32 v45, v47, v53
	v_mul_f32_e32 v45, 0xbfb8aa3b, v45
	v_exp_f32_e32 v45, v45
	v_add_f32_e32 v44, 1.0, v44
	v_rcp_f32_e32 v44, v44
	v_add_f32_e32 v45, 1.0, v45
	v_rcp_f32_e32 v45, v45
	v_mul_f32_e32 v44, 0xc1000000, v44
	v_mul_f32_e32 v44, v54, v44
	v_mul_f32_e32 v46, 0x3fb8aa3b, v44
	v_add_f32_e32 v44, v44, v44
	v_mul_f32_e32 v44, 0x3fb8aa3b, v44
	v_exp_f32_e32 v44, v44
	v_exp_f32_e32 v46, v46
	v_sub_f32_e32 v44, 1.0, v44
	v_max_f32_e32 v44, 0, v44
	v_cmp_gt_f32_e64 s[4:5], s16, v44
	v_mul_f32_e32 v47, 0x4f800000, v44
	s_nop 0
	v_cndmask_b32_e64 v44, v44, v47, s[4:5]
	v_sqrt_f32_e32 v47, v44
	s_nop 0
	v_add_u32_e32 v49, -1, v47
	v_fma_f32 v50, -v49, v47, v44
	v_cmp_ge_f32_e64 s[6:7], 0, v50
	v_add_u32_e32 v50, 1, v47
	s_nop 0
	v_cndmask_b32_e64 v49, v47, v49, s[6:7]
	v_fma_f32 v47, -v50, v47, v44
	v_cmp_lt_f32_e64 s[6:7], 0, v47
	s_nop 1
	v_cndmask_b32_e64 v47, v49, v50, s[6:7]
	v_mul_f32_e32 v49, 0x37800000, v47
	v_cndmask_b32_e64 v47, v47, v49, s[4:5]
	v_cmp_class_f32_e64 s[4:5], v44, v205
	s_nop 1
	v_cndmask_b32_e64 v47, v47, v44, s[4:5]
	v_mul_f32_e32 v45, v45, v47
	v_add_u32_e32 v44, 0x1c00, v74
	v_mul_f32_e32 v45, v73, v45
	ds_write2_b32 v44, v68, v46 offset0:38 offset1:54
	ds_write2_b32 v66, v70, v45 offset0:6 offset1:22
	v_mov_b32_e32 v40, v162
	v_mov_b32_e32 v41, v163
	v_mov_b32_e32 v42, v164
	s_waitcnt vmcnt(2)
	v_add_f32_e32 v32, v32, v40
	v_mul_f32_e32 v32, 0xbfb8aa3b, v32
	v_exp_f32_e32 v32, v32
	s_waitcnt vmcnt(1)
	v_add_f32_e32 v28, v28, v41
	v_mul_f32_e32 v28, 0xbfb8aa3b, v28
	v_exp_f32_e32 v28, v28
	v_add_f32_e32 v32, 1.0, v32
	v_rcp_f32_e32 v32, v32
	v_add_f32_e32 v29, v29, v41
	v_add_f32_e32 v28, 1.0, v28
	v_rcp_f32_e32 v28, v28
	v_mul_f32_e32 v32, 0xc1000000, v32
	s_waitcnt vmcnt(0)
; __device__ __forceinline__ float fexp(float x) { return __builtin_amdgcn_exp2f(x * LOG2E); }
; __device__ __forceinline__ float sigm(float x) { return frcp(1.f + fexp(-x)); }
; __device__ __forceinline__ void lru_item(const Params& p, int l, int item, LAS unsigned char* lds) {
;     ...
;           const int cj = l * 256 + h * 64 + jt * 16 + fr; const float bav = p.ba[cj], bxv = p.bx[cj], sp = p.spl[cj];
; #pragma unroll
;           for (int jj = 0; jj < 4; ++jj) { const int t = fq * 4 + jj; const float r = sigm(pa[jj] + bav), ig = sigm(px[jj] + bxv); const float la = -8.f * r * sp;
;               const float a = fexp(la); float mult = sqrtf(fmaxf(1.f - fexp(2.f * la), 0.f)); if (t0 + t == 0) mult = 1.f;
;               const int li = t * 66 + jt * 16 + fr; const float xcv = xf[li]; sa[li] = a; xf[li] = mult * ig * xcv; }
	v_mul_f32_e32 v32, v42, v32
	v_mul_f32_e32 v36, 0x3fb8aa3b, v32
	v_add_f32_e32 v32, v32, v32
	v_mul_f32_e32 v32, 0x3fb8aa3b, v32
	v_exp_f32_e32 v32, v32
	v_exp_f32_e32 v36, v36
	v_mul_f32_e32 v29, 0xbfb8aa3b, v29
	v_exp_f32_e32 v29, v29
	v_sub_f32_e32 v32, 1.0, v32
	v_max_f32_e32 v32, 0, v32
	v_cmp_gt_f32_e64 s[4:5], s16, v32
	v_mul_f32_e32 v37, 0x4f800000, v32
	ds_write_b32 v74, v36 offset:6656
	v_cndmask_b32_e64 v32, v32, v37, s[4:5]
	v_sqrt_f32_e32 v37, v32
	v_add_f32_e32 v29, 1.0, v29
	v_rcp_f32_e32 v29, v29
	v_add_u32_e32 v38, -1, v37
	v_fma_f32 v39, -v38, v37, v32
	v_cmp_ge_f32_e64 s[6:7], 0, v39
	v_add_u32_e32 v39, 1, v37
	s_nop 0
	v_cndmask_b32_e64 v38, v37, v38, s[6:7]
	v_fma_f32 v37, -v39, v37, v32
	v_cmp_lt_f32_e64 s[6:7], 0, v37
	s_nop 1
	v_cndmask_b32_e64 v37, v38, v39, s[6:7]
	v_mul_f32_e32 v38, 0x37800000, v37
	v_cndmask_b32_e64 v37, v37, v38, s[4:5]
	ds_read2_b32 v[38:39], v75 offset0:96 offset1:112
	v_cmp_class_f32_e64 s[4:5], v32, v205
	s_nop 1
	v_cndmask_b32_e64 v32, v37, v32, s[4:5]
	v_cndmask_b32_e64 v32, v32, 1.0, vcc
	v_mul_f32_e32 v28, v28, v32
	s_waitcnt lgkmcnt(0)
	v_mul_f32_e32 v28, v38, v28
	ds_write2_b32 v75, v48, v28 offset0:80 offset1:96
	v_add_f32_e32 v28, v33, v40
	v_mul_f32_e32 v28, 0xbfb8aa3b, v28
	v_exp_f32_e32 v28, v28
	s_nop 0
	v_add_f32_e32 v28, 1.0, v28
	v_rcp_f32_e32 v28, v28
	s_nop 0
	v_mul_f32_e32 v28, 0xc1000000, v28
	v_mul_f32_e32 v28, v42, v28
	v_mul_f32_e32 v32, 0x3fb8aa3b, v28
	v_add_f32_e32 v28, v28, v28
	v_mul_f32_e32 v28, 0x3fb8aa3b, v28
	v_exp_f32_e32 v28, v28
	v_exp_f32_e32 v32, v32
	v_sub_f32_e32 v28, 1.0, v28
	v_max_f32_e32 v28, 0, v28
	v_cmp_gt_f32_e64 s[4:5], s16, v28
	v_mul_f32_e32 v33, 0x4f800000, v28
	s_nop 0
	v_cndmask_b32_e64 v28, v28, v33, s[4:5]
	v_sqrt_f32_e32 v33, v28
	s_nop 0
	v_add_u32_e32 v36, -1, v33
	v_fma_f32 v37, -v36, v33, v28
	v_cmp_ge_f32_e64 s[6:7], 0, v37
	v_add_u32_e32 v37, 1, v33
	s_nop 0
	v_cndmask_b32_e64 v36, v33, v36, s[6:7]
	v_fma_f32 v33, -v37, v33, v28
	v_cmp_lt_f32_e64 s[6:7], 0, v33
	s_nop 1
	v_cndmask_b32_e64 v33, v36, v37, s[6:7]
	v_mul_f32_e32 v36, 0x37800000, v33
	v_cndmask_b32_e64 v33, v33, v36, s[4:5]
	ds_read2_b32 v[36:37], v75 offset0:162 offset1:178
	v_cmp_class_f32_e64 s[4:5], v28, v205
	ds_write_b32 v74, v32 offset:6920
	s_nop 0
	v_cndmask_b32_e64 v28, v33, v28, s[4:5]
	v_mul_f32_e32 v28, v29, v28
	s_waitcnt lgkmcnt(1)
	v_mul_f32_e32 v28, v36, v28
	ds_write_b32 v74, v28 offset:2696
	v_add_f32_e32 v28, v34, v40
	v_mul_f32_e32 v28, 0xbfb8aa3b, v28
	v_exp_f32_e32 v28, v28
	v_add_f32_e32 v29, v30, v41
	v_mul_f32_e32 v29, 0xbfb8aa3b, v29
	v_exp_f32_e32 v29, v29
	v_add_f32_e32 v28, 1.0, v28
	v_rcp_f32_e32 v28, v28
	v_add_f32_e32 v29, 1.0, v29
	v_rcp_f32_e32 v29, v29
	v_mul_f32_e32 v28, 0xc1000000, v28
	v_mul_f32_e32 v28, v42, v28
	v_mul_f32_e32 v30, 0x3fb8aa3b, v28
	v_add_f32_e32 v28, v28, v28
	v_mul_f32_e32 v28, 0x3fb8aa3b, v28
	v_exp_f32_e32 v28, v28
	v_exp_f32_e32 v30, v30
	v_sub_f32_e32 v28, 1.0, v28
	v_max_f32_e32 v28, 0, v28
	v_cmp_gt_f32_e64 s[4:5], s16, v28
	v_mul_f32_e32 v32, 0x4f800000, v28
	s_nop 0
	v_cndmask_b32_e64 v28, v28, v32, s[4:5]
	v_sqrt_f32_e32 v32, v28
	s_nop 0
	v_add_u32_e32 v33, -1, v32
	v_fma_f32 v34, -v33, v32, v28
	v_cmp_ge_f32_e64 s[6:7], 0, v34
	v_add_u32_e32 v34, 1, v32
	s_nop 0
	v_cndmask_b32_e64 v33, v32, v33, s[6:7]
	v_fma_f32 v32, -v34, v32, v28
	v_cmp_lt_f32_e64 s[6:7], 0, v32
	s_nop 1
	v_cndmask_b32_e64 v32, v33, v34, s[6:7]
	v_mul_f32_e32 v33, 0x37800000, v32
	v_cndmask_b32_e64 v32, v32, v33, s[4:5]
	v_cmp_class_f32_e64 s[4:5], v28, v205
	s_nop 1
	v_cndmask_b32_e64 v28, v32, v28, s[4:5]
	ds_read2_b32 v[32:33], v75 offset0:228 offset1:244
	v_mul_f32_e32 v28, v29, v28
	v_add_f32_e32 v29, v31, v41
	v_mul_f32_e32 v29, 0xbfb8aa3b, v29
	v_exp_f32_e32 v29, v29
	s_waitcnt lgkmcnt(0)
	v_mul_f32_e32 v28, v32, v28
	ds_write_b32 v74, v28 offset:2960
	v_add_f32_e32 v28, v35, v40
	v_mul_f32_e32 v28, 0xbfb8aa3b, v28
	v_exp_f32_e32 v28, v28
	v_add_f32_e32 v29, 1.0, v29
	v_rcp_f32_e32 v31, v29
	ds_write_b32 v74, v30 offset:7184
	v_add_f32_e32 v28, 1.0, v28
	v_rcp_f32_e32 v28, v28
	s_nop 0
	v_mul_f32_e32 v28, 0xc1000000, v28
	v_mul_f32_e32 v28, v42, v28
	v_mul_f32_e32 v29, 0x3fb8aa3b, v28
	v_add_f32_e32 v28, v28, v28
	v_mul_f32_e32 v28, 0x3fb8aa3b, v28
	v_exp_f32_e32 v28, v28
	v_exp_f32_e32 v30, v29
	v_sub_f32_e32 v28, 1.0, v28
	v_max_f32_e32 v28, 0, v28
	v_cmp_gt_f32_e64 s[4:5], s16, v28
	v_mul_f32_e32 v29, 0x4f800000, v28
	s_nop 0
	v_cndmask_b32_e64 v28, v28, v29, s[4:5]
	v_sqrt_f32_e32 v29, v28
	s_nop 0
	v_add_u32_e32 v32, -1, v29
	v_fma_f32 v34, -v32, v29, v28
	v_cmp_ge_f32_e64 s[6:7], 0, v34
	v_add_u32_e32 v34, 1, v29
	s_nop 0
	v_cndmask_b32_e64 v32, v29, v32, s[6:7]
	v_fma_f32 v29, -v34, v29, v28
	v_cmp_lt_f32_e64 s[6:7], 0, v29
	s_nop 1
	v_cndmask_b32_e64 v29, v32, v34, s[6:7]
	v_mul_f32_e32 v32, 0x37800000, v29
	v_cndmask_b32_e64 v29, v29, v32, s[4:5]
	v_cmp_class_f32_e64 s[4:5], v28, v205
	s_nop 1
	v_cndmask_b32_e64 v32, v29, v28, s[4:5]
	ds_read2_b32 v[28:29], v66 offset0:38 offset1:54
	v_mov_b32_e32 v12, v165
	v_mov_b32_e32 v13, v166
	v_mov_b32_e32 v14, v167
	v_mul_f32_e32 v31, v31, v32
	s_waitcnt lgkmcnt(0)
	v_mul_f32_e32 v28, v28, v31
	s_waitcnt vmcnt(2)
	v_add_f32_e32 v8, v8, v12
	v_mul_f32_e32 v8, 0xbfb8aa3b, v8
	v_exp_f32_e32 v8, v8
	s_waitcnt vmcnt(1)
	v_add_f32_e32 v4, v4, v13
	v_mul_f32_e32 v4, 0xbfb8aa3b, v4
	v_exp_f32_e32 v4, v4
	v_add_f32_e32 v8, 1.0, v8
	v_rcp_f32_e32 v8, v8
	v_add_f32_e32 v5, v5, v13
	v_add_f32_e32 v4, 1.0, v4
	v_rcp_f32_e32 v4, v4
	v_mul_f32_e32 v8, 0xc1000000, v8
	s_waitcnt vmcnt(0)
; __device__ __forceinline__ float fexp(float x) { return __builtin_amdgcn_exp2f(x * LOG2E); }
; __device__ __forceinline__ float sigm(float x) { return frcp(1.f + fexp(-x)); }
; __device__ __forceinline__ void lds_barrier() { asm volatile("s_waitcnt lgkmcnt(0)" ::: "memory"); __builtin_amdgcn_s_barrier(); asm volatile("" ::: "memory"); }
; __device__ __forceinline__ void lru_item(const Params& p, int l, int item, LAS unsigned char* lds) {
;     ...
;           const int cj = l * 256 + h * 64 + jt * 16 + fr; const float bav = p.ba[cj], bxv = p.bx[cj], sp = p.spl[cj];
; #pragma unroll
;           for (int jj = 0; jj < 4; ++jj) { const int t = fq * 4 + jj; const float r = sigm(pa[jj] + bav), ig = sigm(px[jj] + bxv); const float la = -8.f * r * sp;
;               const float a = fexp(la); float mult = sqrtf(fmaxf(1.f - fexp(2.f * la), 0.f)); if (t0 + t == 0) mult = 1.f;
;               const int li = t * 66 + jt * 16 + fr; const float xcv = xf[li]; sa[li] = a; xf[li] = mult * ig * xcv; }
;       } }
;     lds_barrier();
	v_mul_f32_e32 v8, v14, v8
	v_mul_f32_e32 v15, 0x3fb8aa3b, v8
	v_add_f32_e32 v8, v8, v8
	v_mul_f32_e32 v8, 0x3fb8aa3b, v8
	v_exp_f32_e32 v8, v8
	v_exp_f32_e32 v15, v15
	v_mul_f32_e32 v5, 0xbfb8aa3b, v5
	v_exp_f32_e32 v5, v5
	v_sub_f32_e32 v8, 1.0, v8
	v_max_f32_e32 v8, 0, v8
	v_cmp_gt_f32_e64 s[4:5], s16, v8
	v_mul_f32_e32 v16, 0x4f800000, v8
	ds_write_b32 v74, v15 offset:6720
	v_cndmask_b32_e64 v8, v8, v16, s[4:5]
	v_sqrt_f32_e32 v16, v8
	v_add_f32_e32 v5, 1.0, v5
	v_rcp_f32_e32 v5, v5
	v_add_u32_e32 v17, -1, v16
	v_fma_f32 v18, -v17, v16, v8
	v_cmp_ge_f32_e64 s[6:7], 0, v18
	v_add_u32_e32 v18, 1, v16
	s_nop 0
	v_cndmask_b32_e64 v17, v16, v17, s[6:7]
	v_fma_f32 v16, -v18, v16, v8
	v_cmp_lt_f32_e64 s[6:7], 0, v16
	s_nop 1
	v_cndmask_b32_e64 v16, v17, v18, s[6:7]
	v_mul_f32_e32 v17, 0x37800000, v16
	v_cndmask_b32_e64 v16, v16, v17, s[4:5]
	v_cmp_class_f32_e64 s[4:5], v8, v205
	s_nop 1
	v_cndmask_b32_e64 v8, v16, v8, s[4:5]
	v_cndmask_b32_e64 v8, v8, 1.0, vcc
	v_mul_f32_e32 v4, v4, v8
	v_mul_f32_e32 v4, v39, v4
	ds_write_b32 v74, v4 offset:2496
	v_add_f32_e32 v4, v9, v12
	v_mul_f32_e32 v4, 0xbfb8aa3b, v4
	v_exp_f32_e32 v4, v4
	s_nop 0
	v_add_f32_e32 v4, 1.0, v4
	v_rcp_f32_e32 v4, v4
	s_nop 0
	v_mul_f32_e32 v4, 0xc1000000, v4
	v_mul_f32_e32 v4, v14, v4
	v_mul_f32_e32 v8, 0x3fb8aa3b, v4
	v_add_f32_e32 v4, v4, v4
	v_mul_f32_e32 v4, 0x3fb8aa3b, v4
	v_exp_f32_e32 v4, v4
	v_exp_f32_e32 v8, v8
	v_sub_f32_e32 v4, 1.0, v4
	v_max_f32_e32 v4, 0, v4
	v_cmp_gt_f32_e32 vcc, s16, v4
	v_mul_f32_e32 v9, 0x4f800000, v4
	ds_write_b32 v74, v8 offset:6984
	v_cndmask_b32_e32 v4, v4, v9, vcc
	v_sqrt_f32_e32 v9, v4
	s_nop 0
	v_add_u32_e32 v15, -1, v9
	v_fma_f32 v16, -v15, v9, v4
	v_cmp_ge_f32_e64 s[4:5], 0, v16
	v_add_u32_e32 v16, 1, v9
	s_nop 0
	v_cndmask_b32_e64 v15, v9, v15, s[4:5]
	v_fma_f32 v9, -v16, v9, v4
	v_cmp_lt_f32_e64 s[4:5], 0, v9
	s_nop 1
	v_cndmask_b32_e64 v9, v15, v16, s[4:5]
	v_mul_f32_e32 v15, 0x37800000, v9
	v_cndmask_b32_e32 v9, v9, v15, vcc
	v_cmp_class_f32_e32 vcc, v4, v205
	s_nop 1
	v_cndmask_b32_e32 v4, v9, v4, vcc
	v_mul_f32_e32 v4, v5, v4
	v_mul_f32_e32 v4, v37, v4
	ds_write_b32 v74, v4 offset:2760
	v_add_f32_e32 v4, v10, v12
	v_mul_f32_e32 v4, 0xbfb8aa3b, v4
	v_exp_f32_e32 v4, v4
	v_add_f32_e32 v5, v6, v13
	v_mul_f32_e32 v5, 0xbfb8aa3b, v5
	v_exp_f32_e32 v5, v5
	v_add_f32_e32 v4, 1.0, v4
	v_rcp_f32_e32 v4, v4
	v_add_f32_e32 v5, 1.0, v5
	v_rcp_f32_e32 v5, v5
	v_mul_f32_e32 v4, 0xc1000000, v4
	v_mul_f32_e32 v4, v14, v4
	v_mul_f32_e32 v6, 0x3fb8aa3b, v4
	v_add_f32_e32 v4, v4, v4
	v_mul_f32_e32 v4, 0x3fb8aa3b, v4
	v_exp_f32_e32 v4, v4
	v_exp_f32_e32 v6, v6
	v_sub_f32_e32 v4, 1.0, v4
	v_max_f32_e32 v4, 0, v4
	v_cmp_gt_f32_e32 vcc, s16, v4
	v_mul_f32_e32 v8, 0x4f800000, v4
	ds_write_b32 v74, v6 offset:7248
	v_cndmask_b32_e32 v4, v4, v8, vcc
	v_sqrt_f32_e32 v8, v4
	s_nop 0
	v_add_u32_e32 v9, -1, v8
	v_fma_f32 v10, -v9, v8, v4
	v_cmp_ge_f32_e64 s[4:5], 0, v10
	v_add_u32_e32 v10, 1, v8
	s_nop 0
	v_cndmask_b32_e64 v9, v8, v9, s[4:5]
	v_fma_f32 v8, -v10, v8, v4
	v_cmp_lt_f32_e64 s[4:5], 0, v8
	s_nop 1
	v_cndmask_b32_e64 v8, v9, v10, s[4:5]
	v_mul_f32_e32 v9, 0x37800000, v8
	v_cndmask_b32_e32 v8, v8, v9, vcc
	v_cmp_class_f32_e32 vcc, v4, v205
	s_nop 1
	v_cndmask_b32_e32 v4, v8, v4, vcc
	v_mul_f32_e32 v4, v5, v4
	v_mul_f32_e32 v4, v33, v4
	ds_write_b32 v74, v4 offset:3024
	v_add_f32_e32 v4, v11, v12
	v_mul_f32_e32 v4, 0xbfb8aa3b, v4
	v_exp_f32_e32 v4, v4
	v_add_f32_e32 v5, v7, v13
	v_mul_f32_e32 v5, 0xbfb8aa3b, v5
	v_exp_f32_e32 v5, v5
	v_add_f32_e32 v4, 1.0, v4
	v_rcp_f32_e32 v4, v4
	v_add_f32_e32 v5, 1.0, v5
	v_rcp_f32_e32 v5, v5
	v_mul_f32_e32 v4, 0xc1000000, v4
	v_mul_f32_e32 v4, v14, v4
	v_mul_f32_e32 v6, 0x3fb8aa3b, v4
	v_add_f32_e32 v4, v4, v4
	v_mul_f32_e32 v4, 0x3fb8aa3b, v4
	v_exp_f32_e32 v4, v4
	v_exp_f32_e32 v6, v6
	v_lshl_add_u32 v14, v3, 2, v79
	v_sub_f32_e32 v4, 1.0, v4
	v_max_f32_e32 v4, 0, v4
	v_cmp_gt_f32_e32 vcc, s16, v4
	v_mul_f32_e32 v7, 0x4f800000, v4
	ds_write2_b32 v44, v30, v6 offset0:70 offset1:86
	v_cndmask_b32_e32 v4, v4, v7, vcc
	v_sqrt_f32_e32 v7, v4
	s_nop 0
	v_add_u32_e32 v8, -1, v7
	v_fma_f32 v9, -v8, v7, v4
	v_cmp_ge_f32_e64 s[4:5], 0, v9
	v_add_u32_e32 v9, 1, v7
	s_nop 0
	v_cndmask_b32_e64 v8, v7, v8, s[4:5]
	v_fma_f32 v7, -v9, v7, v4
	v_cmp_lt_f32_e64 s[4:5], 0, v7
	s_nop 1
	v_cndmask_b32_e64 v7, v8, v9, s[4:5]
	v_mul_f32_e32 v8, 0x37800000, v7
	v_cndmask_b32_e32 v7, v7, v8, vcc
	v_cmp_class_f32_e32 vcc, v4, v205
	s_nop 1
	v_cndmask_b32_e32 v4, v7, v4, vcc
	v_mul_f32_e32 v4, v5, v4
	v_mul_f32_e32 v4, v29, v4
	ds_write2_b32 v66, v28, v4 offset0:38 offset1:54
	s_waitcnt lgkmcnt(0)
	s_barrier
; __device__ __forceinline__ void lds_barrier() { asm volatile("s_waitcnt lgkmcnt(0)" ::: "memory"); __builtin_amdgcn_s_barrier(); asm volatile("" ::: "memory"); }
; __device__ __forceinline__ void lru_item(const Params& p, int l, int item, LAS unsigned char* lds) {
;     ...
;     float Ac[16], Hl[16];
;     { float A = 1.f, H = 0.f;
; #pragma unroll
;       for (int i = 0; i < 16; ++i) { const float a = sa[i * 66 + lane], bt = xf[i * 66 + lane]; H = a * H + bt; A *= a; Ac[i] = A; Hl[i] = H; }
;       ct[(wid * 64 + lane) * 2] = A; ct[(wid * 64 + lane) * 2 + 1] = H; }
;     lds_barrier();
;     { float Ain = 1.f, Hin = 0.f;
;       for (int w = 0; w < wid; ++w) { const float aw = ct[(w * 64 + lane) * 2], hw = ct[(w * 64 + lane) * 2 + 1]; Hin = aw * Hin + hw; Ain *= aw; }
	v_add_u32_e32 v4, 0x1800, v14
	ds_read2_b32 v[22:23], v4 offset0:30 offset1:96
	ds_read_b32 v18, v80 offset:2304
	ds_read2_b32 v[6:7], v4 offset0:162 offset1:228
	v_add_u32_e32 v4, 0x800, v14
	ds_read2_b32 v[20:21], v4 offset0:130 offset1:196
	v_add_u32_e32 v4, 0x1c00, v14
	v_add_u32_e32 v5, 0xc00, v14
	ds_read2_b32 v[8:9], v4 offset0:38 offset1:104
	ds_read2_b32 v[12:13], v5 offset0:6 offset1:72
	s_waitcnt lgkmcnt(4)
	v_fmac_f32_e32 v18, 0, v23
	ds_read2_b32 v[46:47], v4 offset0:170 offset1:236
	ds_read2_b32 v[10:11], v5 offset0:138 offset1:204
	s_waitcnt lgkmcnt(4)
	v_fma_f32 v19, v18, v6, v20
	v_fmac_f32_e32 v21, v19, v7
	s_waitcnt lgkmcnt(2)
	v_fma_f32 v25, v21, v8, v12
	v_fmac_f32_e32 v13, v25, v9
	v_mul_f32_e32 v28, v23, v6
	s_waitcnt lgkmcnt(0)
	v_fma_f32 v17, v13, v46, v10
	v_add_u32_e32 v6, 0x2000, v14
	v_add_u32_e32 v10, 0x1000, v14
	ds_read2_b32 v[40:41], v6 offset0:46 offset1:112
	ds_read2_b32 v[4:5], v10 offset0:14 offset1:80
	ds_read2_b32 v[38:39], v6 offset0:178 offset1:244
	ds_read2_b32 v[42:43], v10 offset0:146 offset1:212
	v_fmac_f32_e32 v11, v17, v47
	v_mov_b32_e32 v6, v7
	v_mov_b32_e32 v26, v8
	s_waitcnt lgkmcnt(2)
	v_fma_f32 v15, v11, v40, v4
	v_fmac_f32_e32 v5, v15, v41
	v_mov_b32_e32 v29, v5
	s_waitcnt lgkmcnt(1)
	v_mov_b32_e32 v7, v38
	v_add_u32_e32 v4, 0x2400, v14
	v_mul_f32_e32 v32, v28, v6
	v_mul_f32_e32 v33, v29, v7
	s_waitcnt lgkmcnt(0)
	v_mov_b32_e32 v27, v42
	ds_read2_b32 v[48:49], v4 offset0:54 offset1:120
	v_mul_f32_e32 v36, v32, v26
	v_mul_f32_e32 v37, v33, v27
	v_fma_f32 v6, v28, v6, v26
	v_fma_f32 v7, v29, v7, v27
	v_mov_b32_e32 v8, v9
	v_mov_b32_e32 v37, v7
	v_mov_b32_e32 v9, v39
	v_mul_f32_e32 v26, v36, v8
	v_mul_f32_e32 v27, v37, v9
	v_mov_b32_e32 v42, v46
	v_add_u32_e32 v6, 0x1400, v14
	v_mul_f32_e32 v30, v26, v42
	v_mul_f32_e32 v31, v27, v43
	v_fma_f32 v8, v36, v8, v42
	v_fma_f32 v9, v37, v9, v43
	ds_read2_b32 v[50:51], v6 offset0:22 offset1:88
	ds_read2_b32 v[42:43], v4 offset0:186 offset1:252
	ds_read2_b32 v[44:45], v6 offset0:154 offset1:220
	ds_read_b32 v67, v14 offset:10488
	v_mov_b32_e32 v31, v9
	v_mov_b32_e32 v46, v47
	s_waitcnt lgkmcnt(4)
	v_mov_b32_e32 v47, v48
	v_mul_f32_e32 v60, v30, v46
	v_mul_f32_e32 v61, v31, v47
	v_mov_b32_e32 v52, v40
	s_waitcnt lgkmcnt(3)
	v_mov_b32_e32 v53, v50
	v_mul_f32_e32 v64, v60, v52
	v_mul_f32_e32 v65, v61, v53
	v_fma_f32 v52, v30, v46, v52
	v_fma_f32 v53, v31, v47, v53
	v_mov_b32_e32 v40, v41
	v_mov_b32_e32 v65, v53
	v_mov_b32_e32 v41, v49
	v_mul_f32_e32 v54, v64, v40
	v_mul_f32_e32 v55, v65, v41
	v_mov_b32_e32 v50, v38
	v_mul_f32_e32 v58, v54, v50
	v_mul_f32_e32 v59, v55, v51
	v_fma_f32 v40, v64, v40, v50
	v_fma_f32 v41, v65, v41, v51
	v_mov_b32_e32 v38, v39
	v_mov_b32_e32 v59, v41
	s_waitcnt lgkmcnt(2)
	v_mov_b32_e32 v39, v42
	v_mul_f32_e32 v56, v58, v38
	v_mul_f32_e32 v57, v59, v39
	v_mov_b32_e32 v46, v48
	s_waitcnt lgkmcnt(1)
	v_mov_b32_e32 v47, v44
	v_mul_f32_e32 v62, v56, v46
	v_mul_f32_e32 v63, v57, v47
	v_fma_f32 v46, v58, v38, v46
	v_fma_f32 v47, v59, v39, v47
	v_mov_b32_e32 v38, v49
	v_mov_b32_e32 v63, v47
	v_mov_b32_e32 v39, v43
	v_mul_f32_e32 v48, v62, v38
	v_mul_f32_e32 v49, v63, v39
	v_mov_b32_e32 v44, v42
	v_mul_f32_e32 v50, v48, v44
	v_mul_f32_e32 v51, v49, v45
	v_fma_f32 v38, v62, v38, v44
	v_fma_f32 v39, v63, v39, v45
	v_mov_b32_e32 v66, v43
	v_mov_b32_e32 v51, v39
	s_waitcnt lgkmcnt(0)
	v_mul_f32_e32 v44, v50, v66
	v_mul_f32_e32 v45, v51, v67
	v_mov_b32_e32 v68, v67
	v_mov_b32_e32 v69, v22
	v_mul_f32_e32 v42, v44, v68
	v_mul_f32_e32 v43, v45, v69
	v_fma_f32 v66, v50, v66, v68
	v_fma_f32 v67, v51, v67, v69
	v_mul_f32_e32 v34, 0, v23
	v_mov_b32_e32 v43, v67
	ds_write_b64 v1, v[42:43]
	s_waitcnt lgkmcnt(0)
	s_barrier
	v_cmp_lt_i32_e32 vcc, 0, v0
	v_mov_b32_e32 v8, 1.0
	s_and_saveexec_b64 s[4:5], vcc
	s_cbranch_execz .LBB0_397
	v_readlane_b32 s6, v255, 9
	v_mov_b32_e32 v8, 1.0
	v_mov_b32_e32 v77, 0
	v_lshl_add_u32 v1, v3, 3, s6
	s_mov_b64 s[6:7], 0
	v_mov_b32_e32 v4, v0

; __device__ __forceinline__ void lru_item(const Params& p, int l, int item, LAS unsigned char* lds) {
;     ...
;       float* sc = (float*)p.hbuf + ((((size_t)b * 4 + h) * 16 + seg) * 8 + wid) * 2048 + lane * 16;
; #pragma unroll
;       for (int q = 0; q < 4; ++q) { f32x4 hv, av;
; #pragma unroll
;           for (int e = 0; e < 4; ++e) { const int i = q * 4 + e; hv[e] = Hl[i] + Ac[i] * Hin; av[e] = Ac[i] * Ain; }
;           *(f32x4*)(sc + q * 4) = hv; *(f32x4*)(sc + 1024 + q * 4) = av; }
;       if (wid == 7) { float* cw = p.lru_carry + (((size_t)b * 4 + h) * 16 + seg) * 128;
;           cw[lane * 2] = Ac[15] * Ain; cw[lane * 2 + 1] = Hl[15] + Ac[15] * Hin; } }
.LBB0_397:
	s_or_b64 exec, exec, s[4:5]
	s_lshl_b64 s[4:5], s[28:29], 6
	s_lshl_b32 s6, s38, 4
	s_or_b32 s4, s4, s6
	s_or_b32 s4, s4, s79
	s_lshl_b64 s[6:7], s[4:5], 16
	v_ashrrev_i32_e32 v1, 31, v0
	s_add_u32 s6, s15, s6
	s_addc_u32 s7, s94, s7
	v_lshlrev_b64 v[66:67], 13, v[0:1]
	v_lshl_add_u64 v[66:67], s[6:7], 0, v[66:67]
	v_lshlrev_b32_e32 v68, 6, v3
	v_mov_b32_e32 v69, v2
	v_mov_b32_e32 v22, v23
	v_mov_b32_e32 v23, v28
	v_lshl_add_u64 v[70:71], v[66:67], 0, v[68:69]
	v_mul_f32_e32 v66, v22, v8
	v_mul_f32_e32 v67, v23, v8
	v_mov_b32_e32 v33, v36
	v_mov_b32_e32 v22, v77
	v_mov_b32_e32 v24, v21
	v_mul_f32_e32 v35, v28, v77
	v_pk_fma_f32 v[20:21], v[32:33], v[22:23], v[24:25] op_sel_hi:[1,0,1]
	v_add_co_u32_e32 v24, vcc, s80, v70
	v_mov_b32_e32 v27, v30
	v_mov_b32_e32 v16, v13
	v_mov_b32_e32 v61, v64
	v_mov_b32_e32 v14, v11
	v_mul_f32_e32 v68, v32, v8
	v_mul_f32_e32 v69, v33, v8
	v_pk_add_f32 v[18:19], v[18:19], v[34:35]
	v_addc_co_u32_e32 v25, vcc, 0, v71, vcc
	v_pk_fma_f32 v[12:13], v[26:27], v[22:23], v[16:17] op_sel_hi:[1,0,1]
	v_pk_fma_f32 v[14:15], v[60:61], v[22:23], v[14:15] op_sel_hi:[1,0,1]
	v_mov_b32_e32 v55, v58
	v_mov_b32_e32 v6, v5
	v_mov_b32_e32 v57, v62
	v_mov_b32_e32 v52, v9
	global_store_dwordx4 v[70:71], v[18:21], off
	global_store_dwordx4 v[24:25], v[66:69], off
	v_pk_fma_f32 v[4:5], v[54:55], v[22:23], v[6:7] op_sel_hi:[1,0,1]
	v_mul_f32_e32 v18, v26, v8
	v_mul_f32_e32 v19, v27, v8
	v_mul_f32_e32 v20, v60, v8
	v_mul_f32_e32 v21, v61, v8
	global_store_dwordx4 v[70:71], v[12:15], off offset:16
	global_store_dwordx4 v[24:25], v[18:21], off offset:16
	v_pk_fma_f32 v[6:7], v[56:57], v[22:23], v[52:53] op_sel_hi:[1,0,1]
	v_mul_f32_e32 v12, v56, v8
	v_mul_f32_e32 v13, v57, v8
	v_mov_b32_e32 v49, v50
	v_mul_f32_e32 v10, v54, v8
	v_mul_f32_e32 v11, v55, v8
	global_store_dwordx4 v[70:71], v[4:7], off offset:32
	global_store_dwordx4 v[24:25], v[10:13], off offset:32
	v_mov_b32_e32 v46, v41
	v_fmac_f32_e32 v39, v44, v77
	v_mul_f32_e32 v12, v48, v8
	v_mul_f32_e32 v13, v49, v8
	v_mul_f32_e32 v9, v42, v77
	v_mul_f32_e32 v10, v42, v8
	v_mul_f32_e32 v11, v43, v9
	v_pk_add_f32 v[6:7], v[42:43], v[8:9]
	v_pk_fma_f32 v[4:5], v[48:49], v[22:23], v[46:47] op_sel_hi:[1,0,1]
	v_mul_f32_e32 v14, v44, v8
	v_mov_b32_e32 v6, v39
	v_mov_b32_e32 v15, v10
	v_cmp_eq_u32_e32 vcc, 7, v0
	global_store_dwordx4 v[70:71], v[4:7], off offset:48
	global_store_dwordx4 v[24:25], v[12:15], off offset:48
	s_and_saveexec_b64 s[6:7], vcc
	s_cbranch_execz .LBB0_399
	s_lshl_b64 s[4:5], s[4:5], 9
	s_add_u32 s4, s41, s4
	v_mov_b32_e32 v11, v7
	s_addc_u32 s5, s14, s5
	v_lshlrev_b32_e32 v0, 2, v78
	global_store_dwordx2 v0, v[10:11], s[4:5]

; #define LAS __attribute__((address_space(3)))
; __device__ __forceinline__ unsigned pk2s(float lo, float hi) { unsigned r; asm("s_nop 0\n\tv_cvt_pk_bf16_f32 %0, %1, %2" : "=v"(r) : "v"(lo), "v"(hi)); return r; }
; __device__ __forceinline__ float fexp2(float x) { return __builtin_amdgcn_exp2f(x); }
; __device__ __forceinline__ f32x4 mfma16(bf16x8 a, bf16x8 b, f32x4 c) { return __builtin_amdgcn_mfma_f32_16x16x32_bf16(a, b, c, 0, 0, 0); }
; __device__ __forceinline__ void attn_item(const Params& p, int l, int item, LAS unsigned char* lds) {
;     ...
;             for (int j = 0; j < 4; ++j) { const int dist = base - (kt * 16 + fq * 4 + j); const int idx = (dist < 256 ? dist : 256) + 63;
;                 const float sv = s[kt][j] * (0.125f * LOG2E) + bias_s[hh * 320 + idx]; s[kt][j] = sv; cmax = fmaxf(cmax, sv); }
;         cmax = fmaxf(cmax, __shfl_xor(cmax, 16)); cmax = fmaxf(cmax, __shfl_xor(cmax, 32));
;         const float mnew = fmaxf(mrun, cmax), alpha = fexp2(mrun - mnew); mrun = mnew;
;         float ps = 0.f;
; #pragma unroll
;         for (int kt = 0; kt < 4; ++kt)
; #pragma unroll
;             for (int j = 0; j < 4; ++j) { const float e = fexp2(s[kt][j] - mnew); s[kt][j] = e; ps += e; }
;         lsum = lsum * alpha + ps;
; #pragma unroll
;         for (int dt = 0; dt < 4; ++dt) o[dt] *= alpha;
; #pragma unroll
;         for (int i = 0; i < 2; ++i) {
;             u32x4 pw; pw.x = pk2s(s[2 * i][0], s[2 * i][1]); pw.y = pk2s(s[2 * i][2], s[2 * i][3]); pw.z = pk2s(s[2 * i + 1][0], s[2 * i + 1][1]); pw.w = pk2s(s[2 * i + 1][2], s[2 * i + 1][3]);
;             const bf16x8 pb = as_bf8(pw);
;             const LAS unsigned char* vp = Vb + (32 * i + 4 * fq + (fr >> 2)) * VST + hh * 128 + (fr & 3) * 8;
; #pragma unroll
;             for (int dt = 0; dt < 4; ++dt) {
;                 const v4i16_t a0 = __builtin_amdgcn_ds_read_tr16_b64_v4i16((LAS v4i16_t*)(vp + dt * 32));
;                 const v4i16_t a1 = __builtin_amdgcn_ds_read_tr16_b64_v4i16((LAS v4i16_t*)(vp + 16 * VST + dt * 32));
;                 const bf16x8 av = __builtin_shufflevector(a0, a1, 0, 1, 2, 3, 4, 5, 6, 7);
;                 o[dt] = mfma16(av, pb, o[dt]); }
.Lattn_near_c:
	v_fmac_f32_e32 v88, 0x3e38aa3b, v72
	v_fmac_f32_e32 v89, 0x3e38aa3b, v73
	v_fmac_f32_e32 v90, 0x3e38aa3b, v74
	v_fmac_f32_e32 v91, 0x3e38aa3b, v75
	v_fmac_f32_e32 v92, 0x3e38aa3b, v76
	v_fmac_f32_e32 v93, 0x3e38aa3b, v77
	v_fmac_f32_e32 v94, 0x3e38aa3b, v78
	v_fmac_f32_e32 v95, 0x3e38aa3b, v79
	v_fmac_f32_e32 v96, 0x3e38aa3b, v48
	v_fmac_f32_e32 v97, 0x3e38aa3b, v49
	v_fmac_f32_e32 v98, 0x3e38aa3b, v50
	v_fmac_f32_e32 v99, 0x3e38aa3b, v51
	s_nop 7
	v_fmac_f32_e32 v100, 0x3e38aa3b, v80
	v_fmac_f32_e32 v101, 0x3e38aa3b, v81
	v_fmac_f32_e32 v102, 0x3e38aa3b, v82
	v_fmac_f32_e32 v103, 0x3e38aa3b, v83
	v_max3_f32 v196, v88, s15, v89
	v_max3_f32 v196, v196, v90, v91
	v_max3_f32 v196, v196, v92, v93
	v_max3_f32 v196, v196, v94, v95
	v_max3_f32 v196, v196, v96, v97
	v_max3_f32 v196, v196, v98, v99
	v_max3_f32 v196, v196, v100, v101
	v_max3_f32 v196, v196, v102, v103
	ds_bpermute_b32 v197, v45, v196
	s_waitcnt lgkmcnt(0)
	v_max_f32_e32 v197, v197, v197
	v_max_f32_e32 v197, v196, v197
	ds_bpermute_b32 v47, v46, v197
	s_waitcnt lgkmcnt(0)
	v_max3_f32 v47, v70, v197, v47
	ds_read_b64_tr_b16 v[164:165], v69 offset:26624
	ds_read_b64_tr_b16 v[166:167], v69 offset:31232
	ds_read_b64_tr_b16 v[168:169], v69 offset:26656
	ds_read_b64_tr_b16 v[170:171], v69 offset:31264
	ds_read_b64_tr_b16 v[172:173], v69 offset:26688
	ds_read_b64_tr_b16 v[174:175], v69 offset:31296
	ds_read_b64_tr_b16 v[176:177], v69 offset:26720
	ds_read_b64_tr_b16 v[178:179], v69 offset:31328
	v_sub_f32_e32 v70, v70, v47
	v_sub_f32_e32 v88, v88, v47
	v_sub_f32_e32 v89, v89, v47
	v_sub_f32_e32 v90, v90, v47
	v_sub_f32_e32 v91, v91, v47
	v_sub_f32_e32 v92, v92, v47
	v_sub_f32_e32 v93, v93, v47
	v_sub_f32_e32 v94, v94, v47
	v_sub_f32_e32 v95, v95, v47
	v_sub_f32_e32 v96, v96, v47
	v_sub_f32_e32 v97, v97, v47
	v_sub_f32_e32 v98, v98, v47
	v_sub_f32_e32 v99, v99, v47
	v_sub_f32_e32 v100, v100, v47
	v_sub_f32_e32 v101, v101, v47
	v_sub_f32_e32 v102, v102, v47
	v_sub_f32_e32 v103, v103, v47
	v_exp_f32_e32 v44, v70
	v_exp_f32_e32 v88, v88
	v_exp_f32_e32 v89, v89
	v_exp_f32_e32 v90, v90
	v_exp_f32_e32 v91, v91
	v_exp_f32_e32 v92, v92
	v_exp_f32_e32 v93, v93
	v_exp_f32_e32 v94, v94
	v_exp_f32_e32 v95, v95
	v_exp_f32_e32 v96, v96
	v_exp_f32_e32 v97, v97
	v_exp_f32_e32 v98, v98
	v_exp_f32_e32 v99, v99
	v_exp_f32_e32 v100, v100
	v_exp_f32_e32 v101, v101
	v_exp_f32_e32 v102, v102
	v_exp_f32_e32 v103, v103
	v_mul_f32_e32 v28, v28, v44
	v_mul_f32_e32 v29, v29, v44
	v_mul_f32_e32 v30, v30, v44
	v_mul_f32_e32 v31, v31, v44
	v_mul_f32_e32 v32, v32, v44
	v_mul_f32_e32 v33, v33, v44
	v_mul_f32_e32 v34, v34, v44
	v_mul_f32_e32 v35, v35, v44
	v_mul_f32_e32 v36, v36, v44
	v_mul_f32_e32 v37, v37, v44
	v_mul_f32_e32 v38, v38, v44
	v_mul_f32_e32 v39, v39, v44
	v_mul_f32_e32 v40, v40, v44
	v_mul_f32_e32 v41, v41, v44
	v_mul_f32_e32 v42, v42, v44
	v_mul_f32_e32 v43, v43, v44
	v_add_f32_e32 v48, 0, v88
	v_add_f32_e32 v48, v89, v48
	v_add_f32_e32 v48, v90, v48
	v_add_f32_e32 v48, v91, v48
	v_add_f32_e32 v48, v92, v48
	v_add_f32_e32 v48, v93, v48
	v_add_f32_e32 v48, v94, v48
	v_add_f32_e32 v48, v95, v48
	v_add_f32_e32 v48, v96, v48
	v_add_f32_e32 v48, v97, v48
	v_add_f32_e32 v48, v98, v48
	v_add_f32_e32 v48, v99, v48
	v_add_f32_e32 v48, v100, v48
	v_add_f32_e32 v48, v101, v48
	v_add_f32_e32 v48, v102, v48
	v_add_f32_e32 v48, v103, v48
	v_fmac_f32_e32 v48, v68, v44
	v_cvt_pk_bf16_f32 v198, v88, v89
	v_cvt_pk_bf16_f32 v199, v90, v91
	v_cvt_pk_bf16_f32 v200, v92, v93
	v_cvt_pk_bf16_f32 v201, v94, v95
	v_cvt_pk_bf16_f32 v214, v96, v97
	v_cvt_pk_bf16_f32 v215, v98, v99
	v_cvt_pk_bf16_f32 v216, v100, v101
	v_cvt_pk_bf16_f32 v217, v102, v103
	s_add_i32 s15, s7, 1
	s_waitcnt lgkmcnt(8)
	v_mfma_f32_16x16x32_bf16 v[28:31], v[148:151], v[198:201], v[28:31]
	v_mfma_f32_16x16x32_bf16 v[32:35], v[152:155], v[198:201], v[32:35]
	v_mfma_f32_16x16x32_bf16 v[36:39], v[156:159], v[198:201], v[36:39]
	v_mfma_f32_16x16x32_bf16 v[40:43], v[160:163], v[198:201], v[40:43]
	s_waitcnt lgkmcnt(0)
	v_mfma_f32_16x16x32_bf16 v[28:31], v[164:167], v[214:217], v[28:31]
	v_mfma_f32_16x16x32_bf16 v[32:35], v[168:171], v[214:217], v[32:35]
	v_mfma_f32_16x16x32_bf16 v[36:39], v[172:175], v[214:217], v[36:39]
	v_mfma_f32_16x16x32_bf16 v[40:43], v[176:179], v[214:217], v[40:43]
	s_cmp_lt_u32 s7, 8
	s_cbranch_scc0 .LBB0_425
	v_mov_b32_e32 v70, v47
	v_mov_b32_e32 v68, v48
	s_mov_b32 s7, s15
	s_branch .LBB0_410

; __device__ __forceinline__ void hgrn_item(const Params& p, int l, int item, int pass, LAS unsigned char* lds) {
;     ...
;     for (int n = 0; n < 8; ++n) {
;         const size_t T0 = (size_t)b * SEQ + seg * 128 + n * 16;
;         float qv[4], fz[4]; unsigned vv[4];
; #pragma unroll
;         for (int j = 0; j < 4; ++j) { qv[j] = bf2f(qn[j]); fz[j] = bf2f(fn[j]); vv[j] = vn[j]; }
;         if (n < 7) HG_LOAD(n + 1);
;         u32x4 vw; vw.x = vv[0] | (vv[1] << 16); vw.y = vv[2] | (vv[3] << 16); vw.z = 0u; vw.w = 0u; const bf16x8 vfrag = as_bf8(vw);
;         float cs[4], kf[4]; float run = 0.f;
; #pragma unroll
;         for (int j = 0; j < 4; ++j) { const float sg = sigm(fz[j]); const float f = lbv + (1.f - lbv) * sg; run += __logf(fmaxf(f, 1e-30f)); cs[j] = run; kf[j] = (1.f - lbv) * sigm(-fz[j]); }
;         { const float t1 = __shfl(run, lane - 16), t2 = __shfl(run, lane - 32), t3 = __shfl(run, lane - 48);
;           const float pre = (fq >= 1 ? t1 : 0.f) + (fq >= 2 ? t2 : 0.f) + (fq >= 3 ? t3 : 0.f);
; #pragma unroll
;           for (int j = 0; j < 4; ++j) cs[j] += pre; }
;         const float blast = __shfl(cs[3], 48 + fr);
;         lds_barrier();
;         { u32x2 w; w.x = pk2(kf[0] * fexp(blast - cs[0]), kf[1] * fexp(blast - cs[1])); w.y = pk2(kf[2] * fexp(blast - cs[2]), kf[3] * fexp(blast - cs[3]));
;           *(LAS u32x2*)(KHt + (wv * 16 + fr) * 16 + fq * 4) = w;
;           if (fq == 0) decs[wv * 16 + fr] = fexp(blast);
;           if (pass == 1) {
; #pragma unroll
;               for (int j = 0; j < 4; ++j) { const int s = fq * 4 + j; Qs[s * 72 + wv * 16 + fr] = f2bf(silu(qv[j]) * fexp(cs[j])); Ks[s * 72 + wv * 16 + fr] = f2bf(kf[j] * fexp(fminf(-cs[j], 80.f))); } } }
;         segb += blast;
;         lds_barrier();
;         f32x4 o = ZERO4;
;         if (pass == 1) {
;             const bf16x8 ka0 = *(const LAS bf16x8*)(Ks + fr * 72 + fq * 8), ka1 = *(const LAS bf16x8*)(Ks + fr * 72 + 32 + fq * 8);
;             const bf16x8 qb0 = *(const LAS bf16x8*)(Qs + fr * 72 + fq * 8), qb1 = *(const LAS bf16x8*)(Qs + fr * 72 + 32 + fq * 8);
;             f32x4 sc = mfma16(ka0, qb0, ZERO4); sc = mfma16(ka1, qb1, sc);
; #pragma unroll
;             for (int j = 0; j < 4; ++j) sc[j] = (fq * 4 + j <= fr) ? sc[j] : 0.f;
;             u32x4 pw; pw.x = pk2(sc[0], sc[1]); pw.y = pk2(sc[2], sc[3]); pw.z = 0u; pw.w = 0u;
.LBB0_419:
	s_or_b64 exec, exec, s[8:9]
	s_waitcnt lgkmcnt(0)
	s_barrier
	v_add_f32_e32 v30, v30, v54
	ds_read2st64_b64 v[54:57], v32 offset0:9 offset1:10
	s_waitcnt vmcnt(8)
	v_lshl_or_b32 v1, v41, 16, v1
	v_add_u32_e32 v41, v43, v42
	ds_read_b128 v[62:65], v41 offset:6656
	v_mov_b32_e32 v60, v2
	s_waitcnt lgkmcnt(1)
	v_mov_b32_e32 v58, v54
	v_mov_b32_e32 v59, v55
	v_mov_b32_e32 v61, v2
	v_lshl_or_b32 v0, v3, 16, v0
	v_mov_b32_e32 v3, v2
	s_waitcnt lgkmcnt(0)
	v_mul_f32_e32 v16, v16, v62
	v_mul_f32_e32 v17, v17, v63
	v_mul_f32_e32 v18, v18, v64
	v_mul_f32_e32 v19, v19, v65
	v_mov_b32_e32 v54, v56
	v_mov_b32_e32 v55, v57
	v_mfma_f32_16x16x32_bf16 v[16:19], v[58:61], v[0:3], v[16:19]
	ds_read_b128 v[58:61], v41 offset:6720
	v_mov_b32_e32 v56, v2
	v_mov_b32_e32 v57, v2
	s_add_u32 s28, s28, 0x16000
	s_addc_u32 s29, s29, 0
	s_waitcnt lgkmcnt(0)
	v_mul_f32_e32 v12, v12, v58
	v_mul_f32_e32 v13, v13, v59
	v_mul_f32_e32 v14, v14, v60
	v_mul_f32_e32 v15, v15, v61
	s_waitcnt vmcnt(7)
	v_and_b32_e32 v52, 0xffff, v44
	s_waitcnt vmcnt(6)
	v_and_b32_e32 v44, 0xffff, v45
	v_mfma_f32_16x16x32_bf16 v[12:15], v[54:57], v[0:3], v[12:15]
	ds_read_b64 v[54:55], v32 offset:5632
	ds_read_b128 v[58:61], v41 offset:6784
	s_waitcnt vmcnt(5)
	v_and_b32_e32 v53, 0xffff, v46
	s_waitcnt vmcnt(4)
	v_and_b32_e32 v45, 0xffff, v47
	s_waitcnt vmcnt(3)
	v_and_b32_e32 v48, 0xffff, v48
	s_waitcnt vmcnt(2)
	v_and_b32_e32 v46, 0xffff, v49
	s_waitcnt lgkmcnt(0)
	v_mul_f32_e32 v8, v8, v58
	v_mul_f32_e32 v9, v9, v59
	v_mul_f32_e32 v10, v10, v60
	v_mul_f32_e32 v11, v11, v61
	s_waitcnt vmcnt(1)
	v_and_b32_e32 v49, 0xffff, v50
	s_waitcnt vmcnt(0)
	v_and_b32_e32 v47, 0xffff, v51
	v_mfma_f32_16x16x32_bf16 v[8:11], v[54:57], v[0:3], v[8:11]
	ds_read_b64 v[54:55], v31 offset:4608
	ds_read_b128 v[58:61], v41 offset:6848
	s_cmp_eq_u32 s28, 0x9a000
	s_waitcnt lgkmcnt(0)
	v_mul_f32_e32 v4, v4, v58
	v_mul_f32_e32 v5, v5, v59
	v_mul_f32_e32 v6, v6, v60
	v_mul_f32_e32 v7, v7, v61
	s_nop 1
	v_mfma_f32_16x16x32_bf16 v[4:7], v[54:57], v[0:3], v[4:7]
	s_cbranch_scc1 .LBB0_421
	v_mov_b32_e32 v41, v47
	v_mov_b32_e32 v1, v46
	v_mov_b32_e32 v3, v45
	v_mov_b32_e32 v0, v44
	s_branch .LBB0_417

; #define LAS __attribute__((address_space(3)))
; __device__ __forceinline__ unsigned pk2(float lo, float hi) { unsigned r; asm("v_cvt_pk_bf16_f32 %0, %1, %2" : "=v"(r) : "v"(lo), "v"(hi)); return r; }
; __device__ __forceinline__ float bflo(unsigned w) { return __uint_as_float(w << 16); }
; __device__ __forceinline__ float bfhi(unsigned w) { return __uint_as_float(w & 0xffff0000u); }
; __device__ __forceinline__ float silu(float x) { return x * sigm(x); }
; __device__ __forceinline__ f32x4 mfma16(bf16x8 a, bf16x8 b, f32x4 c) { return __builtin_amdgcn_mfma_f32_16x16x32_bf16(a, b, c, 0, 0, 0); }
; __device__ __forceinline__ void lds_barrier() { asm volatile("s_waitcnt lgkmcnt(0)" ::: "memory"); __builtin_amdgcn_s_barrier(); asm volatile("" ::: "memory"); }
; __device__ __forceinline__ void hgrn_item(const Params& p, int l, int item, int pass, LAS unsigned char* lds) {
;     ...
; #pragma unroll
;         for (int kt = 0; kt < 4; ++kt) { const u32x2 kh = *(const LAS u32x2*)(KHt + (kt * 16 + fr) * 16 + fq * 4); u32x4 kw; kw.x = kh.x; kw.y = kh.y; kw.z = 0u; kw.w = 0u;
;             const f32x4 dv = *(const LAS f32x4*)(decs + kt * 16 + fq * 4); S[kt] = mfma16(as_bf8(kw), vfrag, S[kt] * dv); }
;         if (pass == 1) {
;             float ss = o[0] * o[0] + o[1] * o[1] + o[2] * o[2] + o[3] * o[3]; ss += __shfl_xor(ss, 16); ss += __shfl_xor(ss, 32);
;             if (fq == 0) ssq[wv * 16 + fr] = ss;
;             lds_barrier();
;             const float tot = ssq[fr] + ssq[16 + fr] + ssq[32 + fr] + ssq[48 + fr]; const float rstd = rsqrtf(tot * (1.f / 64.f) + EPS);
;             const size_t T = T0 + fr; const u32x2 gw = *(const u32x2*)(p.z + T * ZLD + 1536 + head * 64 + wv * 16 + fq * 4);
;             u32x2 w; w.x = pk2(o[0] * rstd * ng[0] * silu(bflo(gw.x)), o[1] * rstd * ng[1] * silu(bfhi(gw.x)));
;             w.y = pk2(o[2] * rstd * ng[2] * silu(bflo(gw.y)), o[3] * rstd * ng[3] * silu(bfhi(gw.y)));
;             *(u32x2*)(p.outs + ((size_t)1 * M + T) * 256 + head * 64 + wv * 16 + fq * 4) = w;
;         }
;     }
;     if (pass == 0) {
;         float* Sp = p.hgS + (iseg + seg) * 4096 + wv * 16 + fr;
; #pragma unroll
;         for (int kt = 0; kt < 4; ++kt)
; #pragma unroll
;             for (int j = 0; j < 4; ++j) Sp[(kt * 16 + fq * 4 + j) * 64] = S[kt][j];
;         if (fq == 0) p.hgD[(iseg + seg) * 64 + wv * 16 + fr] = segb;
;     }
.LBB0_423:
	s_or_b64 exec, exec, s[6:7]
	s_waitcnt lgkmcnt(0)
	s_barrier
	ds_read2st64_b64 v[34:37], v32 offset0:9 offset1:10
	v_lshl_or_b32 v1, v47, 16, v46
	ds_read_b128 v[46:49], v41 offset:6656
	ds_read_b64 v[32:33], v32 offset:5632
	v_lshl_or_b32 v0, v45, 16, v44
	s_waitcnt lgkmcnt(2)
	v_mov_b32_e32 v42, v34
	v_mov_b32_e32 v43, v35
	v_mov_b32_e32 v44, v2
	v_mov_b32_e32 v45, v2
	v_mov_b32_e32 v3, v2
	s_waitcnt lgkmcnt(1)
	v_mul_f32_e32 v18, v18, v48
	v_mul_f32_e32 v19, v19, v49
	v_mul_f32_e32 v16, v16, v46
	v_mul_f32_e32 v17, v17, v47
	v_mov_b32_e32 v34, v36
	v_mov_b32_e32 v35, v37
	v_mfma_f32_16x16x32_bf16 v[16:19], v[42:45], v[0:3], v[16:19]
	ds_read_b128 v[42:45], v41 offset:6720
	v_mov_b32_e32 v36, v2
	v_mov_b32_e32 v37, v2
	v_ashrrev_i32_e32 v21, 31, v20
	s_lshl_b64 s[6:7], s[26:27], 6
	s_waitcnt lgkmcnt(0)
	v_mul_f32_e32 v14, v14, v44
	v_mul_f32_e32 v15, v15, v45
	v_mul_f32_e32 v12, v12, v42
	v_mul_f32_e32 v13, v13, v43
	v_lshl_add_u64 v[20:21], v[20:21], 4, s[6:7]
	v_or_b32_e32 v20, s0, v20
	v_mfma_f32_16x16x32_bf16 v[12:15], v[34:37], v[0:3], v[12:15]
	ds_read_b128 v[36:39], v41 offset:6784
	v_mov_b32_e32 v34, v2
	v_mov_b32_e32 v35, v2
	s_waitcnt lgkmcnt(0)
	v_mul_f32_e32 v10, v10, v38
	v_mul_f32_e32 v11, v11, v39
	v_mul_f32_e32 v8, v8, v36
	v_mul_f32_e32 v9, v9, v37
	s_nop 1
	v_mfma_f32_16x16x32_bf16 v[8:11], v[32:35], v[0:3], v[8:11]
	ds_read_b64 v[32:33], v31 offset:4608
	ds_read_b128 v[36:39], v41 offset:6848
	s_waitcnt lgkmcnt(0)
	v_mul_f32_e32 v6, v6, v38
	v_mul_f32_e32 v7, v7, v39
	v_mul_f32_e32 v4, v4, v36
	v_mul_f32_e32 v5, v5, v37
	s_nop 1
	v_mfma_f32_16x16x32_bf16 v[32:35], v[32:35], v[0:3], v[4:7]
	v_lshlrev_b64 v[0:1], 14, v[20:21]
	s_nop 1
	v_lshl_add_u64 v[4:5], s[20:21], 0, v[0:1]
	v_lshlrev_b32_e32 v0, 2, v25
	v_mov_b32_e32 v1, v2
	v_lshl_add_u64 v[6:7], v[4:5], 0, v[0:1]
	v_lshlrev_b32_e32 v4, 2, v24
	v_mov_b32_e32 v5, v2
	v_lshl_add_u64 v[6:7], v[6:7], 0, v[4:5]
	v_lshlrev_b32_e32 v24, 10, v26
	v_mov_b32_e32 v25, v2
	v_lshlrev_b32_e32 v26, 8, v27
	v_mov_b32_e32 v27, v2
	v_lshl_add_u64 v[24:25], v[6:7], 0, v[24:25]
	v_lshl_add_u64 v[26:27], v[6:7], 0, v[26:27]
	global_store_dword v[24:25], v16, off
	global_store_dword v[26:27], v17, off
	v_lshlrev_b32_e32 v16, 8, v28
	v_mov_b32_e32 v17, v2
	v_lshl_add_u64 v[16:17], v[6:7], 0, v[16:17]
	global_store_dword v[16:17], v18, off
	v_lshlrev_b32_e32 v16, 8, v29
	v_mov_b32_e32 v17, v2
	v_lshl_add_u64 v[6:7], v[6:7], 0, v[16:17]
	global_store_dword v[6:7], v19, off
	v_add_co_u32_e32 v6, vcc, s80, v24
	s_nop 1
	v_addc_co_u32_e32 v7, vcc, 0, v25, vcc
	v_add_co_u32_e32 v16, vcc, s81, v24
	s_nop 1
	v_addc_co_u32_e32 v17, vcc, 0, v25, vcc
	global_store_dword v[16:17], v12, off offset:-4096
	global_store_dword v[6:7], v13, off offset:256
	global_store_dword v[6:7], v14, off offset:512
	global_store_dword v[6:7], v15, off offset:768
	global_store_dword v[16:17], v8, off
	global_store_dword v[16:17], v9, off offset:256
	global_store_dword v[16:17], v10, off offset:512
	global_store_dword v[16:17], v11, off offset:768
	v_add_co_u32_e32 v6, vcc, 0x3000, v24
	s_nop 1
	v_addc_co_u32_e32 v7, vcc, 0, v25, vcc
	global_store_dword v[6:7], v32, off
	global_store_dword v[6:7], v33, off offset:256
	global_store_dword v[6:7], v34, off offset:512
	global_store_dword v[6:7], v35, off offset:768
	s_and_saveexec_b64 s[6:7], s[4:5]
	s_cbranch_execz .LBB0_351
	v_lshlrev_b64 v[6:7], 8, v[20:21]
	v_lshl_add_u64 v[6:7], s[18:19], 0, v[6:7]
	v_lshl_add_u64 v[0:1], v[6:7], 0, v[0:1]
	v_add_f32_e32 v3, v30, v22
	v_lshl_add_u64 v[0:1], v[0:1], 0, v[4:5]
	global_store_dword v[0:1], v3, off
	s_branch .LBB0_351

; #define LAS __attribute__((address_space(3)))
;     __device__ __forceinline__ void fused(f32x4 (&acc)[2][2][4][2], const Unit& u, int wr, int wc, int fr, int fq, LAS unsigned char* lds, int wid, int lane) const {
;         const LAS float* S = (const LAS float*)(lds + 4096);
;         const int col0 = u.pn * BM + wc * 32 + 4 * fq;
;         stats(acc, u, wr, wc, fr, fq, lds, wid, lane, e1);
;         const bool defer = lin_in && !lin_out;
; #pragma unroll
;         for (int ai = 0; ai < 2; ++ai)
; #pragma unroll
;             for (int m = 0; m < 4; ++m) { const int r = ai * HALF + wr * 64 + m * 16 + fr; const float rs = S[r]; const int rb = ai * 8 + wr * 4 + m;
; #pragma unroll
;                 for (int bj = 0; bj < 2; ++bj)
; #pragma unroll
;                     for (int n = 0; n < 2; ++n) { const size_t orm = (size_t)(u.pm * BM + r) * D + col0 + bj * HALF + n * 16, oln = (size_t)(u.pm * BM + rb * 16 + 8 * bj + 2 * wc + n) * D + u.pn * BM + lane * 4;
;                         const f32x4 xv = *(const f32x4*)(xin + (lin_in ? oln : orm)); const f32x4 gv = *(const f32x4*)(g1 + col0 + bj * HALF + n * 16);
;                         const f32x4 o = xv + acc[ai][bj][m][n] * rs * gv; acc[ai][bj][m][n] = o; if (!defer) *(f32x4*)(x + (lin_out ? oln : orm)) = o; }
;                 asm volatile("" : "+v"(acc[ai][0][m][0]), "+v"(acc[ai][0][m][1]), "+v"(acc[ai][1][m][0]), "+v"(acc[ai][1][m][1]));
;                 asm volatile("" ::: "memory"); }
.LBB0_490:
	s_or_b64 exec, exec, s[10:11]
	v_readlane_b32 s10, v255, 22
	s_lshl_b32 s20, s10, 10
	v_readlane_b32 s11, v255, 23
	s_ashr_i32 s21, s20, 31
	s_lshl_b32 s15, s14, 8
	s_lshl_b64 s[10:11], s[20:21], 2
	s_add_u32 s10, s30, s10
	s_addc_u32 s11, s31, s11
	s_cmp_gt_i32 s94, 21
	s_cselect_b64 s[24:25], -1, 0
	s_cmp_lt_i32 s94, 22
	s_cselect_b64 s[30:31], -1, 0
	s_lshl_b32 s16, s69, 1
	v_lshrrev_b32_e32 v0, 2, v156
	s_or_b32 s16, s41, s16
	v_and_b32_e32 v0, 12, v0
	s_add_i32 s28, s16, s39
	v_lshl_or_b32 v0, s69, 5, v0
	s_ashr_i32 s17, s15, 31
	s_ashr_i32 s29, s28, 31
	v_or_b32_e32 v0, s15, v0
	v_mov_b32_e32 v149, s17
	s_lshl_b64 s[16:17], s[28:29], 12
	s_waitcnt lgkmcnt(0)
	v_ashrrev_i32_e32 v1, 31, v0
	s_add_u32 s16, s18, s16
	s_waitcnt lgkmcnt(0)
	s_barrier
	v_lshl_add_u32 v3, v145, 2, 0
	v_lshrrev_b32_e32 v162, 8, v202
	v_bfe_u32 v163, v202, 6, 2
	v_and_b32_e32 v164, 15, v207
	v_lshrrev_b32_e32 v165, 4, v207
	s_lshl_b32 s16, s14, 10
	v_lshlrev_b32_e32 v166, 18, v162
	v_lshl_add_u32 v166, v163, 13, v166
	v_lshl_add_u32 v166, v207, 4, v166
	v_add_u32_e32 v166, s16, v166
	v_lshlrev_b32_e32 v156, 7, v163
	v_lshl_add_u32 v156, v165, 4, v156
	v_add_u32_e32 v156, s16, v156
	v_lshlrev_b32_e32 v157, 18, v162
	v_lshl_add_u32 v157, v164, 12, v157
	v_lshl_add_u32 v157, v163, 7, v157
	v_lshl_add_u32 v157, v165, 4, v157
	v_add_u32_e32 v157, s16, v157
	v_mov_b32_e32 v247, v166
	v_add_u32_e32 v249, 0x1000, v166
	v_add_u32_e32 v251, 0x8000, v166
	v_add_u32_e32 v253, 0x9000, v166
	s_lshl_b32 s16, s35, 20
	s_add_u32 s98, s18, s16
	s_addc_u32 s99, s19, 0
	s_mov_b32 s100, s98
	s_mov_b32 s101, s99
	s_and_b64 vcc, exec, s[24:25]
	s_cbranch_vccnz .Lepi6_defer
	global_load_dwordx4 v[132:135], v156, s[10:11] offset:0
	global_load_dwordx4 v[140:143], v156, s[10:11] offset:64
	global_load_dwordx4 v[148:151], v156, s[10:11] offset:512
	global_load_dwordx4 v[152:155], v156, s[10:11] offset:576
	global_load_dwordx4 v[162:165], v247, s[98:99]
	global_load_dwordx4 v[166:169], v249, s[98:99]
	global_load_dwordx4 v[170:173], v251, s[98:99]
	global_load_dwordx4 v[174:177], v253, s[98:99]
	s_add_u32 s98, s98, 0x10000
	s_addc_u32 s99, s99, 0
	global_load_dwordx4 v[178:181], v247, s[98:99]
	global_load_dwordx4 v[182:185], v249, s[98:99]
	global_load_dwordx4 v[186:189], v251, s[98:99]
	global_load_dwordx4 v[190:193], v253, s[98:99]
	s_add_u32 s98, s98, 0x10000
	s_addc_u32 s99, s99, 0
	global_load_dwordx4 v[194:197], v247, s[98:99]
	global_load_dwordx4 v[198:201], v249, s[98:99]
	global_load_dwordx4 v[214:217], v251, s[98:99]
	global_load_dwordx4 v[218:221], v253, s[98:99]
	s_add_u32 s98, s98, 0x10000
	s_addc_u32 s99, s99, 0
	global_load_dwordx4 v[222:225], v247, s[98:99]
	global_load_dwordx4 v[226:229], v249, s[98:99]
	global_load_dwordx4 v[230:233], v251, s[98:99]
	global_load_dwordx4 v[234:237], v253, s[98:99]
	ds_read_b32 v246, v3 offset:4096
	ds_read_b32 v248, v3 offset:4160
	ds_read_b32 v250, v3 offset:4224
	ds_read_b32 v252, v3 offset:4288
	s_waitcnt lgkmcnt(3)
	v_mul_f32_e32 v100, v100, v246
	v_mul_f32_e32 v101, v101, v246
	v_mul_f32_e32 v102, v102, v246
	v_mul_f32_e32 v103, v103, v246
	v_mul_f32_e32 v108, v108, v246
	v_mul_f32_e32 v109, v109, v246
	v_mul_f32_e32 v110, v110, v246
	v_mul_f32_e32 v111, v111, v246
	v_mul_f32_e32 v116, v116, v246
	v_mul_f32_e32 v117, v117, v246
	v_mul_f32_e32 v118, v118, v246
	v_mul_f32_e32 v119, v119, v246
	v_mul_f32_e32 v124, v124, v246
	v_mul_f32_e32 v125, v125, v246
	v_mul_f32_e32 v126, v126, v246
	v_mul_f32_e32 v127, v127, v246
	s_waitcnt lgkmcnt(2)
	v_mul_f32_e32 v120, v120, v248
	v_mul_f32_e32 v121, v121, v248
	v_mul_f32_e32 v122, v122, v248
	v_mul_f32_e32 v123, v123, v248
	v_mul_f32_e32 v128, v128, v248
	v_mul_f32_e32 v129, v129, v248
	v_mul_f32_e32 v130, v130, v248
	v_mul_f32_e32 v131, v131, v248
	v_mul_f32_e32 v112, v112, v248
	v_mul_f32_e32 v113, v113, v248
	v_mul_f32_e32 v114, v114, v248
	v_mul_f32_e32 v115, v115, v248
	v_mul_f32_e32 v104, v104, v248
	v_mul_f32_e32 v105, v105, v248
	v_mul_f32_e32 v106, v106, v248
	v_mul_f32_e32 v107, v107, v248
	s_waitcnt lgkmcnt(1)
	v_mul_f32_e32 v96, v96, v250
	v_mul_f32_e32 v97, v97, v250
	v_mul_f32_e32 v98, v98, v250
	v_mul_f32_e32 v99, v99, v250
	v_mul_f32_e32 v92, v92, v250
	v_mul_f32_e32 v93, v93, v250
	v_mul_f32_e32 v94, v94, v250
	v_mul_f32_e32 v95, v95, v250
	v_mul_f32_e32 v88, v88, v250
	v_mul_f32_e32 v89, v89, v250
	v_mul_f32_e32 v90, v90, v250
	v_mul_f32_e32 v91, v91, v250
	v_mul_f32_e32 v84, v84, v250
	v_mul_f32_e32 v85, v85, v250
	v_mul_f32_e32 v86, v86, v250
	v_mul_f32_e32 v87, v87, v250
	s_waitcnt lgkmcnt(0)
	v_mul_f32_e32 v80, v80, v252
	v_mul_f32_e32 v81, v81, v252
	v_mul_f32_e32 v82, v82, v252
	v_mul_f32_e32 v83, v83, v252
	v_mul_f32_e32 v76, v76, v252
	v_mul_f32_e32 v77, v77, v252
	v_mul_f32_e32 v78, v78, v252
	v_mul_f32_e32 v79, v79, v252
	v_mul_f32_e32 v72, v72, v252
	v_mul_f32_e32 v73, v73, v252
	v_mul_f32_e32 v74, v74, v252
	v_mul_f32_e32 v75, v75, v252
	v_mul_f32_e32 v68, v68, v252
	v_mul_f32_e32 v69, v69, v252
	v_mul_f32_e32 v70, v70, v252
	v_mul_f32_e32 v71, v71, v252
	ds_read_b32 v246, v3 offset:4608
	ds_read_b32 v248, v3 offset:4672
	ds_read_b32 v250, v3 offset:4736
	ds_read_b32 v252, v3 offset:4800
	s_waitcnt lgkmcnt(3)
	v_mul_f32_e32 v64, v64, v246
	v_mul_f32_e32 v65, v65, v246
	v_mul_f32_e32 v66, v66, v246
	v_mul_f32_e32 v67, v67, v246
	v_mul_f32_e32 v60, v60, v246
	v_mul_f32_e32 v61, v61, v246
	v_mul_f32_e32 v62, v62, v246
	v_mul_f32_e32 v63, v63, v246
	v_mul_f32_e32 v56, v56, v246
	v_mul_f32_e32 v57, v57, v246
	v_mul_f32_e32 v58, v58, v246
	v_mul_f32_e32 v59, v59, v246
	v_mul_f32_e32 v52, v52, v246
	v_mul_f32_e32 v53, v53, v246
	v_mul_f32_e32 v54, v54, v246
	v_mul_f32_e32 v55, v55, v246
	s_waitcnt lgkmcnt(2)
;     __device__ __forceinline__ void fused(f32x4 (&acc)[2][2][4][2], const Unit& u, int wr, int wc, int fr, int fq, LAS unsigned char* lds, int wid, int lane) const {
;     ...
;                     for (int n = 0; n < 2; ++n) { const size_t orm = (size_t)(u.pm * BM + r) * D + col0 + bj * HALF + n * 16, oln = (size_t)(u.pm * BM + rb * 16 + 8 * bj + 2 * wc + n) * D + u.pn * BM + lane * 4;
;                         const f32x4 xv = *(const f32x4*)(xin + (lin_in ? oln : orm)); const f32x4 gv = *(const f32x4*)(g1 + col0 + bj * HALF + n * 16);
;                         const f32x4 o = xv + acc[ai][bj][m][n] * rs * gv; acc[ai][bj][m][n] = o; if (!defer) *(f32x4*)(x + (lin_out ? oln : orm)) = o; }
	v_mul_f32_e32 v48, v48, v248
	v_mul_f32_e32 v49, v49, v248
	v_mul_f32_e32 v50, v50, v248
	v_mul_f32_e32 v51, v51, v248
	v_mul_f32_e32 v44, v44, v248
	v_mul_f32_e32 v45, v45, v248
	v_mul_f32_e32 v46, v46, v248
	v_mul_f32_e32 v47, v47, v248
	v_mul_f32_e32 v40, v40, v248
	v_mul_f32_e32 v41, v41, v248
	v_mul_f32_e32 v42, v42, v248
	v_mul_f32_e32 v43, v43, v248
	v_mul_f32_e32 v36, v36, v248
	v_mul_f32_e32 v37, v37, v248
	v_mul_f32_e32 v38, v38, v248
	v_mul_f32_e32 v39, v39, v248
	s_waitcnt lgkmcnt(1)
	v_mul_f32_e32 v32, v32, v250
	v_mul_f32_e32 v33, v33, v250
	v_mul_f32_e32 v34, v34, v250
	v_mul_f32_e32 v35, v35, v250
	v_mul_f32_e32 v28, v28, v250
	v_mul_f32_e32 v29, v29, v250
	v_mul_f32_e32 v30, v30, v250
	v_mul_f32_e32 v31, v31, v250
	v_mul_f32_e32 v24, v24, v250
	v_mul_f32_e32 v25, v25, v250
	v_mul_f32_e32 v26, v26, v250
	v_mul_f32_e32 v27, v27, v250
	v_mul_f32_e32 v20, v20, v250
	v_mul_f32_e32 v21, v21, v250
	v_mul_f32_e32 v22, v22, v250
	v_mul_f32_e32 v23, v23, v250
	s_waitcnt lgkmcnt(0)
	v_mul_f32_e32 v16, v16, v252
	v_mul_f32_e32 v17, v17, v252
	v_mul_f32_e32 v18, v18, v252
	v_mul_f32_e32 v19, v19, v252
	v_mul_f32_e32 v12, v12, v252
	v_mul_f32_e32 v13, v13, v252
	v_mul_f32_e32 v14, v14, v252
	v_mul_f32_e32 v15, v15, v252
	v_mul_f32_e32 v8, v8, v252
	v_mul_f32_e32 v9, v9, v252
	v_mul_f32_e32 v10, v10, v252
	v_mul_f32_e32 v11, v11, v252
	v_mul_f32_e32 v4, v4, v252
	v_mul_f32_e32 v5, v5, v252
	v_mul_f32_e32 v6, v6, v252
	v_mul_f32_e32 v7, v7, v252
	s_waitcnt vmcnt(15)
	v_fma_f32 v100, v132, v100, v162
	v_fma_f32 v101, v133, v101, v163
	v_fma_f32 v102, v134, v102, v164
	v_fma_f32 v103, v135, v103, v165
	global_store_dwordx4 v247, v[100:103], s[100:101]
	s_add_u32 s98, s98, 0x50000
	s_addc_u32 s99, s99, 0
	global_load_dwordx4 v[162:165], v247, s[98:99]
	s_waitcnt vmcnt(16)
	v_fma_f32 v108, v140, v108, v166
	v_fma_f32 v109, v141, v109, v167
	v_fma_f32 v110, v142, v110, v168
	v_fma_f32 v111, v143, v111, v169
	global_store_dwordx4 v249, v[108:111], s[100:101]
	global_load_dwordx4 v[166:169], v249, s[98:99]
	s_waitcnt vmcnt(17)
	v_fma_f32 v116, v148, v116, v170
	v_fma_f32 v117, v149, v117, v171
	v_fma_f32 v118, v150, v118, v172
	v_fma_f32 v119, v151, v119, v173
	global_store_dwordx4 v251, v[116:119], s[100:101]
	global_load_dwordx4 v[170:173], v251, s[98:99]
	s_waitcnt vmcnt(18)
	v_fma_f32 v124, v152, v124, v174
	v_fma_f32 v125, v153, v125, v175
	v_fma_f32 v126, v154, v126, v176
	v_fma_f32 v127, v155, v127, v177
	global_store_dwordx4 v253, v[124:127], s[100:101]
	global_load_dwordx4 v[174:177], v253, s[98:99]
	s_waitcnt vmcnt(19)
	v_fma_f32 v120, v132, v120, v178
	v_fma_f32 v121, v133, v121, v179
	v_fma_f32 v122, v134, v122, v180
	v_fma_f32 v123, v135, v123, v181
	s_add_u32 s100, s100, 0x10000
	s_addc_u32 s101, s101, 0
	global_store_dwordx4 v247, v[120:123], s[100:101]
	s_add_u32 s98, s98, 0x10000
	s_addc_u32 s99, s99, 0
	global_load_dwordx4 v[178:181], v247, s[98:99]
	s_waitcnt vmcnt(20)
	v_fma_f32 v128, v140, v128, v182
	v_fma_f32 v129, v141, v129, v183
	v_fma_f32 v130, v142, v130, v184
	v_fma_f32 v131, v143, v131, v185
	global_store_dwordx4 v249, v[128:131], s[100:101]
	global_load_dwordx4 v[182:185], v249, s[98:99]
	s_waitcnt vmcnt(21)
	v_fma_f32 v112, v148, v112, v186
	v_fma_f32 v113, v149, v113, v187
	v_fma_f32 v114, v150, v114, v188
	v_fma_f32 v115, v151, v115, v189
	global_store_dwordx4 v251, v[112:115], s[100:101]
	global_load_dwordx4 v[186:189], v251, s[98:99]
	s_waitcnt vmcnt(22)
	v_fma_f32 v104, v152, v104, v190
	v_fma_f32 v105, v153, v105, v191
	v_fma_f32 v106, v154, v106, v192
	v_fma_f32 v107, v155, v107, v193
	global_store_dwordx4 v253, v[104:107], s[100:101]
	global_load_dwordx4 v[190:193], v253, s[98:99]
	s_waitcnt vmcnt(23)
	v_fma_f32 v96, v132, v96, v194
	v_fma_f32 v97, v133, v97, v195
	v_fma_f32 v98, v134, v98, v196
	v_fma_f32 v99, v135, v99, v197
	s_add_u32 s100, s100, 0x10000
	s_addc_u32 s101, s101, 0
	global_store_dwordx4 v247, v[96:99], s[100:101]
	s_add_u32 s98, s98, 0x10000
	s_addc_u32 s99, s99, 0
	global_load_dwordx4 v[194:197], v247, s[98:99]
	s_waitcnt vmcnt(24)
	v_fma_f32 v92, v140, v92, v198
	v_fma_f32 v93, v141, v93, v199
	v_fma_f32 v94, v142, v94, v200
	v_fma_f32 v95, v143, v95, v201
	global_store_dwordx4 v249, v[92:95], s[100:101]
	global_load_dwordx4 v[198:201], v249, s[98:99]
	s_waitcnt vmcnt(25)
	v_fma_f32 v88, v148, v88, v214
	v_fma_f32 v89, v149, v89, v215
	v_fma_f32 v90, v150, v90, v216
	v_fma_f32 v91, v151, v91, v217
	global_store_dwordx4 v251, v[88:91], s[100:101]
	global_load_dwordx4 v[214:217], v251, s[98:99]
	s_waitcnt vmcnt(26)
	v_fma_f32 v84, v152, v84, v218
	v_fma_f32 v85, v153, v85, v219
	v_fma_f32 v86, v154, v86, v220
	v_fma_f32 v87, v155, v87, v221
	global_store_dwordx4 v253, v[84:87], s[100:101]
	global_load_dwordx4 v[218:221], v253, s[98:99]
	s_waitcnt vmcnt(27)
	v_fma_f32 v80, v132, v80, v222
	v_fma_f32 v81, v133, v81, v223
	v_fma_f32 v82, v134, v82, v224
	v_fma_f32 v83, v135, v83, v225
	s_add_u32 s100, s100, 0x10000
	s_addc_u32 s101, s101, 0
	global_store_dwordx4 v247, v[80:83], s[100:101]
	s_add_u32 s98, s98, 0x10000
	s_addc_u32 s99, s99, 0
	global_load_dwordx4 v[222:225], v247, s[98:99]
	s_waitcnt vmcnt(28)
	v_fma_f32 v76, v140, v76, v226
	v_fma_f32 v77, v141, v77, v227
	v_fma_f32 v78, v142, v78, v228
	v_fma_f32 v79, v143, v79, v229
	global_store_dwordx4 v249, v[76:79], s[100:101]
	global_load_dwordx4 v[226:229], v249, s[98:99]
	s_waitcnt vmcnt(29)
	v_fma_f32 v72, v148, v72, v230
	v_fma_f32 v73, v149, v73, v231
	v_fma_f32 v74, v150, v74, v232
	v_fma_f32 v75, v151, v75, v233
	global_store_dwordx4 v251, v[72:75], s[100:101]
	global_load_dwordx4 v[230:233], v251, s[98:99]
	s_waitcnt vmcnt(30)
;     __device__ __forceinline__ void fused(f32x4 (&acc)[2][2][4][2], const Unit& u, int wr, int wc, int fr, int fq, LAS unsigned char* lds, int wid, int lane) const {
;     ...
;                     for (int n = 0; n < 2; ++n) { const size_t orm = (size_t)(u.pm * BM + r) * D + col0 + bj * HALF + n * 16, oln = (size_t)(u.pm * BM + rb * 16 + 8 * bj + 2 * wc + n) * D + u.pn * BM + lane * 4;
;                         const f32x4 xv = *(const f32x4*)(xin + (lin_in ? oln : orm)); const f32x4 gv = *(const f32x4*)(g1 + col0 + bj * HALF + n * 16);
;                         const f32x4 o = xv + acc[ai][bj][m][n] * rs * gv; acc[ai][bj][m][n] = o; if (!defer) *(f32x4*)(x + (lin_out ? oln : orm)) = o; }
;                 asm volatile("" : "+v"(acc[ai][0][m][0]), "+v"(acc[ai][0][m][1]), "+v"(acc[ai][1][m][0]), "+v"(acc[ai][1][m][1]));
;                 asm volatile("" ::: "memory"); }
;         if (defer) {
;             asm volatile("s_waitcnt vmcnt(0)" ::: "memory"); __builtin_amdgcn_s_barrier(); asm volatile("" ::: "memory");
; #pragma unroll
;             for (int ai = 0; ai < 2; ++ai)
; #pragma unroll
;                 for (int m = 0; m < 4; ++m) { const int r = ai * HALF + wr * 64 + m * 16 + fr; float* xp = x + (size_t)(u.pm * BM + r) * D + col0;
; #pragma unroll
;                     for (int bj = 0; bj < 2; ++bj)
; #pragma unroll
;                         for (int n = 0; n < 2; ++n) *(f32x4*)(xp + bj * HALF + n * 16) = acc[ai][bj][m][n]; }
	v_fma_f32 v68, v152, v68, v234
	v_fma_f32 v69, v153, v69, v235
	v_fma_f32 v70, v154, v70, v236
	v_fma_f32 v71, v155, v71, v237
	global_store_dwordx4 v253, v[68:71], s[100:101]
	global_load_dwordx4 v[234:237], v253, s[98:99]
	s_waitcnt vmcnt(30)
	v_fma_f32 v64, v132, v64, v162
	v_fma_f32 v65, v133, v65, v163
	v_fma_f32 v66, v134, v66, v164
	v_fma_f32 v67, v135, v67, v165
	s_add_u32 s100, s100, 0x50000
	s_addc_u32 s101, s101, 0
	global_store_dwordx4 v247, v[64:67], s[100:101]
	s_waitcnt vmcnt(29)
	v_fma_f32 v60, v140, v60, v166
	v_fma_f32 v61, v141, v61, v167
	v_fma_f32 v62, v142, v62, v168
	v_fma_f32 v63, v143, v63, v169
	global_store_dwordx4 v249, v[60:63], s[100:101]
	s_waitcnt vmcnt(28)
	v_fma_f32 v56, v148, v56, v170
	v_fma_f32 v57, v149, v57, v171
	v_fma_f32 v58, v150, v58, v172
	v_fma_f32 v59, v151, v59, v173
	global_store_dwordx4 v251, v[56:59], s[100:101]
	s_waitcnt vmcnt(27)
	v_fma_f32 v52, v152, v52, v174
	v_fma_f32 v53, v153, v53, v175
	v_fma_f32 v54, v154, v54, v176
	v_fma_f32 v55, v155, v55, v177
	global_store_dwordx4 v253, v[52:55], s[100:101]
	s_waitcnt vmcnt(26)
	v_fma_f32 v48, v132, v48, v178
	v_fma_f32 v49, v133, v49, v179
	v_fma_f32 v50, v134, v50, v180
	v_fma_f32 v51, v135, v51, v181
	s_add_u32 s100, s100, 0x10000
	s_addc_u32 s101, s101, 0
	global_store_dwordx4 v247, v[48:51], s[100:101]
	s_waitcnt vmcnt(25)
	v_fma_f32 v44, v140, v44, v182
	v_fma_f32 v45, v141, v45, v183
	v_fma_f32 v46, v142, v46, v184
	v_fma_f32 v47, v143, v47, v185
	global_store_dwordx4 v249, v[44:47], s[100:101]
	s_waitcnt vmcnt(24)
	v_fma_f32 v40, v148, v40, v186
	v_fma_f32 v41, v149, v41, v187
	v_fma_f32 v42, v150, v42, v188
	v_fma_f32 v43, v151, v43, v189
	global_store_dwordx4 v251, v[40:43], s[100:101]
	s_waitcnt vmcnt(23)
	v_fma_f32 v36, v152, v36, v190
	v_fma_f32 v37, v153, v37, v191
	v_fma_f32 v38, v154, v38, v192
	v_fma_f32 v39, v155, v39, v193
	global_store_dwordx4 v253, v[36:39], s[100:101]
	s_waitcnt vmcnt(22)
	v_fma_f32 v32, v132, v32, v194
	v_fma_f32 v33, v133, v33, v195
	v_fma_f32 v34, v134, v34, v196
	v_fma_f32 v35, v135, v35, v197
	s_add_u32 s100, s100, 0x10000
	s_addc_u32 s101, s101, 0
	global_store_dwordx4 v247, v[32:35], s[100:101]
	s_waitcnt vmcnt(21)
	v_fma_f32 v28, v140, v28, v198
	v_fma_f32 v29, v141, v29, v199
	v_fma_f32 v30, v142, v30, v200
	v_fma_f32 v31, v143, v31, v201
	global_store_dwordx4 v249, v[28:31], s[100:101]
	s_waitcnt vmcnt(20)
	v_fma_f32 v24, v148, v24, v214
	v_fma_f32 v25, v149, v25, v215
	v_fma_f32 v26, v150, v26, v216
	v_fma_f32 v27, v151, v27, v217
	global_store_dwordx4 v251, v[24:27], s[100:101]
	s_waitcnt vmcnt(19)
	v_fma_f32 v20, v152, v20, v218
	v_fma_f32 v21, v153, v21, v219
	v_fma_f32 v22, v154, v22, v220
	v_fma_f32 v23, v155, v23, v221
	global_store_dwordx4 v253, v[20:23], s[100:101]
	s_waitcnt vmcnt(18)
	v_fma_f32 v16, v132, v16, v222
	v_fma_f32 v17, v133, v17, v223
	v_fma_f32 v18, v134, v18, v224
	v_fma_f32 v19, v135, v19, v225
	s_add_u32 s100, s100, 0x10000
	s_addc_u32 s101, s101, 0
	global_store_dwordx4 v247, v[16:19], s[100:101]
	s_waitcnt vmcnt(17)
	v_fma_f32 v12, v140, v12, v226
	v_fma_f32 v13, v141, v13, v227
	v_fma_f32 v14, v142, v14, v228
	v_fma_f32 v15, v143, v15, v229
	global_store_dwordx4 v249, v[12:15], s[100:101]
	s_waitcnt vmcnt(16)
	v_fma_f32 v8, v148, v8, v230
	v_fma_f32 v9, v149, v9, v231
	v_fma_f32 v10, v150, v10, v232
	v_fma_f32 v11, v151, v11, v233
	global_store_dwordx4 v251, v[8:11], s[100:101]
	s_waitcnt vmcnt(15)
	v_fma_f32 v4, v152, v4, v234
	v_fma_f32 v5, v153, v5, v235
	v_fma_f32 v6, v154, v6, v236
	v_fma_f32 v7, v155, v7, v237
	global_store_dwordx4 v253, v[4:7], s[100:101]
	s_branch .LBB0_556
.Lepi6_defer:
	global_load_dwordx4 v[132:135], v156, s[10:11] offset:0
	global_load_dwordx4 v[140:143], v156, s[10:11] offset:64
	global_load_dwordx4 v[148:151], v156, s[10:11] offset:512
	global_load_dwordx4 v[152:155], v156, s[10:11] offset:576
	global_load_dwordx4 v[162:165], v247, s[98:99]
	global_load_dwordx4 v[166:169], v249, s[98:99]
	global_load_dwordx4 v[170:173], v251, s[98:99]
	global_load_dwordx4 v[174:177], v253, s[98:99]
	s_add_u32 s98, s98, 0x10000
	s_addc_u32 s99, s99, 0
	global_load_dwordx4 v[178:181], v247, s[98:99]
	global_load_dwordx4 v[182:185], v249, s[98:99]
	global_load_dwordx4 v[186:189], v251, s[98:99]
	global_load_dwordx4 v[190:193], v253, s[98:99]
	s_add_u32 s98, s98, 0x10000
	s_addc_u32 s99, s99, 0
	global_load_dwordx4 v[194:197], v247, s[98:99]
	global_load_dwordx4 v[198:201], v249, s[98:99]
	global_load_dwordx4 v[214:217], v251, s[98:99]
	global_load_dwordx4 v[218:221], v253, s[98:99]
	s_add_u32 s98, s98, 0x10000
	s_addc_u32 s99, s99, 0
	global_load_dwordx4 v[222:225], v247, s[98:99]
	global_load_dwordx4 v[226:229], v249, s[98:99]
	global_load_dwordx4 v[230:233], v251, s[98:99]
	global_load_dwordx4 v[234:237], v253, s[98:99]
	ds_read_b32 v246, v3 offset:4096
	ds_read_b32 v248, v3 offset:4160
	ds_read_b32 v250, v3 offset:4224
	ds_read_b32 v252, v3 offset:4288
	s_waitcnt lgkmcnt(3)
	v_mul_f32_e32 v100, v100, v246
	v_mul_f32_e32 v101, v101, v246
	v_mul_f32_e32 v102, v102, v246
	v_mul_f32_e32 v103, v103, v246
	v_mul_f32_e32 v108, v108, v246
	v_mul_f32_e32 v109, v109, v246
	v_mul_f32_e32 v110, v110, v246
	v_mul_f32_e32 v111, v111, v246
	v_mul_f32_e32 v116, v116, v246
	v_mul_f32_e32 v117, v117, v246
	v_mul_f32_e32 v118, v118, v246
	v_mul_f32_e32 v119, v119, v246
	v_mul_f32_e32 v124, v124, v246
	v_mul_f32_e32 v125, v125, v246
	v_mul_f32_e32 v126, v126, v246
	v_mul_f32_e32 v127, v127, v246
	s_waitcnt lgkmcnt(2)
;     __device__ __forceinline__ void fused(f32x4 (&acc)[2][2][4][2], const Unit& u, int wr, int wc, int fr, int fq, LAS unsigned char* lds, int wid, int lane) const {
;     ...
;                     for (int n = 0; n < 2; ++n) { const size_t orm = (size_t)(u.pm * BM + r) * D + col0 + bj * HALF + n * 16, oln = (size_t)(u.pm * BM + rb * 16 + 8 * bj + 2 * wc + n) * D + u.pn * BM + lane * 4;
;                         const f32x4 xv = *(const f32x4*)(xin + (lin_in ? oln : orm)); const f32x4 gv = *(const f32x4*)(g1 + col0 + bj * HALF + n * 16);
;                         const f32x4 o = xv + acc[ai][bj][m][n] * rs * gv; acc[ai][bj][m][n] = o; if (!defer) *(f32x4*)(x + (lin_out ? oln : orm)) = o; }
;                 asm volatile("" : "+v"(acc[ai][0][m][0]), "+v"(acc[ai][0][m][1]), "+v"(acc[ai][1][m][0]), "+v"(acc[ai][1][m][1]));
;                 asm volatile("" ::: "memory"); }
	v_mul_f32_e32 v120, v120, v248
	v_mul_f32_e32 v121, v121, v248
	v_mul_f32_e32 v122, v122, v248
	v_mul_f32_e32 v123, v123, v248
	v_mul_f32_e32 v128, v128, v248
	v_mul_f32_e32 v129, v129, v248
	v_mul_f32_e32 v130, v130, v248
	v_mul_f32_e32 v131, v131, v248
	v_mul_f32_e32 v112, v112, v248
	v_mul_f32_e32 v113, v113, v248
	v_mul_f32_e32 v114, v114, v248
	v_mul_f32_e32 v115, v115, v248
	v_mul_f32_e32 v104, v104, v248
	v_mul_f32_e32 v105, v105, v248
	v_mul_f32_e32 v106, v106, v248
	v_mul_f32_e32 v107, v107, v248
	s_waitcnt lgkmcnt(1)
	v_mul_f32_e32 v96, v96, v250
	v_mul_f32_e32 v97, v97, v250
	v_mul_f32_e32 v98, v98, v250
	v_mul_f32_e32 v99, v99, v250
	v_mul_f32_e32 v92, v92, v250
	v_mul_f32_e32 v93, v93, v250
	v_mul_f32_e32 v94, v94, v250
	v_mul_f32_e32 v95, v95, v250
	v_mul_f32_e32 v88, v88, v250
	v_mul_f32_e32 v89, v89, v250
	v_mul_f32_e32 v90, v90, v250
	v_mul_f32_e32 v91, v91, v250
	v_mul_f32_e32 v84, v84, v250
	v_mul_f32_e32 v85, v85, v250
	v_mul_f32_e32 v86, v86, v250
	v_mul_f32_e32 v87, v87, v250
	s_waitcnt lgkmcnt(0)
	v_mul_f32_e32 v80, v80, v252
	v_mul_f32_e32 v81, v81, v252
	v_mul_f32_e32 v82, v82, v252
	v_mul_f32_e32 v83, v83, v252
	v_mul_f32_e32 v76, v76, v252
	v_mul_f32_e32 v77, v77, v252
	v_mul_f32_e32 v78, v78, v252
	v_mul_f32_e32 v79, v79, v252
	v_mul_f32_e32 v72, v72, v252
	v_mul_f32_e32 v73, v73, v252
	v_mul_f32_e32 v74, v74, v252
	v_mul_f32_e32 v75, v75, v252
	v_mul_f32_e32 v68, v68, v252
	v_mul_f32_e32 v69, v69, v252
	v_mul_f32_e32 v70, v70, v252
	v_mul_f32_e32 v71, v71, v252
	ds_read_b32 v246, v3 offset:4608
	ds_read_b32 v248, v3 offset:4672
	ds_read_b32 v250, v3 offset:4736
	ds_read_b32 v252, v3 offset:4800
	s_waitcnt lgkmcnt(3)
	v_mul_f32_e32 v64, v64, v246
	v_mul_f32_e32 v65, v65, v246
	v_mul_f32_e32 v66, v66, v246
	v_mul_f32_e32 v67, v67, v246
	v_mul_f32_e32 v60, v60, v246
	v_mul_f32_e32 v61, v61, v246
	v_mul_f32_e32 v62, v62, v246
	v_mul_f32_e32 v63, v63, v246
	v_mul_f32_e32 v56, v56, v246
	v_mul_f32_e32 v57, v57, v246
	v_mul_f32_e32 v58, v58, v246
	v_mul_f32_e32 v59, v59, v246
	v_mul_f32_e32 v52, v52, v246
	v_mul_f32_e32 v53, v53, v246
	v_mul_f32_e32 v54, v54, v246
	v_mul_f32_e32 v55, v55, v246
	s_waitcnt lgkmcnt(2)
	v_mul_f32_e32 v48, v48, v248
	v_mul_f32_e32 v49, v49, v248
	v_mul_f32_e32 v50, v50, v248
	v_mul_f32_e32 v51, v51, v248
	v_mul_f32_e32 v44, v44, v248
	v_mul_f32_e32 v45, v45, v248
	v_mul_f32_e32 v46, v46, v248
	v_mul_f32_e32 v47, v47, v248
	v_mul_f32_e32 v40, v40, v248
	v_mul_f32_e32 v41, v41, v248
	v_mul_f32_e32 v42, v42, v248
	v_mul_f32_e32 v43, v43, v248
	v_mul_f32_e32 v36, v36, v248
	v_mul_f32_e32 v37, v37, v248
	v_mul_f32_e32 v38, v38, v248
	v_mul_f32_e32 v39, v39, v248
	s_waitcnt lgkmcnt(1)
	v_mul_f32_e32 v32, v32, v250
	v_mul_f32_e32 v33, v33, v250
	v_mul_f32_e32 v34, v34, v250
	v_mul_f32_e32 v35, v35, v250
	v_mul_f32_e32 v28, v28, v250
	v_mul_f32_e32 v29, v29, v250
	v_mul_f32_e32 v30, v30, v250
	v_mul_f32_e32 v31, v31, v250
	v_mul_f32_e32 v24, v24, v250
	v_mul_f32_e32 v25, v25, v250
	v_mul_f32_e32 v26, v26, v250
	v_mul_f32_e32 v27, v27, v250
	v_mul_f32_e32 v20, v20, v250
	v_mul_f32_e32 v21, v21, v250
	v_mul_f32_e32 v22, v22, v250
	v_mul_f32_e32 v23, v23, v250
	s_waitcnt lgkmcnt(0)
	v_mul_f32_e32 v16, v16, v252
	v_mul_f32_e32 v17, v17, v252
	v_mul_f32_e32 v18, v18, v252
	v_mul_f32_e32 v19, v19, v252
	v_mul_f32_e32 v12, v12, v252
	v_mul_f32_e32 v13, v13, v252
	v_mul_f32_e32 v14, v14, v252
	v_mul_f32_e32 v15, v15, v252
	v_mul_f32_e32 v8, v8, v252
	v_mul_f32_e32 v9, v9, v252
	v_mul_f32_e32 v10, v10, v252
	v_mul_f32_e32 v11, v11, v252
	v_mul_f32_e32 v4, v4, v252
	v_mul_f32_e32 v5, v5, v252
	v_mul_f32_e32 v6, v6, v252
	v_mul_f32_e32 v7, v7, v252
	s_waitcnt vmcnt(15)
	v_fma_f32 v100, v132, v100, v162
	v_fma_f32 v101, v133, v101, v163
	v_fma_f32 v102, v134, v102, v164
	v_fma_f32 v103, v135, v103, v165
	s_add_u32 s98, s98, 0x50000
	s_addc_u32 s99, s99, 0
	global_load_dwordx4 v[162:165], v247, s[98:99]
	s_waitcnt vmcnt(15)
	v_fma_f32 v108, v140, v108, v166
	v_fma_f32 v109, v141, v109, v167
	v_fma_f32 v110, v142, v110, v168
	v_fma_f32 v111, v143, v111, v169
	global_load_dwordx4 v[166:169], v249, s[98:99]
	s_waitcnt vmcnt(15)
	v_fma_f32 v116, v148, v116, v170
	v_fma_f32 v117, v149, v117, v171
	v_fma_f32 v118, v150, v118, v172
	v_fma_f32 v119, v151, v119, v173
	global_load_dwordx4 v[170:173], v251, s[98:99]
	s_waitcnt vmcnt(15)
	v_fma_f32 v124, v152, v124, v174
	v_fma_f32 v125, v153, v125, v175
	v_fma_f32 v126, v154, v126, v176
	v_fma_f32 v127, v155, v127, v177
	global_load_dwordx4 v[174:177], v253, s[98:99]
	s_waitcnt vmcnt(15)
	v_fma_f32 v120, v132, v120, v178
	v_fma_f32 v121, v133, v121, v179
	v_fma_f32 v122, v134, v122, v180
	v_fma_f32 v123, v135, v123, v181
	s_add_u32 s98, s98, 0x10000
	s_addc_u32 s99, s99, 0
	global_load_dwordx4 v[178:181], v247, s[98:99]
	s_waitcnt vmcnt(15)
	v_fma_f32 v128, v140, v128, v182
	v_fma_f32 v129, v141, v129, v183
	v_fma_f32 v130, v142, v130, v184
	v_fma_f32 v131, v143, v131, v185
	global_load_dwordx4 v[182:185], v249, s[98:99]
	s_waitcnt vmcnt(15)
	v_fma_f32 v112, v148, v112, v186
	v_fma_f32 v113, v149, v113, v187
	v_fma_f32 v114, v150, v114, v188
	v_fma_f32 v115, v151, v115, v189
	global_load_dwordx4 v[186:189], v251, s[98:99]
	s_waitcnt vmcnt(15)
	v_fma_f32 v104, v152, v104, v190
	v_fma_f32 v105, v153, v105, v191
	v_fma_f32 v106, v154, v106, v192
	v_fma_f32 v107, v155, v107, v193
	global_load_dwordx4 v[190:193], v253, s[98:99]
	s_waitcnt vmcnt(15)
	v_fma_f32 v96, v132, v96, v194
	v_fma_f32 v97, v133, v97, v195
	v_fma_f32 v98, v134, v98, v196
	v_fma_f32 v99, v135, v99, v197
	s_add_u32 s98, s98, 0x10000
	s_addc_u32 s99, s99, 0
	global_load_dwordx4 v[194:197], v247, s[98:99]
	s_waitcnt vmcnt(15)
;     __device__ __forceinline__ void fused(f32x4 (&acc)[2][2][4][2], const Unit& u, int wr, int wc, int fr, int fq, LAS unsigned char* lds, int wid, int lane) const {
;     ...
;                     for (int n = 0; n < 2; ++n) { const size_t orm = (size_t)(u.pm * BM + r) * D + col0 + bj * HALF + n * 16, oln = (size_t)(u.pm * BM + rb * 16 + 8 * bj + 2 * wc + n) * D + u.pn * BM + lane * 4;
;                         const f32x4 xv = *(const f32x4*)(xin + (lin_in ? oln : orm)); const f32x4 gv = *(const f32x4*)(g1 + col0 + bj * HALF + n * 16);
;                         const f32x4 o = xv + acc[ai][bj][m][n] * rs * gv; acc[ai][bj][m][n] = o; if (!defer) *(f32x4*)(x + (lin_out ? oln : orm)) = o; }
;                 asm volatile("" : "+v"(acc[ai][0][m][0]), "+v"(acc[ai][0][m][1]), "+v"(acc[ai][1][m][0]), "+v"(acc[ai][1][m][1]));
;                 asm volatile("" ::: "memory"); }
;         if (defer) {
;             asm volatile("s_waitcnt vmcnt(0)" ::: "memory"); __builtin_amdgcn_s_barrier(); asm volatile("" ::: "memory");
; #pragma unroll
;             for (int ai = 0; ai < 2; ++ai)
; #pragma unroll
;                 for (int m = 0; m < 4; ++m) { const int r = ai * HALF + wr * 64 + m * 16 + fr; float* xp = x + (size_t)(u.pm * BM + r) * D + col0;
; #pragma unroll
;                     for (int bj = 0; bj < 2; ++bj)
; #pragma unroll
;                         for (int n = 0; n < 2; ++n) *(f32x4*)(xp + bj * HALF + n * 16) = acc[ai][bj][m][n]; }
	v_fma_f32 v92, v140, v92, v198
	v_fma_f32 v93, v141, v93, v199
	v_fma_f32 v94, v142, v94, v200
	v_fma_f32 v95, v143, v95, v201
	global_load_dwordx4 v[198:201], v249, s[98:99]
	s_waitcnt vmcnt(15)
	v_fma_f32 v88, v148, v88, v214
	v_fma_f32 v89, v149, v89, v215
	v_fma_f32 v90, v150, v90, v216
	v_fma_f32 v91, v151, v91, v217
	global_load_dwordx4 v[214:217], v251, s[98:99]
	s_waitcnt vmcnt(15)
	v_fma_f32 v84, v152, v84, v218
	v_fma_f32 v85, v153, v85, v219
	v_fma_f32 v86, v154, v86, v220
	v_fma_f32 v87, v155, v87, v221
	global_load_dwordx4 v[218:221], v253, s[98:99]
	s_waitcnt vmcnt(15)
	v_fma_f32 v80, v132, v80, v222
	v_fma_f32 v81, v133, v81, v223
	v_fma_f32 v82, v134, v82, v224
	v_fma_f32 v83, v135, v83, v225
	s_add_u32 s98, s98, 0x10000
	s_addc_u32 s99, s99, 0
	global_load_dwordx4 v[222:225], v247, s[98:99]
	s_waitcnt vmcnt(15)
	v_fma_f32 v76, v140, v76, v226
	v_fma_f32 v77, v141, v77, v227
	v_fma_f32 v78, v142, v78, v228
	v_fma_f32 v79, v143, v79, v229
	global_load_dwordx4 v[226:229], v249, s[98:99]
	s_waitcnt vmcnt(15)
	v_fma_f32 v72, v148, v72, v230
	v_fma_f32 v73, v149, v73, v231
	v_fma_f32 v74, v150, v74, v232
	v_fma_f32 v75, v151, v75, v233
	global_load_dwordx4 v[230:233], v251, s[98:99]
	s_waitcnt vmcnt(15)
	v_fma_f32 v68, v152, v68, v234
	v_fma_f32 v69, v153, v69, v235
	v_fma_f32 v70, v154, v70, v236
	v_fma_f32 v71, v155, v71, v237
	global_load_dwordx4 v[234:237], v253, s[98:99]
	s_waitcnt vmcnt(15)
	v_fma_f32 v64, v132, v64, v162
	v_fma_f32 v65, v133, v65, v163
	v_fma_f32 v66, v134, v66, v164
	v_fma_f32 v67, v135, v67, v165
	s_waitcnt vmcnt(14)
	v_fma_f32 v60, v140, v60, v166
	v_fma_f32 v61, v141, v61, v167
	v_fma_f32 v62, v142, v62, v168
	v_fma_f32 v63, v143, v63, v169
	s_waitcnt vmcnt(13)
	v_fma_f32 v56, v148, v56, v170
	v_fma_f32 v57, v149, v57, v171
	v_fma_f32 v58, v150, v58, v172
	v_fma_f32 v59, v151, v59, v173
	s_waitcnt vmcnt(12)
	v_fma_f32 v52, v152, v52, v174
	v_fma_f32 v53, v153, v53, v175
	v_fma_f32 v54, v154, v54, v176
	v_fma_f32 v55, v155, v55, v177
	s_waitcnt vmcnt(11)
	v_fma_f32 v48, v132, v48, v178
	v_fma_f32 v49, v133, v49, v179
	v_fma_f32 v50, v134, v50, v180
	v_fma_f32 v51, v135, v51, v181
	s_waitcnt vmcnt(10)
	v_fma_f32 v44, v140, v44, v182
	v_fma_f32 v45, v141, v45, v183
	v_fma_f32 v46, v142, v46, v184
	v_fma_f32 v47, v143, v47, v185
	s_waitcnt vmcnt(9)
	v_fma_f32 v40, v148, v40, v186
	v_fma_f32 v41, v149, v41, v187
	v_fma_f32 v42, v150, v42, v188
	v_fma_f32 v43, v151, v43, v189
	s_waitcnt vmcnt(8)
	v_fma_f32 v36, v152, v36, v190
	v_fma_f32 v37, v153, v37, v191
	v_fma_f32 v38, v154, v38, v192
	v_fma_f32 v39, v155, v39, v193
	s_waitcnt vmcnt(7)
	v_fma_f32 v32, v132, v32, v194
	v_fma_f32 v33, v133, v33, v195
	v_fma_f32 v34, v134, v34, v196
	v_fma_f32 v35, v135, v35, v197
	s_waitcnt vmcnt(6)
	v_fma_f32 v28, v140, v28, v198
	v_fma_f32 v29, v141, v29, v199
	v_fma_f32 v30, v142, v30, v200
	v_fma_f32 v31, v143, v31, v201
	s_waitcnt vmcnt(5)
	v_fma_f32 v24, v148, v24, v214
	v_fma_f32 v25, v149, v25, v215
	v_fma_f32 v26, v150, v26, v216
	v_fma_f32 v27, v151, v27, v217
	s_waitcnt vmcnt(4)
	v_fma_f32 v20, v152, v20, v218
	v_fma_f32 v21, v153, v21, v219
	v_fma_f32 v22, v154, v22, v220
	v_fma_f32 v23, v155, v23, v221
	s_waitcnt vmcnt(3)
	v_fma_f32 v16, v132, v16, v222
	v_fma_f32 v17, v133, v17, v223
	v_fma_f32 v18, v134, v18, v224
	v_fma_f32 v19, v135, v19, v225
	s_waitcnt vmcnt(2)
	v_fma_f32 v12, v140, v12, v226
	v_fma_f32 v13, v141, v13, v227
	v_fma_f32 v14, v142, v14, v228
	v_fma_f32 v15, v143, v15, v229
	s_waitcnt vmcnt(1)
	v_fma_f32 v8, v148, v8, v230
	v_fma_f32 v9, v149, v9, v231
	v_fma_f32 v10, v150, v10, v232
	v_fma_f32 v11, v151, v11, v233
	s_waitcnt vmcnt(0)
	v_fma_f32 v4, v152, v4, v234
	v_fma_f32 v5, v153, v5, v235
	v_fma_f32 v6, v154, v6, v236
	v_fma_f32 v7, v155, v7, v237
	s_waitcnt vmcnt(0)
	s_barrier
	v_mov_b32_e32 v247, v157
	v_add_u32_e32 v249, 0x40, v157
	v_add_u32_e32 v251, 0x200, v157
	v_add_u32_e32 v253, 0x240, v157
	global_store_dwordx4 v247, v[100:103], s[100:101]
	global_store_dwordx4 v249, v[108:111], s[100:101]
	global_store_dwordx4 v251, v[116:119], s[100:101]
	global_store_dwordx4 v253, v[124:127], s[100:101]
	s_add_u32 s100, s100, 0x10000
	s_addc_u32 s101, s101, 0
	global_store_dwordx4 v247, v[120:123], s[100:101]
	global_store_dwordx4 v249, v[128:131], s[100:101]
	global_store_dwordx4 v251, v[112:115], s[100:101]
	global_store_dwordx4 v253, v[104:107], s[100:101]
	s_add_u32 s100, s100, 0x10000
	s_addc_u32 s101, s101, 0
	global_store_dwordx4 v247, v[96:99], s[100:101]
	global_store_dwordx4 v249, v[92:95], s[100:101]
	global_store_dwordx4 v251, v[88:91], s[100:101]
	global_store_dwordx4 v253, v[84:87], s[100:101]
	s_add_u32 s100, s100, 0x10000
	s_addc_u32 s101, s101, 0
	global_store_dwordx4 v247, v[80:83], s[100:101]
	global_store_dwordx4 v249, v[76:79], s[100:101]
	global_store_dwordx4 v251, v[72:75], s[100:101]
	global_store_dwordx4 v253, v[68:71], s[100:101]
	s_add_u32 s100, s100, 0x50000
	s_addc_u32 s101, s101, 0
	global_store_dwordx4 v247, v[64:67], s[100:101]
	global_store_dwordx4 v249, v[60:63], s[100:101]
	global_store_dwordx4 v251, v[56:59], s[100:101]
	global_store_dwordx4 v253, v[52:55], s[100:101]
	s_add_u32 s100, s100, 0x10000
	s_addc_u32 s101, s101, 0
	global_store_dwordx4 v247, v[48:51], s[100:101]
	global_store_dwordx4 v249, v[44:47], s[100:101]
	global_store_dwordx4 v251, v[40:43], s[100:101]
	global_store_dwordx4 v253, v[36:39], s[100:101]
	s_add_u32 s100, s100, 0x10000
	s_addc_u32 s101, s101, 0
	global_store_dwordx4 v247, v[32:35], s[100:101]
	global_store_dwordx4 v249, v[28:31], s[100:101]
	global_store_dwordx4 v251, v[24:27], s[100:101]
	global_store_dwordx4 v253, v[20:23], s[100:101]
	s_add_u32 s100, s100, 0x10000
	s_addc_u32 s101, s101, 0
	global_store_dwordx4 v247, v[16:19], s[100:101]
	global_store_dwordx4 v249, v[12:15], s[100:101]
	global_store_dwordx4 v251, v[8:11], s[100:101]
	global_store_dwordx4 v253, v[4:7], s[100:101]

; __device__ __forceinline__ unsigned pk2(float lo, float hi) { unsigned r; asm("v_cvt_pk_bf16_f32 %0, %1, %2" : "=v"(r) : "v"(lo), "v"(hi)); return r; }
;     __device__ __forceinline__ void fused(f32x4 (&acc)[2][2][4][2], const Unit& u, int wr, int wc, int fr, int fq, LAS unsigned char* lds, int wid, int lane) const {
;     ...
; #pragma unroll
;             for (int ai = 0; ai < 2; ++ai)
; #pragma unroll
;                 for (int m = 0; m < 4; ++m) { const int r = ai * HALF + wr * 64 + m * 16 + fr; const float rs = S[r]; bf16_t* hp = h + (size_t)(u.pm * BM + r) * D + col0;
; #pragma unroll
;                     for (int bj = 0; bj < 2; ++bj)
; #pragma unroll
;                         for (int n = 0; n < 2; ++n) { const f32x4 gv = *(const f32x4*)(g2 + col0 + bj * HALF + n * 16); const f32x4 o = acc[ai][bj][m][n] * rs * gv;
;                             u32x2 w; w.x = pk2(o[0], o[1]); w.y = pk2(o[2], o[3]); *(u32x2*)(hp + bj * HALF + n * 16) = w; }
;                     asm volatile("" ::: "memory"); }
.LBB0_590:
	s_or_b64 exec, exec, s[8:9]
	s_add_i32 s4, s20, 0x400
	s_ashr_i32 s5, s4, 31
	s_lshl_b64 s[4:5], s[4:5], 2
	s_add_u32 s0, s0, s4
	s_addc_u32 s2, s2, s5
	s_and_b64 s[4:5], exec, s[24:25]
	s_cselect_b32 s2, 0, s2
	s_cselect_b32 s0, 0, s0
	v_mov_b32_e32 v132, s0
	v_mov_b32_e32 v133, s2
	s_waitcnt lgkmcnt(0)
	s_barrier
	s_mov_b32 s16, s0
	s_mov_b32 s17, s2
	v_lshlrev_b32_e32 v156, 2, v0
	v_lshlrev_b32_e32 v162, 1, v0
	v_lshl_add_u32 v162, v145, 11, v162
	s_lshl_b32 s100, s35, 19
	s_add_u32 s98, s10, s100
	s_addc_u32 s99, s11, 0
	global_load_dwordx4 v[132:135], v156, s[16:17] offset:0
	global_load_dwordx4 v[140:143], v156, s[16:17] offset:64
	global_load_dwordx4 v[148:151], v156, s[16:17] offset:512
	global_load_dwordx4 v[152:155], v156, s[16:17] offset:576
	ds_read_b32 v246, v3 offset:4096
	ds_read_b32 v248, v3 offset:4160
	ds_read_b32 v250, v3 offset:4224
	ds_read_b32 v252, v3 offset:4288
	s_waitcnt lgkmcnt(3)
	v_mul_f32_e32 v100, v100, v246
	v_mul_f32_e32 v101, v101, v246
	v_mul_f32_e32 v102, v102, v246
	v_mul_f32_e32 v103, v103, v246
	s_waitcnt vmcnt(0)
	v_mul_f32_e32 v100, v132, v100
	v_mul_f32_e32 v101, v133, v101
	v_mul_f32_e32 v102, v134, v102
	v_mul_f32_e32 v103, v135, v103
	v_cvt_pk_bf16_f32 v100, v100, v101
	v_cvt_pk_bf16_f32 v101, v102, v103
	global_store_dwordx2 v162, v[100:101], s[98:99] offset:0
	v_mul_f32_e32 v108, v108, v246
	v_mul_f32_e32 v109, v109, v246
	v_mul_f32_e32 v110, v110, v246
	v_mul_f32_e32 v111, v111, v246
	v_mul_f32_e32 v108, v140, v108
	v_mul_f32_e32 v109, v141, v109
	v_mul_f32_e32 v110, v142, v110
	v_mul_f32_e32 v111, v143, v111
	v_cvt_pk_bf16_f32 v108, v108, v109
	v_cvt_pk_bf16_f32 v109, v110, v111
	global_store_dwordx2 v162, v[108:109], s[98:99] offset:32
	v_mul_f32_e32 v116, v116, v246
	v_mul_f32_e32 v117, v117, v246
	v_mul_f32_e32 v118, v118, v246
	v_mul_f32_e32 v119, v119, v246
	v_mul_f32_e32 v116, v148, v116
	v_mul_f32_e32 v117, v149, v117
	v_mul_f32_e32 v118, v150, v118
	v_mul_f32_e32 v119, v151, v119
	v_cvt_pk_bf16_f32 v116, v116, v117
	v_cvt_pk_bf16_f32 v117, v118, v119
	global_store_dwordx2 v162, v[116:117], s[98:99] offset:256
	v_mul_f32_e32 v124, v124, v246
	v_mul_f32_e32 v125, v125, v246
	v_mul_f32_e32 v126, v126, v246
	v_mul_f32_e32 v127, v127, v246
	v_mul_f32_e32 v124, v152, v124
	v_mul_f32_e32 v125, v153, v125
	v_mul_f32_e32 v126, v154, v126
	v_mul_f32_e32 v127, v155, v127
	v_cvt_pk_bf16_f32 v124, v124, v125
	v_cvt_pk_bf16_f32 v125, v126, v127
	global_store_dwordx2 v162, v[124:125], s[98:99] offset:288
	s_waitcnt lgkmcnt(2)
	s_add_u32 s98, s98, 0x8000
	s_addc_u32 s99, s99, 0
	v_mul_f32_e32 v120, v120, v248
	v_mul_f32_e32 v121, v121, v248
	v_mul_f32_e32 v122, v122, v248
	v_mul_f32_e32 v123, v123, v248
	v_mul_f32_e32 v120, v132, v120
	v_mul_f32_e32 v121, v133, v121
	v_mul_f32_e32 v122, v134, v122
	v_mul_f32_e32 v123, v135, v123
	v_cvt_pk_bf16_f32 v120, v120, v121
	v_cvt_pk_bf16_f32 v121, v122, v123
	global_store_dwordx2 v162, v[120:121], s[98:99] offset:0
	v_mul_f32_e32 v128, v128, v248
	v_mul_f32_e32 v129, v129, v248
	v_mul_f32_e32 v130, v130, v248
	v_mul_f32_e32 v131, v131, v248
	v_mul_f32_e32 v128, v140, v128
	v_mul_f32_e32 v129, v141, v129
	v_mul_f32_e32 v130, v142, v130
	v_mul_f32_e32 v131, v143, v131
	v_cvt_pk_bf16_f32 v128, v128, v129
	v_cvt_pk_bf16_f32 v129, v130, v131
	global_store_dwordx2 v162, v[128:129], s[98:99] offset:32
	v_mul_f32_e32 v112, v112, v248
	v_mul_f32_e32 v113, v113, v248
	v_mul_f32_e32 v114, v114, v248
	v_mul_f32_e32 v115, v115, v248
	v_mul_f32_e32 v112, v148, v112
	v_mul_f32_e32 v113, v149, v113
	v_mul_f32_e32 v114, v150, v114
	v_mul_f32_e32 v115, v151, v115
	v_cvt_pk_bf16_f32 v112, v112, v113
	v_cvt_pk_bf16_f32 v113, v114, v115
	global_store_dwordx2 v162, v[112:113], s[98:99] offset:256
	v_mul_f32_e32 v104, v104, v248
	v_mul_f32_e32 v105, v105, v248
	v_mul_f32_e32 v106, v106, v248
	v_mul_f32_e32 v107, v107, v248
	v_mul_f32_e32 v104, v152, v104
	v_mul_f32_e32 v105, v153, v105
	v_mul_f32_e32 v106, v154, v106
	v_mul_f32_e32 v107, v155, v107
	v_cvt_pk_bf16_f32 v104, v104, v105
	v_cvt_pk_bf16_f32 v105, v106, v107
	global_store_dwordx2 v162, v[104:105], s[98:99] offset:288
	s_waitcnt lgkmcnt(1)
	s_add_u32 s98, s98, 0x8000
	s_addc_u32 s99, s99, 0
	v_mul_f32_e32 v96, v96, v250
	v_mul_f32_e32 v97, v97, v250
	v_mul_f32_e32 v98, v98, v250
	v_mul_f32_e32 v99, v99, v250
	v_mul_f32_e32 v96, v132, v96
	v_mul_f32_e32 v97, v133, v97
	v_mul_f32_e32 v98, v134, v98
	v_mul_f32_e32 v99, v135, v99
	v_cvt_pk_bf16_f32 v96, v96, v97
	v_cvt_pk_bf16_f32 v97, v98, v99
	global_store_dwordx2 v162, v[96:97], s[98:99] offset:0
	v_mul_f32_e32 v92, v92, v250
	v_mul_f32_e32 v93, v93, v250
	v_mul_f32_e32 v94, v94, v250
	v_mul_f32_e32 v95, v95, v250
	v_mul_f32_e32 v92, v140, v92
	v_mul_f32_e32 v93, v141, v93
	v_mul_f32_e32 v94, v142, v94
	v_mul_f32_e32 v95, v143, v95
	v_cvt_pk_bf16_f32 v92, v92, v93
	v_cvt_pk_bf16_f32 v93, v94, v95
	global_store_dwordx2 v162, v[92:93], s[98:99] offset:32
	v_mul_f32_e32 v88, v88, v250
	v_mul_f32_e32 v89, v89, v250
	v_mul_f32_e32 v90, v90, v250
	v_mul_f32_e32 v91, v91, v250
	v_mul_f32_e32 v88, v148, v88
	v_mul_f32_e32 v89, v149, v89
	v_mul_f32_e32 v90, v150, v90
	v_mul_f32_e32 v91, v151, v91
	v_cvt_pk_bf16_f32 v88, v88, v89
	v_cvt_pk_bf16_f32 v89, v90, v91
	global_store_dwordx2 v162, v[88:89], s[98:99] offset:256
	v_mul_f32_e32 v84, v84, v250
	v_mul_f32_e32 v85, v85, v250
	v_mul_f32_e32 v86, v86, v250
	v_mul_f32_e32 v87, v87, v250
	v_mul_f32_e32 v84, v152, v84
	v_mul_f32_e32 v85, v153, v85
	v_mul_f32_e32 v86, v154, v86
	v_mul_f32_e32 v87, v155, v87
	v_cvt_pk_bf16_f32 v84, v84, v85
	v_cvt_pk_bf16_f32 v85, v86, v87
	global_store_dwordx2 v162, v[84:85], s[98:99] offset:288
	s_waitcnt lgkmcnt(0)
; __device__ __forceinline__ unsigned pk2(float lo, float hi) { unsigned r; asm("v_cvt_pk_bf16_f32 %0, %1, %2" : "=v"(r) : "v"(lo), "v"(hi)); return r; }
;     __device__ __forceinline__ void fused(f32x4 (&acc)[2][2][4][2], const Unit& u, int wr, int wc, int fr, int fq, LAS unsigned char* lds, int wid, int lane) const {
;     ...
; #pragma unroll
;             for (int ai = 0; ai < 2; ++ai)
; #pragma unroll
;                 for (int m = 0; m < 4; ++m) { const int r = ai * HALF + wr * 64 + m * 16 + fr; const float rs = S[r]; bf16_t* hp = h + (size_t)(u.pm * BM + r) * D + col0;
; #pragma unroll
;                     for (int bj = 0; bj < 2; ++bj)
; #pragma unroll
;                         for (int n = 0; n < 2; ++n) { const f32x4 gv = *(const f32x4*)(g2 + col0 + bj * HALF + n * 16); const f32x4 o = acc[ai][bj][m][n] * rs * gv;
;                             u32x2 w; w.x = pk2(o[0], o[1]); w.y = pk2(o[2], o[3]); *(u32x2*)(hp + bj * HALF + n * 16) = w; }
;                     asm volatile("" ::: "memory"); }
	s_add_u32 s98, s98, 0x8000
	s_addc_u32 s99, s99, 0
	v_mul_f32_e32 v80, v80, v252
	v_mul_f32_e32 v81, v81, v252
	v_mul_f32_e32 v82, v82, v252
	v_mul_f32_e32 v83, v83, v252
	v_mul_f32_e32 v80, v132, v80
	v_mul_f32_e32 v81, v133, v81
	v_mul_f32_e32 v82, v134, v82
	v_mul_f32_e32 v83, v135, v83
	v_cvt_pk_bf16_f32 v80, v80, v81
	v_cvt_pk_bf16_f32 v81, v82, v83
	global_store_dwordx2 v162, v[80:81], s[98:99] offset:0
	v_mul_f32_e32 v76, v76, v252
	v_mul_f32_e32 v77, v77, v252
	v_mul_f32_e32 v78, v78, v252
	v_mul_f32_e32 v79, v79, v252
	v_mul_f32_e32 v76, v140, v76
	v_mul_f32_e32 v77, v141, v77
	v_mul_f32_e32 v78, v142, v78
	v_mul_f32_e32 v79, v143, v79
	v_cvt_pk_bf16_f32 v76, v76, v77
	v_cvt_pk_bf16_f32 v77, v78, v79
	global_store_dwordx2 v162, v[76:77], s[98:99] offset:32
	v_mul_f32_e32 v72, v72, v252
	v_mul_f32_e32 v73, v73, v252
	v_mul_f32_e32 v74, v74, v252
	v_mul_f32_e32 v75, v75, v252
	v_mul_f32_e32 v72, v148, v72
	v_mul_f32_e32 v73, v149, v73
	v_mul_f32_e32 v74, v150, v74
	v_mul_f32_e32 v75, v151, v75
	v_cvt_pk_bf16_f32 v72, v72, v73
	v_cvt_pk_bf16_f32 v73, v74, v75
	global_store_dwordx2 v162, v[72:73], s[98:99] offset:256
	v_mul_f32_e32 v68, v68, v252
	v_mul_f32_e32 v69, v69, v252
	v_mul_f32_e32 v70, v70, v252
	v_mul_f32_e32 v71, v71, v252
	v_mul_f32_e32 v68, v152, v68
	v_mul_f32_e32 v69, v153, v69
	v_mul_f32_e32 v70, v154, v70
	v_mul_f32_e32 v71, v155, v71
	v_cvt_pk_bf16_f32 v68, v68, v69
	v_cvt_pk_bf16_f32 v69, v70, v71
	global_store_dwordx2 v162, v[68:69], s[98:99] offset:288
	ds_read_b32 v246, v3 offset:4608
	ds_read_b32 v248, v3 offset:4672
	ds_read_b32 v250, v3 offset:4736
	ds_read_b32 v252, v3 offset:4800
	s_waitcnt lgkmcnt(3)
	s_add_u32 s98, s98, 0x28000
	s_addc_u32 s99, s99, 0
	v_mul_f32_e32 v64, v64, v246
	v_mul_f32_e32 v65, v65, v246
	v_mul_f32_e32 v66, v66, v246
	v_mul_f32_e32 v67, v67, v246
	v_mul_f32_e32 v64, v132, v64
	v_mul_f32_e32 v65, v133, v65
	v_mul_f32_e32 v66, v134, v66
	v_mul_f32_e32 v67, v135, v67
	v_cvt_pk_bf16_f32 v64, v64, v65
	v_cvt_pk_bf16_f32 v65, v66, v67
	global_store_dwordx2 v162, v[64:65], s[98:99] offset:0
	v_mul_f32_e32 v60, v60, v246
	v_mul_f32_e32 v61, v61, v246
	v_mul_f32_e32 v62, v62, v246
	v_mul_f32_e32 v63, v63, v246
	v_mul_f32_e32 v60, v140, v60
	v_mul_f32_e32 v61, v141, v61
	v_mul_f32_e32 v62, v142, v62
	v_mul_f32_e32 v63, v143, v63
	v_cvt_pk_bf16_f32 v60, v60, v61
	v_cvt_pk_bf16_f32 v61, v62, v63
	global_store_dwordx2 v162, v[60:61], s[98:99] offset:32
	v_mul_f32_e32 v56, v56, v246
	v_mul_f32_e32 v57, v57, v246
	v_mul_f32_e32 v58, v58, v246
	v_mul_f32_e32 v59, v59, v246
	v_mul_f32_e32 v56, v148, v56
	v_mul_f32_e32 v57, v149, v57
	v_mul_f32_e32 v58, v150, v58
	v_mul_f32_e32 v59, v151, v59
	v_cvt_pk_bf16_f32 v56, v56, v57
	v_cvt_pk_bf16_f32 v57, v58, v59
	global_store_dwordx2 v162, v[56:57], s[98:99] offset:256
	v_mul_f32_e32 v52, v52, v246
	v_mul_f32_e32 v53, v53, v246
	v_mul_f32_e32 v54, v54, v246
	v_mul_f32_e32 v55, v55, v246
	v_mul_f32_e32 v52, v152, v52
	v_mul_f32_e32 v53, v153, v53
	v_mul_f32_e32 v54, v154, v54
	v_mul_f32_e32 v55, v155, v55
	v_cvt_pk_bf16_f32 v52, v52, v53
	v_cvt_pk_bf16_f32 v53, v54, v55
	global_store_dwordx2 v162, v[52:53], s[98:99] offset:288
	s_waitcnt lgkmcnt(2)
; __device__ __forceinline__ unsigned pk2(float lo, float hi) { unsigned r; asm("v_cvt_pk_bf16_f32 %0, %1, %2" : "=v"(r) : "v"(lo), "v"(hi)); return r; }
;     __device__ __forceinline__ void fused(f32x4 (&acc)[2][2][4][2], const Unit& u, int wr, int wc, int fr, int fq, LAS unsigned char* lds, int wid, int lane) const {
;     ...
; #pragma unroll
;             for (int ai = 0; ai < 2; ++ai)
; #pragma unroll
;                 for (int m = 0; m < 4; ++m) { const int r = ai * HALF + wr * 64 + m * 16 + fr; const float rs = S[r]; bf16_t* hp = h + (size_t)(u.pm * BM + r) * D + col0;
; #pragma unroll
;                     for (int bj = 0; bj < 2; ++bj)
; #pragma unroll
;                         for (int n = 0; n < 2; ++n) { const f32x4 gv = *(const f32x4*)(g2 + col0 + bj * HALF + n * 16); const f32x4 o = acc[ai][bj][m][n] * rs * gv;
;                             u32x2 w; w.x = pk2(o[0], o[1]); w.y = pk2(o[2], o[3]); *(u32x2*)(hp + bj * HALF + n * 16) = w; }
;                     asm volatile("" ::: "memory"); }
	s_add_u32 s98, s98, 0x8000
	s_addc_u32 s99, s99, 0
	v_mul_f32_e32 v48, v48, v248
	v_mul_f32_e32 v49, v49, v248
	v_mul_f32_e32 v50, v50, v248
	v_mul_f32_e32 v51, v51, v248
	v_mul_f32_e32 v48, v132, v48
	v_mul_f32_e32 v49, v133, v49
	v_mul_f32_e32 v50, v134, v50
	v_mul_f32_e32 v51, v135, v51
	v_cvt_pk_bf16_f32 v48, v48, v49
	v_cvt_pk_bf16_f32 v49, v50, v51
	global_store_dwordx2 v162, v[48:49], s[98:99] offset:0
	v_mul_f32_e32 v44, v44, v248
	v_mul_f32_e32 v45, v45, v248
	v_mul_f32_e32 v46, v46, v248
	v_mul_f32_e32 v47, v47, v248
	v_mul_f32_e32 v44, v140, v44
	v_mul_f32_e32 v45, v141, v45
	v_mul_f32_e32 v46, v142, v46
	v_mul_f32_e32 v47, v143, v47
	v_cvt_pk_bf16_f32 v44, v44, v45
	v_cvt_pk_bf16_f32 v45, v46, v47
	global_store_dwordx2 v162, v[44:45], s[98:99] offset:32
	v_mul_f32_e32 v40, v40, v248
	v_mul_f32_e32 v41, v41, v248
	v_mul_f32_e32 v42, v42, v248
	v_mul_f32_e32 v43, v43, v248
	v_mul_f32_e32 v40, v148, v40
	v_mul_f32_e32 v41, v149, v41
	v_mul_f32_e32 v42, v150, v42
	v_mul_f32_e32 v43, v151, v43
	v_cvt_pk_bf16_f32 v40, v40, v41
	v_cvt_pk_bf16_f32 v41, v42, v43
	global_store_dwordx2 v162, v[40:41], s[98:99] offset:256
	v_mul_f32_e32 v36, v36, v248
	v_mul_f32_e32 v37, v37, v248
	v_mul_f32_e32 v38, v38, v248
	v_mul_f32_e32 v39, v39, v248
	v_mul_f32_e32 v36, v152, v36
	v_mul_f32_e32 v37, v153, v37
	v_mul_f32_e32 v38, v154, v38
	v_mul_f32_e32 v39, v155, v39
	v_cvt_pk_bf16_f32 v36, v36, v37
	v_cvt_pk_bf16_f32 v37, v38, v39
	global_store_dwordx2 v162, v[36:37], s[98:99] offset:288
	s_waitcnt lgkmcnt(1)
	s_add_u32 s98, s98, 0x8000
	s_addc_u32 s99, s99, 0
	v_mul_f32_e32 v32, v32, v250
	v_mul_f32_e32 v33, v33, v250
	v_mul_f32_e32 v34, v34, v250
	v_mul_f32_e32 v35, v35, v250
	v_mul_f32_e32 v32, v132, v32
	v_mul_f32_e32 v33, v133, v33
	v_mul_f32_e32 v34, v134, v34
	v_mul_f32_e32 v35, v135, v35
	v_cvt_pk_bf16_f32 v32, v32, v33
	v_cvt_pk_bf16_f32 v33, v34, v35
	global_store_dwordx2 v162, v[32:33], s[98:99] offset:0
	v_mul_f32_e32 v28, v28, v250
	v_mul_f32_e32 v29, v29, v250
	v_mul_f32_e32 v30, v30, v250
	v_mul_f32_e32 v31, v31, v250
	v_mul_f32_e32 v28, v140, v28
	v_mul_f32_e32 v29, v141, v29
	v_mul_f32_e32 v30, v142, v30
	v_mul_f32_e32 v31, v143, v31
	v_cvt_pk_bf16_f32 v28, v28, v29
	v_cvt_pk_bf16_f32 v29, v30, v31
	global_store_dwordx2 v162, v[28:29], s[98:99] offset:32
	v_mul_f32_e32 v24, v24, v250
	v_mul_f32_e32 v25, v25, v250
	v_mul_f32_e32 v26, v26, v250
	v_mul_f32_e32 v27, v27, v250
	v_mul_f32_e32 v24, v148, v24
	v_mul_f32_e32 v25, v149, v25
	v_mul_f32_e32 v26, v150, v26
	v_mul_f32_e32 v27, v151, v27
	v_cvt_pk_bf16_f32 v24, v24, v25
	v_cvt_pk_bf16_f32 v25, v26, v27
	global_store_dwordx2 v162, v[24:25], s[98:99] offset:256
	v_mul_f32_e32 v20, v20, v250
	v_mul_f32_e32 v21, v21, v250
	v_mul_f32_e32 v22, v22, v250
	v_mul_f32_e32 v23, v23, v250
	v_mul_f32_e32 v20, v152, v20
	v_mul_f32_e32 v21, v153, v21
	v_mul_f32_e32 v22, v154, v22
	v_mul_f32_e32 v23, v155, v23
	v_cvt_pk_bf16_f32 v20, v20, v21
	v_cvt_pk_bf16_f32 v21, v22, v23
	global_store_dwordx2 v162, v[20:21], s[98:99] offset:288
	s_waitcnt lgkmcnt(0)
	s_add_u32 s98, s98, 0x8000
	s_addc_u32 s99, s99, 0
	v_mul_f32_e32 v16, v16, v252
	v_mul_f32_e32 v17, v17, v252
	v_mul_f32_e32 v18, v18, v252
	v_mul_f32_e32 v19, v19, v252
	v_mul_f32_e32 v16, v132, v16
	v_mul_f32_e32 v17, v133, v17
	v_mul_f32_e32 v18, v134, v18
	v_mul_f32_e32 v19, v135, v19
	v_cvt_pk_bf16_f32 v16, v16, v17
	v_cvt_pk_bf16_f32 v17, v18, v19
	global_store_dwordx2 v162, v[16:17], s[98:99] offset:0
	v_mul_f32_e32 v12, v12, v252
	v_mul_f32_e32 v13, v13, v252
	v_mul_f32_e32 v14, v14, v252
	v_mul_f32_e32 v15, v15, v252
	v_mul_f32_e32 v12, v140, v12
	v_mul_f32_e32 v13, v141, v13
	v_mul_f32_e32 v14, v142, v14
	v_mul_f32_e32 v15, v143, v15
	v_cvt_pk_bf16_f32 v12, v12, v13
	v_cvt_pk_bf16_f32 v13, v14, v15
	global_store_dwordx2 v162, v[12:13], s[98:99] offset:32
	v_mul_f32_e32 v8, v8, v252
	v_mul_f32_e32 v9, v9, v252
	v_mul_f32_e32 v10, v10, v252
	v_mul_f32_e32 v11, v11, v252
	v_mul_f32_e32 v8, v148, v8
	v_mul_f32_e32 v9, v149, v9
	v_mul_f32_e32 v10, v150, v10
	v_mul_f32_e32 v11, v151, v11
	v_cvt_pk_bf16_f32 v8, v8, v9
	v_cvt_pk_bf16_f32 v9, v10, v11
	global_store_dwordx2 v162, v[8:9], s[98:99] offset:256
	v_mul_f32_e32 v4, v4, v252
	v_mul_f32_e32 v5, v5, v252
	v_mul_f32_e32 v6, v6, v252
	v_mul_f32_e32 v7, v7, v252
	v_mul_f32_e32 v4, v152, v4
	v_mul_f32_e32 v5, v153, v5
	v_mul_f32_e32 v6, v154, v6
	v_mul_f32_e32 v7, v155, v7
	v_cvt_pk_bf16_f32 v4, v4, v5
	v_cvt_pk_bf16_f32 v5, v6, v7
	global_store_dwordx2 v162, v[4:5], s[98:99] offset:288

; __device__ __forceinline__ void phase0(const Params& p, LAS unsigned char* lds) {
;     ...
;     for (int i = gt; i < 1024; i += nth) p.spl[i] = log1pf(expf(-p.lam[i]));
.LBB0_728:
	v_lshl_add_u64 v[6:7], s[4:5], 0, v[4:5]
	global_load_dword v3, v[6:7], off
	s_mov_b32 s0, 0xbfb8aa3b
	v_add_u32_e32 v1, s28, v1
	v_cmp_lt_i32_e32 vcc, s10, v1
	s_or_b64 s[24:25], vcc, s[24:25]
	v_lshl_add_u64 v[6:7], s[6:7], 0, v[4:5]
	v_lshl_add_u64 v[4:5], v[4:5], 0, s[22:23]
	s_waitcnt vmcnt(0)
	v_mul_f32_e32 v8, 0xbfb8aa3b, v3
	v_fma_f32 v9, v3, s0, -v8
	v_rndne_f32_e32 v10, v8
	v_fmac_f32_e32 v9, 0xb2a5705f, v3
	v_sub_f32_e32 v8, v8, v10
	v_add_f32_e32 v8, v8, v9
	v_cvt_i32_f32_e32 v10, v10
	v_exp_f32_e32 v8, v8
	s_mov_b32 s0, 0x42ce8ed0
	v_cmp_nlt_f32_e32 vcc, s0, v3
	s_mov_b32 s0, 0xc2b17218
	v_ldexp_f32 v8, v8, v10
	v_cndmask_b32_e32 v8, 0, v8, vcc
	v_cmp_ngt_f32_e32 vcc, s0, v3
	s_mov_b32 s0, 0x3f2aaaab
	s_nop 0
	v_cndmask_b32_e32 v3, v213, v8, vcc
	v_add_f32_e32 v10, 1.0, v3
	v_add_f32_e32 v11, -1.0, v10
	v_frexp_mant_f32_e32 v12, v10
	v_cvt_f64_f32_e32 v[8:9], v10
	v_sub_f32_e32 v13, v11, v10
	v_frexp_exp_i32_f64_e32 v8, v[8:9]
	v_cmp_gt_f32_e32 vcc, s0, v12
	v_sub_f32_e32 v11, v3, v11
	v_add_f32_e32 v9, 1.0, v13
	v_subbrev_co_u32_e32 v8, vcc, 0, v8, vcc
	v_add_f32_e32 v9, v11, v9
	v_sub_u32_e32 v11, 0, v8
	v_ldexp_f32 v10, v10, v11
	v_add_f32_e32 v12, -1.0, v10
	v_add_f32_e32 v13, 1.0, v10
	v_ldexp_f32 v9, v9, v11
	v_add_f32_e32 v11, 1.0, v12
	v_add_f32_e32 v14, -1.0, v13
	v_sub_f32_e32 v11, v10, v11
	v_sub_f32_e32 v10, v10, v14
	v_add_f32_e32 v14, v9, v11
	v_add_f32_e32 v9, v9, v10
	v_add_f32_e32 v16, v13, v9
	v_rcp_f32_e32 v17, v16
	v_add_f32_e32 v11, v12, v14
	v_sub_f32_e32 v12, v12, v11
	v_sub_f32_e32 v10, v13, v16
	v_mul_f32_e32 v19, v11, v17
	v_add_f32_e32 v18, v14, v12
	v_mul_f32_e32 v12, v16, v19
	v_add_f32_e32 v9, v9, v10
	v_fma_f32 v14, v19, v16, -v12
	v_fmac_f32_e32 v14, v19, v9
	v_add_f32_e32 v10, v12, v14
	v_sub_f32_e32 v13, v11, v10
	v_mov_b32_e32 v15, v10
	v_pk_add_f32 v[10:11], v[10:11], v[12:13] neg_lo:[0,1] neg_hi:[0,1]
	v_cvt_f32_i32_e32 v8, v8
	v_pk_add_f32 v[10:11], v[10:11], v[14:15] neg_lo:[0,1] neg_hi:[0,1]
	s_mov_b32 s0, 0x3f317218
	v_add_f32_e32 v11, v18, v11
	v_add_f32_e32 v10, v10, v11
	v_add_f32_e32 v11, v13, v10
	v_mul_f32_e32 v15, v17, v11
	v_mul_f32_e32 v12, v16, v15
	v_sub_f32_e32 v13, v13, v11
	v_add_f32_e32 v20, v19, v15
	v_fma_f32 v14, v15, v16, -v12
	v_add_f32_e32 v18, v10, v13
	v_sub_f32_e32 v10, v20, v19
	v_fmac_f32_e32 v14, v15, v9
	v_sub_f32_e32 v9, v15, v10
	v_add_f32_e32 v10, v12, v14
	v_sub_f32_e32 v13, v11, v10
	v_mov_b32_e32 v15, v10
	v_pk_add_f32 v[10:11], v[10:11], v[12:13] neg_lo:[0,1] neg_hi:[0,1]
	v_cmp_neq_f32_e32 vcc, s78, v3
	v_pk_add_f32 v[10:11], v[10:11], v[14:15] neg_lo:[0,1] neg_hi:[0,1]
	s_nop 0
	v_add_f32_e32 v11, v18, v11
	v_add_f32_e32 v10, v10, v11
	v_add_f32_e32 v10, v13, v10
	v_mul_f32_e32 v10, v17, v10
	v_add_f32_e32 v9, v9, v10
	v_add_f32_e32 v10, v20, v9
	v_mul_f32_e32 v12, v10, v10
	v_sub_f32_e32 v13, v10, v20
	v_fmamk_f32 v14, v12, 0x3e9b6dac, v206
	v_sub_f32_e32 v13, v9, v13
	v_mul_f32_e32 v9, v10, v12
	v_fmaak_f32 v145, v12, v14, 0x3f2aaada
	v_ldexp_f32 v15, v13, 1
	v_mul_f32_e32 v12, v8, v144
	v_mul_f32_e32 v13, v9, v145
	v_ldexp_f32 v11, v10, 1
	v_fma_f32 v10, v8, s0, -v12
	v_fmac_f32_e32 v10, 0xb102e308, v8
	v_pk_add_f32 v[8:9], v[12:13], v[10:11]
	v_mov_b32_e32 v14, v12
	v_sub_f32_e32 v18, v9, v11
	v_pk_add_f32 v[16:17], v[8:9], v[12:13] neg_lo:[0,1] neg_hi:[0,1]
	v_sub_f32_e32 v12, v13, v18
	v_add_f32_e32 v15, v15, v12
	v_pk_add_f32 v[12:13], v[8:9], v[14:15]
	v_mov_b32_e32 v11, v8
	v_mov_b32_e32 v17, v13
	v_pk_add_f32 v[20:21], v[10:11], v[16:17] neg_lo:[0,1] neg_hi:[0,1]
	v_pk_add_f32 v[10:11], v[10:11], v[16:17]
	v_mov_b32_e32 v19, v8
	v_pk_add_f32 v[16:17], v[10:11], v[8:9] op_sel:[1,0] op_sel_hi:[0,1] neg_lo:[0,1] neg_hi:[0,1]
	v_mov_b32_e32 v18, v15
	v_mov_b32_e32 v14, v13
	v_mov_b32_e32 v15, v11
	v_pk_mov_b32 v[8:9], v[8:9], v[16:17] op_sel:[1,0]
	v_pk_add_f32 v[12:13], v[12:13], v[16:17] op_sel_hi:[1,0] neg_lo:[0,1] neg_hi:[0,1]
	v_pk_add_f32 v[8:9], v[14:15], v[8:9] neg_lo:[0,1] neg_hi:[0,1]
	v_mov_b32_e32 v12, v20
	v_pk_add_f32 v[8:9], v[18:19], v[8:9] neg_lo:[0,1] neg_hi:[0,1]
	v_mov_b32_e32 v21, v11
	v_pk_add_f32 v[12:13], v[12:13], v[8:9]
	s_mov_b32 s0, 0x33800000
	v_pk_add_f32 v[14:15], v[12:13], v[12:13] op_sel:[0,1] op_sel_hi:[1,0]
	s_nop 0
	v_pk_add_f32 v[10:11], v[10:11], v[14:15] op_sel:[1,0] op_sel_hi:[0,1]
	v_mov_b32_e32 v13, v10
	v_mov_b32_e32 v9, v14
	v_pk_add_f32 v[14:15], v[12:13], v[20:21] neg_lo:[0,1] neg_hi:[0,1]
	s_nop 0
	v_sub_f32_e32 v11, v12, v14
	v_pk_add_f32 v[8:9], v[8:9], v[14:15] neg_lo:[0,1] neg_hi:[0,1]
	v_sub_f32_e32 v11, v20, v11
	v_add_f32_e32 v8, v8, v11
	v_add_f32_e32 v8, v8, v9
	v_add_f32_e32 v8, v10, v8
	v_cndmask_b32_e32 v8, v213, v8, vcc
	v_cmp_lt_f32_e64 vcc, |v3|, s0
	s_nop 1
	v_cndmask_b32_e32 v3, v8, v3, vcc
	global_store_dword v[6:7], v3, off
	s_andn2_b64 exec, exec, s[24:25]
	s_cbranch_execnz .LBB0_728

; __device__ __forceinline__ int opaque_bid() { int t = blockIdx.x; asm volatile("" : "+s"(t)); return t; }
; __device__ __forceinline__ int opaque_gd() { int t = gridDim.x; asm volatile("" : "+s"(t)); return t; }
; __device__ __forceinline__ void norm_phase(const float* y, const float* gy, const float* xin, float* xo, const float* gn, bf16_t* h) {
;     ...
;     for (int row = opaque_bid() * 8 + wid; row < M; row += opaque_gd() * 8) {
;         f32x4 xv[4]; const float* xr = xin + (size_t)row * D + lane * 4;
; #pragma unroll
;         for (int i = 0; i < 4; ++i) xv[i] = *(const f32x4*)(xr + i * 256);
;     ...
;         if (h) {
;             float ss = 0.f;
; #pragma unroll
;             for (int i = 0; i < 4; ++i) ss += xv[i][0] * xv[i][0] + xv[i][1] * xv[i][1] + xv[i][2] * xv[i][2] + xv[i][3] * xv[i][3];
.LBB0_732:
	s_or_b64 exec, exec, s[22:23]
	v_mov_b32_e32 v1, v202
	s_mov_b32 s0, s91
	s_nop 0
	v_ashrrev_i32_e32 v0, 6, v1
	v_lshl_add_u32 v0, s0, 3, v0
	s_movk_i32 s0, 0x4000
	v_cmp_gt_i32_e32 vcc, s0, v0
	s_and_saveexec_b64 s[4:5], vcc
	s_cbranch_execz .LBB0_8
	s_cmp_lg_u32 s90, 0x100
	s_cbranch_scc1 .Lnorm0_slow
	s_cmp_eq_u64 s[18:19], 0
	s_cbranch_scc1 .Lnorm0_slow
	v_readlane_b32 s0, v255, 16
	v_readlane_b32 s1, v255, 17
	v_readlane_b32 s6, v255, 18
	v_readlane_b32 s7, v255, 19
	v_readfirstlane_b32 s8, v0
	v_lshlrev_b32_e32 v3, 4, v207
	v_lshlrev_b32_e32 v4, 3, v207
	v_xor_b32_e32 v44, 32, v207
	v_xor_b32_e32 v45, 16, v207
	v_xor_b32_e32 v46, 8, v207
	v_xor_b32_e32 v47, 4, v207
	v_xor_b32_e32 v5, 2, v207
	v_xor_b32_e32 v6, 1, v207
	v_lshlrev_b32_e32 v44, 2, v44
	v_lshlrev_b32_e32 v45, 2, v45
	v_lshlrev_b32_e32 v46, 2, v46
	v_lshlrev_b32_e32 v47, 2, v47
	v_lshlrev_b32_e32 v5, 2, v5
	v_lshlrev_b32_e32 v6, 2, v6
	s_lshl_b32 s9, s8, 12
	s_add_u32 s0, s0, s9
	s_addc_u32 s1, s1, 0
	s_lshl_b32 s9, s8, 11
	s_add_u32 s10, s18, s9
	s_addc_u32 s11, s19, 0
	global_load_dwordx4 v[12:15], v3, s[6:7] offset:0
	global_load_dwordx4 v[16:19], v3, s[6:7] offset:1024
	global_load_dwordx4 v[20:23], v3, s[6:7] offset:2048
	global_load_dwordx4 v[24:27], v3, s[6:7] offset:3072
	global_load_dwordx4 v[48:51], v3, s[0:1] offset:0
	global_load_dwordx4 v[52:55], v3, s[0:1] offset:1024
	global_load_dwordx4 v[56:59], v3, s[0:1] offset:2048
	global_load_dwordx4 v[60:63], v3, s[0:1] offset:3072
	s_add_u32 s0, s0, 0x800000
	s_addc_u32 s1, s1, 0
	global_load_dwordx4 v[64:67], v3, s[0:1] offset:0
	global_load_dwordx4 v[68:71], v3, s[0:1] offset:1024
	global_load_dwordx4 v[72:75], v3, s[0:1] offset:2048
	global_load_dwordx4 v[76:79], v3, s[0:1] offset:3072
	s_add_u32 s0, s0, 0x800000
	s_addc_u32 s1, s1, 0
	global_load_dwordx4 v[80:83], v3, s[0:1] offset:0
	global_load_dwordx4 v[84:87], v3, s[0:1] offset:1024
	global_load_dwordx4 v[88:91], v3, s[0:1] offset:2048
	global_load_dwordx4 v[92:95], v3, s[0:1] offset:3072
	s_add_u32 s0, s0, 0x800000
	s_addc_u32 s1, s1, 0
	global_load_dwordx4 v[96:99], v3, s[0:1] offset:0
	global_load_dwordx4 v[100:103], v3, s[0:1] offset:1024
	global_load_dwordx4 v[104:107], v3, s[0:1] offset:2048
	global_load_dwordx4 v[108:111], v3, s[0:1] offset:3072
	s_add_u32 s0, s0, 0x800000
	s_addc_u32 s1, s1, 0
	global_load_dwordx4 v[112:115], v3, s[0:1] offset:0
	global_load_dwordx4 v[116:119], v3, s[0:1] offset:1024
	global_load_dwordx4 v[120:123], v3, s[0:1] offset:2048
	global_load_dwordx4 v[124:127], v3, s[0:1] offset:3072
	s_add_u32 s0, s0, 0x800000
	s_addc_u32 s1, s1, 0
	global_load_dwordx4 v[128:131], v3, s[0:1] offset:0
	global_load_dwordx4 v[132:135], v3, s[0:1] offset:1024
	global_load_dwordx4 v[148:151], v3, s[0:1] offset:2048
	global_load_dwordx4 v[152:155], v3, s[0:1] offset:3072
	s_add_u32 s0, s0, 0x800000
	s_addc_u32 s1, s1, 0
	global_load_dwordx4 v[156:159], v3, s[0:1] offset:0
	global_load_dwordx4 v[160:163], v3, s[0:1] offset:1024
	global_load_dwordx4 v[164:167], v3, s[0:1] offset:2048
	global_load_dwordx4 v[168:171], v3, s[0:1] offset:3072
	s_add_u32 s0, s0, 0x800000
	s_addc_u32 s1, s1, 0
	global_load_dwordx4 v[172:175], v3, s[0:1] offset:0
	global_load_dwordx4 v[176:179], v3, s[0:1] offset:1024
	global_load_dwordx4 v[180:183], v3, s[0:1] offset:2048
	global_load_dwordx4 v[184:187], v3, s[0:1] offset:3072
	s_waitcnt vmcnt(28)
	v_mul_f32_e32 v36, v53, v53
	v_mul_f32_e32 v28, v49, v49
	v_mul_f32_e32 v7, v61, v61
	v_mul_f32_e32 v8, v57, v57
	v_fma_f32 v36, v52, v52, v36
	v_fma_f32 v28, v48, v48, v28
	v_fma_f32 v7, v60, v60, v7
	v_fma_f32 v8, v56, v56, v8
	v_fma_f32 v36, v54, v54, v36
	v_fma_f32 v28, v50, v50, v28
	v_fma_f32 v7, v62, v62, v7
	v_fma_f32 v8, v58, v58, v8
	v_fma_f32 v36, v55, v55, v36
	v_fma_f32 v28, v51, v51, v28
	v_fma_f32 v7, v63, v63, v7
	v_fma_f32 v8, v59, v59, v8
	v_add_f32_e32 v28, v36, v28
	v_add_f32_e32 v28, v8, v28
	v_add_f32_e32 v28, v7, v28
	s_waitcnt vmcnt(24)
	v_mul_f32_e32 v37, v69, v69
	v_mul_f32_e32 v29, v65, v65
	v_mul_f32_e32 v7, v77, v77
	v_mul_f32_e32 v8, v73, v73
	v_fma_f32 v37, v68, v68, v37
	v_fma_f32 v29, v64, v64, v29
	v_fma_f32 v7, v76, v76, v7
	v_fma_f32 v8, v72, v72, v8
	v_fma_f32 v37, v70, v70, v37
	v_fma_f32 v29, v66, v66, v29
	v_fma_f32 v7, v78, v78, v7
	v_fma_f32 v8, v74, v74, v8
	v_fma_f32 v37, v71, v71, v37
	v_fma_f32 v29, v67, v67, v29
	v_fma_f32 v7, v79, v79, v7
	v_fma_f32 v8, v75, v75, v8
	v_add_f32_e32 v29, v37, v29
	v_add_f32_e32 v29, v8, v29
	v_add_f32_e32 v29, v7, v29
	s_waitcnt vmcnt(20)
	v_mul_f32_e32 v38, v85, v85
	v_mul_f32_e32 v30, v81, v81
	v_mul_f32_e32 v7, v93, v93
	v_mul_f32_e32 v8, v89, v89
	v_fma_f32 v38, v84, v84, v38
	v_fma_f32 v30, v80, v80, v30
	v_fma_f32 v7, v92, v92, v7
	v_fma_f32 v8, v88, v88, v8
	v_fma_f32 v38, v86, v86, v38
	v_fma_f32 v30, v82, v82, v30
	v_fma_f32 v7, v94, v94, v7
	v_fma_f32 v8, v90, v90, v8
	v_fma_f32 v38, v87, v87, v38
	v_fma_f32 v30, v83, v83, v30
	v_fma_f32 v7, v95, v95, v7
	v_fma_f32 v8, v91, v91, v8
	v_add_f32_e32 v30, v38, v30
	v_add_f32_e32 v30, v8, v30
	v_add_f32_e32 v30, v7, v30
	s_waitcnt vmcnt(16)
	v_mul_f32_e32 v39, v101, v101
	v_mul_f32_e32 v31, v97, v97
	v_mul_f32_e32 v7, v109, v109
	v_mul_f32_e32 v8, v105, v105
	v_fma_f32 v39, v100, v100, v39
	v_fma_f32 v31, v96, v96, v31
	v_fma_f32 v7, v108, v108, v7
	v_fma_f32 v8, v104, v104, v8
	v_fma_f32 v39, v102, v102, v39
	v_fma_f32 v31, v98, v98, v31
	v_fma_f32 v7, v110, v110, v7
	v_fma_f32 v8, v106, v106, v8
	v_fma_f32 v39, v103, v103, v39
	v_fma_f32 v31, v99, v99, v31
	v_fma_f32 v7, v111, v111, v7
	v_fma_f32 v8, v107, v107, v8
	v_add_f32_e32 v31, v39, v31
	v_add_f32_e32 v31, v8, v31
	v_add_f32_e32 v31, v7, v31
	s_waitcnt vmcnt(12)
; __device__ __forceinline__ float wave_sum(float v) {
; #pragma unroll
;     for (int o = 32; o >= 1; o >>= 1) v += __shfl_xor(v, o);
;     return v;
; __device__ __forceinline__ void norm_phase(const float* y, const float* gy, const float* xin, float* xo, const float* gn, bf16_t* h) {
;     ...
;             for (int i = 0; i < 4; ++i) ss += xv[i][0] * xv[i][0] + xv[i][1] * xv[i][1] + xv[i][2] * xv[i][2] + xv[i][3] * xv[i][3];
;             ss = wave_sum(ss); const float rs = rsqrtf(ss * (1.f / 1024.f) + EPS);
	v_mul_f32_e32 v40, v117, v117
	v_mul_f32_e32 v32, v113, v113
	v_mul_f32_e32 v7, v125, v125
	v_mul_f32_e32 v8, v121, v121
	v_fma_f32 v40, v116, v116, v40
	v_fma_f32 v32, v112, v112, v32
	v_fma_f32 v7, v124, v124, v7
	v_fma_f32 v8, v120, v120, v8
	v_fma_f32 v40, v118, v118, v40
	v_fma_f32 v32, v114, v114, v32
	v_fma_f32 v7, v126, v126, v7
	v_fma_f32 v8, v122, v122, v8
	v_fma_f32 v40, v119, v119, v40
	v_fma_f32 v32, v115, v115, v32
	v_fma_f32 v7, v127, v127, v7
	v_fma_f32 v8, v123, v123, v8
	v_add_f32_e32 v32, v40, v32
	v_add_f32_e32 v32, v8, v32
	v_add_f32_e32 v32, v7, v32
	s_waitcnt vmcnt(8)
	v_mul_f32_e32 v41, v133, v133
	v_mul_f32_e32 v33, v129, v129
	v_mul_f32_e32 v7, v153, v153
	v_mul_f32_e32 v8, v149, v149
	v_fma_f32 v41, v132, v132, v41
	v_fma_f32 v33, v128, v128, v33
	v_fma_f32 v7, v152, v152, v7
	v_fma_f32 v8, v148, v148, v8
	v_fma_f32 v41, v134, v134, v41
	v_fma_f32 v33, v130, v130, v33
	v_fma_f32 v7, v154, v154, v7
	v_fma_f32 v8, v150, v150, v8
	v_fma_f32 v41, v135, v135, v41
	v_fma_f32 v33, v131, v131, v33
	v_fma_f32 v7, v155, v155, v7
	v_fma_f32 v8, v151, v151, v8
	v_add_f32_e32 v33, v41, v33
	v_add_f32_e32 v33, v8, v33
	v_add_f32_e32 v33, v7, v33
	s_waitcnt vmcnt(4)
	v_mul_f32_e32 v42, v161, v161
	v_mul_f32_e32 v34, v157, v157
	v_mul_f32_e32 v7, v169, v169
	v_mul_f32_e32 v8, v165, v165
	v_fma_f32 v42, v160, v160, v42
	v_fma_f32 v34, v156, v156, v34
	v_fma_f32 v7, v168, v168, v7
	v_fma_f32 v8, v164, v164, v8
	v_fma_f32 v42, v162, v162, v42
	v_fma_f32 v34, v158, v158, v34
	v_fma_f32 v7, v170, v170, v7
	v_fma_f32 v8, v166, v166, v8
	v_fma_f32 v42, v163, v163, v42
	v_fma_f32 v34, v159, v159, v34
	v_fma_f32 v7, v171, v171, v7
	v_fma_f32 v8, v167, v167, v8
	v_add_f32_e32 v34, v42, v34
	v_add_f32_e32 v34, v8, v34
	v_add_f32_e32 v34, v7, v34
	s_waitcnt vmcnt(0)
	v_mul_f32_e32 v43, v177, v177
	v_mul_f32_e32 v35, v173, v173
	v_mul_f32_e32 v7, v185, v185
	v_mul_f32_e32 v8, v181, v181
	v_fma_f32 v43, v176, v176, v43
	v_fma_f32 v35, v172, v172, v35
	v_fma_f32 v7, v184, v184, v7
	v_fma_f32 v8, v180, v180, v8
	v_fma_f32 v43, v178, v178, v43
	v_fma_f32 v35, v174, v174, v35
	v_fma_f32 v7, v186, v186, v7
	v_fma_f32 v8, v182, v182, v8
	v_fma_f32 v43, v179, v179, v43
	v_fma_f32 v35, v175, v175, v35
	v_fma_f32 v7, v187, v187, v7
	v_fma_f32 v8, v183, v183, v8
	v_add_f32_e32 v35, v43, v35
	v_add_f32_e32 v35, v8, v35
	v_add_f32_e32 v35, v7, v35
	ds_bpermute_b32 v36, v44, v28
	ds_bpermute_b32 v37, v44, v29
	ds_bpermute_b32 v38, v44, v30
	ds_bpermute_b32 v39, v44, v31
	ds_bpermute_b32 v40, v44, v32
	ds_bpermute_b32 v41, v44, v33
	ds_bpermute_b32 v42, v44, v34
	ds_bpermute_b32 v43, v44, v35
	s_waitcnt lgkmcnt(7)
	v_add_f32_e32 v28, v28, v36
	s_waitcnt lgkmcnt(6)
	v_add_f32_e32 v29, v29, v37
	s_waitcnt lgkmcnt(5)
	v_add_f32_e32 v30, v30, v38
	s_waitcnt lgkmcnt(4)
	v_add_f32_e32 v31, v31, v39
	s_waitcnt lgkmcnt(3)
	v_add_f32_e32 v32, v32, v40
	s_waitcnt lgkmcnt(2)
	v_add_f32_e32 v33, v33, v41
	s_waitcnt lgkmcnt(1)
	v_add_f32_e32 v34, v34, v42
	s_waitcnt lgkmcnt(0)
	v_add_f32_e32 v35, v35, v43
	ds_bpermute_b32 v36, v45, v28
	ds_bpermute_b32 v37, v45, v29
	ds_bpermute_b32 v38, v45, v30
	ds_bpermute_b32 v39, v45, v31
	ds_bpermute_b32 v40, v45, v32
	ds_bpermute_b32 v41, v45, v33
	ds_bpermute_b32 v42, v45, v34
	ds_bpermute_b32 v43, v45, v35
	s_waitcnt lgkmcnt(7)
	v_add_f32_e32 v28, v28, v36
	s_waitcnt lgkmcnt(6)
	v_add_f32_e32 v29, v29, v37
	s_waitcnt lgkmcnt(5)
	v_add_f32_e32 v30, v30, v38
	s_waitcnt lgkmcnt(4)
	v_add_f32_e32 v31, v31, v39
	s_waitcnt lgkmcnt(3)
	v_add_f32_e32 v32, v32, v40
	s_waitcnt lgkmcnt(2)
	v_add_f32_e32 v33, v33, v41
	s_waitcnt lgkmcnt(1)
	v_add_f32_e32 v34, v34, v42
	s_waitcnt lgkmcnt(0)
	v_add_f32_e32 v35, v35, v43
	ds_bpermute_b32 v36, v46, v28
	ds_bpermute_b32 v37, v46, v29
	ds_bpermute_b32 v38, v46, v30
	ds_bpermute_b32 v39, v46, v31
	ds_bpermute_b32 v40, v46, v32
	ds_bpermute_b32 v41, v46, v33
	ds_bpermute_b32 v42, v46, v34
	ds_bpermute_b32 v43, v46, v35
	s_waitcnt lgkmcnt(7)
	v_add_f32_e32 v28, v28, v36
	s_waitcnt lgkmcnt(6)
	v_add_f32_e32 v29, v29, v37
	s_waitcnt lgkmcnt(5)
	v_add_f32_e32 v30, v30, v38
	s_waitcnt lgkmcnt(4)
	v_add_f32_e32 v31, v31, v39
	s_waitcnt lgkmcnt(3)
	v_add_f32_e32 v32, v32, v40
	s_waitcnt lgkmcnt(2)
	v_add_f32_e32 v33, v33, v41
	s_waitcnt lgkmcnt(1)
	v_add_f32_e32 v34, v34, v42
	s_waitcnt lgkmcnt(0)
	v_add_f32_e32 v35, v35, v43
	ds_bpermute_b32 v36, v47, v28
	ds_bpermute_b32 v37, v47, v29
	ds_bpermute_b32 v38, v47, v30
	ds_bpermute_b32 v39, v47, v31
	ds_bpermute_b32 v40, v47, v32
	ds_bpermute_b32 v41, v47, v33
	ds_bpermute_b32 v42, v47, v34
	ds_bpermute_b32 v43, v47, v35
	s_waitcnt lgkmcnt(7)
	v_add_f32_e32 v28, v28, v36
	s_waitcnt lgkmcnt(6)
	v_add_f32_e32 v29, v29, v37
	s_waitcnt lgkmcnt(5)
	v_add_f32_e32 v30, v30, v38
	s_waitcnt lgkmcnt(4)
	v_add_f32_e32 v31, v31, v39
	s_waitcnt lgkmcnt(3)
	v_add_f32_e32 v32, v32, v40
	s_waitcnt lgkmcnt(2)
	v_add_f32_e32 v33, v33, v41
	s_waitcnt lgkmcnt(1)
	v_add_f32_e32 v34, v34, v42
	s_waitcnt lgkmcnt(0)
	v_add_f32_e32 v35, v35, v43
	ds_bpermute_b32 v36, v5, v28
	ds_bpermute_b32 v37, v5, v29
	ds_bpermute_b32 v38, v5, v30
	ds_bpermute_b32 v39, v5, v31
	ds_bpermute_b32 v40, v5, v32
	ds_bpermute_b32 v41, v5, v33
	ds_bpermute_b32 v42, v5, v34
	ds_bpermute_b32 v43, v5, v35
	s_waitcnt lgkmcnt(7)
	v_add_f32_e32 v28, v28, v36
	s_waitcnt lgkmcnt(6)
	v_add_f32_e32 v29, v29, v37
	s_waitcnt lgkmcnt(5)
	v_add_f32_e32 v30, v30, v38
	s_waitcnt lgkmcnt(4)
	v_add_f32_e32 v31, v31, v39
	s_waitcnt lgkmcnt(3)
	v_add_f32_e32 v32, v32, v40
	s_waitcnt lgkmcnt(2)
	v_add_f32_e32 v33, v33, v41
	s_waitcnt lgkmcnt(1)
	v_add_f32_e32 v34, v34, v42
	s_waitcnt lgkmcnt(0)
; __device__ __forceinline__ unsigned pk2(float lo, float hi) { unsigned r; asm("v_cvt_pk_bf16_f32 %0, %1, %2" : "=v"(r) : "v"(lo), "v"(hi)); return r; }
; __device__ __forceinline__ void norm_phase(const float* y, const float* gy, const float* xin, float* xo, const float* gn, bf16_t* h) {
;     ...
;             ss = wave_sum(ss); const float rs = rsqrtf(ss * (1.f / 1024.f) + EPS);
; #pragma unroll
;             for (int i = 0; i < 4; ++i) { const f32x4 gv = *(const f32x4*)(gn + lane * 4 + i * 256); const f32x4 o = xv[i] * rs * gv;
;                 u32x2 w; w.x = pk2(o[0], o[1]); w.y = pk2(o[2], o[3]); *(u32x2*)(h + (size_t)row * D + lane * 4 + i * 256) = w; }
	v_add_f32_e32 v35, v35, v43
	ds_bpermute_b32 v36, v6, v28
	ds_bpermute_b32 v37, v6, v29
	ds_bpermute_b32 v38, v6, v30
	ds_bpermute_b32 v39, v6, v31
	ds_bpermute_b32 v40, v6, v32
	ds_bpermute_b32 v41, v6, v33
	ds_bpermute_b32 v42, v6, v34
	ds_bpermute_b32 v43, v6, v35
	s_waitcnt lgkmcnt(7)
	v_add_f32_e32 v28, v28, v36
	s_waitcnt lgkmcnt(6)
	v_add_f32_e32 v29, v29, v37
	s_waitcnt lgkmcnt(5)
	v_add_f32_e32 v30, v30, v38
	s_waitcnt lgkmcnt(4)
	v_add_f32_e32 v31, v31, v39
	s_waitcnt lgkmcnt(3)
	v_add_f32_e32 v32, v32, v40
	s_waitcnt lgkmcnt(2)
	v_add_f32_e32 v33, v33, v41
	s_waitcnt lgkmcnt(1)
	v_add_f32_e32 v34, v34, v42
	s_waitcnt lgkmcnt(0)
	v_add_f32_e32 v35, v35, v43
	v_fmamk_f32 v28, v28, 0x3a800000, v204
	v_fmamk_f32 v29, v29, 0x3a800000, v204
	v_fmamk_f32 v30, v30, 0x3a800000, v204
	v_fmamk_f32 v31, v31, 0x3a800000, v204
	v_fmamk_f32 v32, v32, 0x3a800000, v204
	v_fmamk_f32 v33, v33, 0x3a800000, v204
	v_fmamk_f32 v34, v34, 0x3a800000, v204
	v_fmamk_f32 v35, v35, 0x3a800000, v204
	v_mul_f32_e32 v36, 0x4b800000, v28
	v_cmp_gt_f32_e32 vcc, s93, v28
	s_nop 1
	v_cndmask_b32_e32 v28, v28, v36, vcc
	v_rsq_f32_e32 v28, v28
	s_nop 0
	v_mul_f32_e32 v36, 0x45800000, v28
	v_cndmask_b32_e32 v214, v28, v36, vcc
	v_mul_f32_e32 v37, 0x4b800000, v29
	v_cmp_gt_f32_e32 vcc, s93, v29
	s_nop 1
	v_cndmask_b32_e32 v29, v29, v37, vcc
	v_rsq_f32_e32 v29, v29
	s_nop 0
	v_mul_f32_e32 v37, 0x45800000, v29
	v_cndmask_b32_e32 v216, v29, v37, vcc
	v_mul_f32_e32 v38, 0x4b800000, v30
	v_cmp_gt_f32_e32 vcc, s93, v30
	s_nop 1
	v_cndmask_b32_e32 v30, v30, v38, vcc
	v_rsq_f32_e32 v30, v30
	s_nop 0
	v_mul_f32_e32 v38, 0x45800000, v30
	v_cndmask_b32_e32 v218, v30, v38, vcc
	v_mul_f32_e32 v39, 0x4b800000, v31
	v_cmp_gt_f32_e32 vcc, s93, v31
	s_nop 1
	v_cndmask_b32_e32 v31, v31, v39, vcc
	v_rsq_f32_e32 v31, v31
	s_nop 0
	v_mul_f32_e32 v39, 0x45800000, v31
	v_cndmask_b32_e32 v220, v31, v39, vcc
	v_mul_f32_e32 v40, 0x4b800000, v32
	v_cmp_gt_f32_e32 vcc, s93, v32
	s_nop 1
	v_cndmask_b32_e32 v32, v32, v40, vcc
	v_rsq_f32_e32 v32, v32
	s_nop 0
	v_mul_f32_e32 v40, 0x45800000, v32
	v_cndmask_b32_e32 v222, v32, v40, vcc
	v_mul_f32_e32 v41, 0x4b800000, v33
	v_cmp_gt_f32_e32 vcc, s93, v33
	s_nop 1
	v_cndmask_b32_e32 v33, v33, v41, vcc
	v_rsq_f32_e32 v33, v33
	s_nop 0
	v_mul_f32_e32 v41, 0x45800000, v33
	v_cndmask_b32_e32 v224, v33, v41, vcc
	v_mul_f32_e32 v42, 0x4b800000, v34
	v_cmp_gt_f32_e32 vcc, s93, v34
	s_nop 1
	v_cndmask_b32_e32 v34, v34, v42, vcc
	v_rsq_f32_e32 v34, v34
	s_nop 0
	v_mul_f32_e32 v42, 0x45800000, v34
	v_cndmask_b32_e32 v226, v34, v42, vcc
	v_mul_f32_e32 v43, 0x4b800000, v35
	v_cmp_gt_f32_e32 vcc, s93, v35
	s_nop 1
	v_cndmask_b32_e32 v35, v35, v43, vcc
	v_rsq_f32_e32 v35, v35
	s_nop 0
	v_mul_f32_e32 v43, 0x45800000, v35
	v_cndmask_b32_e32 v228, v35, v43, vcc
	v_mul_f32_e32 v48, v48, v214
	v_mul_f32_e32 v49, v49, v214
	v_mul_f32_e32 v50, v50, v214
	v_mul_f32_e32 v51, v51, v214
	v_mul_f32_e32 v48, v12, v48
	v_mul_f32_e32 v49, v13, v49
	v_mul_f32_e32 v50, v14, v50
	v_mul_f32_e32 v51, v15, v51
	v_cvt_pk_bf16_f32 v48, v48, v49
	v_cvt_pk_bf16_f32 v49, v50, v51
	global_store_dwordx2 v4, v[48:49], s[10:11] offset:0
	v_mul_f32_e32 v52, v52, v214
	v_mul_f32_e32 v53, v53, v214
	v_mul_f32_e32 v54, v54, v214
	v_mul_f32_e32 v55, v55, v214
	v_mul_f32_e32 v52, v16, v52
	v_mul_f32_e32 v53, v17, v53
	v_mul_f32_e32 v54, v18, v54
	v_mul_f32_e32 v55, v19, v55
	v_cvt_pk_bf16_f32 v52, v52, v53
	v_cvt_pk_bf16_f32 v53, v54, v55
	global_store_dwordx2 v4, v[52:53], s[10:11] offset:512
	v_mul_f32_e32 v56, v56, v214
	v_mul_f32_e32 v57, v57, v214
	v_mul_f32_e32 v58, v58, v214
	v_mul_f32_e32 v59, v59, v214
	v_mul_f32_e32 v56, v20, v56
	v_mul_f32_e32 v57, v21, v57
	v_mul_f32_e32 v58, v22, v58
	v_mul_f32_e32 v59, v23, v59
	v_cvt_pk_bf16_f32 v56, v56, v57
	v_cvt_pk_bf16_f32 v57, v58, v59
	global_store_dwordx2 v4, v[56:57], s[10:11] offset:1024
	v_mul_f32_e32 v60, v60, v214
	v_mul_f32_e32 v61, v61, v214
	v_mul_f32_e32 v62, v62, v214
	v_mul_f32_e32 v63, v63, v214
	v_mul_f32_e32 v60, v24, v60
	v_mul_f32_e32 v61, v25, v61
	v_mul_f32_e32 v62, v26, v62
	v_mul_f32_e32 v63, v27, v63
	v_cvt_pk_bf16_f32 v60, v60, v61
	v_cvt_pk_bf16_f32 v61, v62, v63
	global_store_dwordx2 v4, v[60:61], s[10:11] offset:1536
	s_add_u32 s10, s10, 0x400000
	s_addc_u32 s11, s11, 0
	v_mul_f32_e32 v64, v64, v216
	v_mul_f32_e32 v65, v65, v216
	v_mul_f32_e32 v66, v66, v216
	v_mul_f32_e32 v67, v67, v216
	v_mul_f32_e32 v64, v12, v64
	v_mul_f32_e32 v65, v13, v65
	v_mul_f32_e32 v66, v14, v66
	v_mul_f32_e32 v67, v15, v67
	v_cvt_pk_bf16_f32 v64, v64, v65
	v_cvt_pk_bf16_f32 v65, v66, v67
	global_store_dwordx2 v4, v[64:65], s[10:11] offset:0
	v_mul_f32_e32 v68, v68, v216
	v_mul_f32_e32 v69, v69, v216
	v_mul_f32_e32 v70, v70, v216
	v_mul_f32_e32 v71, v71, v216
	v_mul_f32_e32 v68, v16, v68
	v_mul_f32_e32 v69, v17, v69
	v_mul_f32_e32 v70, v18, v70
	v_mul_f32_e32 v71, v19, v71
	v_cvt_pk_bf16_f32 v68, v68, v69
	v_cvt_pk_bf16_f32 v69, v70, v71
	global_store_dwordx2 v4, v[68:69], s[10:11] offset:512
	v_mul_f32_e32 v72, v72, v216
	v_mul_f32_e32 v73, v73, v216
	v_mul_f32_e32 v74, v74, v216
	v_mul_f32_e32 v75, v75, v216
	v_mul_f32_e32 v72, v20, v72
	v_mul_f32_e32 v73, v21, v73
	v_mul_f32_e32 v74, v22, v74
	v_mul_f32_e32 v75, v23, v75
	v_cvt_pk_bf16_f32 v72, v72, v73
	v_cvt_pk_bf16_f32 v73, v74, v75
	global_store_dwordx2 v4, v[72:73], s[10:11] offset:1024
	v_mul_f32_e32 v76, v76, v216
	v_mul_f32_e32 v77, v77, v216
	v_mul_f32_e32 v78, v78, v216
	v_mul_f32_e32 v79, v79, v216
	v_mul_f32_e32 v76, v24, v76
	v_mul_f32_e32 v77, v25, v77
	v_mul_f32_e32 v78, v26, v78
	v_mul_f32_e32 v79, v27, v79
	v_cvt_pk_bf16_f32 v76, v76, v77
	v_cvt_pk_bf16_f32 v77, v78, v79
; __device__ __forceinline__ unsigned pk2(float lo, float hi) { unsigned r; asm("v_cvt_pk_bf16_f32 %0, %1, %2" : "=v"(r) : "v"(lo), "v"(hi)); return r; }
; __device__ __forceinline__ void norm_phase(const float* y, const float* gy, const float* xin, float* xo, const float* gn, bf16_t* h) {
;     ...
; #pragma unroll
;             for (int i = 0; i < 4; ++i) { const f32x4 gv = *(const f32x4*)(gn + lane * 4 + i * 256); const f32x4 o = xv[i] * rs * gv;
;                 u32x2 w; w.x = pk2(o[0], o[1]); w.y = pk2(o[2], o[3]); *(u32x2*)(h + (size_t)row * D + lane * 4 + i * 256) = w; }
	global_store_dwordx2 v4, v[76:77], s[10:11] offset:1536
	s_add_u32 s10, s10, 0x400000
	s_addc_u32 s11, s11, 0
	v_mul_f32_e32 v80, v80, v218
	v_mul_f32_e32 v81, v81, v218
	v_mul_f32_e32 v82, v82, v218
	v_mul_f32_e32 v83, v83, v218
	v_mul_f32_e32 v80, v12, v80
	v_mul_f32_e32 v81, v13, v81
	v_mul_f32_e32 v82, v14, v82
	v_mul_f32_e32 v83, v15, v83
	v_cvt_pk_bf16_f32 v80, v80, v81
	v_cvt_pk_bf16_f32 v81, v82, v83
	global_store_dwordx2 v4, v[80:81], s[10:11] offset:0
	v_mul_f32_e32 v84, v84, v218
	v_mul_f32_e32 v85, v85, v218
	v_mul_f32_e32 v86, v86, v218
	v_mul_f32_e32 v87, v87, v218
	v_mul_f32_e32 v84, v16, v84
	v_mul_f32_e32 v85, v17, v85
	v_mul_f32_e32 v86, v18, v86
	v_mul_f32_e32 v87, v19, v87
	v_cvt_pk_bf16_f32 v84, v84, v85
	v_cvt_pk_bf16_f32 v85, v86, v87
	global_store_dwordx2 v4, v[84:85], s[10:11] offset:512
	v_mul_f32_e32 v88, v88, v218
	v_mul_f32_e32 v89, v89, v218
	v_mul_f32_e32 v90, v90, v218
	v_mul_f32_e32 v91, v91, v218
	v_mul_f32_e32 v88, v20, v88
	v_mul_f32_e32 v89, v21, v89
	v_mul_f32_e32 v90, v22, v90
	v_mul_f32_e32 v91, v23, v91
	v_cvt_pk_bf16_f32 v88, v88, v89
	v_cvt_pk_bf16_f32 v89, v90, v91
	global_store_dwordx2 v4, v[88:89], s[10:11] offset:1024
	v_mul_f32_e32 v92, v92, v218
	v_mul_f32_e32 v93, v93, v218
	v_mul_f32_e32 v94, v94, v218
	v_mul_f32_e32 v95, v95, v218
	v_mul_f32_e32 v92, v24, v92
	v_mul_f32_e32 v93, v25, v93
	v_mul_f32_e32 v94, v26, v94
	v_mul_f32_e32 v95, v27, v95
	v_cvt_pk_bf16_f32 v92, v92, v93
	v_cvt_pk_bf16_f32 v93, v94, v95
	global_store_dwordx2 v4, v[92:93], s[10:11] offset:1536
	s_add_u32 s10, s10, 0x400000
	s_addc_u32 s11, s11, 0
	v_mul_f32_e32 v96, v96, v220
	v_mul_f32_e32 v97, v97, v220
	v_mul_f32_e32 v98, v98, v220
	v_mul_f32_e32 v99, v99, v220
	v_mul_f32_e32 v96, v12, v96
	v_mul_f32_e32 v97, v13, v97
	v_mul_f32_e32 v98, v14, v98
	v_mul_f32_e32 v99, v15, v99
	v_cvt_pk_bf16_f32 v96, v96, v97
	v_cvt_pk_bf16_f32 v97, v98, v99
	global_store_dwordx2 v4, v[96:97], s[10:11] offset:0
	v_mul_f32_e32 v100, v100, v220
	v_mul_f32_e32 v101, v101, v220
	v_mul_f32_e32 v102, v102, v220
	v_mul_f32_e32 v103, v103, v220
	v_mul_f32_e32 v100, v16, v100
	v_mul_f32_e32 v101, v17, v101
	v_mul_f32_e32 v102, v18, v102
	v_mul_f32_e32 v103, v19, v103
	v_cvt_pk_bf16_f32 v100, v100, v101
	v_cvt_pk_bf16_f32 v101, v102, v103
	global_store_dwordx2 v4, v[100:101], s[10:11] offset:512
	v_mul_f32_e32 v104, v104, v220
	v_mul_f32_e32 v105, v105, v220
	v_mul_f32_e32 v106, v106, v220
	v_mul_f32_e32 v107, v107, v220
	v_mul_f32_e32 v104, v20, v104
	v_mul_f32_e32 v105, v21, v105
	v_mul_f32_e32 v106, v22, v106
	v_mul_f32_e32 v107, v23, v107
	v_cvt_pk_bf16_f32 v104, v104, v105
	v_cvt_pk_bf16_f32 v105, v106, v107
	global_store_dwordx2 v4, v[104:105], s[10:11] offset:1024
	v_mul_f32_e32 v108, v108, v220
	v_mul_f32_e32 v109, v109, v220
	v_mul_f32_e32 v110, v110, v220
	v_mul_f32_e32 v111, v111, v220
	v_mul_f32_e32 v108, v24, v108
	v_mul_f32_e32 v109, v25, v109
	v_mul_f32_e32 v110, v26, v110
	v_mul_f32_e32 v111, v27, v111
	v_cvt_pk_bf16_f32 v108, v108, v109
	v_cvt_pk_bf16_f32 v109, v110, v111
	global_store_dwordx2 v4, v[108:109], s[10:11] offset:1536
	s_add_u32 s10, s10, 0x400000
	s_addc_u32 s11, s11, 0
	v_mul_f32_e32 v112, v112, v222
	v_mul_f32_e32 v113, v113, v222
	v_mul_f32_e32 v114, v114, v222
	v_mul_f32_e32 v115, v115, v222
	v_mul_f32_e32 v112, v12, v112
	v_mul_f32_e32 v113, v13, v113
	v_mul_f32_e32 v114, v14, v114
	v_mul_f32_e32 v115, v15, v115
	v_cvt_pk_bf16_f32 v112, v112, v113
	v_cvt_pk_bf16_f32 v113, v114, v115
	global_store_dwordx2 v4, v[112:113], s[10:11] offset:0
	v_mul_f32_e32 v116, v116, v222
	v_mul_f32_e32 v117, v117, v222
	v_mul_f32_e32 v118, v118, v222
	v_mul_f32_e32 v119, v119, v222
	v_mul_f32_e32 v116, v16, v116
	v_mul_f32_e32 v117, v17, v117
	v_mul_f32_e32 v118, v18, v118
	v_mul_f32_e32 v119, v19, v119
	v_cvt_pk_bf16_f32 v116, v116, v117
	v_cvt_pk_bf16_f32 v117, v118, v119
	global_store_dwordx2 v4, v[116:117], s[10:11] offset:512
	v_mul_f32_e32 v120, v120, v222
	v_mul_f32_e32 v121, v121, v222
	v_mul_f32_e32 v122, v122, v222
	v_mul_f32_e32 v123, v123, v222
	v_mul_f32_e32 v120, v20, v120
	v_mul_f32_e32 v121, v21, v121
	v_mul_f32_e32 v122, v22, v122
	v_mul_f32_e32 v123, v23, v123
	v_cvt_pk_bf16_f32 v120, v120, v121
	v_cvt_pk_bf16_f32 v121, v122, v123
	global_store_dwordx2 v4, v[120:121], s[10:11] offset:1024
	v_mul_f32_e32 v124, v124, v222
	v_mul_f32_e32 v125, v125, v222
	v_mul_f32_e32 v126, v126, v222
	v_mul_f32_e32 v127, v127, v222
	v_mul_f32_e32 v124, v24, v124
	v_mul_f32_e32 v125, v25, v125
	v_mul_f32_e32 v126, v26, v126
	v_mul_f32_e32 v127, v27, v127
	v_cvt_pk_bf16_f32 v124, v124, v125
	v_cvt_pk_bf16_f32 v125, v126, v127
	global_store_dwordx2 v4, v[124:125], s[10:11] offset:1536
	s_add_u32 s10, s10, 0x400000
; __device__ __forceinline__ unsigned pk2(float lo, float hi) { unsigned r; asm("v_cvt_pk_bf16_f32 %0, %1, %2" : "=v"(r) : "v"(lo), "v"(hi)); return r; }
; __device__ __forceinline__ void norm_phase(const float* y, const float* gy, const float* xin, float* xo, const float* gn, bf16_t* h) {
;     ...
; #pragma unroll
;             for (int i = 0; i < 4; ++i) { const f32x4 gv = *(const f32x4*)(gn + lane * 4 + i * 256); const f32x4 o = xv[i] * rs * gv;
;                 u32x2 w; w.x = pk2(o[0], o[1]); w.y = pk2(o[2], o[3]); *(u32x2*)(h + (size_t)row * D + lane * 4 + i * 256) = w; }
	s_addc_u32 s11, s11, 0
	v_mul_f32_e32 v128, v128, v224
	v_mul_f32_e32 v129, v129, v224
	v_mul_f32_e32 v130, v130, v224
	v_mul_f32_e32 v131, v131, v224
	v_mul_f32_e32 v128, v12, v128
	v_mul_f32_e32 v129, v13, v129
	v_mul_f32_e32 v130, v14, v130
	v_mul_f32_e32 v131, v15, v131
	v_cvt_pk_bf16_f32 v128, v128, v129
	v_cvt_pk_bf16_f32 v129, v130, v131
	global_store_dwordx2 v4, v[128:129], s[10:11] offset:0
	v_mul_f32_e32 v132, v132, v224
	v_mul_f32_e32 v133, v133, v224
	v_mul_f32_e32 v134, v134, v224
	v_mul_f32_e32 v135, v135, v224
	v_mul_f32_e32 v132, v16, v132
	v_mul_f32_e32 v133, v17, v133
	v_mul_f32_e32 v134, v18, v134
	v_mul_f32_e32 v135, v19, v135
	v_cvt_pk_bf16_f32 v132, v132, v133
	v_cvt_pk_bf16_f32 v133, v134, v135
	global_store_dwordx2 v4, v[132:133], s[10:11] offset:512
	v_mul_f32_e32 v148, v148, v224
	v_mul_f32_e32 v149, v149, v224
	v_mul_f32_e32 v150, v150, v224
	v_mul_f32_e32 v151, v151, v224
	v_mul_f32_e32 v148, v20, v148
	v_mul_f32_e32 v149, v21, v149
	v_mul_f32_e32 v150, v22, v150
	v_mul_f32_e32 v151, v23, v151
	v_cvt_pk_bf16_f32 v148, v148, v149
	v_cvt_pk_bf16_f32 v149, v150, v151
	global_store_dwordx2 v4, v[148:149], s[10:11] offset:1024
	v_mul_f32_e32 v152, v152, v224
	v_mul_f32_e32 v153, v153, v224
	v_mul_f32_e32 v154, v154, v224
	v_mul_f32_e32 v155, v155, v224
	v_mul_f32_e32 v152, v24, v152
	v_mul_f32_e32 v153, v25, v153
	v_mul_f32_e32 v154, v26, v154
	v_mul_f32_e32 v155, v27, v155
	v_cvt_pk_bf16_f32 v152, v152, v153
	v_cvt_pk_bf16_f32 v153, v154, v155
	global_store_dwordx2 v4, v[152:153], s[10:11] offset:1536
	s_add_u32 s10, s10, 0x400000
	s_addc_u32 s11, s11, 0
	v_mul_f32_e32 v156, v156, v226
	v_mul_f32_e32 v157, v157, v226
	v_mul_f32_e32 v158, v158, v226
	v_mul_f32_e32 v159, v159, v226
	v_mul_f32_e32 v156, v12, v156
	v_mul_f32_e32 v157, v13, v157
	v_mul_f32_e32 v158, v14, v158
	v_mul_f32_e32 v159, v15, v159
	v_cvt_pk_bf16_f32 v156, v156, v157
	v_cvt_pk_bf16_f32 v157, v158, v159
	global_store_dwordx2 v4, v[156:157], s[10:11] offset:0
	v_mul_f32_e32 v160, v160, v226
	v_mul_f32_e32 v161, v161, v226
	v_mul_f32_e32 v162, v162, v226
	v_mul_f32_e32 v163, v163, v226
	v_mul_f32_e32 v160, v16, v160
	v_mul_f32_e32 v161, v17, v161
	v_mul_f32_e32 v162, v18, v162
	v_mul_f32_e32 v163, v19, v163
	v_cvt_pk_bf16_f32 v160, v160, v161
	v_cvt_pk_bf16_f32 v161, v162, v163
	global_store_dwordx2 v4, v[160:161], s[10:11] offset:512
	v_mul_f32_e32 v164, v164, v226
	v_mul_f32_e32 v165, v165, v226
	v_mul_f32_e32 v166, v166, v226
	v_mul_f32_e32 v167, v167, v226
	v_mul_f32_e32 v164, v20, v164
	v_mul_f32_e32 v165, v21, v165
	v_mul_f32_e32 v166, v22, v166
	v_mul_f32_e32 v167, v23, v167
	v_cvt_pk_bf16_f32 v164, v164, v165
	v_cvt_pk_bf16_f32 v165, v166, v167
	global_store_dwordx2 v4, v[164:165], s[10:11] offset:1024
	v_mul_f32_e32 v168, v168, v226
	v_mul_f32_e32 v169, v169, v226
	v_mul_f32_e32 v170, v170, v226
	v_mul_f32_e32 v171, v171, v226
	v_mul_f32_e32 v168, v24, v168
	v_mul_f32_e32 v169, v25, v169
	v_mul_f32_e32 v170, v26, v170
	v_mul_f32_e32 v171, v27, v171
	v_cvt_pk_bf16_f32 v168, v168, v169
	v_cvt_pk_bf16_f32 v169, v170, v171
	global_store_dwordx2 v4, v[168:169], s[10:11] offset:1536
	s_add_u32 s10, s10, 0x400000
	s_addc_u32 s11, s11, 0
	v_mul_f32_e32 v172, v172, v228
	v_mul_f32_e32 v173, v173, v228
	v_mul_f32_e32 v174, v174, v228
	v_mul_f32_e32 v175, v175, v228
	v_mul_f32_e32 v172, v12, v172
	v_mul_f32_e32 v173, v13, v173
	v_mul_f32_e32 v174, v14, v174
	v_mul_f32_e32 v175, v15, v175
	v_cvt_pk_bf16_f32 v172, v172, v173
	v_cvt_pk_bf16_f32 v173, v174, v175
	global_store_dwordx2 v4, v[172:173], s[10:11] offset:0
	v_mul_f32_e32 v176, v176, v228
	v_mul_f32_e32 v177, v177, v228
	v_mul_f32_e32 v178, v178, v228
	v_mul_f32_e32 v179, v179, v228
	v_mul_f32_e32 v176, v16, v176
	v_mul_f32_e32 v177, v17, v177
	v_mul_f32_e32 v178, v18, v178
	v_mul_f32_e32 v179, v19, v179
	v_cvt_pk_bf16_f32 v176, v176, v177
	v_cvt_pk_bf16_f32 v177, v178, v179
	global_store_dwordx2 v4, v[176:177], s[10:11] offset:512
	v_mul_f32_e32 v180, v180, v228
	v_mul_f32_e32 v181, v181, v228
	v_mul_f32_e32 v182, v182, v228
	v_mul_f32_e32 v183, v183, v228
	v_mul_f32_e32 v180, v20, v180
	v_mul_f32_e32 v181, v21, v181
	v_mul_f32_e32 v182, v22, v182
	v_mul_f32_e32 v183, v23, v183
	v_cvt_pk_bf16_f32 v180, v180, v181
	v_cvt_pk_bf16_f32 v181, v182, v183
	global_store_dwordx2 v4, v[180:181], s[10:11] offset:1024
	v_mul_f32_e32 v184, v184, v228
	v_mul_f32_e32 v185, v185, v228
	v_mul_f32_e32 v186, v186, v228
	v_mul_f32_e32 v187, v187, v228
	v_mul_f32_e32 v184, v24, v184
	v_mul_f32_e32 v185, v25, v185
	v_mul_f32_e32 v186, v26, v186
	v_mul_f32_e32 v187, v27, v187
	v_cvt_pk_bf16_f32 v184, v184, v185
	v_cvt_pk_bf16_f32 v185, v186, v187
	global_store_dwordx2 v4, v[184:185], s[10:11] offset:1536
	s_branch .LBB0_8

; __device__ __forceinline__ unsigned pk2(float lo, float hi) { unsigned r; asm("v_cvt_pk_bf16_f32 %0, %1, %2" : "=v"(r) : "v"(lo), "v"(hi)); return r; }
; __device__ __forceinline__ float bflo(unsigned w) { return __uint_as_float(w << 16); }
; __device__ __forceinline__ float bfhi(unsigned w) { return __uint_as_float(w & 0xffff0000u); }
; __device__ __forceinline__ int opaque_bid() { int t = blockIdx.x; asm volatile("" : "+s"(t)); return t; }
; __device__ __forceinline__ int opaque_gd() { int t = gridDim.x; asm volatile("" : "+s"(t)); return t; }
; __device__ __forceinline__ void norm_phase(const float* y, const float* gy, const float* xin, float* xo, const float* gn, bf16_t* h) {
;     ...
;     for (int row = opaque_bid() * 8 + wid; row < M; row += opaque_gd() * 8) {
;         f32x4 xv[4]; const float* xr = xin + (size_t)row * D + lane * 4;
; #pragma unroll
;         for (int i = 0; i < 4; ++i) xv[i] = *(const f32x4*)(xr + i * 256);
;         if (y) {
;             f32x4 yv[4]; const bf16_t* yr = (const bf16_t*)y + (size_t)row * D + lane * 4; float ss = 0.f;
; #pragma unroll
;             for (int i = 0; i < 4; ++i) { const u32x2 yw = *(const u32x2*)(yr + i * 256); yv[i] = (f32x4){bflo(yw.x), bfhi(yw.x), bflo(yw.y), bfhi(yw.y)}; ss += yv[i][0] * yv[i][0] + yv[i][1] * yv[i][1] + yv[i][2] * yv[i][2] + yv[i][3] * yv[i][3]; }
;             ss = wave_sum(ss); const float rs = rsqrtf(ss * (1.f / 1024.f) + EPS);
; #pragma unroll
;             for (int i = 0; i < 4; ++i) { const f32x4 gv = *(const f32x4*)(gy + lane * 4 + i * 256); xv[i] += yv[i] * rs * gv; }
;         }
;         if (xo) {
; #pragma unroll
;             for (int i = 0; i < 4; ++i) *(f32x4*)(xo + (size_t)row * D + lane * 4 + i * 256) = xv[i];
;         }
;         if (h) {
;             float ss = 0.f;
; #pragma unroll
;             for (int i = 0; i < 4; ++i) ss += xv[i][0] * xv[i][0] + xv[i][1] * xv[i][1] + xv[i][2] * xv[i][2] + xv[i][3] * xv[i][3];
;             ss = wave_sum(ss); const float rs = rsqrtf(ss * (1.f / 1024.f) + EPS);
; #pragma unroll
;             for (int i = 0; i < 4; ++i) { const f32x4 gv = *(const f32x4*)(gn + lane * 4 + i * 256); const f32x4 o = xv[i] * rs * gv;
;                 u32x2 w; w.x = pk2(o[0], o[1]); w.y = pk2(o[2], o[3]); *(u32x2*)(h + (size_t)row * D + lane * 4 + i * 256) = w; }
.LBB0_735:
	s_andn2_b64 vcc, exec, s[8:9]
	s_cbranch_vccnz .LBB0_734
	v_ashrrev_i32_e32 v1, 31, v0
	v_lshlrev_b64 v[10:11], 12, v[0:1]
	v_lshl_add_u64 v[22:23], v[4:5], 0, v[10:11]
	global_load_dwordx4 v[10:13], v[22:23], off offset:1024
	global_load_dwordx4 v[14:17], v[22:23], off
	global_load_dwordx4 v[18:21], v[22:23], off offset:3072
	s_nop 0
	global_load_dwordx4 v[22:25], v[22:23], off offset:2048
	v_and_b32_e32 v3, 64, v207
	global_load_dwordx4 v[26:29], v[6:7], off
	v_xor_b32_e32 v30, 32, v207
	v_add_u32_e32 v3, 64, v3
	v_cmp_lt_i32_e32 vcc, v30, v3
	s_waitcnt vmcnt(4)
	v_mov_b32_e32 v32, v11
	v_cndmask_b32_e32 v30, v207, v30, vcc
	s_waitcnt vmcnt(3)
	v_mov_b32_e32 v33, v15
	v_lshlrev_b32_e32 v46, 2, v30
	v_mov_b32_e32 v30, v10
	v_mov_b32_e32 v31, v14
	s_waitcnt vmcnt(2)
	v_mov_b32_e32 v40, v19
	s_waitcnt vmcnt(1)
	v_mov_b32_e32 v41, v23
	v_mul_f32_e32 v32, v32, v32
	v_mul_f32_e32 v33, v33, v33
	v_mov_b32_e32 v34, v12
	v_mov_b32_e32 v35, v16
	v_mov_b32_e32 v38, v18
	v_mov_b32_e32 v39, v22
	v_mul_f32_e32 v40, v40, v40
	v_mul_f32_e32 v41, v41, v41
	v_fma_f32 v30, v30, v30, v32
	v_fma_f32 v31, v31, v31, v33
	v_mov_b32_e32 v36, v13
	v_mov_b32_e32 v37, v17
	v_mov_b32_e32 v42, v20
	v_mov_b32_e32 v43, v24
	v_fma_f32 v32, v38, v38, v40
	v_fma_f32 v33, v39, v39, v41
	v_fma_f32 v30, v34, v34, v30
	v_fma_f32 v31, v35, v35, v31
	v_mov_b32_e32 v44, v21
	v_mov_b32_e32 v45, v25
	v_fma_f32 v32, v42, v42, v32
	v_fma_f32 v33, v43, v43, v33
	v_fma_f32 v30, v36, v36, v30
	v_fma_f32 v31, v37, v37, v31
	v_fma_f32 v32, v44, v44, v32
	v_fma_f32 v33, v45, v45, v33
	v_add_f32_e32 v30, v30, v31
	v_add_f32_e32 v30, v33, v30
	v_add_f32_e32 v30, v32, v30
	ds_bpermute_b32 v31, v46, v30
	v_xor_b32_e32 v32, 16, v207
	v_cmp_lt_i32_e32 vcc, v32, v3
	s_waitcnt lgkmcnt(0)
	v_add_f32_e32 v30, v30, v31
	v_cndmask_b32_e32 v32, v207, v32, vcc
	v_lshlrev_b32_e32 v32, 2, v32
	ds_bpermute_b32 v31, v32, v30
	v_xor_b32_e32 v32, 8, v207
	v_cmp_lt_i32_e32 vcc, v32, v3
	s_waitcnt lgkmcnt(0)
	v_add_f32_e32 v30, v30, v31
	v_cndmask_b32_e32 v32, v207, v32, vcc
	v_lshlrev_b32_e32 v32, 2, v32
	ds_bpermute_b32 v31, v32, v30
	v_xor_b32_e32 v32, 4, v207
	v_cmp_lt_i32_e32 vcc, v32, v3
	s_waitcnt lgkmcnt(0)
	v_add_f32_e32 v30, v30, v31
	v_cndmask_b32_e32 v32, v207, v32, vcc
	v_lshlrev_b32_e32 v32, 2, v32
	ds_bpermute_b32 v31, v32, v30
	v_xor_b32_e32 v32, 2, v207
	v_cmp_lt_i32_e32 vcc, v32, v3
	s_waitcnt lgkmcnt(0)
	v_add_f32_e32 v30, v30, v31
	v_cndmask_b32_e32 v32, v207, v32, vcc
	v_lshlrev_b32_e32 v32, 2, v32
	ds_bpermute_b32 v31, v32, v30
	v_xor_b32_e32 v32, 1, v207
	v_cmp_lt_i32_e32 vcc, v32, v3
	s_waitcnt lgkmcnt(0)
	v_add_f32_e32 v30, v30, v31
	v_cndmask_b32_e32 v3, v207, v32, vcc
	v_lshlrev_b32_e32 v3, 2, v3
	ds_bpermute_b32 v3, v3, v30
	s_waitcnt lgkmcnt(0)
	v_add_f32_e32 v3, v30, v3
	v_fmamk_f32 v3, v3, 0x3a800000, v204
	v_mul_f32_e32 v30, 0x4b800000, v3
	v_cmp_gt_f32_e32 vcc, s93, v3
	s_nop 1
	v_cndmask_b32_e32 v3, v3, v30, vcc
	v_rsq_f32_e32 v3, v3
	v_lshlrev_b64 v[30:31], 11, v[0:1]
	v_lshl_add_u64 v[30:31], v[8:9], 0, v[30:31]
	v_mul_f32_e32 v1, 0x45800000, v3
	v_cndmask_b32_e32 v32, v3, v1, vcc
	v_mul_f32_e32 v14, v14, v32
	v_mul_f32_e32 v15, v15, v32
	v_mul_f32_e32 v16, v16, v32
	v_mul_f32_e32 v17, v17, v32
	s_waitcnt vmcnt(0)
	v_mul_f32_e32 v14, v26, v14
	v_mul_f32_e32 v15, v27, v15
	v_mul_f32_e32 v16, v28, v16
	v_mul_f32_e32 v17, v29, v17
	v_cvt_pk_bf16_f32 v14, v14, v15
	v_mul_f32_e32 v10, v10, v32
	v_mul_f32_e32 v11, v11, v32
	v_cvt_pk_bf16_f32 v15, v16, v17
	global_store_dwordx2 v[30:31], v[14:15], off
	global_load_dwordx4 v[14:17], v[6:7], off offset:1024
	v_mul_f32_e32 v12, v12, v32
	v_mul_f32_e32 v13, v13, v32
	s_waitcnt vmcnt(0)
	v_mul_f32_e32 v10, v14, v10
	v_mul_f32_e32 v11, v15, v11
	v_mul_f32_e32 v12, v16, v12
	v_mul_f32_e32 v13, v17, v13
	v_cvt_pk_bf16_f32 v10, v10, v11
	v_mul_f32_e32 v14, v22, v32
	v_mul_f32_e32 v15, v23, v32
	v_cvt_pk_bf16_f32 v11, v12, v13
	global_store_dwordx2 v[30:31], v[10:11], off offset:512
	global_load_dwordx4 v[10:13], v[6:7], off offset:2048
	v_mul_f32_e32 v16, v24, v32
	v_mul_f32_e32 v17, v25, v32
	s_waitcnt vmcnt(0)
	v_mul_f32_e32 v10, v10, v14
	v_mul_f32_e32 v11, v11, v15
	v_mul_f32_e32 v12, v12, v16
	v_mul_f32_e32 v13, v13, v17
	v_cvt_pk_bf16_f32 v10, v10, v11
	v_mul_f32_e32 v14, v18, v32
	v_mul_f32_e32 v15, v19, v32
	v_cvt_pk_bf16_f32 v11, v12, v13
	global_store_dwordx2 v[30:31], v[10:11], off offset:1024
	global_load_dwordx4 v[10:13], v[6:7], off offset:3072
	v_mul_f32_e32 v16, v20, v32
	v_mul_f32_e32 v17, v21, v32
	s_waitcnt vmcnt(0)
	v_mul_f32_e32 v10, v10, v14
	v_mul_f32_e32 v11, v11, v15
	v_mul_f32_e32 v12, v12, v16
	v_mul_f32_e32 v13, v13, v17
	v_cvt_pk_bf16_f32 v10, v10, v11
	s_nop 0
	v_cvt_pk_bf16_f32 v11, v12, v13
	global_store_dwordx2 v[30:31], v[10:11], off offset:1536
	s_branch .LBB0_734
